# 16x16x32 K-loops: second k-step fragment reads issued one per MFMA gap right after the first MFMA
# baseline (speedup 1.0000x reference)
.LBB0_20:
	s_mov_b32 s18, 0x10000
	s_mov_b32 s19, 0
	v_lshl_add_u64 v[138:139], s[18:19], 0, v[132:133]
	s_mov_b32 s18, 0x20000
	s_mov_b32 s19, 0
	v_lshl_add_u64 v[194:195], s[18:19], 0, v[132:133]
	s_mov_b32 s18, 0x30000
	s_mov_b32 s19, 0
	v_lshl_add_u64 v[196:197], s[18:19], 0, v[132:133]
	s_mov_b32 s18, 0x10000
	s_mov_b32 s19, 0
	v_lshl_add_u64 v[214:215], s[18:19], 0, v[134:135]
	s_mov_b32 s18, 0x580000
	s_mov_b32 s19, 0
	v_lshl_add_u64 v[232:233], s[18:19], 0, v[134:135]
	s_mov_b32 s18, 0x590000
	s_mov_b32 s19, 0
	v_lshl_add_u64 v[234:235], s[18:19], 0, v[134:135]
	v_lshrrev_b32_e32 v168, 3, v0
	v_and_b32_e32 v170, 15, v168
	v_lshlrev_b32_e32 v169, 1, v170
	v_cmp_gt_u32_e32 vcc, 12, v170
	s_nop 1
	v_mov_b32_e32 v171, 15
	v_cndmask_b32_e64 v171, v171, 8, vcc
	v_cmp_gt_u32_e32 vcc, 4, v170
	v_sub_u32_e32 v169, v169, v171
	v_lshlrev_b32_e32 v171, 1, v170
	v_add_u32_e32 v171, 1, v171
	s_nop 1
	v_cndmask_b32_e32 v169, v169, v171, vcc
	v_and_b32_e32 v168, 16, v168
	v_add_u32_e32 v168, v168, v169
	v_mul_u32_u24_e32 v168, 0x90, v168
	v_and_b32_e32 v169, 7, v0
	v_lshl_add_u32 v236, v169, 4, v168
	v_add_u32_e32 v237, 0x9000, v236
	v_and_b32_e32 v170, 15, v0
	v_lshlrev_b32_e32 v169, 1, v170
	v_cmp_gt_u32_e32 vcc, 12, v170
	s_nop 1
	v_mov_b32_e32 v171, 15
	v_cndmask_b32_e64 v171, v171, 8, vcc
	v_cmp_gt_u32_e32 vcc, 4, v170
	v_sub_u32_e32 v169, v169, v171
	v_lshlrev_b32_e32 v171, 1, v170
	v_add_u32_e32 v171, 1, v171
	s_nop 1
	v_cndmask_b32_e32 v169, v169, v171, vcc
	v_bfe_u32 v168, v0, 4, 2
	v_and_b32_e32 v170, 1, v168
	v_lshrrev_b32_e32 v168, 1, v168
	v_lshl_or_b32 v168, v170, 1, v168
	v_lshlrev_b32_e32 v168, 4, v168
	v_lshrrev_b32_e32 v170, 1, v0
	v_and_b32_e32 v170, 64, v170
	v_add_u32_e32 v170, v170, v169
	v_mul_u32_u24_e32 v170, 0x90, v170
	v_add_u32_e32 v238, v170, v168
	v_and_b32_e32 v170, 64, v0
	v_add_u32_e32 v170, v170, v169
	v_mul_u32_u24_e32 v170, 0x90, v170
	v_add_u32_e32 v239, v170, v168
	s_barrier
	s_waitcnt vmcnt(15)
	ds_write_b128 v236, v[68:71]
	s_waitcnt vmcnt(13)
	ds_write_b128 v236, v[72:75] offset:4608
	s_waitcnt vmcnt(11)
	ds_write_b128 v236, v[76:79] offset:9216
	s_waitcnt vmcnt(9)
	ds_write_b128 v236, v[80:83] offset:13824
	s_waitcnt vmcnt(7)
	ds_write_b128 v236, v[84:87] offset:18432
	s_waitcnt vmcnt(5)
	ds_write_b128 v236, v[88:91] offset:23040
	s_waitcnt vmcnt(3)
	ds_write_b128 v236, v[92:95] offset:27648
	s_waitcnt vmcnt(1)
	ds_write_b128 v236, v[96:99] offset:32256
	global_load_dwordx4 v[68:71], v[132:133], off offset:256
	global_load_dwordx4 v[72:75], v[138:139], off offset:256
	global_load_dwordx4 v[76:79], v[194:195], off offset:256
	global_load_dwordx4 v[80:83], v[196:197], off offset:256
	global_load_dwordx4 v[84:87], v[134:135], off offset:256
	global_load_dwordx4 v[88:91], v[214:215], off offset:256
	global_load_dwordx4 v[92:95], v[232:233], off offset:256
	global_load_dwordx4 v[96:99], v[234:235], off offset:256
	s_waitcnt lgkmcnt(0)
	s_barrier
	ds_read_b128 v[140:143], v238
	ds_read_b128 v[172:175], v239 offset:18432
	ds_read_b128 v[176:179], v239 offset:20736
	ds_read_b128 v[144:147], v238 offset:2304
	ds_read_b128 v[180:183], v239 offset:23040
	ds_read_b128 v[148:151], v238 offset:4608
	ds_read_b128 v[184:187], v239 offset:25344
	ds_read_b128 v[152:155], v238 offset:6912
	s_setprio 1
	s_waitcnt lgkmcnt(6)
	v_mfma_f32_16x16x32_bf16 v[52:55], v[172:175], v[140:143], 0
	ds_write_b128 v237, v[100:103]
	s_waitcnt lgkmcnt(6)
	v_mfma_f32_16x16x32_bf16 v[60:63], v[176:179], v[140:143], 0
	ds_read_b128 v[156:159], v238 offset:64
	s_waitcnt lgkmcnt(6)
	v_mfma_f32_16x16x32_bf16 v[56:59], v[172:175], v[144:147], 0
	ds_read_b128 v[216:219], v239 offset:18496
	ds_write_b128 v237, v[104:107] offset:4608
	v_mfma_f32_16x16x32_bf16 v[64:67], v[176:179], v[144:147], 0
	ds_read_b128 v[220:223], v239 offset:20800
	s_waitcnt lgkmcnt(8)
	v_mfma_f32_16x16x32_bf16 v[36:39], v[180:183], v[140:143], 0
	ds_read_b128 v[160:163], v238 offset:2368
	ds_write_b128 v237, v[108:111] offset:9216
	global_load_dwordx4 v[100:103], v[132:133], off offset:384
	v_mfma_f32_16x16x32_bf16 v[40:43], v[180:183], v[144:147], 0
	ds_read_b128 v[224:227], v239 offset:23104
	s_waitcnt lgkmcnt(10)
	v_mfma_f32_16x16x32_bf16 v[20:23], v[172:175], v[148:151], 0
	ds_read_b128 v[164:167], v238 offset:4672
	v_mfma_f32_16x16x32_bf16 v[28:31], v[176:179], v[148:151], 0
	ds_read_b128 v[228:231], v239 offset:25408
	v_mfma_f32_16x16x32_bf16 v[4:7], v[180:183], v[148:151], 0
	ds_read_b128 v[168:171], v238 offset:6976
	s_waitcnt lgkmcnt(12)
	v_mfma_f32_16x16x32_bf16 v[44:47], v[184:187], v[140:143], 0
	v_mfma_f32_16x16x32_bf16 v[48:51], v[184:187], v[144:147], 0
	ds_write_b128 v237, v[112:115] offset:13824
	global_load_dwordx4 v[104:107], v[138:139], off offset:384
	v_mfma_f32_16x16x32_bf16 v[12:15], v[184:187], v[148:151], 0
	s_waitcnt lgkmcnt(12)
	v_mfma_f32_16x16x32_bf16 v[24:27], v[172:175], v[152:155], 0
	ds_write_b128 v237, v[116:119] offset:18432
	global_load_dwordx4 v[108:111], v[194:195], off offset:384
	v_mfma_f32_16x16x32_bf16 v[32:35], v[176:179], v[152:155], 0
	v_mfma_f32_16x16x32_bf16 v[8:11], v[180:183], v[152:155], 0
	v_mfma_f32_16x16x32_bf16 v[16:19], v[184:187], v[152:155], 0
	s_waitcnt lgkmcnt(10)
	v_mfma_f32_16x16x32_bf16 v[52:55], v[216:219], v[156:159], v[52:55]
	s_waitcnt lgkmcnt(8)
	v_mfma_f32_16x16x32_bf16 v[60:63], v[220:223], v[156:159], v[60:63]
	s_waitcnt lgkmcnt(7)
	v_mfma_f32_16x16x32_bf16 v[56:59], v[216:219], v[160:163], v[56:59]
	ds_write_b128 v237, v[120:123] offset:23040
	global_load_dwordx4 v[112:115], v[196:197], off offset:384
	v_mfma_f32_16x16x32_bf16 v[64:67], v[220:223], v[160:163], v[64:67]
	s_waitcnt lgkmcnt(6)
	v_mfma_f32_16x16x32_bf16 v[36:39], v[224:227], v[156:159], v[36:39]
	ds_write_b128 v237, v[124:127] offset:27648
	global_load_dwordx4 v[116:119], v[134:135], off offset:384
	v_mfma_f32_16x16x32_bf16 v[40:43], v[224:227], v[160:163], v[40:43]
	s_waitcnt lgkmcnt(6)
	v_mfma_f32_16x16x32_bf16 v[20:23], v[216:219], v[164:167], v[20:23]
	s_waitcnt vmcnt(13)
	ds_write_b128 v237, v[128:131] offset:32256
	global_load_dwordx4 v[120:123], v[214:215], off offset:384
	v_mfma_f32_16x16x32_bf16 v[28:31], v[220:223], v[164:167], v[28:31]
	v_mfma_f32_16x16x32_bf16 v[4:7], v[224:227], v[164:167], v[4:7]
	global_load_dwordx4 v[124:127], v[232:233], off offset:384
	s_waitcnt lgkmcnt(6)
	v_mfma_f32_16x16x32_bf16 v[44:47], v[228:231], v[156:159], v[44:47]
	v_mfma_f32_16x16x32_bf16 v[48:51], v[228:231], v[160:163], v[48:51]
	global_load_dwordx4 v[128:131], v[234:235], off offset:384
	v_mfma_f32_16x16x32_bf16 v[12:15], v[228:231], v[164:167], v[12:15]
	s_waitcnt lgkmcnt(5)
	v_mfma_f32_16x16x32_bf16 v[24:27], v[216:219], v[168:171], v[24:27]
	v_mfma_f32_16x16x32_bf16 v[32:35], v[220:223], v[168:171], v[32:35]
	v_mfma_f32_16x16x32_bf16 v[8:11], v[224:227], v[168:171], v[8:11]
	v_mfma_f32_16x16x32_bf16 v[16:19], v[228:231], v[168:171], v[16:19]
	s_setprio 0
	s_waitcnt lgkmcnt(0)
	s_barrier
	ds_read_b128 v[140:143], v238 offset:36864
	ds_read_b128 v[172:175], v239 offset:55296
	ds_read_b128 v[176:179], v239 offset:57600
	ds_read_b128 v[144:147], v238 offset:39168
	ds_read_b128 v[180:183], v239 offset:59904
	ds_read_b128 v[148:151], v238 offset:41472
	ds_read_b128 v[184:187], v239 offset:62208
	ds_read_b128 v[152:155], v238 offset:43776
	s_setprio 1
	s_waitcnt lgkmcnt(6)
	v_mfma_f32_16x16x32_bf16 v[52:55], v[172:175], v[140:143], v[52:55]
	s_waitcnt vmcnt(15)
	ds_write_b128 v236, v[68:71]
	s_waitcnt lgkmcnt(6)
	v_mfma_f32_16x16x32_bf16 v[60:63], v[176:179], v[140:143], v[60:63]
	ds_read_b128 v[156:159], v238 offset:36928
	s_waitcnt lgkmcnt(6)
	v_mfma_f32_16x16x32_bf16 v[56:59], v[172:175], v[144:147], v[56:59]
	ds_read_b128 v[216:219], v239 offset:55360
	s_waitcnt vmcnt(14)
	ds_write_b128 v236, v[72:75] offset:4608
	v_mfma_f32_16x16x32_bf16 v[64:67], v[176:179], v[144:147], v[64:67]
	ds_read_b128 v[220:223], v239 offset:57664
	s_waitcnt lgkmcnt(8)
	v_mfma_f32_16x16x32_bf16 v[36:39], v[180:183], v[140:143], v[36:39]
	ds_read_b128 v[160:163], v238 offset:39232
	s_waitcnt vmcnt(13)
	ds_write_b128 v236, v[76:79] offset:9216
	global_load_dwordx4 v[68:71], v[132:133], off offset:512
	v_mfma_f32_16x16x32_bf16 v[40:43], v[180:183], v[144:147], v[40:43]
	ds_read_b128 v[224:227], v239 offset:59968
	s_waitcnt lgkmcnt(10)
	v_mfma_f32_16x16x32_bf16 v[20:23], v[172:175], v[148:151], v[20:23]
	ds_read_b128 v[164:167], v238 offset:41536
	v_mfma_f32_16x16x32_bf16 v[28:31], v[176:179], v[148:151], v[28:31]
	ds_read_b128 v[228:231], v239 offset:62272
	v_mfma_f32_16x16x32_bf16 v[4:7], v[180:183], v[148:151], v[4:7]
	ds_read_b128 v[168:171], v238 offset:43840
	s_waitcnt lgkmcnt(12)
	v_mfma_f32_16x16x32_bf16 v[44:47], v[184:187], v[140:143], v[44:47]
	v_mfma_f32_16x16x32_bf16 v[48:51], v[184:187], v[144:147], v[48:51]
	s_waitcnt vmcnt(13)
	ds_write_b128 v236, v[80:83] offset:13824
	global_load_dwordx4 v[72:75], v[138:139], off offset:512
	v_mfma_f32_16x16x32_bf16 v[12:15], v[184:187], v[148:151], v[12:15]
	s_waitcnt lgkmcnt(12)
	v_mfma_f32_16x16x32_bf16 v[24:27], v[172:175], v[152:155], v[24:27]
	s_waitcnt vmcnt(13)
	ds_write_b128 v236, v[84:87] offset:18432
	global_load_dwordx4 v[76:79], v[194:195], off offset:512
	v_mfma_f32_16x16x32_bf16 v[32:35], v[176:179], v[152:155], v[32:35]
	v_mfma_f32_16x16x32_bf16 v[8:11], v[180:183], v[152:155], v[8:11]
	v_mfma_f32_16x16x32_bf16 v[16:19], v[184:187], v[152:155], v[16:19]
	s_waitcnt lgkmcnt(10)
	v_mfma_f32_16x16x32_bf16 v[52:55], v[216:219], v[156:159], v[52:55]
	s_waitcnt lgkmcnt(8)
	v_mfma_f32_16x16x32_bf16 v[60:63], v[220:223], v[156:159], v[60:63]
	s_waitcnt lgkmcnt(7)
	v_mfma_f32_16x16x32_bf16 v[56:59], v[216:219], v[160:163], v[56:59]
	s_waitcnt vmcnt(13)
	ds_write_b128 v236, v[88:91] offset:23040
	global_load_dwordx4 v[80:83], v[196:197], off offset:512
	v_mfma_f32_16x16x32_bf16 v[64:67], v[220:223], v[160:163], v[64:67]
	s_waitcnt lgkmcnt(6)
	v_mfma_f32_16x16x32_bf16 v[36:39], v[224:227], v[156:159], v[36:39]
	s_waitcnt vmcnt(13)
	ds_write_b128 v236, v[92:95] offset:27648
	global_load_dwordx4 v[84:87], v[134:135], off offset:512
	v_mfma_f32_16x16x32_bf16 v[40:43], v[224:227], v[160:163], v[40:43]
	s_waitcnt lgkmcnt(6)
	v_mfma_f32_16x16x32_bf16 v[20:23], v[216:219], v[164:167], v[20:23]
	s_waitcnt vmcnt(13)
	ds_write_b128 v236, v[96:99] offset:32256
	global_load_dwordx4 v[88:91], v[214:215], off offset:512
	v_mfma_f32_16x16x32_bf16 v[28:31], v[220:223], v[164:167], v[28:31]
	v_mfma_f32_16x16x32_bf16 v[4:7], v[224:227], v[164:167], v[4:7]
	global_load_dwordx4 v[92:95], v[232:233], off offset:512
	s_waitcnt lgkmcnt(6)
	v_mfma_f32_16x16x32_bf16 v[44:47], v[228:231], v[156:159], v[44:47]
	v_mfma_f32_16x16x32_bf16 v[48:51], v[228:231], v[160:163], v[48:51]
	global_load_dwordx4 v[96:99], v[234:235], off offset:512
	v_mfma_f32_16x16x32_bf16 v[12:15], v[228:231], v[164:167], v[12:15]
	s_waitcnt lgkmcnt(5)
	v_mfma_f32_16x16x32_bf16 v[24:27], v[216:219], v[168:171], v[24:27]
	v_mfma_f32_16x16x32_bf16 v[32:35], v[220:223], v[168:171], v[32:35]
	v_mfma_f32_16x16x32_bf16 v[8:11], v[224:227], v[168:171], v[8:11]
	v_mfma_f32_16x16x32_bf16 v[16:19], v[228:231], v[168:171], v[16:19]
	s_setprio 0
	s_waitcnt lgkmcnt(0)
	s_barrier
	ds_read_b128 v[140:143], v238
	ds_read_b128 v[172:175], v239 offset:18432
	ds_read_b128 v[176:179], v239 offset:20736
	ds_read_b128 v[144:147], v238 offset:2304
	ds_read_b128 v[180:183], v239 offset:23040
	ds_read_b128 v[148:151], v238 offset:4608
	ds_read_b128 v[184:187], v239 offset:25344
	ds_read_b128 v[152:155], v238 offset:6912
	s_setprio 1
	s_waitcnt lgkmcnt(6)
	v_mfma_f32_16x16x32_bf16 v[52:55], v[172:175], v[140:143], v[52:55]
	s_waitcnt vmcnt(15)
	ds_write_b128 v237, v[100:103]
	s_waitcnt lgkmcnt(6)
	v_mfma_f32_16x16x32_bf16 v[60:63], v[176:179], v[140:143], v[60:63]
	ds_read_b128 v[156:159], v238 offset:64
	s_waitcnt lgkmcnt(6)
	v_mfma_f32_16x16x32_bf16 v[56:59], v[172:175], v[144:147], v[56:59]
	ds_read_b128 v[216:219], v239 offset:18496
	s_waitcnt vmcnt(14)
	ds_write_b128 v237, v[104:107] offset:4608
	v_mfma_f32_16x16x32_bf16 v[64:67], v[176:179], v[144:147], v[64:67]
	ds_read_b128 v[220:223], v239 offset:20800
	s_waitcnt lgkmcnt(8)
	v_mfma_f32_16x16x32_bf16 v[36:39], v[180:183], v[140:143], v[36:39]
	ds_read_b128 v[160:163], v238 offset:2368
	s_waitcnt vmcnt(13)
	ds_write_b128 v237, v[108:111] offset:9216
	global_load_dwordx4 v[100:103], v[132:133], off offset:640
	v_mfma_f32_16x16x32_bf16 v[40:43], v[180:183], v[144:147], v[40:43]
	ds_read_b128 v[224:227], v239 offset:23104
	s_waitcnt lgkmcnt(10)
	v_mfma_f32_16x16x32_bf16 v[20:23], v[172:175], v[148:151], v[20:23]
	ds_read_b128 v[164:167], v238 offset:4672
	v_mfma_f32_16x16x32_bf16 v[28:31], v[176:179], v[148:151], v[28:31]
	ds_read_b128 v[228:231], v239 offset:25408
	v_mfma_f32_16x16x32_bf16 v[4:7], v[180:183], v[148:151], v[4:7]
	ds_read_b128 v[168:171], v238 offset:6976
	s_waitcnt lgkmcnt(12)
	v_mfma_f32_16x16x32_bf16 v[44:47], v[184:187], v[140:143], v[44:47]
	v_mfma_f32_16x16x32_bf16 v[48:51], v[184:187], v[144:147], v[48:51]
	s_waitcnt vmcnt(13)
	ds_write_b128 v237, v[112:115] offset:13824
	global_load_dwordx4 v[104:107], v[138:139], off offset:640
	v_mfma_f32_16x16x32_bf16 v[12:15], v[184:187], v[148:151], v[12:15]
	s_waitcnt lgkmcnt(12)
	v_mfma_f32_16x16x32_bf16 v[24:27], v[172:175], v[152:155], v[24:27]
	s_waitcnt vmcnt(13)
	ds_write_b128 v237, v[116:119] offset:18432
	global_load_dwordx4 v[108:111], v[194:195], off offset:640
	v_mfma_f32_16x16x32_bf16 v[32:35], v[176:179], v[152:155], v[32:35]
	v_mfma_f32_16x16x32_bf16 v[8:11], v[180:183], v[152:155], v[8:11]
	v_mfma_f32_16x16x32_bf16 v[16:19], v[184:187], v[152:155], v[16:19]
	s_waitcnt lgkmcnt(10)
	v_mfma_f32_16x16x32_bf16 v[52:55], v[216:219], v[156:159], v[52:55]
	s_waitcnt lgkmcnt(8)
	v_mfma_f32_16x16x32_bf16 v[60:63], v[220:223], v[156:159], v[60:63]
	s_waitcnt lgkmcnt(7)
	v_mfma_f32_16x16x32_bf16 v[56:59], v[216:219], v[160:163], v[56:59]
	s_waitcnt vmcnt(13)
	ds_write_b128 v237, v[120:123] offset:23040
	global_load_dwordx4 v[112:115], v[196:197], off offset:640
	v_mfma_f32_16x16x32_bf16 v[64:67], v[220:223], v[160:163], v[64:67]
	s_waitcnt lgkmcnt(6)
	v_mfma_f32_16x16x32_bf16 v[36:39], v[224:227], v[156:159], v[36:39]
	s_waitcnt vmcnt(13)
	ds_write_b128 v237, v[124:127] offset:27648
	global_load_dwordx4 v[116:119], v[134:135], off offset:640
	v_mfma_f32_16x16x32_bf16 v[40:43], v[224:227], v[160:163], v[40:43]
	s_waitcnt lgkmcnt(6)
	v_mfma_f32_16x16x32_bf16 v[20:23], v[216:219], v[164:167], v[20:23]
	s_waitcnt vmcnt(13)
	ds_write_b128 v237, v[128:131] offset:32256
	global_load_dwordx4 v[120:123], v[214:215], off offset:640
	v_mfma_f32_16x16x32_bf16 v[28:31], v[220:223], v[164:167], v[28:31]
	v_mfma_f32_16x16x32_bf16 v[4:7], v[224:227], v[164:167], v[4:7]
	global_load_dwordx4 v[124:127], v[232:233], off offset:640
	s_waitcnt lgkmcnt(6)
	v_mfma_f32_16x16x32_bf16 v[44:47], v[228:231], v[156:159], v[44:47]
	v_mfma_f32_16x16x32_bf16 v[48:51], v[228:231], v[160:163], v[48:51]
	global_load_dwordx4 v[128:131], v[234:235], off offset:640
	v_mfma_f32_16x16x32_bf16 v[12:15], v[228:231], v[164:167], v[12:15]
	s_waitcnt lgkmcnt(5)
	v_mfma_f32_16x16x32_bf16 v[24:27], v[216:219], v[168:171], v[24:27]
	v_mfma_f32_16x16x32_bf16 v[32:35], v[220:223], v[168:171], v[32:35]
	v_mfma_f32_16x16x32_bf16 v[8:11], v[224:227], v[168:171], v[8:11]
	v_mfma_f32_16x16x32_bf16 v[16:19], v[228:231], v[168:171], v[16:19]
	s_setprio 0
	s_waitcnt lgkmcnt(0)
	s_barrier
	ds_read_b128 v[140:143], v238 offset:36864
	ds_read_b128 v[172:175], v239 offset:55296
	ds_read_b128 v[176:179], v239 offset:57600
	ds_read_b128 v[144:147], v238 offset:39168
	ds_read_b128 v[180:183], v239 offset:59904
	ds_read_b128 v[148:151], v238 offset:41472
	ds_read_b128 v[184:187], v239 offset:62208
	ds_read_b128 v[152:155], v238 offset:43776
	s_setprio 1
	s_waitcnt lgkmcnt(6)
	v_mfma_f32_16x16x32_bf16 v[52:55], v[172:175], v[140:143], v[52:55]
	s_waitcnt vmcnt(15)
	ds_write_b128 v236, v[68:71]
	s_waitcnt lgkmcnt(6)
	v_mfma_f32_16x16x32_bf16 v[60:63], v[176:179], v[140:143], v[60:63]
	ds_read_b128 v[156:159], v238 offset:36928
	s_waitcnt lgkmcnt(6)
	v_mfma_f32_16x16x32_bf16 v[56:59], v[172:175], v[144:147], v[56:59]
	ds_read_b128 v[216:219], v239 offset:55360
	s_waitcnt vmcnt(14)
	ds_write_b128 v236, v[72:75] offset:4608
	v_mfma_f32_16x16x32_bf16 v[64:67], v[176:179], v[144:147], v[64:67]
	ds_read_b128 v[220:223], v239 offset:57664
	s_waitcnt lgkmcnt(8)
	v_mfma_f32_16x16x32_bf16 v[36:39], v[180:183], v[140:143], v[36:39]
	ds_read_b128 v[160:163], v238 offset:39232
	s_waitcnt vmcnt(13)
	ds_write_b128 v236, v[76:79] offset:9216
	global_load_dwordx4 v[68:71], v[132:133], off offset:768
	v_mfma_f32_16x16x32_bf16 v[40:43], v[180:183], v[144:147], v[40:43]
	ds_read_b128 v[224:227], v239 offset:59968
	s_waitcnt lgkmcnt(10)
	v_mfma_f32_16x16x32_bf16 v[20:23], v[172:175], v[148:151], v[20:23]
	ds_read_b128 v[164:167], v238 offset:41536
	v_mfma_f32_16x16x32_bf16 v[28:31], v[176:179], v[148:151], v[28:31]
	ds_read_b128 v[228:231], v239 offset:62272
	v_mfma_f32_16x16x32_bf16 v[4:7], v[180:183], v[148:151], v[4:7]
	ds_read_b128 v[168:171], v238 offset:43840
	s_waitcnt lgkmcnt(12)
	v_mfma_f32_16x16x32_bf16 v[44:47], v[184:187], v[140:143], v[44:47]
	v_mfma_f32_16x16x32_bf16 v[48:51], v[184:187], v[144:147], v[48:51]
	s_waitcnt vmcnt(13)
	ds_write_b128 v236, v[80:83] offset:13824
	global_load_dwordx4 v[72:75], v[138:139], off offset:768
	v_mfma_f32_16x16x32_bf16 v[12:15], v[184:187], v[148:151], v[12:15]
	s_waitcnt lgkmcnt(12)
	v_mfma_f32_16x16x32_bf16 v[24:27], v[172:175], v[152:155], v[24:27]
	s_waitcnt vmcnt(13)
	ds_write_b128 v236, v[84:87] offset:18432
	global_load_dwordx4 v[76:79], v[194:195], off offset:768
	v_mfma_f32_16x16x32_bf16 v[32:35], v[176:179], v[152:155], v[32:35]
	v_mfma_f32_16x16x32_bf16 v[8:11], v[180:183], v[152:155], v[8:11]
	v_mfma_f32_16x16x32_bf16 v[16:19], v[184:187], v[152:155], v[16:19]
	s_waitcnt lgkmcnt(10)
	v_mfma_f32_16x16x32_bf16 v[52:55], v[216:219], v[156:159], v[52:55]
	s_waitcnt lgkmcnt(8)
	v_mfma_f32_16x16x32_bf16 v[60:63], v[220:223], v[156:159], v[60:63]
	s_waitcnt lgkmcnt(7)
	v_mfma_f32_16x16x32_bf16 v[56:59], v[216:219], v[160:163], v[56:59]
	s_waitcnt vmcnt(13)
	ds_write_b128 v236, v[88:91] offset:23040
	global_load_dwordx4 v[80:83], v[196:197], off offset:768
	v_mfma_f32_16x16x32_bf16 v[64:67], v[220:223], v[160:163], v[64:67]
	s_waitcnt lgkmcnt(6)
	v_mfma_f32_16x16x32_bf16 v[36:39], v[224:227], v[156:159], v[36:39]
	s_waitcnt vmcnt(13)
	ds_write_b128 v236, v[92:95] offset:27648
	global_load_dwordx4 v[84:87], v[134:135], off offset:768
	v_mfma_f32_16x16x32_bf16 v[40:43], v[224:227], v[160:163], v[40:43]
	s_waitcnt lgkmcnt(6)
	v_mfma_f32_16x16x32_bf16 v[20:23], v[216:219], v[164:167], v[20:23]
	s_waitcnt vmcnt(13)
	ds_write_b128 v236, v[96:99] offset:32256
	global_load_dwordx4 v[88:91], v[214:215], off offset:768
	v_mfma_f32_16x16x32_bf16 v[28:31], v[220:223], v[164:167], v[28:31]
	v_mfma_f32_16x16x32_bf16 v[4:7], v[224:227], v[164:167], v[4:7]
	global_load_dwordx4 v[92:95], v[232:233], off offset:768
	s_waitcnt lgkmcnt(6)
	v_mfma_f32_16x16x32_bf16 v[44:47], v[228:231], v[156:159], v[44:47]
	v_mfma_f32_16x16x32_bf16 v[48:51], v[228:231], v[160:163], v[48:51]
	global_load_dwordx4 v[96:99], v[234:235], off offset:768
	v_mfma_f32_16x16x32_bf16 v[12:15], v[228:231], v[164:167], v[12:15]
	s_waitcnt lgkmcnt(5)
	v_mfma_f32_16x16x32_bf16 v[24:27], v[216:219], v[168:171], v[24:27]
	v_mfma_f32_16x16x32_bf16 v[32:35], v[220:223], v[168:171], v[32:35]
	v_mfma_f32_16x16x32_bf16 v[8:11], v[224:227], v[168:171], v[8:11]
	v_mfma_f32_16x16x32_bf16 v[16:19], v[228:231], v[168:171], v[16:19]
	s_setprio 0
	s_waitcnt lgkmcnt(0)
	s_barrier
	ds_read_b128 v[140:143], v238
	ds_read_b128 v[172:175], v239 offset:18432
	ds_read_b128 v[176:179], v239 offset:20736
	ds_read_b128 v[144:147], v238 offset:2304
	ds_read_b128 v[180:183], v239 offset:23040
	ds_read_b128 v[148:151], v238 offset:4608
	ds_read_b128 v[184:187], v239 offset:25344
	ds_read_b128 v[152:155], v238 offset:6912
	s_setprio 1
	s_waitcnt lgkmcnt(6)
	v_mfma_f32_16x16x32_bf16 v[52:55], v[172:175], v[140:143], v[52:55]
	s_waitcnt vmcnt(15)
	ds_write_b128 v237, v[100:103]
	s_waitcnt lgkmcnt(6)
	v_mfma_f32_16x16x32_bf16 v[60:63], v[176:179], v[140:143], v[60:63]
	ds_read_b128 v[156:159], v238 offset:64
	s_waitcnt lgkmcnt(6)
	v_mfma_f32_16x16x32_bf16 v[56:59], v[172:175], v[144:147], v[56:59]
	ds_read_b128 v[216:219], v239 offset:18496
	s_waitcnt vmcnt(14)
	ds_write_b128 v237, v[104:107] offset:4608
	v_mfma_f32_16x16x32_bf16 v[64:67], v[176:179], v[144:147], v[64:67]
	ds_read_b128 v[220:223], v239 offset:20800
	s_waitcnt lgkmcnt(8)
	v_mfma_f32_16x16x32_bf16 v[36:39], v[180:183], v[140:143], v[36:39]
	ds_read_b128 v[160:163], v238 offset:2368
	s_waitcnt vmcnt(13)
	ds_write_b128 v237, v[108:111] offset:9216
	global_load_dwordx4 v[100:103], v[132:133], off offset:896
	v_mfma_f32_16x16x32_bf16 v[40:43], v[180:183], v[144:147], v[40:43]
	ds_read_b128 v[224:227], v239 offset:23104
	s_waitcnt lgkmcnt(10)
	v_mfma_f32_16x16x32_bf16 v[20:23], v[172:175], v[148:151], v[20:23]
	ds_read_b128 v[164:167], v238 offset:4672
	v_mfma_f32_16x16x32_bf16 v[28:31], v[176:179], v[148:151], v[28:31]
	ds_read_b128 v[228:231], v239 offset:25408
	v_mfma_f32_16x16x32_bf16 v[4:7], v[180:183], v[148:151], v[4:7]
	ds_read_b128 v[168:171], v238 offset:6976
	s_waitcnt lgkmcnt(12)
	v_mfma_f32_16x16x32_bf16 v[44:47], v[184:187], v[140:143], v[44:47]
	v_mfma_f32_16x16x32_bf16 v[48:51], v[184:187], v[144:147], v[48:51]
	s_waitcnt vmcnt(13)
	ds_write_b128 v237, v[112:115] offset:13824
	global_load_dwordx4 v[104:107], v[138:139], off offset:896
	v_mfma_f32_16x16x32_bf16 v[12:15], v[184:187], v[148:151], v[12:15]
	s_waitcnt lgkmcnt(12)
	v_mfma_f32_16x16x32_bf16 v[24:27], v[172:175], v[152:155], v[24:27]
	s_waitcnt vmcnt(13)
	ds_write_b128 v237, v[116:119] offset:18432
	global_load_dwordx4 v[108:111], v[194:195], off offset:896
	v_mfma_f32_16x16x32_bf16 v[32:35], v[176:179], v[152:155], v[32:35]
	v_mfma_f32_16x16x32_bf16 v[8:11], v[180:183], v[152:155], v[8:11]
	v_mfma_f32_16x16x32_bf16 v[16:19], v[184:187], v[152:155], v[16:19]
	s_waitcnt lgkmcnt(10)
	v_mfma_f32_16x16x32_bf16 v[52:55], v[216:219], v[156:159], v[52:55]
	s_waitcnt lgkmcnt(8)
	v_mfma_f32_16x16x32_bf16 v[60:63], v[220:223], v[156:159], v[60:63]
	s_waitcnt lgkmcnt(7)
	v_mfma_f32_16x16x32_bf16 v[56:59], v[216:219], v[160:163], v[56:59]
	s_waitcnt vmcnt(13)
	ds_write_b128 v237, v[120:123] offset:23040
	global_load_dwordx4 v[112:115], v[196:197], off offset:896
	v_mfma_f32_16x16x32_bf16 v[64:67], v[220:223], v[160:163], v[64:67]
	s_waitcnt lgkmcnt(6)
	v_mfma_f32_16x16x32_bf16 v[36:39], v[224:227], v[156:159], v[36:39]
	s_waitcnt vmcnt(13)
	ds_write_b128 v237, v[124:127] offset:27648
	global_load_dwordx4 v[116:119], v[134:135], off offset:896
	v_mfma_f32_16x16x32_bf16 v[40:43], v[224:227], v[160:163], v[40:43]
	s_waitcnt lgkmcnt(6)
	v_mfma_f32_16x16x32_bf16 v[20:23], v[216:219], v[164:167], v[20:23]
	s_waitcnt vmcnt(13)
	ds_write_b128 v237, v[128:131] offset:32256
	global_load_dwordx4 v[120:123], v[214:215], off offset:896
	v_mfma_f32_16x16x32_bf16 v[28:31], v[220:223], v[164:167], v[28:31]
	v_mfma_f32_16x16x32_bf16 v[4:7], v[224:227], v[164:167], v[4:7]
	global_load_dwordx4 v[124:127], v[232:233], off offset:896
	s_waitcnt lgkmcnt(6)
	v_mfma_f32_16x16x32_bf16 v[44:47], v[228:231], v[156:159], v[44:47]
	v_mfma_f32_16x16x32_bf16 v[48:51], v[228:231], v[160:163], v[48:51]
	global_load_dwordx4 v[128:131], v[234:235], off offset:896
	v_mfma_f32_16x16x32_bf16 v[12:15], v[228:231], v[164:167], v[12:15]
	s_waitcnt lgkmcnt(5)
	v_mfma_f32_16x16x32_bf16 v[24:27], v[216:219], v[168:171], v[24:27]
	v_mfma_f32_16x16x32_bf16 v[32:35], v[220:223], v[168:171], v[32:35]
	v_mfma_f32_16x16x32_bf16 v[8:11], v[224:227], v[168:171], v[8:11]
	v_mfma_f32_16x16x32_bf16 v[16:19], v[228:231], v[168:171], v[16:19]
	s_setprio 0
	s_waitcnt lgkmcnt(0)
	s_barrier
	ds_read_b128 v[140:143], v238 offset:36864
	ds_read_b128 v[172:175], v239 offset:55296
	ds_read_b128 v[176:179], v239 offset:57600
	ds_read_b128 v[144:147], v238 offset:39168
	ds_read_b128 v[180:183], v239 offset:59904
	ds_read_b128 v[148:151], v238 offset:41472
	ds_read_b128 v[184:187], v239 offset:62208
	ds_read_b128 v[152:155], v238 offset:43776
	s_setprio 1
	s_waitcnt lgkmcnt(6)
	v_mfma_f32_16x16x32_bf16 v[52:55], v[172:175], v[140:143], v[52:55]
	s_waitcnt vmcnt(15)
	ds_write_b128 v236, v[68:71]
	s_waitcnt lgkmcnt(6)
	v_mfma_f32_16x16x32_bf16 v[60:63], v[176:179], v[140:143], v[60:63]
	ds_read_b128 v[156:159], v238 offset:36928
	s_waitcnt lgkmcnt(6)
	v_mfma_f32_16x16x32_bf16 v[56:59], v[172:175], v[144:147], v[56:59]
	ds_read_b128 v[216:219], v239 offset:55360
	s_waitcnt vmcnt(14)
	ds_write_b128 v236, v[72:75] offset:4608
	v_mfma_f32_16x16x32_bf16 v[64:67], v[176:179], v[144:147], v[64:67]
	ds_read_b128 v[220:223], v239 offset:57664
	s_waitcnt lgkmcnt(8)
	v_mfma_f32_16x16x32_bf16 v[36:39], v[180:183], v[140:143], v[36:39]
	ds_read_b128 v[160:163], v238 offset:39232
	s_waitcnt vmcnt(13)
	ds_write_b128 v236, v[76:79] offset:9216
	global_load_dwordx4 v[68:71], v[132:133], off offset:1024
	v_mfma_f32_16x16x32_bf16 v[40:43], v[180:183], v[144:147], v[40:43]
	ds_read_b128 v[224:227], v239 offset:59968
	s_waitcnt lgkmcnt(10)
	v_mfma_f32_16x16x32_bf16 v[20:23], v[172:175], v[148:151], v[20:23]
	ds_read_b128 v[164:167], v238 offset:41536
	v_mfma_f32_16x16x32_bf16 v[28:31], v[176:179], v[148:151], v[28:31]
	ds_read_b128 v[228:231], v239 offset:62272
	v_mfma_f32_16x16x32_bf16 v[4:7], v[180:183], v[148:151], v[4:7]
	ds_read_b128 v[168:171], v238 offset:43840
	s_waitcnt lgkmcnt(12)
	v_mfma_f32_16x16x32_bf16 v[44:47], v[184:187], v[140:143], v[44:47]
	v_mfma_f32_16x16x32_bf16 v[48:51], v[184:187], v[144:147], v[48:51]
	s_waitcnt vmcnt(13)
	ds_write_b128 v236, v[80:83] offset:13824
	global_load_dwordx4 v[72:75], v[138:139], off offset:1024
	v_mfma_f32_16x16x32_bf16 v[12:15], v[184:187], v[148:151], v[12:15]
	s_waitcnt lgkmcnt(12)
	v_mfma_f32_16x16x32_bf16 v[24:27], v[172:175], v[152:155], v[24:27]
	s_waitcnt vmcnt(13)
	ds_write_b128 v236, v[84:87] offset:18432
	global_load_dwordx4 v[76:79], v[194:195], off offset:1024
	v_mfma_f32_16x16x32_bf16 v[32:35], v[176:179], v[152:155], v[32:35]
	v_mfma_f32_16x16x32_bf16 v[8:11], v[180:183], v[152:155], v[8:11]
	v_mfma_f32_16x16x32_bf16 v[16:19], v[184:187], v[152:155], v[16:19]
	s_waitcnt lgkmcnt(10)
	v_mfma_f32_16x16x32_bf16 v[52:55], v[216:219], v[156:159], v[52:55]
	s_waitcnt lgkmcnt(8)
	v_mfma_f32_16x16x32_bf16 v[60:63], v[220:223], v[156:159], v[60:63]
	s_waitcnt lgkmcnt(7)
	v_mfma_f32_16x16x32_bf16 v[56:59], v[216:219], v[160:163], v[56:59]
	s_waitcnt vmcnt(13)
	ds_write_b128 v236, v[88:91] offset:23040
	global_load_dwordx4 v[80:83], v[196:197], off offset:1024
	v_mfma_f32_16x16x32_bf16 v[64:67], v[220:223], v[160:163], v[64:67]
	s_waitcnt lgkmcnt(6)
	v_mfma_f32_16x16x32_bf16 v[36:39], v[224:227], v[156:159], v[36:39]
	s_waitcnt vmcnt(13)
	ds_write_b128 v236, v[92:95] offset:27648
	global_load_dwordx4 v[84:87], v[134:135], off offset:1024
	v_mfma_f32_16x16x32_bf16 v[40:43], v[224:227], v[160:163], v[40:43]
	s_waitcnt lgkmcnt(6)
	v_mfma_f32_16x16x32_bf16 v[20:23], v[216:219], v[164:167], v[20:23]
	s_waitcnt vmcnt(13)
	ds_write_b128 v236, v[96:99] offset:32256
	global_load_dwordx4 v[88:91], v[214:215], off offset:1024
	v_mfma_f32_16x16x32_bf16 v[28:31], v[220:223], v[164:167], v[28:31]
	v_mfma_f32_16x16x32_bf16 v[4:7], v[224:227], v[164:167], v[4:7]
	global_load_dwordx4 v[92:95], v[232:233], off offset:1024
	s_waitcnt lgkmcnt(6)
	v_mfma_f32_16x16x32_bf16 v[44:47], v[228:231], v[156:159], v[44:47]
	v_mfma_f32_16x16x32_bf16 v[48:51], v[228:231], v[160:163], v[48:51]
	global_load_dwordx4 v[96:99], v[234:235], off offset:1024
	v_mfma_f32_16x16x32_bf16 v[12:15], v[228:231], v[164:167], v[12:15]
	s_waitcnt lgkmcnt(5)
	v_mfma_f32_16x16x32_bf16 v[24:27], v[216:219], v[168:171], v[24:27]
	v_mfma_f32_16x16x32_bf16 v[32:35], v[220:223], v[168:171], v[32:35]
	v_mfma_f32_16x16x32_bf16 v[8:11], v[224:227], v[168:171], v[8:11]
	v_mfma_f32_16x16x32_bf16 v[16:19], v[228:231], v[168:171], v[16:19]
	s_setprio 0
	s_waitcnt lgkmcnt(0)
	s_barrier
	ds_read_b128 v[140:143], v238
	ds_read_b128 v[172:175], v239 offset:18432
	ds_read_b128 v[176:179], v239 offset:20736
	ds_read_b128 v[144:147], v238 offset:2304
	ds_read_b128 v[180:183], v239 offset:23040
	ds_read_b128 v[148:151], v238 offset:4608
	ds_read_b128 v[184:187], v239 offset:25344
	ds_read_b128 v[152:155], v238 offset:6912
	s_setprio 1
	s_waitcnt lgkmcnt(6)
	v_mfma_f32_16x16x32_bf16 v[52:55], v[172:175], v[140:143], v[52:55]
	s_waitcnt vmcnt(15)
	ds_write_b128 v237, v[100:103]
	s_waitcnt lgkmcnt(6)
	v_mfma_f32_16x16x32_bf16 v[60:63], v[176:179], v[140:143], v[60:63]
	ds_read_b128 v[156:159], v238 offset:64
	s_waitcnt lgkmcnt(6)
	v_mfma_f32_16x16x32_bf16 v[56:59], v[172:175], v[144:147], v[56:59]
	ds_read_b128 v[216:219], v239 offset:18496
	s_waitcnt vmcnt(14)
	ds_write_b128 v237, v[104:107] offset:4608
	v_mfma_f32_16x16x32_bf16 v[64:67], v[176:179], v[144:147], v[64:67]
	ds_read_b128 v[220:223], v239 offset:20800
	s_waitcnt lgkmcnt(8)
	v_mfma_f32_16x16x32_bf16 v[36:39], v[180:183], v[140:143], v[36:39]
	ds_read_b128 v[160:163], v238 offset:2368
	s_waitcnt vmcnt(13)
	ds_write_b128 v237, v[108:111] offset:9216
	global_load_dwordx4 v[100:103], v[132:133], off offset:1152
	v_mfma_f32_16x16x32_bf16 v[40:43], v[180:183], v[144:147], v[40:43]
	ds_read_b128 v[224:227], v239 offset:23104
	s_waitcnt lgkmcnt(10)
	v_mfma_f32_16x16x32_bf16 v[20:23], v[172:175], v[148:151], v[20:23]
	ds_read_b128 v[164:167], v238 offset:4672
	v_mfma_f32_16x16x32_bf16 v[28:31], v[176:179], v[148:151], v[28:31]
	ds_read_b128 v[228:231], v239 offset:25408
	v_mfma_f32_16x16x32_bf16 v[4:7], v[180:183], v[148:151], v[4:7]
	ds_read_b128 v[168:171], v238 offset:6976
	s_waitcnt lgkmcnt(12)
	v_mfma_f32_16x16x32_bf16 v[44:47], v[184:187], v[140:143], v[44:47]
	v_mfma_f32_16x16x32_bf16 v[48:51], v[184:187], v[144:147], v[48:51]
	s_waitcnt vmcnt(13)
	ds_write_b128 v237, v[112:115] offset:13824
	global_load_dwordx4 v[104:107], v[138:139], off offset:1152
	v_mfma_f32_16x16x32_bf16 v[12:15], v[184:187], v[148:151], v[12:15]
	s_waitcnt lgkmcnt(12)
	v_mfma_f32_16x16x32_bf16 v[24:27], v[172:175], v[152:155], v[24:27]
	s_waitcnt vmcnt(13)
	ds_write_b128 v237, v[116:119] offset:18432
	global_load_dwordx4 v[108:111], v[194:195], off offset:1152
	v_mfma_f32_16x16x32_bf16 v[32:35], v[176:179], v[152:155], v[32:35]
	v_mfma_f32_16x16x32_bf16 v[8:11], v[180:183], v[152:155], v[8:11]
	v_mfma_f32_16x16x32_bf16 v[16:19], v[184:187], v[152:155], v[16:19]
	s_waitcnt lgkmcnt(10)
	v_mfma_f32_16x16x32_bf16 v[52:55], v[216:219], v[156:159], v[52:55]
	s_waitcnt lgkmcnt(8)
	v_mfma_f32_16x16x32_bf16 v[60:63], v[220:223], v[156:159], v[60:63]
	s_waitcnt lgkmcnt(7)
	v_mfma_f32_16x16x32_bf16 v[56:59], v[216:219], v[160:163], v[56:59]
	s_waitcnt vmcnt(13)
	ds_write_b128 v237, v[120:123] offset:23040
	global_load_dwordx4 v[112:115], v[196:197], off offset:1152
	v_mfma_f32_16x16x32_bf16 v[64:67], v[220:223], v[160:163], v[64:67]
	s_waitcnt lgkmcnt(6)
	v_mfma_f32_16x16x32_bf16 v[36:39], v[224:227], v[156:159], v[36:39]
	s_waitcnt vmcnt(13)
	ds_write_b128 v237, v[124:127] offset:27648
	global_load_dwordx4 v[116:119], v[134:135], off offset:1152
	v_mfma_f32_16x16x32_bf16 v[40:43], v[224:227], v[160:163], v[40:43]
	s_waitcnt lgkmcnt(6)
	v_mfma_f32_16x16x32_bf16 v[20:23], v[216:219], v[164:167], v[20:23]
	s_waitcnt vmcnt(13)
	ds_write_b128 v237, v[128:131] offset:32256
	global_load_dwordx4 v[120:123], v[214:215], off offset:1152
	v_mfma_f32_16x16x32_bf16 v[28:31], v[220:223], v[164:167], v[28:31]
	v_mfma_f32_16x16x32_bf16 v[4:7], v[224:227], v[164:167], v[4:7]
	global_load_dwordx4 v[124:127], v[232:233], off offset:1152
	s_waitcnt lgkmcnt(6)
	v_mfma_f32_16x16x32_bf16 v[44:47], v[228:231], v[156:159], v[44:47]
	v_mfma_f32_16x16x32_bf16 v[48:51], v[228:231], v[160:163], v[48:51]
	global_load_dwordx4 v[128:131], v[234:235], off offset:1152
	v_mfma_f32_16x16x32_bf16 v[12:15], v[228:231], v[164:167], v[12:15]
	s_waitcnt lgkmcnt(5)
	v_mfma_f32_16x16x32_bf16 v[24:27], v[216:219], v[168:171], v[24:27]
	v_mfma_f32_16x16x32_bf16 v[32:35], v[220:223], v[168:171], v[32:35]
	v_mfma_f32_16x16x32_bf16 v[8:11], v[224:227], v[168:171], v[8:11]
	v_mfma_f32_16x16x32_bf16 v[16:19], v[228:231], v[168:171], v[16:19]
	s_setprio 0
	s_waitcnt lgkmcnt(0)
	s_barrier
	ds_read_b128 v[140:143], v238 offset:36864
	ds_read_b128 v[172:175], v239 offset:55296
	ds_read_b128 v[176:179], v239 offset:57600
	ds_read_b128 v[144:147], v238 offset:39168
	ds_read_b128 v[180:183], v239 offset:59904
	ds_read_b128 v[148:151], v238 offset:41472
	ds_read_b128 v[184:187], v239 offset:62208
	ds_read_b128 v[152:155], v238 offset:43776
	s_setprio 1
	s_waitcnt lgkmcnt(6)
	v_mfma_f32_16x16x32_bf16 v[52:55], v[172:175], v[140:143], v[52:55]
	s_waitcnt vmcnt(15)
	ds_write_b128 v236, v[68:71]
	s_waitcnt lgkmcnt(6)
	v_mfma_f32_16x16x32_bf16 v[60:63], v[176:179], v[140:143], v[60:63]
	ds_read_b128 v[156:159], v238 offset:36928
	s_waitcnt lgkmcnt(6)
	v_mfma_f32_16x16x32_bf16 v[56:59], v[172:175], v[144:147], v[56:59]
	ds_read_b128 v[216:219], v239 offset:55360
	s_waitcnt vmcnt(14)
	ds_write_b128 v236, v[72:75] offset:4608
	v_mfma_f32_16x16x32_bf16 v[64:67], v[176:179], v[144:147], v[64:67]
	ds_read_b128 v[220:223], v239 offset:57664
	s_waitcnt lgkmcnt(8)
	v_mfma_f32_16x16x32_bf16 v[36:39], v[180:183], v[140:143], v[36:39]
	ds_read_b128 v[160:163], v238 offset:39232
	s_waitcnt vmcnt(13)
	ds_write_b128 v236, v[76:79] offset:9216
	global_load_dwordx4 v[68:71], v[132:133], off offset:1280
	v_mfma_f32_16x16x32_bf16 v[40:43], v[180:183], v[144:147], v[40:43]
	ds_read_b128 v[224:227], v239 offset:59968
	s_waitcnt lgkmcnt(10)
	v_mfma_f32_16x16x32_bf16 v[20:23], v[172:175], v[148:151], v[20:23]
	ds_read_b128 v[164:167], v238 offset:41536
	v_mfma_f32_16x16x32_bf16 v[28:31], v[176:179], v[148:151], v[28:31]
	ds_read_b128 v[228:231], v239 offset:62272
	v_mfma_f32_16x16x32_bf16 v[4:7], v[180:183], v[148:151], v[4:7]
	ds_read_b128 v[168:171], v238 offset:43840
	s_waitcnt lgkmcnt(12)
	v_mfma_f32_16x16x32_bf16 v[44:47], v[184:187], v[140:143], v[44:47]
	v_mfma_f32_16x16x32_bf16 v[48:51], v[184:187], v[144:147], v[48:51]
	s_waitcnt vmcnt(13)
	ds_write_b128 v236, v[80:83] offset:13824
	global_load_dwordx4 v[72:75], v[138:139], off offset:1280
	v_mfma_f32_16x16x32_bf16 v[12:15], v[184:187], v[148:151], v[12:15]
	s_waitcnt lgkmcnt(12)
	v_mfma_f32_16x16x32_bf16 v[24:27], v[172:175], v[152:155], v[24:27]
	s_waitcnt vmcnt(13)
	ds_write_b128 v236, v[84:87] offset:18432
	global_load_dwordx4 v[76:79], v[194:195], off offset:1280
	v_mfma_f32_16x16x32_bf16 v[32:35], v[176:179], v[152:155], v[32:35]
	v_mfma_f32_16x16x32_bf16 v[8:11], v[180:183], v[152:155], v[8:11]
	v_mfma_f32_16x16x32_bf16 v[16:19], v[184:187], v[152:155], v[16:19]
	s_waitcnt lgkmcnt(10)
	v_mfma_f32_16x16x32_bf16 v[52:55], v[216:219], v[156:159], v[52:55]
	s_waitcnt lgkmcnt(8)
	v_mfma_f32_16x16x32_bf16 v[60:63], v[220:223], v[156:159], v[60:63]
	s_waitcnt lgkmcnt(7)
	v_mfma_f32_16x16x32_bf16 v[56:59], v[216:219], v[160:163], v[56:59]
	s_waitcnt vmcnt(13)
	ds_write_b128 v236, v[88:91] offset:23040
	global_load_dwordx4 v[80:83], v[196:197], off offset:1280
	v_mfma_f32_16x16x32_bf16 v[64:67], v[220:223], v[160:163], v[64:67]
	s_waitcnt lgkmcnt(6)
	v_mfma_f32_16x16x32_bf16 v[36:39], v[224:227], v[156:159], v[36:39]
	s_waitcnt vmcnt(13)
	ds_write_b128 v236, v[92:95] offset:27648
	global_load_dwordx4 v[84:87], v[134:135], off offset:1280
	v_mfma_f32_16x16x32_bf16 v[40:43], v[224:227], v[160:163], v[40:43]
	s_waitcnt lgkmcnt(6)
	v_mfma_f32_16x16x32_bf16 v[20:23], v[216:219], v[164:167], v[20:23]
	s_waitcnt vmcnt(13)
	ds_write_b128 v236, v[96:99] offset:32256
	global_load_dwordx4 v[88:91], v[214:215], off offset:1280
	v_mfma_f32_16x16x32_bf16 v[28:31], v[220:223], v[164:167], v[28:31]
	v_mfma_f32_16x16x32_bf16 v[4:7], v[224:227], v[164:167], v[4:7]
	global_load_dwordx4 v[92:95], v[232:233], off offset:1280
	s_waitcnt lgkmcnt(6)
	v_mfma_f32_16x16x32_bf16 v[44:47], v[228:231], v[156:159], v[44:47]
	v_mfma_f32_16x16x32_bf16 v[48:51], v[228:231], v[160:163], v[48:51]
	global_load_dwordx4 v[96:99], v[234:235], off offset:1280
	v_mfma_f32_16x16x32_bf16 v[12:15], v[228:231], v[164:167], v[12:15]
	s_waitcnt lgkmcnt(5)
	v_mfma_f32_16x16x32_bf16 v[24:27], v[216:219], v[168:171], v[24:27]
	v_mfma_f32_16x16x32_bf16 v[32:35], v[220:223], v[168:171], v[32:35]
	v_mfma_f32_16x16x32_bf16 v[8:11], v[224:227], v[168:171], v[8:11]
	v_mfma_f32_16x16x32_bf16 v[16:19], v[228:231], v[168:171], v[16:19]
	s_setprio 0
	s_waitcnt lgkmcnt(0)
	s_barrier
	ds_read_b128 v[140:143], v238
	ds_read_b128 v[172:175], v239 offset:18432
	ds_read_b128 v[176:179], v239 offset:20736
	ds_read_b128 v[144:147], v238 offset:2304
	ds_read_b128 v[180:183], v239 offset:23040
	ds_read_b128 v[148:151], v238 offset:4608
	ds_read_b128 v[184:187], v239 offset:25344
	ds_read_b128 v[152:155], v238 offset:6912
	s_setprio 1
	s_waitcnt lgkmcnt(6)
	v_mfma_f32_16x16x32_bf16 v[52:55], v[172:175], v[140:143], v[52:55]
	s_waitcnt vmcnt(15)
	ds_write_b128 v237, v[100:103]
	s_waitcnt lgkmcnt(6)
	v_mfma_f32_16x16x32_bf16 v[60:63], v[176:179], v[140:143], v[60:63]
	ds_read_b128 v[156:159], v238 offset:64
	s_waitcnt lgkmcnt(6)
	v_mfma_f32_16x16x32_bf16 v[56:59], v[172:175], v[144:147], v[56:59]
	ds_read_b128 v[216:219], v239 offset:18496
	s_waitcnt vmcnt(14)
	ds_write_b128 v237, v[104:107] offset:4608
	v_mfma_f32_16x16x32_bf16 v[64:67], v[176:179], v[144:147], v[64:67]
	ds_read_b128 v[220:223], v239 offset:20800
	s_waitcnt lgkmcnt(8)
	v_mfma_f32_16x16x32_bf16 v[36:39], v[180:183], v[140:143], v[36:39]
	ds_read_b128 v[160:163], v238 offset:2368
	s_waitcnt vmcnt(13)
	ds_write_b128 v237, v[108:111] offset:9216
	global_load_dwordx4 v[100:103], v[132:133], off offset:1408
	v_mfma_f32_16x16x32_bf16 v[40:43], v[180:183], v[144:147], v[40:43]
	ds_read_b128 v[224:227], v239 offset:23104
	s_waitcnt lgkmcnt(10)
	v_mfma_f32_16x16x32_bf16 v[20:23], v[172:175], v[148:151], v[20:23]
	ds_read_b128 v[164:167], v238 offset:4672
	v_mfma_f32_16x16x32_bf16 v[28:31], v[176:179], v[148:151], v[28:31]
	ds_read_b128 v[228:231], v239 offset:25408
	v_mfma_f32_16x16x32_bf16 v[4:7], v[180:183], v[148:151], v[4:7]
	ds_read_b128 v[168:171], v238 offset:6976
	s_waitcnt lgkmcnt(12)
	v_mfma_f32_16x16x32_bf16 v[44:47], v[184:187], v[140:143], v[44:47]
	v_mfma_f32_16x16x32_bf16 v[48:51], v[184:187], v[144:147], v[48:51]
	s_waitcnt vmcnt(13)
	ds_write_b128 v237, v[112:115] offset:13824
	global_load_dwordx4 v[104:107], v[138:139], off offset:1408
	v_mfma_f32_16x16x32_bf16 v[12:15], v[184:187], v[148:151], v[12:15]
	s_waitcnt lgkmcnt(12)
	v_mfma_f32_16x16x32_bf16 v[24:27], v[172:175], v[152:155], v[24:27]
	s_waitcnt vmcnt(13)
	ds_write_b128 v237, v[116:119] offset:18432
	global_load_dwordx4 v[108:111], v[194:195], off offset:1408
	v_mfma_f32_16x16x32_bf16 v[32:35], v[176:179], v[152:155], v[32:35]
	v_mfma_f32_16x16x32_bf16 v[8:11], v[180:183], v[152:155], v[8:11]
	v_mfma_f32_16x16x32_bf16 v[16:19], v[184:187], v[152:155], v[16:19]
	s_waitcnt lgkmcnt(10)
	v_mfma_f32_16x16x32_bf16 v[52:55], v[216:219], v[156:159], v[52:55]
	s_waitcnt lgkmcnt(8)
	v_mfma_f32_16x16x32_bf16 v[60:63], v[220:223], v[156:159], v[60:63]
	s_waitcnt lgkmcnt(7)
	v_mfma_f32_16x16x32_bf16 v[56:59], v[216:219], v[160:163], v[56:59]
	s_waitcnt vmcnt(13)
	ds_write_b128 v237, v[120:123] offset:23040
	global_load_dwordx4 v[112:115], v[196:197], off offset:1408
	v_mfma_f32_16x16x32_bf16 v[64:67], v[220:223], v[160:163], v[64:67]
	s_waitcnt lgkmcnt(6)
	v_mfma_f32_16x16x32_bf16 v[36:39], v[224:227], v[156:159], v[36:39]
	s_waitcnt vmcnt(13)
	ds_write_b128 v237, v[124:127] offset:27648
	global_load_dwordx4 v[116:119], v[134:135], off offset:1408
	v_mfma_f32_16x16x32_bf16 v[40:43], v[224:227], v[160:163], v[40:43]
	s_waitcnt lgkmcnt(6)
	v_mfma_f32_16x16x32_bf16 v[20:23], v[216:219], v[164:167], v[20:23]
	s_waitcnt vmcnt(13)
	ds_write_b128 v237, v[128:131] offset:32256
	global_load_dwordx4 v[120:123], v[214:215], off offset:1408
	v_mfma_f32_16x16x32_bf16 v[28:31], v[220:223], v[164:167], v[28:31]
	v_mfma_f32_16x16x32_bf16 v[4:7], v[224:227], v[164:167], v[4:7]
	global_load_dwordx4 v[124:127], v[232:233], off offset:1408
	s_waitcnt lgkmcnt(6)
	v_mfma_f32_16x16x32_bf16 v[44:47], v[228:231], v[156:159], v[44:47]
	v_mfma_f32_16x16x32_bf16 v[48:51], v[228:231], v[160:163], v[48:51]
	global_load_dwordx4 v[128:131], v[234:235], off offset:1408
	v_mfma_f32_16x16x32_bf16 v[12:15], v[228:231], v[164:167], v[12:15]
	s_waitcnt lgkmcnt(5)
	v_mfma_f32_16x16x32_bf16 v[24:27], v[216:219], v[168:171], v[24:27]
	v_mfma_f32_16x16x32_bf16 v[32:35], v[220:223], v[168:171], v[32:35]
	v_mfma_f32_16x16x32_bf16 v[8:11], v[224:227], v[168:171], v[8:11]
	v_mfma_f32_16x16x32_bf16 v[16:19], v[228:231], v[168:171], v[16:19]
	s_setprio 0
	s_waitcnt lgkmcnt(0)
	s_barrier
	ds_read_b128 v[140:143], v238 offset:36864
	ds_read_b128 v[172:175], v239 offset:55296
	ds_read_b128 v[176:179], v239 offset:57600
	ds_read_b128 v[144:147], v238 offset:39168
	ds_read_b128 v[180:183], v239 offset:59904
	ds_read_b128 v[148:151], v238 offset:41472
	ds_read_b128 v[184:187], v239 offset:62208
	ds_read_b128 v[152:155], v238 offset:43776
	s_setprio 1
	s_waitcnt lgkmcnt(6)
	v_mfma_f32_16x16x32_bf16 v[52:55], v[172:175], v[140:143], v[52:55]
	s_waitcnt vmcnt(15)
	ds_write_b128 v236, v[68:71]
	s_waitcnt lgkmcnt(6)
	v_mfma_f32_16x16x32_bf16 v[60:63], v[176:179], v[140:143], v[60:63]
	ds_read_b128 v[156:159], v238 offset:36928
	s_waitcnt lgkmcnt(6)
	v_mfma_f32_16x16x32_bf16 v[56:59], v[172:175], v[144:147], v[56:59]
	ds_read_b128 v[216:219], v239 offset:55360
	s_waitcnt vmcnt(14)
	ds_write_b128 v236, v[72:75] offset:4608
	v_mfma_f32_16x16x32_bf16 v[64:67], v[176:179], v[144:147], v[64:67]
	ds_read_b128 v[220:223], v239 offset:57664
	s_waitcnt lgkmcnt(8)
	v_mfma_f32_16x16x32_bf16 v[36:39], v[180:183], v[140:143], v[36:39]
	ds_read_b128 v[160:163], v238 offset:39232
	s_waitcnt vmcnt(13)
	ds_write_b128 v236, v[76:79] offset:9216
	global_load_dwordx4 v[68:71], v[132:133], off offset:1536
	v_mfma_f32_16x16x32_bf16 v[40:43], v[180:183], v[144:147], v[40:43]
	ds_read_b128 v[224:227], v239 offset:59968
	s_waitcnt lgkmcnt(10)
	v_mfma_f32_16x16x32_bf16 v[20:23], v[172:175], v[148:151], v[20:23]
	ds_read_b128 v[164:167], v238 offset:41536
	v_mfma_f32_16x16x32_bf16 v[28:31], v[176:179], v[148:151], v[28:31]
	ds_read_b128 v[228:231], v239 offset:62272
	v_mfma_f32_16x16x32_bf16 v[4:7], v[180:183], v[148:151], v[4:7]
	ds_read_b128 v[168:171], v238 offset:43840
	s_waitcnt lgkmcnt(12)
	v_mfma_f32_16x16x32_bf16 v[44:47], v[184:187], v[140:143], v[44:47]
	v_mfma_f32_16x16x32_bf16 v[48:51], v[184:187], v[144:147], v[48:51]
	s_waitcnt vmcnt(13)
	ds_write_b128 v236, v[80:83] offset:13824
	global_load_dwordx4 v[72:75], v[138:139], off offset:1536
	v_mfma_f32_16x16x32_bf16 v[12:15], v[184:187], v[148:151], v[12:15]
	s_waitcnt lgkmcnt(12)
	v_mfma_f32_16x16x32_bf16 v[24:27], v[172:175], v[152:155], v[24:27]
	s_waitcnt vmcnt(13)
	ds_write_b128 v236, v[84:87] offset:18432
	global_load_dwordx4 v[76:79], v[194:195], off offset:1536
	v_mfma_f32_16x16x32_bf16 v[32:35], v[176:179], v[152:155], v[32:35]
	v_mfma_f32_16x16x32_bf16 v[8:11], v[180:183], v[152:155], v[8:11]
	v_mfma_f32_16x16x32_bf16 v[16:19], v[184:187], v[152:155], v[16:19]
	s_waitcnt lgkmcnt(10)
	v_mfma_f32_16x16x32_bf16 v[52:55], v[216:219], v[156:159], v[52:55]
	s_waitcnt lgkmcnt(8)
	v_mfma_f32_16x16x32_bf16 v[60:63], v[220:223], v[156:159], v[60:63]
	s_waitcnt lgkmcnt(7)
	v_mfma_f32_16x16x32_bf16 v[56:59], v[216:219], v[160:163], v[56:59]
	s_waitcnt vmcnt(13)
	ds_write_b128 v236, v[88:91] offset:23040
	global_load_dwordx4 v[80:83], v[196:197], off offset:1536
	v_mfma_f32_16x16x32_bf16 v[64:67], v[220:223], v[160:163], v[64:67]
	s_waitcnt lgkmcnt(6)
	v_mfma_f32_16x16x32_bf16 v[36:39], v[224:227], v[156:159], v[36:39]
	s_waitcnt vmcnt(13)
	ds_write_b128 v236, v[92:95] offset:27648
	global_load_dwordx4 v[84:87], v[134:135], off offset:1536
	v_mfma_f32_16x16x32_bf16 v[40:43], v[224:227], v[160:163], v[40:43]
	s_waitcnt lgkmcnt(6)
	v_mfma_f32_16x16x32_bf16 v[20:23], v[216:219], v[164:167], v[20:23]
	s_waitcnt vmcnt(13)
	ds_write_b128 v236, v[96:99] offset:32256
	global_load_dwordx4 v[88:91], v[214:215], off offset:1536
	v_mfma_f32_16x16x32_bf16 v[28:31], v[220:223], v[164:167], v[28:31]
	v_mfma_f32_16x16x32_bf16 v[4:7], v[224:227], v[164:167], v[4:7]
	global_load_dwordx4 v[92:95], v[232:233], off offset:1536
	s_waitcnt lgkmcnt(6)
	v_mfma_f32_16x16x32_bf16 v[44:47], v[228:231], v[156:159], v[44:47]
	v_mfma_f32_16x16x32_bf16 v[48:51], v[228:231], v[160:163], v[48:51]
	global_load_dwordx4 v[96:99], v[234:235], off offset:1536
	v_mfma_f32_16x16x32_bf16 v[12:15], v[228:231], v[164:167], v[12:15]
	s_waitcnt lgkmcnt(5)
	v_mfma_f32_16x16x32_bf16 v[24:27], v[216:219], v[168:171], v[24:27]
	v_mfma_f32_16x16x32_bf16 v[32:35], v[220:223], v[168:171], v[32:35]
	v_mfma_f32_16x16x32_bf16 v[8:11], v[224:227], v[168:171], v[8:11]
	v_mfma_f32_16x16x32_bf16 v[16:19], v[228:231], v[168:171], v[16:19]
	s_setprio 0
	s_waitcnt lgkmcnt(0)
	s_barrier
	ds_read_b128 v[140:143], v238
	ds_read_b128 v[172:175], v239 offset:18432
	ds_read_b128 v[176:179], v239 offset:20736
	ds_read_b128 v[144:147], v238 offset:2304
	ds_read_b128 v[180:183], v239 offset:23040
	ds_read_b128 v[148:151], v238 offset:4608
	ds_read_b128 v[184:187], v239 offset:25344
	ds_read_b128 v[152:155], v238 offset:6912
	s_setprio 1
	s_waitcnt lgkmcnt(6)
	v_mfma_f32_16x16x32_bf16 v[52:55], v[172:175], v[140:143], v[52:55]
	s_waitcnt vmcnt(15)
	ds_write_b128 v237, v[100:103]
	s_waitcnt lgkmcnt(6)
	v_mfma_f32_16x16x32_bf16 v[60:63], v[176:179], v[140:143], v[60:63]
	ds_read_b128 v[156:159], v238 offset:64
	s_waitcnt lgkmcnt(6)
	v_mfma_f32_16x16x32_bf16 v[56:59], v[172:175], v[144:147], v[56:59]
	ds_read_b128 v[216:219], v239 offset:18496
	s_waitcnt vmcnt(14)
	ds_write_b128 v237, v[104:107] offset:4608
	v_mfma_f32_16x16x32_bf16 v[64:67], v[176:179], v[144:147], v[64:67]
	ds_read_b128 v[220:223], v239 offset:20800
	s_waitcnt lgkmcnt(8)
	v_mfma_f32_16x16x32_bf16 v[36:39], v[180:183], v[140:143], v[36:39]
	ds_read_b128 v[160:163], v238 offset:2368
	s_waitcnt vmcnt(13)
	ds_write_b128 v237, v[108:111] offset:9216
	global_load_dwordx4 v[100:103], v[132:133], off offset:1664
	v_mfma_f32_16x16x32_bf16 v[40:43], v[180:183], v[144:147], v[40:43]
	ds_read_b128 v[224:227], v239 offset:23104
	s_waitcnt lgkmcnt(10)
	v_mfma_f32_16x16x32_bf16 v[20:23], v[172:175], v[148:151], v[20:23]
	ds_read_b128 v[164:167], v238 offset:4672
	v_mfma_f32_16x16x32_bf16 v[28:31], v[176:179], v[148:151], v[28:31]
	ds_read_b128 v[228:231], v239 offset:25408
	v_mfma_f32_16x16x32_bf16 v[4:7], v[180:183], v[148:151], v[4:7]
	ds_read_b128 v[168:171], v238 offset:6976
	s_waitcnt lgkmcnt(12)
	v_mfma_f32_16x16x32_bf16 v[44:47], v[184:187], v[140:143], v[44:47]
	v_mfma_f32_16x16x32_bf16 v[48:51], v[184:187], v[144:147], v[48:51]
	s_waitcnt vmcnt(13)
	ds_write_b128 v237, v[112:115] offset:13824
	global_load_dwordx4 v[104:107], v[138:139], off offset:1664
	v_mfma_f32_16x16x32_bf16 v[12:15], v[184:187], v[148:151], v[12:15]
	s_waitcnt lgkmcnt(12)
	v_mfma_f32_16x16x32_bf16 v[24:27], v[172:175], v[152:155], v[24:27]
	s_waitcnt vmcnt(13)
	ds_write_b128 v237, v[116:119] offset:18432
	global_load_dwordx4 v[108:111], v[194:195], off offset:1664
	v_mfma_f32_16x16x32_bf16 v[32:35], v[176:179], v[152:155], v[32:35]
	v_mfma_f32_16x16x32_bf16 v[8:11], v[180:183], v[152:155], v[8:11]
	v_mfma_f32_16x16x32_bf16 v[16:19], v[184:187], v[152:155], v[16:19]
	s_waitcnt lgkmcnt(10)
	v_mfma_f32_16x16x32_bf16 v[52:55], v[216:219], v[156:159], v[52:55]
	s_waitcnt lgkmcnt(8)
	v_mfma_f32_16x16x32_bf16 v[60:63], v[220:223], v[156:159], v[60:63]
	s_waitcnt lgkmcnt(7)
	v_mfma_f32_16x16x32_bf16 v[56:59], v[216:219], v[160:163], v[56:59]
	s_waitcnt vmcnt(13)
	ds_write_b128 v237, v[120:123] offset:23040
	global_load_dwordx4 v[112:115], v[196:197], off offset:1664
	v_mfma_f32_16x16x32_bf16 v[64:67], v[220:223], v[160:163], v[64:67]
	s_waitcnt lgkmcnt(6)
	v_mfma_f32_16x16x32_bf16 v[36:39], v[224:227], v[156:159], v[36:39]
	s_waitcnt vmcnt(13)
	ds_write_b128 v237, v[124:127] offset:27648
	global_load_dwordx4 v[116:119], v[134:135], off offset:1664
	v_mfma_f32_16x16x32_bf16 v[40:43], v[224:227], v[160:163], v[40:43]
	s_waitcnt lgkmcnt(6)
	v_mfma_f32_16x16x32_bf16 v[20:23], v[216:219], v[164:167], v[20:23]
	s_waitcnt vmcnt(13)
	ds_write_b128 v237, v[128:131] offset:32256
	global_load_dwordx4 v[120:123], v[214:215], off offset:1664
	v_mfma_f32_16x16x32_bf16 v[28:31], v[220:223], v[164:167], v[28:31]
	v_mfma_f32_16x16x32_bf16 v[4:7], v[224:227], v[164:167], v[4:7]
	global_load_dwordx4 v[124:127], v[232:233], off offset:1664
	s_waitcnt lgkmcnt(6)
	v_mfma_f32_16x16x32_bf16 v[44:47], v[228:231], v[156:159], v[44:47]
	v_mfma_f32_16x16x32_bf16 v[48:51], v[228:231], v[160:163], v[48:51]
	global_load_dwordx4 v[128:131], v[234:235], off offset:1664
	v_mfma_f32_16x16x32_bf16 v[12:15], v[228:231], v[164:167], v[12:15]
	s_waitcnt lgkmcnt(5)
	v_mfma_f32_16x16x32_bf16 v[24:27], v[216:219], v[168:171], v[24:27]
	v_mfma_f32_16x16x32_bf16 v[32:35], v[220:223], v[168:171], v[32:35]
	v_mfma_f32_16x16x32_bf16 v[8:11], v[224:227], v[168:171], v[8:11]
	v_mfma_f32_16x16x32_bf16 v[16:19], v[228:231], v[168:171], v[16:19]
	s_setprio 0
	s_waitcnt lgkmcnt(0)
	s_barrier
	ds_read_b128 v[140:143], v238 offset:36864
	ds_read_b128 v[172:175], v239 offset:55296
	ds_read_b128 v[176:179], v239 offset:57600
	ds_read_b128 v[144:147], v238 offset:39168
	ds_read_b128 v[180:183], v239 offset:59904
	ds_read_b128 v[148:151], v238 offset:41472
	ds_read_b128 v[184:187], v239 offset:62208
	ds_read_b128 v[152:155], v238 offset:43776
	s_setprio 1
	s_waitcnt lgkmcnt(6)
	v_mfma_f32_16x16x32_bf16 v[52:55], v[172:175], v[140:143], v[52:55]
	s_waitcnt vmcnt(15)
	ds_write_b128 v236, v[68:71]
	s_waitcnt lgkmcnt(6)
	v_mfma_f32_16x16x32_bf16 v[60:63], v[176:179], v[140:143], v[60:63]
	ds_read_b128 v[156:159], v238 offset:36928
	s_waitcnt lgkmcnt(6)
	v_mfma_f32_16x16x32_bf16 v[56:59], v[172:175], v[144:147], v[56:59]
	ds_read_b128 v[216:219], v239 offset:55360
	s_waitcnt vmcnt(14)
	ds_write_b128 v236, v[72:75] offset:4608
	v_mfma_f32_16x16x32_bf16 v[64:67], v[176:179], v[144:147], v[64:67]
	ds_read_b128 v[220:223], v239 offset:57664
	s_waitcnt lgkmcnt(8)
	v_mfma_f32_16x16x32_bf16 v[36:39], v[180:183], v[140:143], v[36:39]
	ds_read_b128 v[160:163], v238 offset:39232
	s_waitcnt vmcnt(13)
	ds_write_b128 v236, v[76:79] offset:9216
	global_load_dwordx4 v[68:71], v[132:133], off offset:1792
	v_mfma_f32_16x16x32_bf16 v[40:43], v[180:183], v[144:147], v[40:43]
	ds_read_b128 v[224:227], v239 offset:59968
	s_waitcnt lgkmcnt(10)
	v_mfma_f32_16x16x32_bf16 v[20:23], v[172:175], v[148:151], v[20:23]
	ds_read_b128 v[164:167], v238 offset:41536
	v_mfma_f32_16x16x32_bf16 v[28:31], v[176:179], v[148:151], v[28:31]
	ds_read_b128 v[228:231], v239 offset:62272
	v_mfma_f32_16x16x32_bf16 v[4:7], v[180:183], v[148:151], v[4:7]
	ds_read_b128 v[168:171], v238 offset:43840
	s_waitcnt lgkmcnt(12)
	v_mfma_f32_16x16x32_bf16 v[44:47], v[184:187], v[140:143], v[44:47]
	v_mfma_f32_16x16x32_bf16 v[48:51], v[184:187], v[144:147], v[48:51]
	s_waitcnt vmcnt(13)
	ds_write_b128 v236, v[80:83] offset:13824
	global_load_dwordx4 v[72:75], v[138:139], off offset:1792
	v_mfma_f32_16x16x32_bf16 v[12:15], v[184:187], v[148:151], v[12:15]
	s_waitcnt lgkmcnt(12)
	v_mfma_f32_16x16x32_bf16 v[24:27], v[172:175], v[152:155], v[24:27]
	s_waitcnt vmcnt(13)
	ds_write_b128 v236, v[84:87] offset:18432
	global_load_dwordx4 v[76:79], v[194:195], off offset:1792
	v_mfma_f32_16x16x32_bf16 v[32:35], v[176:179], v[152:155], v[32:35]
	v_mfma_f32_16x16x32_bf16 v[8:11], v[180:183], v[152:155], v[8:11]
	v_mfma_f32_16x16x32_bf16 v[16:19], v[184:187], v[152:155], v[16:19]
	s_waitcnt lgkmcnt(10)
	v_mfma_f32_16x16x32_bf16 v[52:55], v[216:219], v[156:159], v[52:55]
	s_waitcnt lgkmcnt(8)
	v_mfma_f32_16x16x32_bf16 v[60:63], v[220:223], v[156:159], v[60:63]
	s_waitcnt lgkmcnt(7)
	v_mfma_f32_16x16x32_bf16 v[56:59], v[216:219], v[160:163], v[56:59]
	s_waitcnt vmcnt(13)
	ds_write_b128 v236, v[88:91] offset:23040
	global_load_dwordx4 v[80:83], v[196:197], off offset:1792
	v_mfma_f32_16x16x32_bf16 v[64:67], v[220:223], v[160:163], v[64:67]
	s_waitcnt lgkmcnt(6)
	v_mfma_f32_16x16x32_bf16 v[36:39], v[224:227], v[156:159], v[36:39]
	s_waitcnt vmcnt(13)
	ds_write_b128 v236, v[92:95] offset:27648
	global_load_dwordx4 v[84:87], v[134:135], off offset:1792
	v_mfma_f32_16x16x32_bf16 v[40:43], v[224:227], v[160:163], v[40:43]
	s_waitcnt lgkmcnt(6)
	v_mfma_f32_16x16x32_bf16 v[20:23], v[216:219], v[164:167], v[20:23]
	s_waitcnt vmcnt(13)
	ds_write_b128 v236, v[96:99] offset:32256
	global_load_dwordx4 v[88:91], v[214:215], off offset:1792
	v_mfma_f32_16x16x32_bf16 v[28:31], v[220:223], v[164:167], v[28:31]
	v_mfma_f32_16x16x32_bf16 v[4:7], v[224:227], v[164:167], v[4:7]
	global_load_dwordx4 v[92:95], v[232:233], off offset:1792
	s_waitcnt lgkmcnt(6)
	v_mfma_f32_16x16x32_bf16 v[44:47], v[228:231], v[156:159], v[44:47]
	v_mfma_f32_16x16x32_bf16 v[48:51], v[228:231], v[160:163], v[48:51]
	global_load_dwordx4 v[96:99], v[234:235], off offset:1792
	v_mfma_f32_16x16x32_bf16 v[12:15], v[228:231], v[164:167], v[12:15]
	s_waitcnt lgkmcnt(5)
	v_mfma_f32_16x16x32_bf16 v[24:27], v[216:219], v[168:171], v[24:27]
	v_mfma_f32_16x16x32_bf16 v[32:35], v[220:223], v[168:171], v[32:35]
	v_mfma_f32_16x16x32_bf16 v[8:11], v[224:227], v[168:171], v[8:11]
	v_mfma_f32_16x16x32_bf16 v[16:19], v[228:231], v[168:171], v[16:19]
	s_setprio 0
	s_waitcnt lgkmcnt(0)
	s_barrier
	ds_read_b128 v[140:143], v238
	ds_read_b128 v[172:175], v239 offset:18432
	ds_read_b128 v[176:179], v239 offset:20736
	ds_read_b128 v[144:147], v238 offset:2304
	ds_read_b128 v[180:183], v239 offset:23040
	ds_read_b128 v[148:151], v238 offset:4608
	ds_read_b128 v[184:187], v239 offset:25344
	ds_read_b128 v[152:155], v238 offset:6912
	s_setprio 1
	s_waitcnt lgkmcnt(6)
	v_mfma_f32_16x16x32_bf16 v[52:55], v[172:175], v[140:143], v[52:55]
	s_waitcnt vmcnt(15)
	ds_write_b128 v237, v[100:103]
	s_waitcnt lgkmcnt(6)
	v_mfma_f32_16x16x32_bf16 v[60:63], v[176:179], v[140:143], v[60:63]
	ds_read_b128 v[156:159], v238 offset:64
	s_waitcnt lgkmcnt(6)
	v_mfma_f32_16x16x32_bf16 v[56:59], v[172:175], v[144:147], v[56:59]
	ds_read_b128 v[216:219], v239 offset:18496
	s_waitcnt vmcnt(14)
	ds_write_b128 v237, v[104:107] offset:4608
	v_mfma_f32_16x16x32_bf16 v[64:67], v[176:179], v[144:147], v[64:67]
	ds_read_b128 v[220:223], v239 offset:20800
	s_waitcnt lgkmcnt(8)
	v_mfma_f32_16x16x32_bf16 v[36:39], v[180:183], v[140:143], v[36:39]
	ds_read_b128 v[160:163], v238 offset:2368
	s_waitcnt vmcnt(13)
	ds_write_b128 v237, v[108:111] offset:9216
	global_load_dwordx4 v[100:103], v[132:133], off offset:1920
	v_mfma_f32_16x16x32_bf16 v[40:43], v[180:183], v[144:147], v[40:43]
	ds_read_b128 v[224:227], v239 offset:23104
	s_waitcnt lgkmcnt(10)
	v_mfma_f32_16x16x32_bf16 v[20:23], v[172:175], v[148:151], v[20:23]
	ds_read_b128 v[164:167], v238 offset:4672
	v_mfma_f32_16x16x32_bf16 v[28:31], v[176:179], v[148:151], v[28:31]
	ds_read_b128 v[228:231], v239 offset:25408
	v_mfma_f32_16x16x32_bf16 v[4:7], v[180:183], v[148:151], v[4:7]
	ds_read_b128 v[168:171], v238 offset:6976
	s_waitcnt lgkmcnt(12)
	v_mfma_f32_16x16x32_bf16 v[44:47], v[184:187], v[140:143], v[44:47]
	v_mfma_f32_16x16x32_bf16 v[48:51], v[184:187], v[144:147], v[48:51]
	s_waitcnt vmcnt(13)
	ds_write_b128 v237, v[112:115] offset:13824
	global_load_dwordx4 v[104:107], v[138:139], off offset:1920
	v_mfma_f32_16x16x32_bf16 v[12:15], v[184:187], v[148:151], v[12:15]
	s_waitcnt lgkmcnt(12)
	v_mfma_f32_16x16x32_bf16 v[24:27], v[172:175], v[152:155], v[24:27]
	s_waitcnt vmcnt(13)
	ds_write_b128 v237, v[116:119] offset:18432
	global_load_dwordx4 v[108:111], v[194:195], off offset:1920
	v_mfma_f32_16x16x32_bf16 v[32:35], v[176:179], v[152:155], v[32:35]
	v_mfma_f32_16x16x32_bf16 v[8:11], v[180:183], v[152:155], v[8:11]
	v_mfma_f32_16x16x32_bf16 v[16:19], v[184:187], v[152:155], v[16:19]
	s_waitcnt lgkmcnt(10)
	v_mfma_f32_16x16x32_bf16 v[52:55], v[216:219], v[156:159], v[52:55]
	s_waitcnt lgkmcnt(8)
	v_mfma_f32_16x16x32_bf16 v[60:63], v[220:223], v[156:159], v[60:63]
	s_waitcnt lgkmcnt(7)
	v_mfma_f32_16x16x32_bf16 v[56:59], v[216:219], v[160:163], v[56:59]
	s_waitcnt vmcnt(13)
	ds_write_b128 v237, v[120:123] offset:23040
	global_load_dwordx4 v[112:115], v[196:197], off offset:1920
	v_mfma_f32_16x16x32_bf16 v[64:67], v[220:223], v[160:163], v[64:67]
	s_waitcnt lgkmcnt(6)
	v_mfma_f32_16x16x32_bf16 v[36:39], v[224:227], v[156:159], v[36:39]
	s_waitcnt vmcnt(13)
	ds_write_b128 v237, v[124:127] offset:27648
	global_load_dwordx4 v[116:119], v[134:135], off offset:1920
	v_mfma_f32_16x16x32_bf16 v[40:43], v[224:227], v[160:163], v[40:43]
	s_waitcnt lgkmcnt(6)
	v_mfma_f32_16x16x32_bf16 v[20:23], v[216:219], v[164:167], v[20:23]
	s_waitcnt vmcnt(13)
	ds_write_b128 v237, v[128:131] offset:32256
	global_load_dwordx4 v[120:123], v[214:215], off offset:1920
	v_mfma_f32_16x16x32_bf16 v[28:31], v[220:223], v[164:167], v[28:31]
	v_mfma_f32_16x16x32_bf16 v[4:7], v[224:227], v[164:167], v[4:7]
	global_load_dwordx4 v[124:127], v[232:233], off offset:1920
	s_waitcnt lgkmcnt(6)
	v_mfma_f32_16x16x32_bf16 v[44:47], v[228:231], v[156:159], v[44:47]
	v_mfma_f32_16x16x32_bf16 v[48:51], v[228:231], v[160:163], v[48:51]
	global_load_dwordx4 v[128:131], v[234:235], off offset:1920
	v_mfma_f32_16x16x32_bf16 v[12:15], v[228:231], v[164:167], v[12:15]
	s_waitcnt lgkmcnt(5)
	v_mfma_f32_16x16x32_bf16 v[24:27], v[216:219], v[168:171], v[24:27]
	v_mfma_f32_16x16x32_bf16 v[32:35], v[220:223], v[168:171], v[32:35]
	v_mfma_f32_16x16x32_bf16 v[8:11], v[224:227], v[168:171], v[8:11]
	v_mfma_f32_16x16x32_bf16 v[16:19], v[228:231], v[168:171], v[16:19]
	s_setprio 0
	s_waitcnt lgkmcnt(0)
	s_barrier
	ds_read_b128 v[140:143], v238 offset:36864
	ds_read_b128 v[172:175], v239 offset:55296
	ds_read_b128 v[176:179], v239 offset:57600
	ds_read_b128 v[144:147], v238 offset:39168
	ds_read_b128 v[180:183], v239 offset:59904
	ds_read_b128 v[148:151], v238 offset:41472
	ds_read_b128 v[184:187], v239 offset:62208
	ds_read_b128 v[152:155], v238 offset:43776
	s_setprio 1
	s_waitcnt lgkmcnt(6)
	v_mfma_f32_16x16x32_bf16 v[52:55], v[172:175], v[140:143], v[52:55]
	s_waitcnt vmcnt(15)
	ds_write_b128 v236, v[68:71]
	s_waitcnt lgkmcnt(6)
	v_mfma_f32_16x16x32_bf16 v[60:63], v[176:179], v[140:143], v[60:63]
	ds_read_b128 v[156:159], v238 offset:36928
	s_waitcnt lgkmcnt(6)
	v_mfma_f32_16x16x32_bf16 v[56:59], v[172:175], v[144:147], v[56:59]
	ds_read_b128 v[216:219], v239 offset:55360
	s_waitcnt vmcnt(14)
	ds_write_b128 v236, v[72:75] offset:4608
	v_mfma_f32_16x16x32_bf16 v[64:67], v[176:179], v[144:147], v[64:67]
	ds_read_b128 v[220:223], v239 offset:57664
	s_waitcnt lgkmcnt(8)
	v_mfma_f32_16x16x32_bf16 v[36:39], v[180:183], v[140:143], v[36:39]
	ds_read_b128 v[160:163], v238 offset:39232
	s_waitcnt vmcnt(13)
	ds_write_b128 v236, v[76:79] offset:9216
	v_mfma_f32_16x16x32_bf16 v[40:43], v[180:183], v[144:147], v[40:43]
	ds_read_b128 v[224:227], v239 offset:59968
	s_waitcnt lgkmcnt(10)
	v_mfma_f32_16x16x32_bf16 v[20:23], v[172:175], v[148:151], v[20:23]
	ds_read_b128 v[164:167], v238 offset:41536
	v_mfma_f32_16x16x32_bf16 v[28:31], v[176:179], v[148:151], v[28:31]
	ds_read_b128 v[228:231], v239 offset:62272
	v_mfma_f32_16x16x32_bf16 v[4:7], v[180:183], v[148:151], v[4:7]
	ds_read_b128 v[168:171], v238 offset:43840
	s_waitcnt lgkmcnt(12)
	v_mfma_f32_16x16x32_bf16 v[44:47], v[184:187], v[140:143], v[44:47]
	v_mfma_f32_16x16x32_bf16 v[48:51], v[184:187], v[144:147], v[48:51]
	s_waitcnt vmcnt(12)
	ds_write_b128 v236, v[80:83] offset:13824
	v_mfma_f32_16x16x32_bf16 v[12:15], v[184:187], v[148:151], v[12:15]
	s_waitcnt lgkmcnt(12)
	v_mfma_f32_16x16x32_bf16 v[24:27], v[172:175], v[152:155], v[24:27]
	s_waitcnt vmcnt(11)
	ds_write_b128 v236, v[84:87] offset:18432
	v_mfma_f32_16x16x32_bf16 v[32:35], v[176:179], v[152:155], v[32:35]
	v_mfma_f32_16x16x32_bf16 v[8:11], v[180:183], v[152:155], v[8:11]
	v_mfma_f32_16x16x32_bf16 v[16:19], v[184:187], v[152:155], v[16:19]
	s_waitcnt lgkmcnt(10)
	v_mfma_f32_16x16x32_bf16 v[52:55], v[216:219], v[156:159], v[52:55]
	s_waitcnt lgkmcnt(8)
	v_mfma_f32_16x16x32_bf16 v[60:63], v[220:223], v[156:159], v[60:63]
	s_waitcnt lgkmcnt(7)
	v_mfma_f32_16x16x32_bf16 v[56:59], v[216:219], v[160:163], v[56:59]
	s_waitcnt vmcnt(10)
	ds_write_b128 v236, v[88:91] offset:23040
	v_mfma_f32_16x16x32_bf16 v[64:67], v[220:223], v[160:163], v[64:67]
	s_waitcnt lgkmcnt(6)
	v_mfma_f32_16x16x32_bf16 v[36:39], v[224:227], v[156:159], v[36:39]
	s_waitcnt vmcnt(9)
	ds_write_b128 v236, v[92:95] offset:27648
	v_mfma_f32_16x16x32_bf16 v[40:43], v[224:227], v[160:163], v[40:43]
	s_waitcnt lgkmcnt(6)
	v_mfma_f32_16x16x32_bf16 v[20:23], v[216:219], v[164:167], v[20:23]
	s_waitcnt vmcnt(8)
	ds_write_b128 v236, v[96:99] offset:32256
	v_mfma_f32_16x16x32_bf16 v[28:31], v[220:223], v[164:167], v[28:31]
	v_mfma_f32_16x16x32_bf16 v[4:7], v[224:227], v[164:167], v[4:7]
	s_waitcnt lgkmcnt(6)
	v_mfma_f32_16x16x32_bf16 v[44:47], v[228:231], v[156:159], v[44:47]
	v_mfma_f32_16x16x32_bf16 v[48:51], v[228:231], v[160:163], v[48:51]
	v_mfma_f32_16x16x32_bf16 v[12:15], v[228:231], v[164:167], v[12:15]
	s_waitcnt lgkmcnt(5)
	v_mfma_f32_16x16x32_bf16 v[24:27], v[216:219], v[168:171], v[24:27]
	v_mfma_f32_16x16x32_bf16 v[32:35], v[220:223], v[168:171], v[32:35]
	v_mfma_f32_16x16x32_bf16 v[8:11], v[224:227], v[168:171], v[8:11]
	v_mfma_f32_16x16x32_bf16 v[16:19], v[228:231], v[168:171], v[16:19]
	s_setprio 0
	s_waitcnt lgkmcnt(0)
	s_barrier
	ds_read_b128 v[140:143], v238
	ds_read_b128 v[172:175], v239 offset:18432
	ds_read_b128 v[176:179], v239 offset:20736
	ds_read_b128 v[144:147], v238 offset:2304
	ds_read_b128 v[180:183], v239 offset:23040
	ds_read_b128 v[148:151], v238 offset:4608
	ds_read_b128 v[184:187], v239 offset:25344
	ds_read_b128 v[152:155], v238 offset:6912
	s_setprio 1
	s_waitcnt lgkmcnt(6)
	v_mfma_f32_16x16x32_bf16 v[52:55], v[172:175], v[140:143], v[52:55]
	s_waitcnt vmcnt(7)
	ds_write_b128 v237, v[100:103]
	s_waitcnt lgkmcnt(6)
	v_mfma_f32_16x16x32_bf16 v[60:63], v[176:179], v[140:143], v[60:63]
	ds_read_b128 v[156:159], v238 offset:64
	s_waitcnt lgkmcnt(6)
	v_mfma_f32_16x16x32_bf16 v[56:59], v[172:175], v[144:147], v[56:59]
	ds_read_b128 v[216:219], v239 offset:18496
	s_waitcnt vmcnt(6)
	ds_write_b128 v237, v[104:107] offset:4608
	v_mfma_f32_16x16x32_bf16 v[64:67], v[176:179], v[144:147], v[64:67]
	ds_read_b128 v[220:223], v239 offset:20800
	s_waitcnt lgkmcnt(8)
	v_mfma_f32_16x16x32_bf16 v[36:39], v[180:183], v[140:143], v[36:39]
	ds_read_b128 v[160:163], v238 offset:2368
	s_waitcnt vmcnt(5)
	ds_write_b128 v237, v[108:111] offset:9216
	v_mfma_f32_16x16x32_bf16 v[40:43], v[180:183], v[144:147], v[40:43]
	ds_read_b128 v[224:227], v239 offset:23104
	s_waitcnt lgkmcnt(10)
	v_mfma_f32_16x16x32_bf16 v[20:23], v[172:175], v[148:151], v[20:23]
	ds_read_b128 v[164:167], v238 offset:4672
	v_mfma_f32_16x16x32_bf16 v[28:31], v[176:179], v[148:151], v[28:31]
	ds_read_b128 v[228:231], v239 offset:25408
	v_mfma_f32_16x16x32_bf16 v[4:7], v[180:183], v[148:151], v[4:7]
	ds_read_b128 v[168:171], v238 offset:6976
	s_waitcnt lgkmcnt(12)
	v_mfma_f32_16x16x32_bf16 v[44:47], v[184:187], v[140:143], v[44:47]
	v_mfma_f32_16x16x32_bf16 v[48:51], v[184:187], v[144:147], v[48:51]
	s_waitcnt vmcnt(4)
	ds_write_b128 v237, v[112:115] offset:13824
	v_mfma_f32_16x16x32_bf16 v[12:15], v[184:187], v[148:151], v[12:15]
	s_waitcnt lgkmcnt(12)
	v_mfma_f32_16x16x32_bf16 v[24:27], v[172:175], v[152:155], v[24:27]
	s_waitcnt vmcnt(3)
	ds_write_b128 v237, v[116:119] offset:18432
	v_mfma_f32_16x16x32_bf16 v[32:35], v[176:179], v[152:155], v[32:35]
	v_mfma_f32_16x16x32_bf16 v[8:11], v[180:183], v[152:155], v[8:11]
	v_mfma_f32_16x16x32_bf16 v[16:19], v[184:187], v[152:155], v[16:19]
	s_waitcnt lgkmcnt(10)
	v_mfma_f32_16x16x32_bf16 v[52:55], v[216:219], v[156:159], v[52:55]
	s_waitcnt lgkmcnt(8)
	v_mfma_f32_16x16x32_bf16 v[60:63], v[220:223], v[156:159], v[60:63]
	s_waitcnt lgkmcnt(7)
	v_mfma_f32_16x16x32_bf16 v[56:59], v[216:219], v[160:163], v[56:59]
	s_waitcnt vmcnt(2)
	ds_write_b128 v237, v[120:123] offset:23040
	v_mfma_f32_16x16x32_bf16 v[64:67], v[220:223], v[160:163], v[64:67]
	s_waitcnt lgkmcnt(6)
	v_mfma_f32_16x16x32_bf16 v[36:39], v[224:227], v[156:159], v[36:39]
	s_waitcnt vmcnt(1)
	ds_write_b128 v237, v[124:127] offset:27648
	v_mfma_f32_16x16x32_bf16 v[40:43], v[224:227], v[160:163], v[40:43]
	s_waitcnt lgkmcnt(6)
	v_mfma_f32_16x16x32_bf16 v[20:23], v[216:219], v[164:167], v[20:23]
	s_waitcnt vmcnt(0)
	ds_write_b128 v237, v[128:131] offset:32256
	v_mfma_f32_16x16x32_bf16 v[28:31], v[220:223], v[164:167], v[28:31]
	v_mfma_f32_16x16x32_bf16 v[4:7], v[224:227], v[164:167], v[4:7]
	s_waitcnt lgkmcnt(6)
	v_mfma_f32_16x16x32_bf16 v[44:47], v[228:231], v[156:159], v[44:47]
	v_mfma_f32_16x16x32_bf16 v[48:51], v[228:231], v[160:163], v[48:51]
	v_mfma_f32_16x16x32_bf16 v[12:15], v[228:231], v[164:167], v[12:15]
	s_waitcnt lgkmcnt(5)
	v_mfma_f32_16x16x32_bf16 v[24:27], v[216:219], v[168:171], v[24:27]
	v_mfma_f32_16x16x32_bf16 v[32:35], v[220:223], v[168:171], v[32:35]
	v_mfma_f32_16x16x32_bf16 v[8:11], v[224:227], v[168:171], v[8:11]
	v_mfma_f32_16x16x32_bf16 v[16:19], v[228:231], v[168:171], v[16:19]
	s_setprio 0
	s_waitcnt lgkmcnt(0)
	s_barrier
	ds_read_b128 v[140:143], v238 offset:36864
	ds_read_b128 v[172:175], v239 offset:55296
	ds_read_b128 v[176:179], v239 offset:57600
	ds_read_b128 v[144:147], v238 offset:39168
	ds_read_b128 v[180:183], v239 offset:59904
	ds_read_b128 v[148:151], v238 offset:41472
	ds_read_b128 v[184:187], v239 offset:62208
	ds_read_b128 v[152:155], v238 offset:43776
	s_setprio 1
	s_waitcnt lgkmcnt(6)
	v_mfma_f32_16x16x32_bf16 v[52:55], v[172:175], v[140:143], v[52:55]
	s_waitcnt lgkmcnt(5)
	v_mfma_f32_16x16x32_bf16 v[60:63], v[176:179], v[140:143], v[60:63]
	ds_read_b128 v[156:159], v238 offset:36928
	s_waitcnt lgkmcnt(5)
	v_mfma_f32_16x16x32_bf16 v[56:59], v[172:175], v[144:147], v[56:59]
	ds_read_b128 v[216:219], v239 offset:55360
	v_mfma_f32_16x16x32_bf16 v[64:67], v[176:179], v[144:147], v[64:67]
	ds_read_b128 v[220:223], v239 offset:57664
	s_waitcnt lgkmcnt(6)
	v_mfma_f32_16x16x32_bf16 v[36:39], v[180:183], v[140:143], v[36:39]
	ds_read_b128 v[160:163], v238 offset:39232
	v_mfma_f32_16x16x32_bf16 v[40:43], v[180:183], v[144:147], v[40:43]
	ds_read_b128 v[224:227], v239 offset:59968
	s_waitcnt lgkmcnt(7)
	v_mfma_f32_16x16x32_bf16 v[20:23], v[172:175], v[148:151], v[20:23]
	ds_read_b128 v[164:167], v238 offset:41536
	v_mfma_f32_16x16x32_bf16 v[28:31], v[176:179], v[148:151], v[28:31]
	ds_read_b128 v[228:231], v239 offset:62272
	v_mfma_f32_16x16x32_bf16 v[4:7], v[180:183], v[148:151], v[4:7]
	ds_read_b128 v[168:171], v238 offset:43840
	s_waitcnt lgkmcnt(9)
	v_mfma_f32_16x16x32_bf16 v[44:47], v[184:187], v[140:143], v[44:47]
	v_mfma_f32_16x16x32_bf16 v[48:51], v[184:187], v[144:147], v[48:51]
	v_mfma_f32_16x16x32_bf16 v[12:15], v[184:187], v[148:151], v[12:15]
	s_waitcnt lgkmcnt(8)
	v_mfma_f32_16x16x32_bf16 v[24:27], v[172:175], v[152:155], v[24:27]
	v_mfma_f32_16x16x32_bf16 v[32:35], v[176:179], v[152:155], v[32:35]
	v_mfma_f32_16x16x32_bf16 v[8:11], v[180:183], v[152:155], v[8:11]
	v_mfma_f32_16x16x32_bf16 v[16:19], v[184:187], v[152:155], v[16:19]
	s_waitcnt lgkmcnt(6)
	v_mfma_f32_16x16x32_bf16 v[52:55], v[216:219], v[156:159], v[52:55]
	s_waitcnt lgkmcnt(5)
	v_mfma_f32_16x16x32_bf16 v[60:63], v[220:223], v[156:159], v[60:63]
	s_waitcnt lgkmcnt(4)
	v_mfma_f32_16x16x32_bf16 v[56:59], v[216:219], v[160:163], v[56:59]
	v_mfma_f32_16x16x32_bf16 v[64:67], v[220:223], v[160:163], v[64:67]
	s_waitcnt lgkmcnt(3)
	v_mfma_f32_16x16x32_bf16 v[36:39], v[224:227], v[156:159], v[36:39]
	v_mfma_f32_16x16x32_bf16 v[40:43], v[224:227], v[160:163], v[40:43]
	s_waitcnt lgkmcnt(2)
	v_mfma_f32_16x16x32_bf16 v[20:23], v[216:219], v[164:167], v[20:23]
	v_mfma_f32_16x16x32_bf16 v[28:31], v[220:223], v[164:167], v[28:31]
	v_mfma_f32_16x16x32_bf16 v[4:7], v[224:227], v[164:167], v[4:7]
	s_waitcnt lgkmcnt(1)
	v_mfma_f32_16x16x32_bf16 v[44:47], v[228:231], v[156:159], v[44:47]
	v_mfma_f32_16x16x32_bf16 v[48:51], v[228:231], v[160:163], v[48:51]
	v_mfma_f32_16x16x32_bf16 v[12:15], v[228:231], v[164:167], v[12:15]
	s_waitcnt lgkmcnt(0)
	v_mfma_f32_16x16x32_bf16 v[24:27], v[216:219], v[168:171], v[24:27]
	v_mfma_f32_16x16x32_bf16 v[32:35], v[220:223], v[168:171], v[32:35]
	v_mfma_f32_16x16x32_bf16 v[8:11], v[224:227], v[168:171], v[8:11]
	v_mfma_f32_16x16x32_bf16 v[16:19], v[228:231], v[168:171], v[16:19]
	s_setprio 0
	s_nop 7
	s_nop 4
	s_nop 4
	v_permlane16_swap_b32_e32 v52, v56
	v_permlane16_swap_b32_e32 v53, v57
	v_permlane16_swap_b32_e32 v54, v58
	v_permlane16_swap_b32_e32 v55, v59
	v_permlane16_swap_b32_e32 v60, v64
	v_permlane16_swap_b32_e32 v61, v65
	v_permlane16_swap_b32_e32 v62, v66
	v_permlane16_swap_b32_e32 v63, v67
	v_permlane16_swap_b32_e32 v36, v40
	v_permlane16_swap_b32_e32 v37, v41
	v_permlane16_swap_b32_e32 v38, v42
	v_permlane16_swap_b32_e32 v39, v43
	v_permlane16_swap_b32_e32 v44, v48
	v_permlane16_swap_b32_e32 v45, v49
	v_permlane16_swap_b32_e32 v46, v50
	v_permlane16_swap_b32_e32 v47, v51
	v_permlane16_swap_b32_e32 v20, v24
	v_permlane16_swap_b32_e32 v21, v25
	v_permlane16_swap_b32_e32 v22, v26
	v_permlane16_swap_b32_e32 v23, v27
	v_permlane16_swap_b32_e32 v28, v32
	v_permlane16_swap_b32_e32 v29, v33
	v_permlane16_swap_b32_e32 v30, v34
	v_permlane16_swap_b32_e32 v31, v35
	v_permlane16_swap_b32_e32 v4, v8
	v_permlane16_swap_b32_e32 v5, v9
	v_permlane16_swap_b32_e32 v6, v10
	v_permlane16_swap_b32_e32 v7, v11
	v_permlane16_swap_b32_e32 v12, v16
	v_permlane16_swap_b32_e32 v13, v17
	v_permlane16_swap_b32_e32 v14, v18
	v_permlane16_swap_b32_e32 v15, v19
	s_nop 1
	v_permlane32_swap_b32_e32 v52, v56
	v_permlane32_swap_b32_e32 v53, v57
	v_permlane32_swap_b32_e32 v54, v58
	v_permlane32_swap_b32_e32 v55, v59
	v_permlane32_swap_b32_e32 v60, v64
	v_permlane32_swap_b32_e32 v61, v65
	v_permlane32_swap_b32_e32 v62, v66
	v_permlane32_swap_b32_e32 v63, v67
	v_permlane32_swap_b32_e32 v36, v40
	v_permlane32_swap_b32_e32 v37, v41
	v_permlane32_swap_b32_e32 v38, v42
	v_permlane32_swap_b32_e32 v39, v43
	v_permlane32_swap_b32_e32 v44, v48
	v_permlane32_swap_b32_e32 v45, v49
	v_permlane32_swap_b32_e32 v46, v50
	v_permlane32_swap_b32_e32 v47, v51
	v_permlane32_swap_b32_e32 v20, v24
	v_permlane32_swap_b32_e32 v21, v25
	v_permlane32_swap_b32_e32 v22, v26
	v_permlane32_swap_b32_e32 v23, v27
	v_permlane32_swap_b32_e32 v28, v32
	v_permlane32_swap_b32_e32 v29, v33
	v_permlane32_swap_b32_e32 v30, v34
	v_permlane32_swap_b32_e32 v31, v35
	v_permlane32_swap_b32_e32 v4, v8
	v_permlane32_swap_b32_e32 v5, v9
	v_permlane32_swap_b32_e32 v6, v10
	v_permlane32_swap_b32_e32 v7, v11
	v_permlane32_swap_b32_e32 v12, v16
	v_permlane32_swap_b32_e32 v13, v17
	v_permlane32_swap_b32_e32 v14, v18
	v_permlane32_swap_b32_e32 v15, v19
	s_nop 1
	s_barrier
	s_load_dword s34, s[62:63], 0x0
	s_waitcnt lgkmcnt(0)
	s_add_i32 s34, s34, s21
	s_cmpk_gt_i32 s34, 0xaff
	s_cselect_b64 s[18:19], -1, 0
	s_and_b64 vcc, exec, s[18:19]
	s_cbranch_vccnz .LBB0_22
	s_lshl_b32 s20, s34, 18
	v_readlane_b32 s24, v252, 47
	v_mov_b32_e32 v2, v0
	s_and_b32 s20, s20, 0xfc0000
	v_readlane_b32 s30, v252, 53
	v_readlane_b32 s31, v252, 54
	v_ashrrev_i32_e32 v68, 3, v2
	s_add_u32 s22, s30, s20
	v_ashrrev_i32_e32 v69, 31, v68
	s_addc_u32 s23, s31, 0
	v_lshlrev_b64 v[68:69], 11, v[68:69]
	v_lshlrev_b32_e32 v2, 4, v2
	v_lshl_add_u64 v[70:71], s[22:23], 0, v[68:69]
	v_and_b32_e32 v2, 0x70, v2
	v_readlane_b32 s25, v252, 48
	s_ashr_i32 s24, s34, 6
	v_lshl_add_u64 v[132:133], v[70:71], 0, v[2:3]
	s_ashr_i32 s25, s24, 31
	v_add_co_u32_e32 v76, vcc, s33, v132
	s_lshl_b64 s[24:25], s[24:25], 17
	s_nop 0
	v_addc_co_u32_e32 v77, vcc, 0, v133, vcc
	s_add_u32 s24, s37, s24
	v_add_co_u32_e32 v80, vcc, s78, v132
	s_addc_u32 s25, s40, s25
	s_nop 0
	v_addc_co_u32_e32 v81, vcc, 0, v133, vcc
	v_lshl_add_u64 v[68:69], s[24:25], 0, v[68:69]
	v_add_co_u32_e32 v84, vcc, s79, v132
	v_lshl_add_u64 v[134:135], v[68:69], 0, v[2:3]
	s_nop 0
	v_addc_co_u32_e32 v85, vcc, 0, v133, vcc
	v_add_co_u32_e32 v92, vcc, s33, v134
	v_readlane_b32 s26, v252, 49
	s_nop 0
	v_addc_co_u32_e32 v93, vcc, 0, v135, vcc
	v_add_co_u32_e32 v96, vcc, 0x580000, v134
	v_readlane_b32 s27, v252, 50
	s_nop 0
	v_addc_co_u32_e32 v97, vcc, 0, v135, vcc
	v_add_co_u32_e32 v128, vcc, 0x590000, v134
	v_readlane_b32 s28, v252, 51
	s_nop 0
	v_addc_co_u32_e32 v129, vcc, 0, v135, vcc
	global_load_dwordx4 v[68:71], v[132:133], off
	global_load_dwordx4 v[100:103], v[132:133], off offset:128
	global_load_dwordx4 v[72:75], v[76:77], off
	global_load_dwordx4 v[104:107], v[76:77], off offset:128
	s_nop 0
	global_load_dwordx4 v[76:79], v[80:81], off
	global_load_dwordx4 v[108:111], v[80:81], off offset:128
	s_nop 0
	global_load_dwordx4 v[80:83], v[84:85], off
	global_load_dwordx4 v[112:115], v[84:85], off offset:128
	s_nop 0
	global_load_dwordx4 v[84:87], v[134:135], off
	global_load_dwordx4 v[116:119], v[134:135], off offset:128
	global_load_dwordx4 v[88:91], v[92:93], off
	global_load_dwordx4 v[120:123], v[92:93], off offset:128
	s_nop 0
	global_load_dwordx4 v[92:95], v[96:97], off
	global_load_dwordx4 v[124:127], v[96:97], off offset:128
	s_nop 0
	global_load_dwordx4 v[96:99], v[128:129], off
	s_nop 0
	global_load_dwordx4 v[128:131], v[128:129], off offset:128
	v_readlane_b32 s29, v252, 52

.LBB0_300:
	s_and_b32 s0, s76, 0xfffffe00
	s_cmpk_eq_i32 s0, 0xc00
	s_cselect_b64 s[0:1], -1, 0
	s_and_b64 s[0:1], s[26:27], s[0:1]
	s_cmpk_lt_i32 s76, 0xd00
	s_movk_i32 s2, 0xff00
	s_cselect_b32 s2, 0x100, s2
	s_and_b64 s[0:1], s[0:1], exec
	s_cselect_b32 s77, s2, 0
	s_add_i32 s77, s77, s76
	s_cmpk_lt_i32 s77, 0xd00
	s_mov_b64 s[0:1], -1
	s_cbranch_scc0 .LBB0_423
	s_mov_b32 s0, 0x10000
	s_mov_b32 s1, 0
	v_lshl_add_u64 v[134:135], s[0:1], 0, v[148:149]
	s_mov_b32 s0, 0x20000
	s_mov_b32 s1, 0
	v_lshl_add_u64 v[194:195], s[0:1], 0, v[148:149]
	s_mov_b32 s0, 0x30000
	s_mov_b32 s1, 0
	v_lshl_add_u64 v[196:197], s[0:1], 0, v[148:149]
	s_mov_b32 s0, 0x10000
	s_mov_b32 s1, 0
	v_lshl_add_u64 v[214:215], s[0:1], 0, v[150:151]
	s_mov_b32 s0, 0x20000
	s_mov_b32 s1, 0
	v_lshl_add_u64 v[236:237], s[0:1], 0, v[150:151]
	s_mov_b32 s0, 0x30000
	s_mov_b32 s1, 0
	v_lshl_add_u64 v[238:239], s[0:1], 0, v[150:151]
	v_lshrrev_b32_e32 v172, 3, v0
	v_and_b32_e32 v174, 15, v172
	v_lshlrev_b32_e32 v173, 1, v174
	v_cmp_gt_u32_e32 vcc, 12, v174
	s_nop 1
	v_mov_b32_e32 v175, 15
	v_cndmask_b32_e64 v175, v175, 8, vcc
	v_cmp_gt_u32_e32 vcc, 4, v174
	v_sub_u32_e32 v173, v173, v175
	v_lshlrev_b32_e32 v175, 1, v174
	v_add_u32_e32 v175, 1, v175
	s_nop 1
	v_cndmask_b32_e32 v173, v173, v175, vcc
	v_and_b32_e32 v172, 16, v172
	v_add_u32_e32 v172, v172, v173
	v_mul_u32_u24_e32 v172, 0x90, v172
	v_and_b32_e32 v173, 7, v0
	v_lshl_add_u32 v240, v173, 4, v172
	v_add_u32_e32 v241, 0x9000, v240
	v_and_b32_e32 v174, 15, v0
	v_lshlrev_b32_e32 v173, 1, v174
	v_cmp_gt_u32_e32 vcc, 12, v174
	s_nop 1
	v_mov_b32_e32 v175, 15
	v_cndmask_b32_e64 v175, v175, 8, vcc
	v_cmp_gt_u32_e32 vcc, 4, v174
	v_sub_u32_e32 v173, v173, v175
	v_lshlrev_b32_e32 v175, 1, v174
	v_add_u32_e32 v175, 1, v175
	s_nop 1
	v_cndmask_b32_e32 v173, v173, v175, vcc
	v_bfe_u32 v172, v0, 4, 2
	v_and_b32_e32 v174, 1, v172
	v_lshrrev_b32_e32 v172, 1, v172
	v_lshl_or_b32 v172, v174, 1, v172
	v_lshlrev_b32_e32 v172, 4, v172
	v_lshrrev_b32_e32 v174, 1, v0
	v_and_b32_e32 v174, 64, v174
	v_add_u32_e32 v174, v174, v173
	v_mul_u32_u24_e32 v174, 0x90, v174
	v_add_u32_e32 v242, v174, v172
	v_and_b32_e32 v174, 64, v0
	v_add_u32_e32 v174, v174, v173
	v_mul_u32_u24_e32 v174, 0x90, v174
	v_add_u32_e32 v243, v174, v172
	s_barrier
	s_waitcnt vmcnt(15)
	ds_write_b128 v240, v[68:71]
	s_waitcnt vmcnt(13)
	ds_write_b128 v240, v[72:75] offset:4608
	s_waitcnt vmcnt(11)
	ds_write_b128 v240, v[76:79] offset:9216
	s_waitcnt vmcnt(9)
	ds_write_b128 v240, v[80:83] offset:13824
	s_waitcnt vmcnt(7)
	ds_write_b128 v240, v[84:87] offset:18432
	s_waitcnt vmcnt(5)
	ds_write_b128 v240, v[88:91] offset:23040
	s_waitcnt vmcnt(3)
	ds_write_b128 v240, v[92:95] offset:27648
	s_waitcnt vmcnt(1)
	ds_write_b128 v240, v[96:99] offset:32256
	global_load_dwordx4 v[68:71], v[148:149], off offset:256
	global_load_dwordx4 v[72:75], v[134:135], off offset:256
	global_load_dwordx4 v[76:79], v[194:195], off offset:256
	global_load_dwordx4 v[80:83], v[196:197], off offset:256
	global_load_dwordx4 v[84:87], v[150:151], off offset:256
	global_load_dwordx4 v[88:91], v[214:215], off offset:256
	global_load_dwordx4 v[92:95], v[236:237], off offset:256
	global_load_dwordx4 v[96:99], v[238:239], off offset:256
	s_waitcnt lgkmcnt(0)
	s_barrier
	ds_read_b128 v[136:139], v242
	ds_read_b128 v[176:179], v243 offset:18432
	ds_read_b128 v[180:183], v243 offset:20736
	ds_read_b128 v[140:143], v242 offset:2304
	ds_read_b128 v[184:187], v243 offset:23040
	ds_read_b128 v[152:155], v242 offset:4608
	ds_read_b128 v[216:219], v243 offset:25344
	ds_read_b128 v[156:159], v242 offset:6912
	s_setprio 1
	s_waitcnt lgkmcnt(6)
	v_mfma_f32_16x16x32_bf16 v[52:55], v[176:179], v[136:139], 0
	ds_write_b128 v241, v[100:103]
	s_waitcnt lgkmcnt(6)
	v_mfma_f32_16x16x32_bf16 v[60:63], v[180:183], v[136:139], 0
	ds_read_b128 v[160:163], v242 offset:64
	s_waitcnt lgkmcnt(6)
	v_mfma_f32_16x16x32_bf16 v[56:59], v[176:179], v[140:143], 0
	ds_read_b128 v[220:223], v243 offset:18496
	ds_write_b128 v241, v[104:107] offset:4608
	v_mfma_f32_16x16x32_bf16 v[64:67], v[180:183], v[140:143], 0
	ds_read_b128 v[224:227], v243 offset:20800
	s_waitcnt lgkmcnt(8)
	v_mfma_f32_16x16x32_bf16 v[36:39], v[184:187], v[136:139], 0
	ds_read_b128 v[164:167], v242 offset:2368
	ds_write_b128 v241, v[108:111] offset:9216
	global_load_dwordx4 v[100:103], v[148:149], off offset:384
	v_mfma_f32_16x16x32_bf16 v[40:43], v[184:187], v[140:143], 0
	ds_read_b128 v[228:231], v243 offset:23104
	s_waitcnt lgkmcnt(10)
	v_mfma_f32_16x16x32_bf16 v[20:23], v[176:179], v[152:155], 0
	ds_read_b128 v[168:171], v242 offset:4672
	v_mfma_f32_16x16x32_bf16 v[28:31], v[180:183], v[152:155], 0
	ds_read_b128 v[232:235], v243 offset:25408
	v_mfma_f32_16x16x32_bf16 v[4:7], v[184:187], v[152:155], 0
	ds_read_b128 v[172:175], v242 offset:6976
	s_waitcnt lgkmcnt(12)
	v_mfma_f32_16x16x32_bf16 v[44:47], v[216:219], v[136:139], 0
	v_mfma_f32_16x16x32_bf16 v[48:51], v[216:219], v[140:143], 0
	ds_write_b128 v241, v[112:115] offset:13824
	global_load_dwordx4 v[104:107], v[134:135], off offset:384
	v_mfma_f32_16x16x32_bf16 v[12:15], v[216:219], v[152:155], 0
	s_waitcnt lgkmcnt(12)
	v_mfma_f32_16x16x32_bf16 v[24:27], v[176:179], v[156:159], 0
	ds_write_b128 v241, v[116:119] offset:18432
	global_load_dwordx4 v[108:111], v[194:195], off offset:384
	v_mfma_f32_16x16x32_bf16 v[32:35], v[180:183], v[156:159], 0
	v_mfma_f32_16x16x32_bf16 v[8:11], v[184:187], v[156:159], 0
	v_mfma_f32_16x16x32_bf16 v[16:19], v[216:219], v[156:159], 0
	s_waitcnt lgkmcnt(10)
	v_mfma_f32_16x16x32_bf16 v[52:55], v[220:223], v[160:163], v[52:55]
	s_waitcnt lgkmcnt(8)
	v_mfma_f32_16x16x32_bf16 v[60:63], v[224:227], v[160:163], v[60:63]
	s_waitcnt lgkmcnt(7)
	v_mfma_f32_16x16x32_bf16 v[56:59], v[220:223], v[164:167], v[56:59]
	ds_write_b128 v241, v[120:123] offset:23040
	global_load_dwordx4 v[112:115], v[196:197], off offset:384
	v_mfma_f32_16x16x32_bf16 v[64:67], v[224:227], v[164:167], v[64:67]
	s_waitcnt lgkmcnt(6)
	v_mfma_f32_16x16x32_bf16 v[36:39], v[228:231], v[160:163], v[36:39]
	ds_write_b128 v241, v[124:127] offset:27648
	global_load_dwordx4 v[116:119], v[150:151], off offset:384
	v_mfma_f32_16x16x32_bf16 v[40:43], v[228:231], v[164:167], v[40:43]
	s_waitcnt lgkmcnt(6)
	v_mfma_f32_16x16x32_bf16 v[20:23], v[220:223], v[168:171], v[20:23]
	s_waitcnt vmcnt(13)
	ds_write_b128 v241, v[128:131] offset:32256
	global_load_dwordx4 v[120:123], v[214:215], off offset:384
	v_mfma_f32_16x16x32_bf16 v[28:31], v[224:227], v[168:171], v[28:31]
	v_mfma_f32_16x16x32_bf16 v[4:7], v[228:231], v[168:171], v[4:7]
	global_load_dwordx4 v[124:127], v[236:237], off offset:384
	s_waitcnt lgkmcnt(6)
	v_mfma_f32_16x16x32_bf16 v[44:47], v[232:235], v[160:163], v[44:47]
	v_mfma_f32_16x16x32_bf16 v[48:51], v[232:235], v[164:167], v[48:51]
	global_load_dwordx4 v[128:131], v[238:239], off offset:384
	v_mfma_f32_16x16x32_bf16 v[12:15], v[232:235], v[168:171], v[12:15]
	s_waitcnt lgkmcnt(5)
	v_mfma_f32_16x16x32_bf16 v[24:27], v[220:223], v[172:175], v[24:27]
	v_mfma_f32_16x16x32_bf16 v[32:35], v[224:227], v[172:175], v[32:35]
	v_mfma_f32_16x16x32_bf16 v[8:11], v[228:231], v[172:175], v[8:11]
	v_mfma_f32_16x16x32_bf16 v[16:19], v[232:235], v[172:175], v[16:19]
	s_setprio 0
	s_waitcnt lgkmcnt(0)
	s_barrier
	ds_read_b128 v[136:139], v242 offset:36864
	ds_read_b128 v[176:179], v243 offset:55296
	ds_read_b128 v[180:183], v243 offset:57600
	ds_read_b128 v[140:143], v242 offset:39168
	ds_read_b128 v[184:187], v243 offset:59904
	ds_read_b128 v[152:155], v242 offset:41472
	ds_read_b128 v[216:219], v243 offset:62208
	ds_read_b128 v[156:159], v242 offset:43776
	s_setprio 1
	s_waitcnt lgkmcnt(6)
	v_mfma_f32_16x16x32_bf16 v[52:55], v[176:179], v[136:139], v[52:55]
	s_waitcnt vmcnt(15)
	ds_write_b128 v240, v[68:71]
	s_waitcnt lgkmcnt(6)
	v_mfma_f32_16x16x32_bf16 v[60:63], v[180:183], v[136:139], v[60:63]
	ds_read_b128 v[160:163], v242 offset:36928
	s_waitcnt lgkmcnt(6)
	v_mfma_f32_16x16x32_bf16 v[56:59], v[176:179], v[140:143], v[56:59]
	ds_read_b128 v[220:223], v243 offset:55360
	s_waitcnt vmcnt(14)
	ds_write_b128 v240, v[72:75] offset:4608
	v_mfma_f32_16x16x32_bf16 v[64:67], v[180:183], v[140:143], v[64:67]
	ds_read_b128 v[224:227], v243 offset:57664
	s_waitcnt lgkmcnt(8)
	v_mfma_f32_16x16x32_bf16 v[36:39], v[184:187], v[136:139], v[36:39]
	ds_read_b128 v[164:167], v242 offset:39232
	s_waitcnt vmcnt(13)
	ds_write_b128 v240, v[76:79] offset:9216
	global_load_dwordx4 v[68:71], v[148:149], off offset:512
	v_mfma_f32_16x16x32_bf16 v[40:43], v[184:187], v[140:143], v[40:43]
	ds_read_b128 v[228:231], v243 offset:59968
	s_waitcnt lgkmcnt(10)
	v_mfma_f32_16x16x32_bf16 v[20:23], v[176:179], v[152:155], v[20:23]
	ds_read_b128 v[168:171], v242 offset:41536
	v_mfma_f32_16x16x32_bf16 v[28:31], v[180:183], v[152:155], v[28:31]
	ds_read_b128 v[232:235], v243 offset:62272
	v_mfma_f32_16x16x32_bf16 v[4:7], v[184:187], v[152:155], v[4:7]
	ds_read_b128 v[172:175], v242 offset:43840
	s_waitcnt lgkmcnt(12)
	v_mfma_f32_16x16x32_bf16 v[44:47], v[216:219], v[136:139], v[44:47]
	v_mfma_f32_16x16x32_bf16 v[48:51], v[216:219], v[140:143], v[48:51]
	s_waitcnt vmcnt(13)
	ds_write_b128 v240, v[80:83] offset:13824
	global_load_dwordx4 v[72:75], v[134:135], off offset:512
	v_mfma_f32_16x16x32_bf16 v[12:15], v[216:219], v[152:155], v[12:15]
	s_waitcnt lgkmcnt(12)
	v_mfma_f32_16x16x32_bf16 v[24:27], v[176:179], v[156:159], v[24:27]
	s_waitcnt vmcnt(13)
	ds_write_b128 v240, v[84:87] offset:18432
	global_load_dwordx4 v[76:79], v[194:195], off offset:512
	v_mfma_f32_16x16x32_bf16 v[32:35], v[180:183], v[156:159], v[32:35]
	v_mfma_f32_16x16x32_bf16 v[8:11], v[184:187], v[156:159], v[8:11]
	v_mfma_f32_16x16x32_bf16 v[16:19], v[216:219], v[156:159], v[16:19]
	s_waitcnt lgkmcnt(10)
	v_mfma_f32_16x16x32_bf16 v[52:55], v[220:223], v[160:163], v[52:55]
	s_waitcnt lgkmcnt(8)
	v_mfma_f32_16x16x32_bf16 v[60:63], v[224:227], v[160:163], v[60:63]
	s_waitcnt lgkmcnt(7)
	v_mfma_f32_16x16x32_bf16 v[56:59], v[220:223], v[164:167], v[56:59]
	s_waitcnt vmcnt(13)
	ds_write_b128 v240, v[88:91] offset:23040
	global_load_dwordx4 v[80:83], v[196:197], off offset:512
	v_mfma_f32_16x16x32_bf16 v[64:67], v[224:227], v[164:167], v[64:67]
	s_waitcnt lgkmcnt(6)
	v_mfma_f32_16x16x32_bf16 v[36:39], v[228:231], v[160:163], v[36:39]
	s_waitcnt vmcnt(13)
	ds_write_b128 v240, v[92:95] offset:27648
	global_load_dwordx4 v[84:87], v[150:151], off offset:512
	v_mfma_f32_16x16x32_bf16 v[40:43], v[228:231], v[164:167], v[40:43]
	s_waitcnt lgkmcnt(6)
	v_mfma_f32_16x16x32_bf16 v[20:23], v[220:223], v[168:171], v[20:23]
	s_waitcnt vmcnt(13)
	ds_write_b128 v240, v[96:99] offset:32256
	global_load_dwordx4 v[88:91], v[214:215], off offset:512
	v_mfma_f32_16x16x32_bf16 v[28:31], v[224:227], v[168:171], v[28:31]
	v_mfma_f32_16x16x32_bf16 v[4:7], v[228:231], v[168:171], v[4:7]
	global_load_dwordx4 v[92:95], v[236:237], off offset:512
	s_waitcnt lgkmcnt(6)
	v_mfma_f32_16x16x32_bf16 v[44:47], v[232:235], v[160:163], v[44:47]
	v_mfma_f32_16x16x32_bf16 v[48:51], v[232:235], v[164:167], v[48:51]
	global_load_dwordx4 v[96:99], v[238:239], off offset:512
	v_mfma_f32_16x16x32_bf16 v[12:15], v[232:235], v[168:171], v[12:15]
	s_waitcnt lgkmcnt(5)
	v_mfma_f32_16x16x32_bf16 v[24:27], v[220:223], v[172:175], v[24:27]
	v_mfma_f32_16x16x32_bf16 v[32:35], v[224:227], v[172:175], v[32:35]
	v_mfma_f32_16x16x32_bf16 v[8:11], v[228:231], v[172:175], v[8:11]
	v_mfma_f32_16x16x32_bf16 v[16:19], v[232:235], v[172:175], v[16:19]
	s_setprio 0
	s_waitcnt lgkmcnt(0)
	s_barrier
	ds_read_b128 v[136:139], v242
	ds_read_b128 v[176:179], v243 offset:18432
	ds_read_b128 v[180:183], v243 offset:20736
	ds_read_b128 v[140:143], v242 offset:2304
	ds_read_b128 v[184:187], v243 offset:23040
	ds_read_b128 v[152:155], v242 offset:4608
	ds_read_b128 v[216:219], v243 offset:25344
	ds_read_b128 v[156:159], v242 offset:6912
	s_setprio 1
	s_waitcnt lgkmcnt(6)
	v_mfma_f32_16x16x32_bf16 v[52:55], v[176:179], v[136:139], v[52:55]
	s_waitcnt vmcnt(15)
	ds_write_b128 v241, v[100:103]
	s_waitcnt lgkmcnt(6)
	v_mfma_f32_16x16x32_bf16 v[60:63], v[180:183], v[136:139], v[60:63]
	ds_read_b128 v[160:163], v242 offset:64
	s_waitcnt lgkmcnt(6)
	v_mfma_f32_16x16x32_bf16 v[56:59], v[176:179], v[140:143], v[56:59]
	ds_read_b128 v[220:223], v243 offset:18496
	s_waitcnt vmcnt(14)
	ds_write_b128 v241, v[104:107] offset:4608
	v_mfma_f32_16x16x32_bf16 v[64:67], v[180:183], v[140:143], v[64:67]
	ds_read_b128 v[224:227], v243 offset:20800
	s_waitcnt lgkmcnt(8)
	v_mfma_f32_16x16x32_bf16 v[36:39], v[184:187], v[136:139], v[36:39]
	ds_read_b128 v[164:167], v242 offset:2368
	s_waitcnt vmcnt(13)
	ds_write_b128 v241, v[108:111] offset:9216
	global_load_dwordx4 v[100:103], v[148:149], off offset:640
	v_mfma_f32_16x16x32_bf16 v[40:43], v[184:187], v[140:143], v[40:43]
	ds_read_b128 v[228:231], v243 offset:23104
	s_waitcnt lgkmcnt(10)
	v_mfma_f32_16x16x32_bf16 v[20:23], v[176:179], v[152:155], v[20:23]
	ds_read_b128 v[168:171], v242 offset:4672
	v_mfma_f32_16x16x32_bf16 v[28:31], v[180:183], v[152:155], v[28:31]
	ds_read_b128 v[232:235], v243 offset:25408
	v_mfma_f32_16x16x32_bf16 v[4:7], v[184:187], v[152:155], v[4:7]
	ds_read_b128 v[172:175], v242 offset:6976
	s_waitcnt lgkmcnt(12)
	v_mfma_f32_16x16x32_bf16 v[44:47], v[216:219], v[136:139], v[44:47]
	v_mfma_f32_16x16x32_bf16 v[48:51], v[216:219], v[140:143], v[48:51]
	s_waitcnt vmcnt(13)
	ds_write_b128 v241, v[112:115] offset:13824
	global_load_dwordx4 v[104:107], v[134:135], off offset:640
	v_mfma_f32_16x16x32_bf16 v[12:15], v[216:219], v[152:155], v[12:15]
	s_waitcnt lgkmcnt(12)
	v_mfma_f32_16x16x32_bf16 v[24:27], v[176:179], v[156:159], v[24:27]
	s_waitcnt vmcnt(13)
	ds_write_b128 v241, v[116:119] offset:18432
	global_load_dwordx4 v[108:111], v[194:195], off offset:640
	v_mfma_f32_16x16x32_bf16 v[32:35], v[180:183], v[156:159], v[32:35]
	v_mfma_f32_16x16x32_bf16 v[8:11], v[184:187], v[156:159], v[8:11]
	v_mfma_f32_16x16x32_bf16 v[16:19], v[216:219], v[156:159], v[16:19]
	s_waitcnt lgkmcnt(10)
	v_mfma_f32_16x16x32_bf16 v[52:55], v[220:223], v[160:163], v[52:55]
	s_waitcnt lgkmcnt(8)
	v_mfma_f32_16x16x32_bf16 v[60:63], v[224:227], v[160:163], v[60:63]
	s_waitcnt lgkmcnt(7)
	v_mfma_f32_16x16x32_bf16 v[56:59], v[220:223], v[164:167], v[56:59]
	s_waitcnt vmcnt(13)
	ds_write_b128 v241, v[120:123] offset:23040
	global_load_dwordx4 v[112:115], v[196:197], off offset:640
	v_mfma_f32_16x16x32_bf16 v[64:67], v[224:227], v[164:167], v[64:67]
	s_waitcnt lgkmcnt(6)
	v_mfma_f32_16x16x32_bf16 v[36:39], v[228:231], v[160:163], v[36:39]
	s_waitcnt vmcnt(13)
	ds_write_b128 v241, v[124:127] offset:27648
	global_load_dwordx4 v[116:119], v[150:151], off offset:640
	v_mfma_f32_16x16x32_bf16 v[40:43], v[228:231], v[164:167], v[40:43]
	s_waitcnt lgkmcnt(6)
	v_mfma_f32_16x16x32_bf16 v[20:23], v[220:223], v[168:171], v[20:23]
	s_waitcnt vmcnt(13)
	ds_write_b128 v241, v[128:131] offset:32256
	global_load_dwordx4 v[120:123], v[214:215], off offset:640
	v_mfma_f32_16x16x32_bf16 v[28:31], v[224:227], v[168:171], v[28:31]
	v_mfma_f32_16x16x32_bf16 v[4:7], v[228:231], v[168:171], v[4:7]
	global_load_dwordx4 v[124:127], v[236:237], off offset:640
	s_waitcnt lgkmcnt(6)
	v_mfma_f32_16x16x32_bf16 v[44:47], v[232:235], v[160:163], v[44:47]
	v_mfma_f32_16x16x32_bf16 v[48:51], v[232:235], v[164:167], v[48:51]
	global_load_dwordx4 v[128:131], v[238:239], off offset:640
	v_mfma_f32_16x16x32_bf16 v[12:15], v[232:235], v[168:171], v[12:15]
	s_waitcnt lgkmcnt(5)
	v_mfma_f32_16x16x32_bf16 v[24:27], v[220:223], v[172:175], v[24:27]
	v_mfma_f32_16x16x32_bf16 v[32:35], v[224:227], v[172:175], v[32:35]
	v_mfma_f32_16x16x32_bf16 v[8:11], v[228:231], v[172:175], v[8:11]
	v_mfma_f32_16x16x32_bf16 v[16:19], v[232:235], v[172:175], v[16:19]
	s_setprio 0
	s_waitcnt lgkmcnt(0)
	s_barrier
	ds_read_b128 v[136:139], v242 offset:36864
	ds_read_b128 v[176:179], v243 offset:55296
	ds_read_b128 v[180:183], v243 offset:57600
	ds_read_b128 v[140:143], v242 offset:39168
	ds_read_b128 v[184:187], v243 offset:59904
	ds_read_b128 v[152:155], v242 offset:41472
	ds_read_b128 v[216:219], v243 offset:62208
	ds_read_b128 v[156:159], v242 offset:43776
	s_setprio 1
	s_waitcnt lgkmcnt(6)
	v_mfma_f32_16x16x32_bf16 v[52:55], v[176:179], v[136:139], v[52:55]
	s_waitcnt vmcnt(15)
	ds_write_b128 v240, v[68:71]
	s_waitcnt lgkmcnt(6)
	v_mfma_f32_16x16x32_bf16 v[60:63], v[180:183], v[136:139], v[60:63]
	ds_read_b128 v[160:163], v242 offset:36928
	s_waitcnt lgkmcnt(6)
	v_mfma_f32_16x16x32_bf16 v[56:59], v[176:179], v[140:143], v[56:59]
	ds_read_b128 v[220:223], v243 offset:55360
	s_waitcnt vmcnt(14)
	ds_write_b128 v240, v[72:75] offset:4608
	v_mfma_f32_16x16x32_bf16 v[64:67], v[180:183], v[140:143], v[64:67]
	ds_read_b128 v[224:227], v243 offset:57664
	s_waitcnt lgkmcnt(8)
	v_mfma_f32_16x16x32_bf16 v[36:39], v[184:187], v[136:139], v[36:39]
	ds_read_b128 v[164:167], v242 offset:39232
	s_waitcnt vmcnt(13)
	ds_write_b128 v240, v[76:79] offset:9216
	global_load_dwordx4 v[68:71], v[148:149], off offset:768
	v_mfma_f32_16x16x32_bf16 v[40:43], v[184:187], v[140:143], v[40:43]
	ds_read_b128 v[228:231], v243 offset:59968
	s_waitcnt lgkmcnt(10)
	v_mfma_f32_16x16x32_bf16 v[20:23], v[176:179], v[152:155], v[20:23]
	ds_read_b128 v[168:171], v242 offset:41536
	v_mfma_f32_16x16x32_bf16 v[28:31], v[180:183], v[152:155], v[28:31]
	ds_read_b128 v[232:235], v243 offset:62272
	v_mfma_f32_16x16x32_bf16 v[4:7], v[184:187], v[152:155], v[4:7]
	ds_read_b128 v[172:175], v242 offset:43840
	s_waitcnt lgkmcnt(12)
	v_mfma_f32_16x16x32_bf16 v[44:47], v[216:219], v[136:139], v[44:47]
	v_mfma_f32_16x16x32_bf16 v[48:51], v[216:219], v[140:143], v[48:51]
	s_waitcnt vmcnt(13)
	ds_write_b128 v240, v[80:83] offset:13824
	global_load_dwordx4 v[72:75], v[134:135], off offset:768
	v_mfma_f32_16x16x32_bf16 v[12:15], v[216:219], v[152:155], v[12:15]
	s_waitcnt lgkmcnt(12)
	v_mfma_f32_16x16x32_bf16 v[24:27], v[176:179], v[156:159], v[24:27]
	s_waitcnt vmcnt(13)
	ds_write_b128 v240, v[84:87] offset:18432
	global_load_dwordx4 v[76:79], v[194:195], off offset:768
	v_mfma_f32_16x16x32_bf16 v[32:35], v[180:183], v[156:159], v[32:35]
	v_mfma_f32_16x16x32_bf16 v[8:11], v[184:187], v[156:159], v[8:11]
	v_mfma_f32_16x16x32_bf16 v[16:19], v[216:219], v[156:159], v[16:19]
	s_waitcnt lgkmcnt(10)
	v_mfma_f32_16x16x32_bf16 v[52:55], v[220:223], v[160:163], v[52:55]
	s_waitcnt lgkmcnt(8)
	v_mfma_f32_16x16x32_bf16 v[60:63], v[224:227], v[160:163], v[60:63]
	s_waitcnt lgkmcnt(7)
	v_mfma_f32_16x16x32_bf16 v[56:59], v[220:223], v[164:167], v[56:59]
	s_waitcnt vmcnt(13)
	ds_write_b128 v240, v[88:91] offset:23040
	global_load_dwordx4 v[80:83], v[196:197], off offset:768
	v_mfma_f32_16x16x32_bf16 v[64:67], v[224:227], v[164:167], v[64:67]
	s_waitcnt lgkmcnt(6)
	v_mfma_f32_16x16x32_bf16 v[36:39], v[228:231], v[160:163], v[36:39]
	s_waitcnt vmcnt(13)
	ds_write_b128 v240, v[92:95] offset:27648
	global_load_dwordx4 v[84:87], v[150:151], off offset:768
	v_mfma_f32_16x16x32_bf16 v[40:43], v[228:231], v[164:167], v[40:43]
	s_waitcnt lgkmcnt(6)
	v_mfma_f32_16x16x32_bf16 v[20:23], v[220:223], v[168:171], v[20:23]
	s_waitcnt vmcnt(13)
	ds_write_b128 v240, v[96:99] offset:32256
	global_load_dwordx4 v[88:91], v[214:215], off offset:768
	v_mfma_f32_16x16x32_bf16 v[28:31], v[224:227], v[168:171], v[28:31]
	v_mfma_f32_16x16x32_bf16 v[4:7], v[228:231], v[168:171], v[4:7]
	global_load_dwordx4 v[92:95], v[236:237], off offset:768
	s_waitcnt lgkmcnt(6)
	v_mfma_f32_16x16x32_bf16 v[44:47], v[232:235], v[160:163], v[44:47]
	v_mfma_f32_16x16x32_bf16 v[48:51], v[232:235], v[164:167], v[48:51]
	global_load_dwordx4 v[96:99], v[238:239], off offset:768
	v_mfma_f32_16x16x32_bf16 v[12:15], v[232:235], v[168:171], v[12:15]
	s_waitcnt lgkmcnt(5)
	v_mfma_f32_16x16x32_bf16 v[24:27], v[220:223], v[172:175], v[24:27]
	v_mfma_f32_16x16x32_bf16 v[32:35], v[224:227], v[172:175], v[32:35]
	v_mfma_f32_16x16x32_bf16 v[8:11], v[228:231], v[172:175], v[8:11]
	v_mfma_f32_16x16x32_bf16 v[16:19], v[232:235], v[172:175], v[16:19]
	s_setprio 0
	s_waitcnt lgkmcnt(0)
	s_barrier
	ds_read_b128 v[136:139], v242
	ds_read_b128 v[176:179], v243 offset:18432
	ds_read_b128 v[180:183], v243 offset:20736
	ds_read_b128 v[140:143], v242 offset:2304
	ds_read_b128 v[184:187], v243 offset:23040
	ds_read_b128 v[152:155], v242 offset:4608
	ds_read_b128 v[216:219], v243 offset:25344
	ds_read_b128 v[156:159], v242 offset:6912
	s_setprio 1
	s_waitcnt lgkmcnt(6)
	v_mfma_f32_16x16x32_bf16 v[52:55], v[176:179], v[136:139], v[52:55]
	s_waitcnt vmcnt(15)
	ds_write_b128 v241, v[100:103]
	s_waitcnt lgkmcnt(6)
	v_mfma_f32_16x16x32_bf16 v[60:63], v[180:183], v[136:139], v[60:63]
	ds_read_b128 v[160:163], v242 offset:64
	s_waitcnt lgkmcnt(6)
	v_mfma_f32_16x16x32_bf16 v[56:59], v[176:179], v[140:143], v[56:59]
	ds_read_b128 v[220:223], v243 offset:18496
	s_waitcnt vmcnt(14)
	ds_write_b128 v241, v[104:107] offset:4608
	v_mfma_f32_16x16x32_bf16 v[64:67], v[180:183], v[140:143], v[64:67]
	ds_read_b128 v[224:227], v243 offset:20800
	s_waitcnt lgkmcnt(8)
	v_mfma_f32_16x16x32_bf16 v[36:39], v[184:187], v[136:139], v[36:39]
	ds_read_b128 v[164:167], v242 offset:2368
	s_waitcnt vmcnt(13)
	ds_write_b128 v241, v[108:111] offset:9216
	global_load_dwordx4 v[100:103], v[148:149], off offset:896
	v_mfma_f32_16x16x32_bf16 v[40:43], v[184:187], v[140:143], v[40:43]
	ds_read_b128 v[228:231], v243 offset:23104
	s_waitcnt lgkmcnt(10)
	v_mfma_f32_16x16x32_bf16 v[20:23], v[176:179], v[152:155], v[20:23]
	ds_read_b128 v[168:171], v242 offset:4672
	v_mfma_f32_16x16x32_bf16 v[28:31], v[180:183], v[152:155], v[28:31]
	ds_read_b128 v[232:235], v243 offset:25408
	v_mfma_f32_16x16x32_bf16 v[4:7], v[184:187], v[152:155], v[4:7]
	ds_read_b128 v[172:175], v242 offset:6976
	s_waitcnt lgkmcnt(12)
	v_mfma_f32_16x16x32_bf16 v[44:47], v[216:219], v[136:139], v[44:47]
	v_mfma_f32_16x16x32_bf16 v[48:51], v[216:219], v[140:143], v[48:51]
	s_waitcnt vmcnt(13)
	ds_write_b128 v241, v[112:115] offset:13824
	global_load_dwordx4 v[104:107], v[134:135], off offset:896
	v_mfma_f32_16x16x32_bf16 v[12:15], v[216:219], v[152:155], v[12:15]
	s_waitcnt lgkmcnt(12)
	v_mfma_f32_16x16x32_bf16 v[24:27], v[176:179], v[156:159], v[24:27]
	s_waitcnt vmcnt(13)
	ds_write_b128 v241, v[116:119] offset:18432
	global_load_dwordx4 v[108:111], v[194:195], off offset:896
	v_mfma_f32_16x16x32_bf16 v[32:35], v[180:183], v[156:159], v[32:35]
	v_mfma_f32_16x16x32_bf16 v[8:11], v[184:187], v[156:159], v[8:11]
	v_mfma_f32_16x16x32_bf16 v[16:19], v[216:219], v[156:159], v[16:19]
	s_waitcnt lgkmcnt(10)
	v_mfma_f32_16x16x32_bf16 v[52:55], v[220:223], v[160:163], v[52:55]
	s_waitcnt lgkmcnt(8)
	v_mfma_f32_16x16x32_bf16 v[60:63], v[224:227], v[160:163], v[60:63]
	s_waitcnt lgkmcnt(7)
	v_mfma_f32_16x16x32_bf16 v[56:59], v[220:223], v[164:167], v[56:59]
	s_waitcnt vmcnt(13)
	ds_write_b128 v241, v[120:123] offset:23040
	global_load_dwordx4 v[112:115], v[196:197], off offset:896
	v_mfma_f32_16x16x32_bf16 v[64:67], v[224:227], v[164:167], v[64:67]
	s_waitcnt lgkmcnt(6)
	v_mfma_f32_16x16x32_bf16 v[36:39], v[228:231], v[160:163], v[36:39]
	s_waitcnt vmcnt(13)
	ds_write_b128 v241, v[124:127] offset:27648
	global_load_dwordx4 v[116:119], v[150:151], off offset:896
	v_mfma_f32_16x16x32_bf16 v[40:43], v[228:231], v[164:167], v[40:43]
	s_waitcnt lgkmcnt(6)
	v_mfma_f32_16x16x32_bf16 v[20:23], v[220:223], v[168:171], v[20:23]
	s_waitcnt vmcnt(13)
	ds_write_b128 v241, v[128:131] offset:32256
	global_load_dwordx4 v[120:123], v[214:215], off offset:896
	v_mfma_f32_16x16x32_bf16 v[28:31], v[224:227], v[168:171], v[28:31]
	v_mfma_f32_16x16x32_bf16 v[4:7], v[228:231], v[168:171], v[4:7]
	global_load_dwordx4 v[124:127], v[236:237], off offset:896
	s_waitcnt lgkmcnt(6)
	v_mfma_f32_16x16x32_bf16 v[44:47], v[232:235], v[160:163], v[44:47]
	v_mfma_f32_16x16x32_bf16 v[48:51], v[232:235], v[164:167], v[48:51]
	global_load_dwordx4 v[128:131], v[238:239], off offset:896
	v_mfma_f32_16x16x32_bf16 v[12:15], v[232:235], v[168:171], v[12:15]
	s_waitcnt lgkmcnt(5)
	v_mfma_f32_16x16x32_bf16 v[24:27], v[220:223], v[172:175], v[24:27]
	v_mfma_f32_16x16x32_bf16 v[32:35], v[224:227], v[172:175], v[32:35]
	v_mfma_f32_16x16x32_bf16 v[8:11], v[228:231], v[172:175], v[8:11]
	v_mfma_f32_16x16x32_bf16 v[16:19], v[232:235], v[172:175], v[16:19]
	s_setprio 0
	s_waitcnt lgkmcnt(0)
	s_barrier
	ds_read_b128 v[136:139], v242 offset:36864
	ds_read_b128 v[176:179], v243 offset:55296
	ds_read_b128 v[180:183], v243 offset:57600
	ds_read_b128 v[140:143], v242 offset:39168
	ds_read_b128 v[184:187], v243 offset:59904
	ds_read_b128 v[152:155], v242 offset:41472
	ds_read_b128 v[216:219], v243 offset:62208
	ds_read_b128 v[156:159], v242 offset:43776
	s_setprio 1
	s_waitcnt lgkmcnt(6)
	v_mfma_f32_16x16x32_bf16 v[52:55], v[176:179], v[136:139], v[52:55]
	s_waitcnt vmcnt(15)
	ds_write_b128 v240, v[68:71]
	s_waitcnt lgkmcnt(6)
	v_mfma_f32_16x16x32_bf16 v[60:63], v[180:183], v[136:139], v[60:63]
	ds_read_b128 v[160:163], v242 offset:36928
	s_waitcnt lgkmcnt(6)
	v_mfma_f32_16x16x32_bf16 v[56:59], v[176:179], v[140:143], v[56:59]
	ds_read_b128 v[220:223], v243 offset:55360
	s_waitcnt vmcnt(14)
	ds_write_b128 v240, v[72:75] offset:4608
	v_mfma_f32_16x16x32_bf16 v[64:67], v[180:183], v[140:143], v[64:67]
	ds_read_b128 v[224:227], v243 offset:57664
	s_waitcnt lgkmcnt(8)
	v_mfma_f32_16x16x32_bf16 v[36:39], v[184:187], v[136:139], v[36:39]
	ds_read_b128 v[164:167], v242 offset:39232
	s_waitcnt vmcnt(13)
	ds_write_b128 v240, v[76:79] offset:9216
	global_load_dwordx4 v[68:71], v[148:149], off offset:1024
	v_mfma_f32_16x16x32_bf16 v[40:43], v[184:187], v[140:143], v[40:43]
	ds_read_b128 v[228:231], v243 offset:59968
	s_waitcnt lgkmcnt(10)
	v_mfma_f32_16x16x32_bf16 v[20:23], v[176:179], v[152:155], v[20:23]
	ds_read_b128 v[168:171], v242 offset:41536
	v_mfma_f32_16x16x32_bf16 v[28:31], v[180:183], v[152:155], v[28:31]
	ds_read_b128 v[232:235], v243 offset:62272
	v_mfma_f32_16x16x32_bf16 v[4:7], v[184:187], v[152:155], v[4:7]
	ds_read_b128 v[172:175], v242 offset:43840
	s_waitcnt lgkmcnt(12)
	v_mfma_f32_16x16x32_bf16 v[44:47], v[216:219], v[136:139], v[44:47]
	v_mfma_f32_16x16x32_bf16 v[48:51], v[216:219], v[140:143], v[48:51]
	s_waitcnt vmcnt(13)
	ds_write_b128 v240, v[80:83] offset:13824
	global_load_dwordx4 v[72:75], v[134:135], off offset:1024
	v_mfma_f32_16x16x32_bf16 v[12:15], v[216:219], v[152:155], v[12:15]
	s_waitcnt lgkmcnt(12)
	v_mfma_f32_16x16x32_bf16 v[24:27], v[176:179], v[156:159], v[24:27]
	s_waitcnt vmcnt(13)
	ds_write_b128 v240, v[84:87] offset:18432
	global_load_dwordx4 v[76:79], v[194:195], off offset:1024
	v_mfma_f32_16x16x32_bf16 v[32:35], v[180:183], v[156:159], v[32:35]
	v_mfma_f32_16x16x32_bf16 v[8:11], v[184:187], v[156:159], v[8:11]
	v_mfma_f32_16x16x32_bf16 v[16:19], v[216:219], v[156:159], v[16:19]
	s_waitcnt lgkmcnt(10)
	v_mfma_f32_16x16x32_bf16 v[52:55], v[220:223], v[160:163], v[52:55]
	s_waitcnt lgkmcnt(8)
	v_mfma_f32_16x16x32_bf16 v[60:63], v[224:227], v[160:163], v[60:63]
	s_waitcnt lgkmcnt(7)
	v_mfma_f32_16x16x32_bf16 v[56:59], v[220:223], v[164:167], v[56:59]
	s_waitcnt vmcnt(13)
	ds_write_b128 v240, v[88:91] offset:23040
	global_load_dwordx4 v[80:83], v[196:197], off offset:1024
	v_mfma_f32_16x16x32_bf16 v[64:67], v[224:227], v[164:167], v[64:67]
	s_waitcnt lgkmcnt(6)
	v_mfma_f32_16x16x32_bf16 v[36:39], v[228:231], v[160:163], v[36:39]
	s_waitcnt vmcnt(13)
	ds_write_b128 v240, v[92:95] offset:27648
	global_load_dwordx4 v[84:87], v[150:151], off offset:1024
	v_mfma_f32_16x16x32_bf16 v[40:43], v[228:231], v[164:167], v[40:43]
	s_waitcnt lgkmcnt(6)
	v_mfma_f32_16x16x32_bf16 v[20:23], v[220:223], v[168:171], v[20:23]
	s_waitcnt vmcnt(13)
	ds_write_b128 v240, v[96:99] offset:32256
	global_load_dwordx4 v[88:91], v[214:215], off offset:1024
	v_mfma_f32_16x16x32_bf16 v[28:31], v[224:227], v[168:171], v[28:31]
	v_mfma_f32_16x16x32_bf16 v[4:7], v[228:231], v[168:171], v[4:7]
	global_load_dwordx4 v[92:95], v[236:237], off offset:1024
	s_waitcnt lgkmcnt(6)
	v_mfma_f32_16x16x32_bf16 v[44:47], v[232:235], v[160:163], v[44:47]
	v_mfma_f32_16x16x32_bf16 v[48:51], v[232:235], v[164:167], v[48:51]
	global_load_dwordx4 v[96:99], v[238:239], off offset:1024
	v_mfma_f32_16x16x32_bf16 v[12:15], v[232:235], v[168:171], v[12:15]
	s_waitcnt lgkmcnt(5)
	v_mfma_f32_16x16x32_bf16 v[24:27], v[220:223], v[172:175], v[24:27]
	v_mfma_f32_16x16x32_bf16 v[32:35], v[224:227], v[172:175], v[32:35]
	v_mfma_f32_16x16x32_bf16 v[8:11], v[228:231], v[172:175], v[8:11]
	v_mfma_f32_16x16x32_bf16 v[16:19], v[232:235], v[172:175], v[16:19]
	s_setprio 0
	s_waitcnt lgkmcnt(0)
	s_barrier
	ds_read_b128 v[136:139], v242
	ds_read_b128 v[176:179], v243 offset:18432
	ds_read_b128 v[180:183], v243 offset:20736
	ds_read_b128 v[140:143], v242 offset:2304
	ds_read_b128 v[184:187], v243 offset:23040
	ds_read_b128 v[152:155], v242 offset:4608
	ds_read_b128 v[216:219], v243 offset:25344
	ds_read_b128 v[156:159], v242 offset:6912
	s_setprio 1
	s_waitcnt lgkmcnt(6)
	v_mfma_f32_16x16x32_bf16 v[52:55], v[176:179], v[136:139], v[52:55]
	s_waitcnt vmcnt(15)
	ds_write_b128 v241, v[100:103]
	s_waitcnt lgkmcnt(6)
	v_mfma_f32_16x16x32_bf16 v[60:63], v[180:183], v[136:139], v[60:63]
	ds_read_b128 v[160:163], v242 offset:64
	s_waitcnt lgkmcnt(6)
	v_mfma_f32_16x16x32_bf16 v[56:59], v[176:179], v[140:143], v[56:59]
	ds_read_b128 v[220:223], v243 offset:18496
	s_waitcnt vmcnt(14)
	ds_write_b128 v241, v[104:107] offset:4608
	v_mfma_f32_16x16x32_bf16 v[64:67], v[180:183], v[140:143], v[64:67]
	ds_read_b128 v[224:227], v243 offset:20800
	s_waitcnt lgkmcnt(8)
	v_mfma_f32_16x16x32_bf16 v[36:39], v[184:187], v[136:139], v[36:39]
	ds_read_b128 v[164:167], v242 offset:2368
	s_waitcnt vmcnt(13)
	ds_write_b128 v241, v[108:111] offset:9216
	global_load_dwordx4 v[100:103], v[148:149], off offset:1152
	v_mfma_f32_16x16x32_bf16 v[40:43], v[184:187], v[140:143], v[40:43]
	ds_read_b128 v[228:231], v243 offset:23104
	s_waitcnt lgkmcnt(10)
	v_mfma_f32_16x16x32_bf16 v[20:23], v[176:179], v[152:155], v[20:23]
	ds_read_b128 v[168:171], v242 offset:4672
	v_mfma_f32_16x16x32_bf16 v[28:31], v[180:183], v[152:155], v[28:31]
	ds_read_b128 v[232:235], v243 offset:25408
	v_mfma_f32_16x16x32_bf16 v[4:7], v[184:187], v[152:155], v[4:7]
	ds_read_b128 v[172:175], v242 offset:6976
	s_waitcnt lgkmcnt(12)
	v_mfma_f32_16x16x32_bf16 v[44:47], v[216:219], v[136:139], v[44:47]
	v_mfma_f32_16x16x32_bf16 v[48:51], v[216:219], v[140:143], v[48:51]
	s_waitcnt vmcnt(13)
	ds_write_b128 v241, v[112:115] offset:13824
	global_load_dwordx4 v[104:107], v[134:135], off offset:1152
	v_mfma_f32_16x16x32_bf16 v[12:15], v[216:219], v[152:155], v[12:15]
	s_waitcnt lgkmcnt(12)
	v_mfma_f32_16x16x32_bf16 v[24:27], v[176:179], v[156:159], v[24:27]
	s_waitcnt vmcnt(13)
	ds_write_b128 v241, v[116:119] offset:18432
	global_load_dwordx4 v[108:111], v[194:195], off offset:1152
	v_mfma_f32_16x16x32_bf16 v[32:35], v[180:183], v[156:159], v[32:35]
	v_mfma_f32_16x16x32_bf16 v[8:11], v[184:187], v[156:159], v[8:11]
	v_mfma_f32_16x16x32_bf16 v[16:19], v[216:219], v[156:159], v[16:19]
	s_waitcnt lgkmcnt(10)
	v_mfma_f32_16x16x32_bf16 v[52:55], v[220:223], v[160:163], v[52:55]
	s_waitcnt lgkmcnt(8)
	v_mfma_f32_16x16x32_bf16 v[60:63], v[224:227], v[160:163], v[60:63]
	s_waitcnt lgkmcnt(7)
	v_mfma_f32_16x16x32_bf16 v[56:59], v[220:223], v[164:167], v[56:59]
	s_waitcnt vmcnt(13)
	ds_write_b128 v241, v[120:123] offset:23040
	global_load_dwordx4 v[112:115], v[196:197], off offset:1152
	v_mfma_f32_16x16x32_bf16 v[64:67], v[224:227], v[164:167], v[64:67]
	s_waitcnt lgkmcnt(6)
	v_mfma_f32_16x16x32_bf16 v[36:39], v[228:231], v[160:163], v[36:39]
	s_waitcnt vmcnt(13)
	ds_write_b128 v241, v[124:127] offset:27648
	global_load_dwordx4 v[116:119], v[150:151], off offset:1152
	v_mfma_f32_16x16x32_bf16 v[40:43], v[228:231], v[164:167], v[40:43]
	s_waitcnt lgkmcnt(6)
	v_mfma_f32_16x16x32_bf16 v[20:23], v[220:223], v[168:171], v[20:23]
	s_waitcnt vmcnt(13)
	ds_write_b128 v241, v[128:131] offset:32256
	global_load_dwordx4 v[120:123], v[214:215], off offset:1152
	v_mfma_f32_16x16x32_bf16 v[28:31], v[224:227], v[168:171], v[28:31]
	v_mfma_f32_16x16x32_bf16 v[4:7], v[228:231], v[168:171], v[4:7]
	global_load_dwordx4 v[124:127], v[236:237], off offset:1152
	s_waitcnt lgkmcnt(6)
	v_mfma_f32_16x16x32_bf16 v[44:47], v[232:235], v[160:163], v[44:47]
	v_mfma_f32_16x16x32_bf16 v[48:51], v[232:235], v[164:167], v[48:51]
	global_load_dwordx4 v[128:131], v[238:239], off offset:1152
	v_mfma_f32_16x16x32_bf16 v[12:15], v[232:235], v[168:171], v[12:15]
	s_waitcnt lgkmcnt(5)
	v_mfma_f32_16x16x32_bf16 v[24:27], v[220:223], v[172:175], v[24:27]
	v_mfma_f32_16x16x32_bf16 v[32:35], v[224:227], v[172:175], v[32:35]
	v_mfma_f32_16x16x32_bf16 v[8:11], v[228:231], v[172:175], v[8:11]
	v_mfma_f32_16x16x32_bf16 v[16:19], v[232:235], v[172:175], v[16:19]
	s_setprio 0
	s_waitcnt lgkmcnt(0)
	s_barrier
	ds_read_b128 v[136:139], v242 offset:36864
	ds_read_b128 v[176:179], v243 offset:55296
	ds_read_b128 v[180:183], v243 offset:57600
	ds_read_b128 v[140:143], v242 offset:39168
	ds_read_b128 v[184:187], v243 offset:59904
	ds_read_b128 v[152:155], v242 offset:41472
	ds_read_b128 v[216:219], v243 offset:62208
	ds_read_b128 v[156:159], v242 offset:43776
	s_setprio 1
	s_waitcnt lgkmcnt(6)
	v_mfma_f32_16x16x32_bf16 v[52:55], v[176:179], v[136:139], v[52:55]
	s_waitcnt vmcnt(15)
	ds_write_b128 v240, v[68:71]
	s_waitcnt lgkmcnt(6)
	v_mfma_f32_16x16x32_bf16 v[60:63], v[180:183], v[136:139], v[60:63]
	ds_read_b128 v[160:163], v242 offset:36928
	s_waitcnt lgkmcnt(6)
	v_mfma_f32_16x16x32_bf16 v[56:59], v[176:179], v[140:143], v[56:59]
	ds_read_b128 v[220:223], v243 offset:55360
	s_waitcnt vmcnt(14)
	ds_write_b128 v240, v[72:75] offset:4608
	v_mfma_f32_16x16x32_bf16 v[64:67], v[180:183], v[140:143], v[64:67]
	ds_read_b128 v[224:227], v243 offset:57664
	s_waitcnt lgkmcnt(8)
	v_mfma_f32_16x16x32_bf16 v[36:39], v[184:187], v[136:139], v[36:39]
	ds_read_b128 v[164:167], v242 offset:39232
	s_waitcnt vmcnt(13)
	ds_write_b128 v240, v[76:79] offset:9216
	global_load_dwordx4 v[68:71], v[148:149], off offset:1280
	v_mfma_f32_16x16x32_bf16 v[40:43], v[184:187], v[140:143], v[40:43]
	ds_read_b128 v[228:231], v243 offset:59968
	s_waitcnt lgkmcnt(10)
	v_mfma_f32_16x16x32_bf16 v[20:23], v[176:179], v[152:155], v[20:23]
	ds_read_b128 v[168:171], v242 offset:41536
	v_mfma_f32_16x16x32_bf16 v[28:31], v[180:183], v[152:155], v[28:31]
	ds_read_b128 v[232:235], v243 offset:62272
	v_mfma_f32_16x16x32_bf16 v[4:7], v[184:187], v[152:155], v[4:7]
	ds_read_b128 v[172:175], v242 offset:43840
	s_waitcnt lgkmcnt(12)
	v_mfma_f32_16x16x32_bf16 v[44:47], v[216:219], v[136:139], v[44:47]
	v_mfma_f32_16x16x32_bf16 v[48:51], v[216:219], v[140:143], v[48:51]
	s_waitcnt vmcnt(13)
	ds_write_b128 v240, v[80:83] offset:13824
	global_load_dwordx4 v[72:75], v[134:135], off offset:1280
	v_mfma_f32_16x16x32_bf16 v[12:15], v[216:219], v[152:155], v[12:15]
	s_waitcnt lgkmcnt(12)
	v_mfma_f32_16x16x32_bf16 v[24:27], v[176:179], v[156:159], v[24:27]
	s_waitcnt vmcnt(13)
	ds_write_b128 v240, v[84:87] offset:18432
	global_load_dwordx4 v[76:79], v[194:195], off offset:1280
	v_mfma_f32_16x16x32_bf16 v[32:35], v[180:183], v[156:159], v[32:35]
	v_mfma_f32_16x16x32_bf16 v[8:11], v[184:187], v[156:159], v[8:11]
	v_mfma_f32_16x16x32_bf16 v[16:19], v[216:219], v[156:159], v[16:19]
	s_waitcnt lgkmcnt(10)
	v_mfma_f32_16x16x32_bf16 v[52:55], v[220:223], v[160:163], v[52:55]
	s_waitcnt lgkmcnt(8)
	v_mfma_f32_16x16x32_bf16 v[60:63], v[224:227], v[160:163], v[60:63]
	s_waitcnt lgkmcnt(7)
	v_mfma_f32_16x16x32_bf16 v[56:59], v[220:223], v[164:167], v[56:59]
	s_waitcnt vmcnt(13)
	ds_write_b128 v240, v[88:91] offset:23040
	global_load_dwordx4 v[80:83], v[196:197], off offset:1280
	v_mfma_f32_16x16x32_bf16 v[64:67], v[224:227], v[164:167], v[64:67]
	s_waitcnt lgkmcnt(6)
	v_mfma_f32_16x16x32_bf16 v[36:39], v[228:231], v[160:163], v[36:39]
	s_waitcnt vmcnt(13)
	ds_write_b128 v240, v[92:95] offset:27648
	global_load_dwordx4 v[84:87], v[150:151], off offset:1280
	v_mfma_f32_16x16x32_bf16 v[40:43], v[228:231], v[164:167], v[40:43]
	s_waitcnt lgkmcnt(6)
	v_mfma_f32_16x16x32_bf16 v[20:23], v[220:223], v[168:171], v[20:23]
	s_waitcnt vmcnt(13)
	ds_write_b128 v240, v[96:99] offset:32256
	global_load_dwordx4 v[88:91], v[214:215], off offset:1280
	v_mfma_f32_16x16x32_bf16 v[28:31], v[224:227], v[168:171], v[28:31]
	v_mfma_f32_16x16x32_bf16 v[4:7], v[228:231], v[168:171], v[4:7]
	global_load_dwordx4 v[92:95], v[236:237], off offset:1280
	s_waitcnt lgkmcnt(6)
	v_mfma_f32_16x16x32_bf16 v[44:47], v[232:235], v[160:163], v[44:47]
	v_mfma_f32_16x16x32_bf16 v[48:51], v[232:235], v[164:167], v[48:51]
	global_load_dwordx4 v[96:99], v[238:239], off offset:1280
	v_mfma_f32_16x16x32_bf16 v[12:15], v[232:235], v[168:171], v[12:15]
	s_waitcnt lgkmcnt(5)
	v_mfma_f32_16x16x32_bf16 v[24:27], v[220:223], v[172:175], v[24:27]
	v_mfma_f32_16x16x32_bf16 v[32:35], v[224:227], v[172:175], v[32:35]
	v_mfma_f32_16x16x32_bf16 v[8:11], v[228:231], v[172:175], v[8:11]
	v_mfma_f32_16x16x32_bf16 v[16:19], v[232:235], v[172:175], v[16:19]
	s_setprio 0
	s_waitcnt lgkmcnt(0)
	s_barrier
	ds_read_b128 v[136:139], v242
	ds_read_b128 v[176:179], v243 offset:18432
	ds_read_b128 v[180:183], v243 offset:20736
	ds_read_b128 v[140:143], v242 offset:2304
	ds_read_b128 v[184:187], v243 offset:23040
	ds_read_b128 v[152:155], v242 offset:4608
	ds_read_b128 v[216:219], v243 offset:25344
	ds_read_b128 v[156:159], v242 offset:6912
	s_setprio 1
	s_waitcnt lgkmcnt(6)
	v_mfma_f32_16x16x32_bf16 v[52:55], v[176:179], v[136:139], v[52:55]
	s_waitcnt vmcnt(15)
	ds_write_b128 v241, v[100:103]
	s_waitcnt lgkmcnt(6)
	v_mfma_f32_16x16x32_bf16 v[60:63], v[180:183], v[136:139], v[60:63]
	ds_read_b128 v[160:163], v242 offset:64
	s_waitcnt lgkmcnt(6)
	v_mfma_f32_16x16x32_bf16 v[56:59], v[176:179], v[140:143], v[56:59]
	ds_read_b128 v[220:223], v243 offset:18496
	s_waitcnt vmcnt(14)
	ds_write_b128 v241, v[104:107] offset:4608
	v_mfma_f32_16x16x32_bf16 v[64:67], v[180:183], v[140:143], v[64:67]
	ds_read_b128 v[224:227], v243 offset:20800
	s_waitcnt lgkmcnt(8)
	v_mfma_f32_16x16x32_bf16 v[36:39], v[184:187], v[136:139], v[36:39]
	ds_read_b128 v[164:167], v242 offset:2368
	s_waitcnt vmcnt(13)
	ds_write_b128 v241, v[108:111] offset:9216
	global_load_dwordx4 v[100:103], v[148:149], off offset:1408
	v_mfma_f32_16x16x32_bf16 v[40:43], v[184:187], v[140:143], v[40:43]
	ds_read_b128 v[228:231], v243 offset:23104
	s_waitcnt lgkmcnt(10)
	v_mfma_f32_16x16x32_bf16 v[20:23], v[176:179], v[152:155], v[20:23]
	ds_read_b128 v[168:171], v242 offset:4672
	v_mfma_f32_16x16x32_bf16 v[28:31], v[180:183], v[152:155], v[28:31]
	ds_read_b128 v[232:235], v243 offset:25408
	v_mfma_f32_16x16x32_bf16 v[4:7], v[184:187], v[152:155], v[4:7]
	ds_read_b128 v[172:175], v242 offset:6976
	s_waitcnt lgkmcnt(12)
	v_mfma_f32_16x16x32_bf16 v[44:47], v[216:219], v[136:139], v[44:47]
	v_mfma_f32_16x16x32_bf16 v[48:51], v[216:219], v[140:143], v[48:51]
	s_waitcnt vmcnt(13)
	ds_write_b128 v241, v[112:115] offset:13824
	global_load_dwordx4 v[104:107], v[134:135], off offset:1408
	v_mfma_f32_16x16x32_bf16 v[12:15], v[216:219], v[152:155], v[12:15]
	s_waitcnt lgkmcnt(12)
	v_mfma_f32_16x16x32_bf16 v[24:27], v[176:179], v[156:159], v[24:27]
	s_waitcnt vmcnt(13)
	ds_write_b128 v241, v[116:119] offset:18432
	global_load_dwordx4 v[108:111], v[194:195], off offset:1408
	v_mfma_f32_16x16x32_bf16 v[32:35], v[180:183], v[156:159], v[32:35]
	v_mfma_f32_16x16x32_bf16 v[8:11], v[184:187], v[156:159], v[8:11]
	v_mfma_f32_16x16x32_bf16 v[16:19], v[216:219], v[156:159], v[16:19]
	s_waitcnt lgkmcnt(10)
	v_mfma_f32_16x16x32_bf16 v[52:55], v[220:223], v[160:163], v[52:55]
	s_waitcnt lgkmcnt(8)
	v_mfma_f32_16x16x32_bf16 v[60:63], v[224:227], v[160:163], v[60:63]
	s_waitcnt lgkmcnt(7)
	v_mfma_f32_16x16x32_bf16 v[56:59], v[220:223], v[164:167], v[56:59]
	s_waitcnt vmcnt(13)
	ds_write_b128 v241, v[120:123] offset:23040
	global_load_dwordx4 v[112:115], v[196:197], off offset:1408
	v_mfma_f32_16x16x32_bf16 v[64:67], v[224:227], v[164:167], v[64:67]
	s_waitcnt lgkmcnt(6)
	v_mfma_f32_16x16x32_bf16 v[36:39], v[228:231], v[160:163], v[36:39]
	s_waitcnt vmcnt(13)
	ds_write_b128 v241, v[124:127] offset:27648
	global_load_dwordx4 v[116:119], v[150:151], off offset:1408
	v_mfma_f32_16x16x32_bf16 v[40:43], v[228:231], v[164:167], v[40:43]
	s_waitcnt lgkmcnt(6)
	v_mfma_f32_16x16x32_bf16 v[20:23], v[220:223], v[168:171], v[20:23]
	s_waitcnt vmcnt(13)
	ds_write_b128 v241, v[128:131] offset:32256
	global_load_dwordx4 v[120:123], v[214:215], off offset:1408
	v_mfma_f32_16x16x32_bf16 v[28:31], v[224:227], v[168:171], v[28:31]
	v_mfma_f32_16x16x32_bf16 v[4:7], v[228:231], v[168:171], v[4:7]
	global_load_dwordx4 v[124:127], v[236:237], off offset:1408
	s_waitcnt lgkmcnt(6)
	v_mfma_f32_16x16x32_bf16 v[44:47], v[232:235], v[160:163], v[44:47]
	v_mfma_f32_16x16x32_bf16 v[48:51], v[232:235], v[164:167], v[48:51]
	global_load_dwordx4 v[128:131], v[238:239], off offset:1408
	v_mfma_f32_16x16x32_bf16 v[12:15], v[232:235], v[168:171], v[12:15]
	s_waitcnt lgkmcnt(5)
	v_mfma_f32_16x16x32_bf16 v[24:27], v[220:223], v[172:175], v[24:27]
	v_mfma_f32_16x16x32_bf16 v[32:35], v[224:227], v[172:175], v[32:35]
	v_mfma_f32_16x16x32_bf16 v[8:11], v[228:231], v[172:175], v[8:11]
	v_mfma_f32_16x16x32_bf16 v[16:19], v[232:235], v[172:175], v[16:19]
	s_setprio 0
	s_waitcnt lgkmcnt(0)
	s_barrier
	ds_read_b128 v[136:139], v242 offset:36864
	ds_read_b128 v[176:179], v243 offset:55296
	ds_read_b128 v[180:183], v243 offset:57600
	ds_read_b128 v[140:143], v242 offset:39168
	ds_read_b128 v[184:187], v243 offset:59904
	ds_read_b128 v[152:155], v242 offset:41472
	ds_read_b128 v[216:219], v243 offset:62208
	ds_read_b128 v[156:159], v242 offset:43776
	s_setprio 1
	s_waitcnt lgkmcnt(6)
	v_mfma_f32_16x16x32_bf16 v[52:55], v[176:179], v[136:139], v[52:55]
	s_waitcnt vmcnt(15)
	ds_write_b128 v240, v[68:71]
	s_waitcnt lgkmcnt(6)
	v_mfma_f32_16x16x32_bf16 v[60:63], v[180:183], v[136:139], v[60:63]
	ds_read_b128 v[160:163], v242 offset:36928
	s_waitcnt lgkmcnt(6)
	v_mfma_f32_16x16x32_bf16 v[56:59], v[176:179], v[140:143], v[56:59]
	ds_read_b128 v[220:223], v243 offset:55360
	s_waitcnt vmcnt(14)
	ds_write_b128 v240, v[72:75] offset:4608
	v_mfma_f32_16x16x32_bf16 v[64:67], v[180:183], v[140:143], v[64:67]
	ds_read_b128 v[224:227], v243 offset:57664
	s_waitcnt lgkmcnt(8)
	v_mfma_f32_16x16x32_bf16 v[36:39], v[184:187], v[136:139], v[36:39]
	ds_read_b128 v[164:167], v242 offset:39232
	s_waitcnt vmcnt(13)
	ds_write_b128 v240, v[76:79] offset:9216
	global_load_dwordx4 v[68:71], v[148:149], off offset:1536
	v_mfma_f32_16x16x32_bf16 v[40:43], v[184:187], v[140:143], v[40:43]
	ds_read_b128 v[228:231], v243 offset:59968
	s_waitcnt lgkmcnt(10)
	v_mfma_f32_16x16x32_bf16 v[20:23], v[176:179], v[152:155], v[20:23]
	ds_read_b128 v[168:171], v242 offset:41536
	v_mfma_f32_16x16x32_bf16 v[28:31], v[180:183], v[152:155], v[28:31]
	ds_read_b128 v[232:235], v243 offset:62272
	v_mfma_f32_16x16x32_bf16 v[4:7], v[184:187], v[152:155], v[4:7]
	ds_read_b128 v[172:175], v242 offset:43840
	s_waitcnt lgkmcnt(12)
	v_mfma_f32_16x16x32_bf16 v[44:47], v[216:219], v[136:139], v[44:47]
	v_mfma_f32_16x16x32_bf16 v[48:51], v[216:219], v[140:143], v[48:51]
	s_waitcnt vmcnt(13)
	ds_write_b128 v240, v[80:83] offset:13824
	global_load_dwordx4 v[72:75], v[134:135], off offset:1536
	v_mfma_f32_16x16x32_bf16 v[12:15], v[216:219], v[152:155], v[12:15]
	s_waitcnt lgkmcnt(12)
	v_mfma_f32_16x16x32_bf16 v[24:27], v[176:179], v[156:159], v[24:27]
	s_waitcnt vmcnt(13)
	ds_write_b128 v240, v[84:87] offset:18432
	global_load_dwordx4 v[76:79], v[194:195], off offset:1536
	v_mfma_f32_16x16x32_bf16 v[32:35], v[180:183], v[156:159], v[32:35]
	v_mfma_f32_16x16x32_bf16 v[8:11], v[184:187], v[156:159], v[8:11]
	v_mfma_f32_16x16x32_bf16 v[16:19], v[216:219], v[156:159], v[16:19]
	s_waitcnt lgkmcnt(10)
	v_mfma_f32_16x16x32_bf16 v[52:55], v[220:223], v[160:163], v[52:55]
	s_waitcnt lgkmcnt(8)
	v_mfma_f32_16x16x32_bf16 v[60:63], v[224:227], v[160:163], v[60:63]
	s_waitcnt lgkmcnt(7)
	v_mfma_f32_16x16x32_bf16 v[56:59], v[220:223], v[164:167], v[56:59]
	s_waitcnt vmcnt(13)
	ds_write_b128 v240, v[88:91] offset:23040
	global_load_dwordx4 v[80:83], v[196:197], off offset:1536
	v_mfma_f32_16x16x32_bf16 v[64:67], v[224:227], v[164:167], v[64:67]
	s_waitcnt lgkmcnt(6)
	v_mfma_f32_16x16x32_bf16 v[36:39], v[228:231], v[160:163], v[36:39]
	s_waitcnt vmcnt(13)
	ds_write_b128 v240, v[92:95] offset:27648
	global_load_dwordx4 v[84:87], v[150:151], off offset:1536
	v_mfma_f32_16x16x32_bf16 v[40:43], v[228:231], v[164:167], v[40:43]
	s_waitcnt lgkmcnt(6)
	v_mfma_f32_16x16x32_bf16 v[20:23], v[220:223], v[168:171], v[20:23]
	s_waitcnt vmcnt(13)
	ds_write_b128 v240, v[96:99] offset:32256
	global_load_dwordx4 v[88:91], v[214:215], off offset:1536
	v_mfma_f32_16x16x32_bf16 v[28:31], v[224:227], v[168:171], v[28:31]
	v_mfma_f32_16x16x32_bf16 v[4:7], v[228:231], v[168:171], v[4:7]
	global_load_dwordx4 v[92:95], v[236:237], off offset:1536
	s_waitcnt lgkmcnt(6)
	v_mfma_f32_16x16x32_bf16 v[44:47], v[232:235], v[160:163], v[44:47]
	v_mfma_f32_16x16x32_bf16 v[48:51], v[232:235], v[164:167], v[48:51]
	global_load_dwordx4 v[96:99], v[238:239], off offset:1536
	v_mfma_f32_16x16x32_bf16 v[12:15], v[232:235], v[168:171], v[12:15]
	s_waitcnt lgkmcnt(5)
	v_mfma_f32_16x16x32_bf16 v[24:27], v[220:223], v[172:175], v[24:27]
	v_mfma_f32_16x16x32_bf16 v[32:35], v[224:227], v[172:175], v[32:35]
	v_mfma_f32_16x16x32_bf16 v[8:11], v[228:231], v[172:175], v[8:11]
	v_mfma_f32_16x16x32_bf16 v[16:19], v[232:235], v[172:175], v[16:19]
	s_setprio 0
	s_waitcnt lgkmcnt(0)
	s_barrier
	ds_read_b128 v[136:139], v242
	ds_read_b128 v[176:179], v243 offset:18432
	ds_read_b128 v[180:183], v243 offset:20736
	ds_read_b128 v[140:143], v242 offset:2304
	ds_read_b128 v[184:187], v243 offset:23040
	ds_read_b128 v[152:155], v242 offset:4608
	ds_read_b128 v[216:219], v243 offset:25344
	ds_read_b128 v[156:159], v242 offset:6912
	s_setprio 1
	s_waitcnt lgkmcnt(6)
	v_mfma_f32_16x16x32_bf16 v[52:55], v[176:179], v[136:139], v[52:55]
	s_waitcnt vmcnt(15)
	ds_write_b128 v241, v[100:103]
	s_waitcnt lgkmcnt(6)
	v_mfma_f32_16x16x32_bf16 v[60:63], v[180:183], v[136:139], v[60:63]
	ds_read_b128 v[160:163], v242 offset:64
	s_waitcnt lgkmcnt(6)
	v_mfma_f32_16x16x32_bf16 v[56:59], v[176:179], v[140:143], v[56:59]
	ds_read_b128 v[220:223], v243 offset:18496
	s_waitcnt vmcnt(14)
	ds_write_b128 v241, v[104:107] offset:4608
	v_mfma_f32_16x16x32_bf16 v[64:67], v[180:183], v[140:143], v[64:67]
	ds_read_b128 v[224:227], v243 offset:20800
	s_waitcnt lgkmcnt(8)
	v_mfma_f32_16x16x32_bf16 v[36:39], v[184:187], v[136:139], v[36:39]
	ds_read_b128 v[164:167], v242 offset:2368
	s_waitcnt vmcnt(13)
	ds_write_b128 v241, v[108:111] offset:9216
	global_load_dwordx4 v[100:103], v[148:149], off offset:1664
	v_mfma_f32_16x16x32_bf16 v[40:43], v[184:187], v[140:143], v[40:43]
	ds_read_b128 v[228:231], v243 offset:23104
	s_waitcnt lgkmcnt(10)
	v_mfma_f32_16x16x32_bf16 v[20:23], v[176:179], v[152:155], v[20:23]
	ds_read_b128 v[168:171], v242 offset:4672
	v_mfma_f32_16x16x32_bf16 v[28:31], v[180:183], v[152:155], v[28:31]
	ds_read_b128 v[232:235], v243 offset:25408
	v_mfma_f32_16x16x32_bf16 v[4:7], v[184:187], v[152:155], v[4:7]
	ds_read_b128 v[172:175], v242 offset:6976
	s_waitcnt lgkmcnt(12)
	v_mfma_f32_16x16x32_bf16 v[44:47], v[216:219], v[136:139], v[44:47]
	v_mfma_f32_16x16x32_bf16 v[48:51], v[216:219], v[140:143], v[48:51]
	s_waitcnt vmcnt(13)
	ds_write_b128 v241, v[112:115] offset:13824
	global_load_dwordx4 v[104:107], v[134:135], off offset:1664
	v_mfma_f32_16x16x32_bf16 v[12:15], v[216:219], v[152:155], v[12:15]
	s_waitcnt lgkmcnt(12)
	v_mfma_f32_16x16x32_bf16 v[24:27], v[176:179], v[156:159], v[24:27]
	s_waitcnt vmcnt(13)
	ds_write_b128 v241, v[116:119] offset:18432
	global_load_dwordx4 v[108:111], v[194:195], off offset:1664
	v_mfma_f32_16x16x32_bf16 v[32:35], v[180:183], v[156:159], v[32:35]
	v_mfma_f32_16x16x32_bf16 v[8:11], v[184:187], v[156:159], v[8:11]
	v_mfma_f32_16x16x32_bf16 v[16:19], v[216:219], v[156:159], v[16:19]
	s_waitcnt lgkmcnt(10)
	v_mfma_f32_16x16x32_bf16 v[52:55], v[220:223], v[160:163], v[52:55]
	s_waitcnt lgkmcnt(8)
	v_mfma_f32_16x16x32_bf16 v[60:63], v[224:227], v[160:163], v[60:63]
	s_waitcnt lgkmcnt(7)
	v_mfma_f32_16x16x32_bf16 v[56:59], v[220:223], v[164:167], v[56:59]
	s_waitcnt vmcnt(13)
	ds_write_b128 v241, v[120:123] offset:23040
	global_load_dwordx4 v[112:115], v[196:197], off offset:1664
	v_mfma_f32_16x16x32_bf16 v[64:67], v[224:227], v[164:167], v[64:67]
	s_waitcnt lgkmcnt(6)
	v_mfma_f32_16x16x32_bf16 v[36:39], v[228:231], v[160:163], v[36:39]
	s_waitcnt vmcnt(13)
	ds_write_b128 v241, v[124:127] offset:27648
	global_load_dwordx4 v[116:119], v[150:151], off offset:1664
	v_mfma_f32_16x16x32_bf16 v[40:43], v[228:231], v[164:167], v[40:43]
	s_waitcnt lgkmcnt(6)
	v_mfma_f32_16x16x32_bf16 v[20:23], v[220:223], v[168:171], v[20:23]
	s_waitcnt vmcnt(13)
	ds_write_b128 v241, v[128:131] offset:32256
	global_load_dwordx4 v[120:123], v[214:215], off offset:1664
	v_mfma_f32_16x16x32_bf16 v[28:31], v[224:227], v[168:171], v[28:31]
	v_mfma_f32_16x16x32_bf16 v[4:7], v[228:231], v[168:171], v[4:7]
	global_load_dwordx4 v[124:127], v[236:237], off offset:1664
	s_waitcnt lgkmcnt(6)
	v_mfma_f32_16x16x32_bf16 v[44:47], v[232:235], v[160:163], v[44:47]
	v_mfma_f32_16x16x32_bf16 v[48:51], v[232:235], v[164:167], v[48:51]
	global_load_dwordx4 v[128:131], v[238:239], off offset:1664
	v_mfma_f32_16x16x32_bf16 v[12:15], v[232:235], v[168:171], v[12:15]
	s_waitcnt lgkmcnt(5)
	v_mfma_f32_16x16x32_bf16 v[24:27], v[220:223], v[172:175], v[24:27]
	v_mfma_f32_16x16x32_bf16 v[32:35], v[224:227], v[172:175], v[32:35]
	v_mfma_f32_16x16x32_bf16 v[8:11], v[228:231], v[172:175], v[8:11]
	v_mfma_f32_16x16x32_bf16 v[16:19], v[232:235], v[172:175], v[16:19]
	s_setprio 0
	s_waitcnt lgkmcnt(0)
	s_barrier
	ds_read_b128 v[136:139], v242 offset:36864
	ds_read_b128 v[176:179], v243 offset:55296
	ds_read_b128 v[180:183], v243 offset:57600
	ds_read_b128 v[140:143], v242 offset:39168
	ds_read_b128 v[184:187], v243 offset:59904
	ds_read_b128 v[152:155], v242 offset:41472
	ds_read_b128 v[216:219], v243 offset:62208
	ds_read_b128 v[156:159], v242 offset:43776
	s_setprio 1
	s_waitcnt lgkmcnt(6)
	v_mfma_f32_16x16x32_bf16 v[52:55], v[176:179], v[136:139], v[52:55]
	s_waitcnt vmcnt(15)
	ds_write_b128 v240, v[68:71]
	s_waitcnt lgkmcnt(6)
	v_mfma_f32_16x16x32_bf16 v[60:63], v[180:183], v[136:139], v[60:63]
	ds_read_b128 v[160:163], v242 offset:36928
	s_waitcnt lgkmcnt(6)
	v_mfma_f32_16x16x32_bf16 v[56:59], v[176:179], v[140:143], v[56:59]
	ds_read_b128 v[220:223], v243 offset:55360
	s_waitcnt vmcnt(14)
	ds_write_b128 v240, v[72:75] offset:4608
	v_mfma_f32_16x16x32_bf16 v[64:67], v[180:183], v[140:143], v[64:67]
	ds_read_b128 v[224:227], v243 offset:57664
	s_waitcnt lgkmcnt(8)
	v_mfma_f32_16x16x32_bf16 v[36:39], v[184:187], v[136:139], v[36:39]
	ds_read_b128 v[164:167], v242 offset:39232
	s_waitcnt vmcnt(13)
	ds_write_b128 v240, v[76:79] offset:9216
	global_load_dwordx4 v[68:71], v[148:149], off offset:1792
	v_mfma_f32_16x16x32_bf16 v[40:43], v[184:187], v[140:143], v[40:43]
	ds_read_b128 v[228:231], v243 offset:59968
	s_waitcnt lgkmcnt(10)
	v_mfma_f32_16x16x32_bf16 v[20:23], v[176:179], v[152:155], v[20:23]
	ds_read_b128 v[168:171], v242 offset:41536
	v_mfma_f32_16x16x32_bf16 v[28:31], v[180:183], v[152:155], v[28:31]
	ds_read_b128 v[232:235], v243 offset:62272
	v_mfma_f32_16x16x32_bf16 v[4:7], v[184:187], v[152:155], v[4:7]
	ds_read_b128 v[172:175], v242 offset:43840
	s_waitcnt lgkmcnt(12)
	v_mfma_f32_16x16x32_bf16 v[44:47], v[216:219], v[136:139], v[44:47]
	v_mfma_f32_16x16x32_bf16 v[48:51], v[216:219], v[140:143], v[48:51]
	s_waitcnt vmcnt(13)
	ds_write_b128 v240, v[80:83] offset:13824
	global_load_dwordx4 v[72:75], v[134:135], off offset:1792
	v_mfma_f32_16x16x32_bf16 v[12:15], v[216:219], v[152:155], v[12:15]
	s_waitcnt lgkmcnt(12)
	v_mfma_f32_16x16x32_bf16 v[24:27], v[176:179], v[156:159], v[24:27]
	s_waitcnt vmcnt(13)
	ds_write_b128 v240, v[84:87] offset:18432
	global_load_dwordx4 v[76:79], v[194:195], off offset:1792
	v_mfma_f32_16x16x32_bf16 v[32:35], v[180:183], v[156:159], v[32:35]
	v_mfma_f32_16x16x32_bf16 v[8:11], v[184:187], v[156:159], v[8:11]
	v_mfma_f32_16x16x32_bf16 v[16:19], v[216:219], v[156:159], v[16:19]
	s_waitcnt lgkmcnt(10)
	v_mfma_f32_16x16x32_bf16 v[52:55], v[220:223], v[160:163], v[52:55]
	s_waitcnt lgkmcnt(8)
	v_mfma_f32_16x16x32_bf16 v[60:63], v[224:227], v[160:163], v[60:63]
	s_waitcnt lgkmcnt(7)
	v_mfma_f32_16x16x32_bf16 v[56:59], v[220:223], v[164:167], v[56:59]
	s_waitcnt vmcnt(13)
	ds_write_b128 v240, v[88:91] offset:23040
	global_load_dwordx4 v[80:83], v[196:197], off offset:1792
	v_mfma_f32_16x16x32_bf16 v[64:67], v[224:227], v[164:167], v[64:67]
	s_waitcnt lgkmcnt(6)
	v_mfma_f32_16x16x32_bf16 v[36:39], v[228:231], v[160:163], v[36:39]
	s_waitcnt vmcnt(13)
	ds_write_b128 v240, v[92:95] offset:27648
	global_load_dwordx4 v[84:87], v[150:151], off offset:1792
	v_mfma_f32_16x16x32_bf16 v[40:43], v[228:231], v[164:167], v[40:43]
	s_waitcnt lgkmcnt(6)
	v_mfma_f32_16x16x32_bf16 v[20:23], v[220:223], v[168:171], v[20:23]
	s_waitcnt vmcnt(13)
	ds_write_b128 v240, v[96:99] offset:32256
	global_load_dwordx4 v[88:91], v[214:215], off offset:1792
	v_mfma_f32_16x16x32_bf16 v[28:31], v[224:227], v[168:171], v[28:31]
	v_mfma_f32_16x16x32_bf16 v[4:7], v[228:231], v[168:171], v[4:7]
	global_load_dwordx4 v[92:95], v[236:237], off offset:1792
	s_waitcnt lgkmcnt(6)
	v_mfma_f32_16x16x32_bf16 v[44:47], v[232:235], v[160:163], v[44:47]
	v_mfma_f32_16x16x32_bf16 v[48:51], v[232:235], v[164:167], v[48:51]
	global_load_dwordx4 v[96:99], v[238:239], off offset:1792
	v_mfma_f32_16x16x32_bf16 v[12:15], v[232:235], v[168:171], v[12:15]
	s_waitcnt lgkmcnt(5)
	v_mfma_f32_16x16x32_bf16 v[24:27], v[220:223], v[172:175], v[24:27]
	v_mfma_f32_16x16x32_bf16 v[32:35], v[224:227], v[172:175], v[32:35]
	v_mfma_f32_16x16x32_bf16 v[8:11], v[228:231], v[172:175], v[8:11]
	v_mfma_f32_16x16x32_bf16 v[16:19], v[232:235], v[172:175], v[16:19]
	s_setprio 0
	s_waitcnt lgkmcnt(0)
	s_barrier
	ds_read_b128 v[136:139], v242
	ds_read_b128 v[176:179], v243 offset:18432
	ds_read_b128 v[180:183], v243 offset:20736
	ds_read_b128 v[140:143], v242 offset:2304
	ds_read_b128 v[184:187], v243 offset:23040
	ds_read_b128 v[152:155], v242 offset:4608
	ds_read_b128 v[216:219], v243 offset:25344
	ds_read_b128 v[156:159], v242 offset:6912
	s_setprio 1
	s_waitcnt lgkmcnt(6)
	v_mfma_f32_16x16x32_bf16 v[52:55], v[176:179], v[136:139], v[52:55]
	s_waitcnt vmcnt(15)
	ds_write_b128 v241, v[100:103]
	s_waitcnt lgkmcnt(6)
	v_mfma_f32_16x16x32_bf16 v[60:63], v[180:183], v[136:139], v[60:63]
	ds_read_b128 v[160:163], v242 offset:64
	s_waitcnt lgkmcnt(6)
	v_mfma_f32_16x16x32_bf16 v[56:59], v[176:179], v[140:143], v[56:59]
	ds_read_b128 v[220:223], v243 offset:18496
	s_waitcnt vmcnt(14)
	ds_write_b128 v241, v[104:107] offset:4608
	v_mfma_f32_16x16x32_bf16 v[64:67], v[180:183], v[140:143], v[64:67]
	ds_read_b128 v[224:227], v243 offset:20800
	s_waitcnt lgkmcnt(8)
	v_mfma_f32_16x16x32_bf16 v[36:39], v[184:187], v[136:139], v[36:39]
	ds_read_b128 v[164:167], v242 offset:2368
	s_waitcnt vmcnt(13)
	ds_write_b128 v241, v[108:111] offset:9216
	global_load_dwordx4 v[100:103], v[148:149], off offset:1920
	v_mfma_f32_16x16x32_bf16 v[40:43], v[184:187], v[140:143], v[40:43]
	ds_read_b128 v[228:231], v243 offset:23104
	s_waitcnt lgkmcnt(10)
	v_mfma_f32_16x16x32_bf16 v[20:23], v[176:179], v[152:155], v[20:23]
	ds_read_b128 v[168:171], v242 offset:4672
	v_mfma_f32_16x16x32_bf16 v[28:31], v[180:183], v[152:155], v[28:31]
	ds_read_b128 v[232:235], v243 offset:25408
	v_mfma_f32_16x16x32_bf16 v[4:7], v[184:187], v[152:155], v[4:7]
	ds_read_b128 v[172:175], v242 offset:6976
	s_waitcnt lgkmcnt(12)
	v_mfma_f32_16x16x32_bf16 v[44:47], v[216:219], v[136:139], v[44:47]
	v_mfma_f32_16x16x32_bf16 v[48:51], v[216:219], v[140:143], v[48:51]
	s_waitcnt vmcnt(13)
	ds_write_b128 v241, v[112:115] offset:13824
	global_load_dwordx4 v[104:107], v[134:135], off offset:1920
	v_mfma_f32_16x16x32_bf16 v[12:15], v[216:219], v[152:155], v[12:15]
	s_waitcnt lgkmcnt(12)
	v_mfma_f32_16x16x32_bf16 v[24:27], v[176:179], v[156:159], v[24:27]
	s_waitcnt vmcnt(13)
	ds_write_b128 v241, v[116:119] offset:18432
	global_load_dwordx4 v[108:111], v[194:195], off offset:1920
	v_mfma_f32_16x16x32_bf16 v[32:35], v[180:183], v[156:159], v[32:35]
	v_mfma_f32_16x16x32_bf16 v[8:11], v[184:187], v[156:159], v[8:11]
	v_mfma_f32_16x16x32_bf16 v[16:19], v[216:219], v[156:159], v[16:19]
	s_waitcnt lgkmcnt(10)
	v_mfma_f32_16x16x32_bf16 v[52:55], v[220:223], v[160:163], v[52:55]
	s_waitcnt lgkmcnt(8)
	v_mfma_f32_16x16x32_bf16 v[60:63], v[224:227], v[160:163], v[60:63]
	s_waitcnt lgkmcnt(7)
	v_mfma_f32_16x16x32_bf16 v[56:59], v[220:223], v[164:167], v[56:59]
	s_waitcnt vmcnt(13)
	ds_write_b128 v241, v[120:123] offset:23040
	global_load_dwordx4 v[112:115], v[196:197], off offset:1920
	v_mfma_f32_16x16x32_bf16 v[64:67], v[224:227], v[164:167], v[64:67]
	s_waitcnt lgkmcnt(6)
	v_mfma_f32_16x16x32_bf16 v[36:39], v[228:231], v[160:163], v[36:39]
	s_waitcnt vmcnt(13)
	ds_write_b128 v241, v[124:127] offset:27648
	global_load_dwordx4 v[116:119], v[150:151], off offset:1920
	v_mfma_f32_16x16x32_bf16 v[40:43], v[228:231], v[164:167], v[40:43]
	s_waitcnt lgkmcnt(6)
	v_mfma_f32_16x16x32_bf16 v[20:23], v[220:223], v[168:171], v[20:23]
	s_waitcnt vmcnt(13)
	ds_write_b128 v241, v[128:131] offset:32256
	global_load_dwordx4 v[120:123], v[214:215], off offset:1920
	v_mfma_f32_16x16x32_bf16 v[28:31], v[224:227], v[168:171], v[28:31]
	v_mfma_f32_16x16x32_bf16 v[4:7], v[228:231], v[168:171], v[4:7]
	global_load_dwordx4 v[124:127], v[236:237], off offset:1920
	s_waitcnt lgkmcnt(6)
	v_mfma_f32_16x16x32_bf16 v[44:47], v[232:235], v[160:163], v[44:47]
	v_mfma_f32_16x16x32_bf16 v[48:51], v[232:235], v[164:167], v[48:51]
	global_load_dwordx4 v[128:131], v[238:239], off offset:1920
	v_mfma_f32_16x16x32_bf16 v[12:15], v[232:235], v[168:171], v[12:15]
	s_waitcnt lgkmcnt(5)
	v_mfma_f32_16x16x32_bf16 v[24:27], v[220:223], v[172:175], v[24:27]
	v_mfma_f32_16x16x32_bf16 v[32:35], v[224:227], v[172:175], v[32:35]
	v_mfma_f32_16x16x32_bf16 v[8:11], v[228:231], v[172:175], v[8:11]
	v_mfma_f32_16x16x32_bf16 v[16:19], v[232:235], v[172:175], v[16:19]
	s_setprio 0
	s_waitcnt lgkmcnt(0)
	s_barrier
	ds_read_b128 v[136:139], v242 offset:36864
	ds_read_b128 v[176:179], v243 offset:55296
	ds_read_b128 v[180:183], v243 offset:57600
	ds_read_b128 v[140:143], v242 offset:39168
	ds_read_b128 v[184:187], v243 offset:59904
	ds_read_b128 v[152:155], v242 offset:41472
	ds_read_b128 v[216:219], v243 offset:62208
	ds_read_b128 v[156:159], v242 offset:43776
	s_setprio 1
	s_waitcnt lgkmcnt(6)
	v_mfma_f32_16x16x32_bf16 v[52:55], v[176:179], v[136:139], v[52:55]
	s_waitcnt vmcnt(15)
	ds_write_b128 v240, v[68:71]
	s_waitcnt lgkmcnt(6)
	v_mfma_f32_16x16x32_bf16 v[60:63], v[180:183], v[136:139], v[60:63]
	ds_read_b128 v[160:163], v242 offset:36928
	s_waitcnt lgkmcnt(6)
	v_mfma_f32_16x16x32_bf16 v[56:59], v[176:179], v[140:143], v[56:59]
	ds_read_b128 v[220:223], v243 offset:55360
	s_waitcnt vmcnt(14)
	ds_write_b128 v240, v[72:75] offset:4608
	v_mfma_f32_16x16x32_bf16 v[64:67], v[180:183], v[140:143], v[64:67]
	ds_read_b128 v[224:227], v243 offset:57664
	s_waitcnt lgkmcnt(8)
	v_mfma_f32_16x16x32_bf16 v[36:39], v[184:187], v[136:139], v[36:39]
	ds_read_b128 v[164:167], v242 offset:39232
	s_waitcnt vmcnt(13)
	ds_write_b128 v240, v[76:79] offset:9216
	v_mfma_f32_16x16x32_bf16 v[40:43], v[184:187], v[140:143], v[40:43]
	ds_read_b128 v[228:231], v243 offset:59968
	s_waitcnt lgkmcnt(10)
	v_mfma_f32_16x16x32_bf16 v[20:23], v[176:179], v[152:155], v[20:23]
	ds_read_b128 v[168:171], v242 offset:41536
	v_mfma_f32_16x16x32_bf16 v[28:31], v[180:183], v[152:155], v[28:31]
	ds_read_b128 v[232:235], v243 offset:62272
	v_mfma_f32_16x16x32_bf16 v[4:7], v[184:187], v[152:155], v[4:7]
	ds_read_b128 v[172:175], v242 offset:43840
	s_waitcnt lgkmcnt(12)
	v_mfma_f32_16x16x32_bf16 v[44:47], v[216:219], v[136:139], v[44:47]
	v_mfma_f32_16x16x32_bf16 v[48:51], v[216:219], v[140:143], v[48:51]
	s_waitcnt vmcnt(12)
	ds_write_b128 v240, v[80:83] offset:13824
	v_mfma_f32_16x16x32_bf16 v[12:15], v[216:219], v[152:155], v[12:15]
	s_waitcnt lgkmcnt(12)
	v_mfma_f32_16x16x32_bf16 v[24:27], v[176:179], v[156:159], v[24:27]
	s_waitcnt vmcnt(11)
	ds_write_b128 v240, v[84:87] offset:18432
	v_mfma_f32_16x16x32_bf16 v[32:35], v[180:183], v[156:159], v[32:35]
	v_mfma_f32_16x16x32_bf16 v[8:11], v[184:187], v[156:159], v[8:11]
	v_mfma_f32_16x16x32_bf16 v[16:19], v[216:219], v[156:159], v[16:19]
	s_waitcnt lgkmcnt(10)
	v_mfma_f32_16x16x32_bf16 v[52:55], v[220:223], v[160:163], v[52:55]
	s_waitcnt lgkmcnt(8)
	v_mfma_f32_16x16x32_bf16 v[60:63], v[224:227], v[160:163], v[60:63]
	s_waitcnt lgkmcnt(7)
	v_mfma_f32_16x16x32_bf16 v[56:59], v[220:223], v[164:167], v[56:59]
	s_waitcnt vmcnt(10)
	ds_write_b128 v240, v[88:91] offset:23040
	v_mfma_f32_16x16x32_bf16 v[64:67], v[224:227], v[164:167], v[64:67]
	s_waitcnt lgkmcnt(6)
	v_mfma_f32_16x16x32_bf16 v[36:39], v[228:231], v[160:163], v[36:39]
	s_waitcnt vmcnt(9)
	ds_write_b128 v240, v[92:95] offset:27648
	v_mfma_f32_16x16x32_bf16 v[40:43], v[228:231], v[164:167], v[40:43]
	s_waitcnt lgkmcnt(6)
	v_mfma_f32_16x16x32_bf16 v[20:23], v[220:223], v[168:171], v[20:23]
	s_waitcnt vmcnt(8)
	ds_write_b128 v240, v[96:99] offset:32256
	v_mfma_f32_16x16x32_bf16 v[28:31], v[224:227], v[168:171], v[28:31]
	v_mfma_f32_16x16x32_bf16 v[4:7], v[228:231], v[168:171], v[4:7]
	s_waitcnt lgkmcnt(6)
	v_mfma_f32_16x16x32_bf16 v[44:47], v[232:235], v[160:163], v[44:47]
	v_mfma_f32_16x16x32_bf16 v[48:51], v[232:235], v[164:167], v[48:51]
	v_mfma_f32_16x16x32_bf16 v[12:15], v[232:235], v[168:171], v[12:15]
	s_waitcnt lgkmcnt(5)
	v_mfma_f32_16x16x32_bf16 v[24:27], v[220:223], v[172:175], v[24:27]
	v_mfma_f32_16x16x32_bf16 v[32:35], v[224:227], v[172:175], v[32:35]
	v_mfma_f32_16x16x32_bf16 v[8:11], v[228:231], v[172:175], v[8:11]
	v_mfma_f32_16x16x32_bf16 v[16:19], v[232:235], v[172:175], v[16:19]
	s_setprio 0
	s_waitcnt lgkmcnt(0)
	s_barrier
	ds_read_b128 v[136:139], v242
	ds_read_b128 v[176:179], v243 offset:18432
	ds_read_b128 v[180:183], v243 offset:20736
	ds_read_b128 v[140:143], v242 offset:2304
	ds_read_b128 v[184:187], v243 offset:23040
	ds_read_b128 v[152:155], v242 offset:4608
	ds_read_b128 v[216:219], v243 offset:25344
	ds_read_b128 v[156:159], v242 offset:6912
	s_setprio 1
	s_waitcnt lgkmcnt(6)
	v_mfma_f32_16x16x32_bf16 v[52:55], v[176:179], v[136:139], v[52:55]
	s_waitcnt vmcnt(7)
	ds_write_b128 v241, v[100:103]
	s_waitcnt lgkmcnt(6)
	v_mfma_f32_16x16x32_bf16 v[60:63], v[180:183], v[136:139], v[60:63]
	ds_read_b128 v[160:163], v242 offset:64
	s_waitcnt lgkmcnt(6)
	v_mfma_f32_16x16x32_bf16 v[56:59], v[176:179], v[140:143], v[56:59]
	ds_read_b128 v[220:223], v243 offset:18496
	s_waitcnt vmcnt(6)
	ds_write_b128 v241, v[104:107] offset:4608
	v_mfma_f32_16x16x32_bf16 v[64:67], v[180:183], v[140:143], v[64:67]
	ds_read_b128 v[224:227], v243 offset:20800
	s_waitcnt lgkmcnt(8)
	v_mfma_f32_16x16x32_bf16 v[36:39], v[184:187], v[136:139], v[36:39]
	ds_read_b128 v[164:167], v242 offset:2368
	s_waitcnt vmcnt(5)
	ds_write_b128 v241, v[108:111] offset:9216
	v_mfma_f32_16x16x32_bf16 v[40:43], v[184:187], v[140:143], v[40:43]
	ds_read_b128 v[228:231], v243 offset:23104
	s_waitcnt lgkmcnt(10)
	v_mfma_f32_16x16x32_bf16 v[20:23], v[176:179], v[152:155], v[20:23]
	ds_read_b128 v[168:171], v242 offset:4672
	v_mfma_f32_16x16x32_bf16 v[28:31], v[180:183], v[152:155], v[28:31]
	ds_read_b128 v[232:235], v243 offset:25408
	v_mfma_f32_16x16x32_bf16 v[4:7], v[184:187], v[152:155], v[4:7]
	ds_read_b128 v[172:175], v242 offset:6976
	s_waitcnt lgkmcnt(12)
	v_mfma_f32_16x16x32_bf16 v[44:47], v[216:219], v[136:139], v[44:47]
	v_mfma_f32_16x16x32_bf16 v[48:51], v[216:219], v[140:143], v[48:51]
	s_waitcnt vmcnt(4)
	ds_write_b128 v241, v[112:115] offset:13824
	v_mfma_f32_16x16x32_bf16 v[12:15], v[216:219], v[152:155], v[12:15]
	s_waitcnt lgkmcnt(12)
	v_mfma_f32_16x16x32_bf16 v[24:27], v[176:179], v[156:159], v[24:27]
	s_waitcnt vmcnt(3)
	ds_write_b128 v241, v[116:119] offset:18432
	v_mfma_f32_16x16x32_bf16 v[32:35], v[180:183], v[156:159], v[32:35]
	v_mfma_f32_16x16x32_bf16 v[8:11], v[184:187], v[156:159], v[8:11]
	v_mfma_f32_16x16x32_bf16 v[16:19], v[216:219], v[156:159], v[16:19]
	s_waitcnt lgkmcnt(10)
	v_mfma_f32_16x16x32_bf16 v[52:55], v[220:223], v[160:163], v[52:55]
	s_waitcnt lgkmcnt(8)
	v_mfma_f32_16x16x32_bf16 v[60:63], v[224:227], v[160:163], v[60:63]
	s_waitcnt lgkmcnt(7)
	v_mfma_f32_16x16x32_bf16 v[56:59], v[220:223], v[164:167], v[56:59]
	s_waitcnt vmcnt(2)
	ds_write_b128 v241, v[120:123] offset:23040
	v_mfma_f32_16x16x32_bf16 v[64:67], v[224:227], v[164:167], v[64:67]
	s_waitcnt lgkmcnt(6)
	v_mfma_f32_16x16x32_bf16 v[36:39], v[228:231], v[160:163], v[36:39]
	s_waitcnt vmcnt(1)
	ds_write_b128 v241, v[124:127] offset:27648
	v_mfma_f32_16x16x32_bf16 v[40:43], v[228:231], v[164:167], v[40:43]
	s_waitcnt lgkmcnt(6)
	v_mfma_f32_16x16x32_bf16 v[20:23], v[220:223], v[168:171], v[20:23]
	s_waitcnt vmcnt(0)
	ds_write_b128 v241, v[128:131] offset:32256
	v_mfma_f32_16x16x32_bf16 v[28:31], v[224:227], v[168:171], v[28:31]
	v_mfma_f32_16x16x32_bf16 v[4:7], v[228:231], v[168:171], v[4:7]
	s_waitcnt lgkmcnt(6)
	v_mfma_f32_16x16x32_bf16 v[44:47], v[232:235], v[160:163], v[44:47]
	v_mfma_f32_16x16x32_bf16 v[48:51], v[232:235], v[164:167], v[48:51]
	v_mfma_f32_16x16x32_bf16 v[12:15], v[232:235], v[168:171], v[12:15]
	s_waitcnt lgkmcnt(5)
	v_mfma_f32_16x16x32_bf16 v[24:27], v[220:223], v[172:175], v[24:27]
	v_mfma_f32_16x16x32_bf16 v[32:35], v[224:227], v[172:175], v[32:35]
	v_mfma_f32_16x16x32_bf16 v[8:11], v[228:231], v[172:175], v[8:11]
	v_mfma_f32_16x16x32_bf16 v[16:19], v[232:235], v[172:175], v[16:19]
	s_setprio 0
	s_waitcnt lgkmcnt(0)
	s_barrier
	ds_read_b128 v[136:139], v242 offset:36864
	ds_read_b128 v[176:179], v243 offset:55296
	ds_read_b128 v[180:183], v243 offset:57600
	ds_read_b128 v[140:143], v242 offset:39168
	ds_read_b128 v[184:187], v243 offset:59904
	ds_read_b128 v[152:155], v242 offset:41472
	ds_read_b128 v[216:219], v243 offset:62208
	ds_read_b128 v[156:159], v242 offset:43776
	s_setprio 1
	s_waitcnt lgkmcnt(6)
	v_mfma_f32_16x16x32_bf16 v[52:55], v[176:179], v[136:139], v[52:55]
	s_waitcnt lgkmcnt(5)
	v_mfma_f32_16x16x32_bf16 v[60:63], v[180:183], v[136:139], v[60:63]
	ds_read_b128 v[160:163], v242 offset:36928
	s_waitcnt lgkmcnt(5)
	v_mfma_f32_16x16x32_bf16 v[56:59], v[176:179], v[140:143], v[56:59]
	ds_read_b128 v[220:223], v243 offset:55360
	v_mfma_f32_16x16x32_bf16 v[64:67], v[180:183], v[140:143], v[64:67]
	ds_read_b128 v[224:227], v243 offset:57664
	s_waitcnt lgkmcnt(6)
	v_mfma_f32_16x16x32_bf16 v[36:39], v[184:187], v[136:139], v[36:39]
	ds_read_b128 v[164:167], v242 offset:39232
	v_mfma_f32_16x16x32_bf16 v[40:43], v[184:187], v[140:143], v[40:43]
	ds_read_b128 v[228:231], v243 offset:59968
	s_waitcnt lgkmcnt(7)
	v_mfma_f32_16x16x32_bf16 v[20:23], v[176:179], v[152:155], v[20:23]
	ds_read_b128 v[168:171], v242 offset:41536
	v_mfma_f32_16x16x32_bf16 v[28:31], v[180:183], v[152:155], v[28:31]
	ds_read_b128 v[232:235], v243 offset:62272
	v_mfma_f32_16x16x32_bf16 v[4:7], v[184:187], v[152:155], v[4:7]
	ds_read_b128 v[172:175], v242 offset:43840
	s_waitcnt lgkmcnt(9)
	v_mfma_f32_16x16x32_bf16 v[44:47], v[216:219], v[136:139], v[44:47]
	v_mfma_f32_16x16x32_bf16 v[48:51], v[216:219], v[140:143], v[48:51]
	v_mfma_f32_16x16x32_bf16 v[12:15], v[216:219], v[152:155], v[12:15]
	s_waitcnt lgkmcnt(8)
	v_mfma_f32_16x16x32_bf16 v[24:27], v[176:179], v[156:159], v[24:27]
	v_mfma_f32_16x16x32_bf16 v[32:35], v[180:183], v[156:159], v[32:35]
	v_mfma_f32_16x16x32_bf16 v[8:11], v[184:187], v[156:159], v[8:11]
	v_mfma_f32_16x16x32_bf16 v[16:19], v[216:219], v[156:159], v[16:19]
	s_waitcnt lgkmcnt(6)
	v_mfma_f32_16x16x32_bf16 v[52:55], v[220:223], v[160:163], v[52:55]
	s_waitcnt lgkmcnt(5)
	v_mfma_f32_16x16x32_bf16 v[60:63], v[224:227], v[160:163], v[60:63]
	s_waitcnt lgkmcnt(4)
	v_mfma_f32_16x16x32_bf16 v[56:59], v[220:223], v[164:167], v[56:59]
	v_mfma_f32_16x16x32_bf16 v[64:67], v[224:227], v[164:167], v[64:67]
	s_waitcnt lgkmcnt(3)
	v_mfma_f32_16x16x32_bf16 v[36:39], v[228:231], v[160:163], v[36:39]
	v_mfma_f32_16x16x32_bf16 v[40:43], v[228:231], v[164:167], v[40:43]
	s_waitcnt lgkmcnt(2)
	v_mfma_f32_16x16x32_bf16 v[20:23], v[220:223], v[168:171], v[20:23]
	v_mfma_f32_16x16x32_bf16 v[28:31], v[224:227], v[168:171], v[28:31]
	v_mfma_f32_16x16x32_bf16 v[4:7], v[228:231], v[168:171], v[4:7]
	s_waitcnt lgkmcnt(1)
	v_mfma_f32_16x16x32_bf16 v[44:47], v[232:235], v[160:163], v[44:47]
	v_mfma_f32_16x16x32_bf16 v[48:51], v[232:235], v[164:167], v[48:51]
	v_mfma_f32_16x16x32_bf16 v[12:15], v[232:235], v[168:171], v[12:15]
	s_waitcnt lgkmcnt(0)
	v_mfma_f32_16x16x32_bf16 v[24:27], v[220:223], v[172:175], v[24:27]
	v_mfma_f32_16x16x32_bf16 v[32:35], v[224:227], v[172:175], v[32:35]
	v_mfma_f32_16x16x32_bf16 v[8:11], v[228:231], v[172:175], v[8:11]
	v_mfma_f32_16x16x32_bf16 v[16:19], v[232:235], v[172:175], v[16:19]
	s_setprio 0
	s_nop 7
	s_nop 4
	s_nop 4
	v_permlane16_swap_b32_e32 v52, v56
	v_permlane16_swap_b32_e32 v53, v57
	v_permlane16_swap_b32_e32 v54, v58
	v_permlane16_swap_b32_e32 v55, v59
	v_permlane16_swap_b32_e32 v60, v64
	v_permlane16_swap_b32_e32 v61, v65
	v_permlane16_swap_b32_e32 v62, v66
	v_permlane16_swap_b32_e32 v63, v67
	v_permlane16_swap_b32_e32 v36, v40
	v_permlane16_swap_b32_e32 v37, v41
	v_permlane16_swap_b32_e32 v38, v42
	v_permlane16_swap_b32_e32 v39, v43
	v_permlane16_swap_b32_e32 v44, v48
	v_permlane16_swap_b32_e32 v45, v49
	v_permlane16_swap_b32_e32 v46, v50
	v_permlane16_swap_b32_e32 v47, v51
	v_permlane16_swap_b32_e32 v20, v24
	v_permlane16_swap_b32_e32 v21, v25
	v_permlane16_swap_b32_e32 v22, v26
	v_permlane16_swap_b32_e32 v23, v27
	v_permlane16_swap_b32_e32 v28, v32
	v_permlane16_swap_b32_e32 v29, v33
	v_permlane16_swap_b32_e32 v30, v34
	v_permlane16_swap_b32_e32 v31, v35
	v_permlane16_swap_b32_e32 v4, v8
	v_permlane16_swap_b32_e32 v5, v9
	v_permlane16_swap_b32_e32 v6, v10
	v_permlane16_swap_b32_e32 v7, v11
	v_permlane16_swap_b32_e32 v12, v16
	v_permlane16_swap_b32_e32 v13, v17
	v_permlane16_swap_b32_e32 v14, v18
	v_permlane16_swap_b32_e32 v15, v19
	s_nop 1
	v_permlane32_swap_b32_e32 v52, v56
	v_permlane32_swap_b32_e32 v53, v57
	v_permlane32_swap_b32_e32 v54, v58
	v_permlane32_swap_b32_e32 v55, v59
	v_permlane32_swap_b32_e32 v60, v64
	v_permlane32_swap_b32_e32 v61, v65
	v_permlane32_swap_b32_e32 v62, v66
	v_permlane32_swap_b32_e32 v63, v67
	v_permlane32_swap_b32_e32 v36, v40
	v_permlane32_swap_b32_e32 v37, v41
	v_permlane32_swap_b32_e32 v38, v42
	v_permlane32_swap_b32_e32 v39, v43
	v_permlane32_swap_b32_e32 v44, v48
	v_permlane32_swap_b32_e32 v45, v49
	v_permlane32_swap_b32_e32 v46, v50
	v_permlane32_swap_b32_e32 v47, v51
	v_permlane32_swap_b32_e32 v20, v24
	v_permlane32_swap_b32_e32 v21, v25
	v_permlane32_swap_b32_e32 v22, v26
	v_permlane32_swap_b32_e32 v23, v27
	v_permlane32_swap_b32_e32 v28, v32
	v_permlane32_swap_b32_e32 v29, v33
	v_permlane32_swap_b32_e32 v30, v34
	v_permlane32_swap_b32_e32 v31, v35
	v_permlane32_swap_b32_e32 v4, v8
	v_permlane32_swap_b32_e32 v5, v9
	v_permlane32_swap_b32_e32 v6, v10
	v_permlane32_swap_b32_e32 v7, v11
	v_permlane32_swap_b32_e32 v12, v16
	v_permlane32_swap_b32_e32 v13, v17
	v_permlane32_swap_b32_e32 v14, v18
	v_permlane32_swap_b32_e32 v15, v19
	s_nop 1
	v_mov_b32_e32 v188, 0x12010
	s_add_i32 s2, s76, s70
	s_and_b32 s0, s2, 0xfffffe00
	s_cmpk_eq_i32 s0, 0xc00
	s_cselect_b64 s[0:1], -1, 0
	s_and_b64 s[0:1], s[26:27], s[0:1]
	s_cmpk_lt_i32 s2, 0xd00
	s_movk_i32 s3, 0xff00
	s_cselect_b32 s3, 0x100, s3
	s_and_b64 s[0:1], s[0:1], exec
	s_cselect_b32 s0, s3, 0
	s_add_i32 s0, s0, s2
	s_cmpk_lt_i32 s2, 0xe10
	s_cselect_b32 s0, s0, 0xd00
	s_cmpk_gt_i32 s0, 0xcff
	v_mov_b64_e32 v[146:147], v[150:151]
	v_mov_b64_e32 v[144:145], v[148:149]
	s_barrier
	s_cbranch_scc1 .LBB0_303
	s_lshl_b32 s1, s0, 18
	v_readlane_b32 s12, v252, 47
	v_mov_b32_e32 v2, v0
	s_and_b32 s1, s1, 0xfc0000
	v_readlane_b32 s18, v252, 53
	v_readlane_b32 s19, v252, 54
	v_ashrrev_i32_e32 v68, 3, v2
	s_add_u32 s2, s18, s1
	v_ashrrev_i32_e32 v69, 31, v68
	s_addc_u32 s3, s19, 0
	v_lshlrev_b64 v[68:69], 11, v[68:69]
	v_lshlrev_b32_e32 v2, 4, v2
	v_lshl_add_u64 v[70:71], s[2:3], 0, v[68:69]
	v_and_b32_e32 v2, 0x70, v2
	s_ashr_i32 s0, s0, 6
	v_lshl_add_u64 v[144:145], v[70:71], 0, v[2:3]
	s_ashr_i32 s1, s0, 31
	v_add_co_u32_e32 v76, vcc, s33, v144
	s_lshl_b64 s[0:1], s[0:1], 18
	s_nop 0
	v_addc_co_u32_e32 v77, vcc, 0, v145, vcc
	s_add_u32 s0, s68, s0
	v_add_co_u32_e32 v80, vcc, s78, v144
	s_addc_u32 s1, s69, s1
	s_nop 0
	v_addc_co_u32_e32 v81, vcc, 0, v145, vcc
	v_lshl_add_u64 v[68:69], s[0:1], 0, v[68:69]
	v_add_co_u32_e32 v84, vcc, s79, v144
	v_lshl_add_u64 v[146:147], v[68:69], 0, v[2:3]
	s_nop 0
	v_addc_co_u32_e32 v85, vcc, 0, v145, vcc
	v_add_co_u32_e32 v92, vcc, s33, v146
	v_readlane_b32 s13, v252, 48
	s_nop 0
	v_addc_co_u32_e32 v93, vcc, 0, v147, vcc
	v_add_co_u32_e32 v96, vcc, s78, v146
	v_readlane_b32 s14, v252, 49
	s_nop 0
	v_addc_co_u32_e32 v97, vcc, 0, v147, vcc
	v_add_co_u32_e32 v128, vcc, 0x30000, v146
	v_readlane_b32 s15, v252, 50
	s_nop 0
	v_addc_co_u32_e32 v129, vcc, 0, v147, vcc
	global_load_dwordx4 v[68:71], v[144:145], off
	global_load_dwordx4 v[100:103], v[144:145], off offset:128
	global_load_dwordx4 v[72:75], v[76:77], off
	global_load_dwordx4 v[104:107], v[76:77], off offset:128
	s_nop 0
	global_load_dwordx4 v[76:79], v[80:81], off
	global_load_dwordx4 v[108:111], v[80:81], off offset:128
	s_nop 0
	global_load_dwordx4 v[80:83], v[84:85], off
	global_load_dwordx4 v[112:115], v[84:85], off offset:128
	s_nop 0
	global_load_dwordx4 v[84:87], v[146:147], off
	global_load_dwordx4 v[116:119], v[146:147], off offset:128
	global_load_dwordx4 v[88:91], v[92:93], off
	global_load_dwordx4 v[120:123], v[92:93], off offset:128
	s_nop 0
	global_load_dwordx4 v[92:95], v[96:97], off
	global_load_dwordx4 v[124:127], v[96:97], off offset:128
	s_nop 0
	global_load_dwordx4 v[96:99], v[128:129], off
	s_nop 0
	global_load_dwordx4 v[128:131], v[128:129], off offset:128
	v_readlane_b32 s16, v252, 51
	v_readlane_b32 s17, v252, 52

.LBB0_581:
	s_or_b64 exec, exec, s[20:21]
	s_lshl_b32 s0, s36, 1
	s_and_b32 s20, s0, 0xffffff80
	s_mul_i32 s0, s37, 0x1600
	v_readlane_b32 s22, v252, 60
	v_readlane_b32 s23, v252, 61
	s_add_u32 s0, s22, s0
	s_addc_u32 s1, s23, 0
	s_mul_i32 s22, s20, 0x1600
	s_mul_hi_i32 s21, s20, 0x1600
	s_add_u32 s22, s34, s22
	v_mov_b32_e32 v141, v0
	s_waitcnt vmcnt(0)
	s_addc_u32 s23, s35, s21
	v_mov_b64_e32 v[4:5], s[0:1]
	v_ashrrev_i32_e32 v6, 3, v141
	v_mad_i64_i32 v[132:133], s[0:1], v6, s73, v[4:5]
	v_lshlrev_b32_e32 v2, 4, v141
	v_mov_b64_e32 v[4:5], s[22:23]
	v_and_b32_e32 v2, 0x70, v2
	v_mad_i64_i32 v[134:135], s[0:1], v6, s73, v[4:5]
	s_waitcnt vmcnt(13)
	v_lshl_add_u64 v[72:73], v[132:133], 0, v[2:3]
	s_mov_b32 s0, 0x2c000
	s_waitcnt vmcnt(9)
	v_add_co_u32_e32 v80, vcc, s0, v72
	s_mov_b32 s1, 0x58000
	s_nop 0
	v_addc_co_u32_e32 v81, vcc, 0, v73, vcc
	s_waitcnt vmcnt(5)
	v_add_co_u32_e32 v88, vcc, s1, v72
	s_mov_b32 s21, 0x84000
	s_nop 0
	v_addc_co_u32_e32 v89, vcc, 0, v73, vcc
	s_waitcnt vmcnt(1)
	v_add_co_u32_e32 v96, vcc, s21, v72
	v_lshl_add_u64 v[104:105], v[134:135], 0, v[2:3]
	s_nop 0
	v_addc_co_u32_e32 v97, vcc, 0, v73, vcc
	s_mov_b32 s0, 0x2c000
	s_mov_b32 s1, 0
	v_lshl_add_u64 v[74:75], s[0:1], 0, v[72:73]
	s_mov_b32 s0, 0x58000
	s_mov_b32 s1, 0
	v_lshl_add_u64 v[106:107], s[0:1], 0, v[72:73]
	s_mov_b32 s0, 0x84000
	s_mov_b32 s1, 0
	v_lshl_add_u64 v[188:189], s[0:1], 0, v[72:73]
	s_mov_b32 s0, 0x2c000
	s_mov_b32 s1, 0
	v_lshl_add_u64 v[214:215], s[0:1], 0, v[104:105]
	s_mov_b32 s0, 0x58000
	s_mov_b32 s1, 0
	v_lshl_add_u64 v[236:237], s[0:1], 0, v[104:105]
	s_mov_b32 s0, 0x84000
	s_mov_b32 s1, 0
	v_lshl_add_u64 v[238:239], s[0:1], 0, v[104:105]
	v_lshrrev_b32_e32 v172, 3, v0
	v_and_b32_e32 v174, 15, v172
	v_lshlrev_b32_e32 v173, 1, v174
	v_cmp_gt_u32_e32 vcc, 12, v174
	s_nop 1
	v_mov_b32_e32 v175, 15
	v_cndmask_b32_e64 v175, v175, 8, vcc
	v_cmp_gt_u32_e32 vcc, 4, v174
	v_sub_u32_e32 v173, v173, v175
	v_lshlrev_b32_e32 v175, 1, v174
	v_add_u32_e32 v175, 1, v175
	s_nop 1
	v_cndmask_b32_e32 v173, v173, v175, vcc
	v_and_b32_e32 v172, 16, v172
	v_add_u32_e32 v172, v172, v173
	v_mul_u32_u24_e32 v172, 0x90, v172
	v_and_b32_e32 v173, 7, v0
	v_lshl_add_u32 v213, v173, 4, v172
	v_add_u32_e32 v240, 0x9000, v213
	v_and_b32_e32 v174, 15, v0
	v_lshlrev_b32_e32 v173, 1, v174
	v_cmp_gt_u32_e32 vcc, 12, v174
	s_nop 1
	v_mov_b32_e32 v175, 15
	v_cndmask_b32_e64 v175, v175, 8, vcc
	v_cmp_gt_u32_e32 vcc, 4, v174
	v_sub_u32_e32 v173, v173, v175
	v_lshlrev_b32_e32 v175, 1, v174
	v_add_u32_e32 v175, 1, v175
	s_nop 1
	v_cndmask_b32_e32 v173, v173, v175, vcc
	v_bfe_u32 v172, v0, 4, 2
	v_and_b32_e32 v174, 1, v172
	v_lshrrev_b32_e32 v172, 1, v172
	v_lshl_or_b32 v172, v174, 1, v172
	v_lshlrev_b32_e32 v172, 4, v172
	v_lshrrev_b32_e32 v174, 1, v0
	v_and_b32_e32 v174, 64, v174
	v_add_u32_e32 v174, v174, v173
	v_mul_u32_u24_e32 v174, 0x90, v174
	v_add_u32_e32 v241, v174, v172
	v_and_b32_e32 v174, 64, v0
	v_add_u32_e32 v174, v174, v173
	v_mul_u32_u24_e32 v174, 0x90, v174
	v_add_u32_e32 v242, v174, v172
	global_load_dwordx4 v[68:71], v[72:73], off
	global_load_dwordx4 v[76:79], v[74:75], off
	global_load_dwordx4 v[80:83], v[106:107], off
	global_load_dwordx4 v[84:87], v[188:189], off
	global_load_dwordx4 v[88:91], v[104:105], off
	global_load_dwordx4 v[92:95], v[214:215], off
	global_load_dwordx4 v[96:99], v[236:237], off
	global_load_dwordx4 v[100:103], v[238:239], off
	global_load_dwordx4 v[108:111], v[72:73], off offset:128
	global_load_dwordx4 v[112:115], v[74:75], off offset:128
	global_load_dwordx4 v[116:119], v[106:107], off offset:128
	global_load_dwordx4 v[120:123], v[188:189], off offset:128
	global_load_dwordx4 v[124:127], v[104:105], off offset:128
	global_load_dwordx4 v[128:131], v[214:215], off offset:128
	global_load_dwordx4 v[136:139], v[236:237], off offset:128
	global_load_dwordx4 v[140:143], v[238:239], off offset:128
	s_barrier
	s_waitcnt vmcnt(15)
	ds_write_b128 v213, v[68:71]
	s_waitcnt vmcnt(14)
	ds_write_b128 v213, v[76:79] offset:4608
	s_waitcnt vmcnt(13)
	ds_write_b128 v213, v[80:83] offset:9216
	s_waitcnt vmcnt(12)
	ds_write_b128 v213, v[84:87] offset:13824
	s_waitcnt vmcnt(11)
	ds_write_b128 v213, v[88:91] offset:18432
	s_waitcnt vmcnt(10)
	ds_write_b128 v213, v[92:95] offset:23040
	s_waitcnt vmcnt(9)
	ds_write_b128 v213, v[96:99] offset:27648
	s_waitcnt vmcnt(8)
	ds_write_b128 v213, v[100:103] offset:32256
	global_load_dwordx4 v[68:71], v[72:73], off offset:256
	global_load_dwordx4 v[76:79], v[74:75], off offset:256
	global_load_dwordx4 v[80:83], v[106:107], off offset:256
	global_load_dwordx4 v[84:87], v[188:189], off offset:256
	global_load_dwordx4 v[88:91], v[104:105], off offset:256
	global_load_dwordx4 v[92:95], v[214:215], off offset:256
	global_load_dwordx4 v[96:99], v[236:237], off offset:256
	global_load_dwordx4 v[100:103], v[238:239], off offset:256
	s_waitcnt lgkmcnt(0)
	s_barrier
	ds_read_b128 v[144:147], v241
	ds_read_b128 v[176:179], v242 offset:18432
	ds_read_b128 v[180:183], v242 offset:20736
	ds_read_b128 v[148:151], v241 offset:2304
	ds_read_b128 v[184:187], v242 offset:23040
	ds_read_b128 v[152:155], v241 offset:4608
	ds_read_b128 v[216:219], v242 offset:25344
	ds_read_b128 v[156:159], v241 offset:6912
	s_setprio 1
	s_waitcnt lgkmcnt(6)
	v_mfma_f32_16x16x32_bf16 v[52:55], v[176:179], v[144:147], 0
	s_waitcnt vmcnt(15)
	ds_write_b128 v240, v[108:111]
	s_waitcnt lgkmcnt(6)
	v_mfma_f32_16x16x32_bf16 v[60:63], v[180:183], v[144:147], 0
	ds_read_b128 v[160:163], v241 offset:64
	s_waitcnt lgkmcnt(6)
	v_mfma_f32_16x16x32_bf16 v[56:59], v[176:179], v[148:151], 0
	ds_read_b128 v[220:223], v242 offset:18496
	s_waitcnt vmcnt(14)
	ds_write_b128 v240, v[112:115] offset:4608
	v_mfma_f32_16x16x32_bf16 v[64:67], v[180:183], v[148:151], 0
	ds_read_b128 v[224:227], v242 offset:20800
	s_waitcnt lgkmcnt(8)
	v_mfma_f32_16x16x32_bf16 v[36:39], v[184:187], v[144:147], 0
	ds_read_b128 v[164:167], v241 offset:2368
	s_waitcnt vmcnt(13)
	ds_write_b128 v240, v[116:119] offset:9216
	global_load_dwordx4 v[108:111], v[72:73], off offset:384
	v_mfma_f32_16x16x32_bf16 v[40:43], v[184:187], v[148:151], 0
	ds_read_b128 v[228:231], v242 offset:23104
	s_waitcnt lgkmcnt(10)
	v_mfma_f32_16x16x32_bf16 v[20:23], v[176:179], v[152:155], 0
	ds_read_b128 v[168:171], v241 offset:4672
	v_mfma_f32_16x16x32_bf16 v[28:31], v[180:183], v[152:155], 0
	ds_read_b128 v[232:235], v242 offset:25408
	v_mfma_f32_16x16x32_bf16 v[4:7], v[184:187], v[152:155], 0
	ds_read_b128 v[172:175], v241 offset:6976
	s_waitcnt lgkmcnt(12)
	v_mfma_f32_16x16x32_bf16 v[44:47], v[216:219], v[144:147], 0
	v_mfma_f32_16x16x32_bf16 v[48:51], v[216:219], v[148:151], 0
	s_waitcnt vmcnt(13)
	ds_write_b128 v240, v[120:123] offset:13824
	global_load_dwordx4 v[112:115], v[74:75], off offset:384
	v_mfma_f32_16x16x32_bf16 v[12:15], v[216:219], v[152:155], 0
	s_waitcnt lgkmcnt(12)
	v_mfma_f32_16x16x32_bf16 v[24:27], v[176:179], v[156:159], 0
	s_waitcnt vmcnt(13)
	ds_write_b128 v240, v[124:127] offset:18432
	global_load_dwordx4 v[116:119], v[106:107], off offset:384
	v_mfma_f32_16x16x32_bf16 v[32:35], v[180:183], v[156:159], 0
	v_mfma_f32_16x16x32_bf16 v[8:11], v[184:187], v[156:159], 0
	v_mfma_f32_16x16x32_bf16 v[16:19], v[216:219], v[156:159], 0
	s_waitcnt lgkmcnt(10)
	v_mfma_f32_16x16x32_bf16 v[52:55], v[220:223], v[160:163], v[52:55]
	s_waitcnt lgkmcnt(8)
	v_mfma_f32_16x16x32_bf16 v[60:63], v[224:227], v[160:163], v[60:63]
	s_waitcnt lgkmcnt(7)
	v_mfma_f32_16x16x32_bf16 v[56:59], v[220:223], v[164:167], v[56:59]
	s_waitcnt vmcnt(13)
	ds_write_b128 v240, v[128:131] offset:23040
	global_load_dwordx4 v[120:123], v[188:189], off offset:384
	v_mfma_f32_16x16x32_bf16 v[64:67], v[224:227], v[164:167], v[64:67]
	s_waitcnt lgkmcnt(6)
	v_mfma_f32_16x16x32_bf16 v[36:39], v[228:231], v[160:163], v[36:39]
	s_waitcnt vmcnt(13)
	ds_write_b128 v240, v[136:139] offset:27648
	global_load_dwordx4 v[124:127], v[104:105], off offset:384
	v_mfma_f32_16x16x32_bf16 v[40:43], v[228:231], v[164:167], v[40:43]
	s_waitcnt lgkmcnt(6)
	v_mfma_f32_16x16x32_bf16 v[20:23], v[220:223], v[168:171], v[20:23]
	s_waitcnt vmcnt(13)
	ds_write_b128 v240, v[140:143] offset:32256
	global_load_dwordx4 v[128:131], v[214:215], off offset:384
	v_mfma_f32_16x16x32_bf16 v[28:31], v[224:227], v[168:171], v[28:31]
	v_mfma_f32_16x16x32_bf16 v[4:7], v[228:231], v[168:171], v[4:7]
	global_load_dwordx4 v[136:139], v[236:237], off offset:384
	s_waitcnt lgkmcnt(6)
	v_mfma_f32_16x16x32_bf16 v[44:47], v[232:235], v[160:163], v[44:47]
	v_mfma_f32_16x16x32_bf16 v[48:51], v[232:235], v[164:167], v[48:51]
	global_load_dwordx4 v[140:143], v[238:239], off offset:384
	v_mfma_f32_16x16x32_bf16 v[12:15], v[232:235], v[168:171], v[12:15]
	s_waitcnt lgkmcnt(5)
	v_mfma_f32_16x16x32_bf16 v[24:27], v[220:223], v[172:175], v[24:27]
	v_mfma_f32_16x16x32_bf16 v[32:35], v[224:227], v[172:175], v[32:35]
	v_mfma_f32_16x16x32_bf16 v[8:11], v[228:231], v[172:175], v[8:11]
	v_mfma_f32_16x16x32_bf16 v[16:19], v[232:235], v[172:175], v[16:19]
	s_setprio 0
	s_waitcnt lgkmcnt(0)
	s_barrier
	ds_read_b128 v[144:147], v241 offset:36864
	ds_read_b128 v[176:179], v242 offset:55296
	ds_read_b128 v[180:183], v242 offset:57600
	ds_read_b128 v[148:151], v241 offset:39168
	ds_read_b128 v[184:187], v242 offset:59904
	ds_read_b128 v[152:155], v241 offset:41472
	ds_read_b128 v[216:219], v242 offset:62208
	ds_read_b128 v[156:159], v241 offset:43776
	s_setprio 1
	s_waitcnt lgkmcnt(6)
	v_mfma_f32_16x16x32_bf16 v[52:55], v[176:179], v[144:147], v[52:55]
	s_waitcnt vmcnt(15)
	ds_write_b128 v213, v[68:71]
	s_waitcnt lgkmcnt(6)
	v_mfma_f32_16x16x32_bf16 v[60:63], v[180:183], v[144:147], v[60:63]
	ds_read_b128 v[160:163], v241 offset:36928
	s_waitcnt lgkmcnt(6)
	v_mfma_f32_16x16x32_bf16 v[56:59], v[176:179], v[148:151], v[56:59]
	ds_read_b128 v[220:223], v242 offset:55360
	s_waitcnt vmcnt(14)
	ds_write_b128 v213, v[76:79] offset:4608
	v_mfma_f32_16x16x32_bf16 v[64:67], v[180:183], v[148:151], v[64:67]
	ds_read_b128 v[224:227], v242 offset:57664
	s_waitcnt lgkmcnt(8)
	v_mfma_f32_16x16x32_bf16 v[36:39], v[184:187], v[144:147], v[36:39]
	ds_read_b128 v[164:167], v241 offset:39232
	s_waitcnt vmcnt(13)
	ds_write_b128 v213, v[80:83] offset:9216
	global_load_dwordx4 v[68:71], v[72:73], off offset:512
	v_mfma_f32_16x16x32_bf16 v[40:43], v[184:187], v[148:151], v[40:43]
	ds_read_b128 v[228:231], v242 offset:59968
	s_waitcnt lgkmcnt(10)
	v_mfma_f32_16x16x32_bf16 v[20:23], v[176:179], v[152:155], v[20:23]
	ds_read_b128 v[168:171], v241 offset:41536
	v_mfma_f32_16x16x32_bf16 v[28:31], v[180:183], v[152:155], v[28:31]
	ds_read_b128 v[232:235], v242 offset:62272
	v_mfma_f32_16x16x32_bf16 v[4:7], v[184:187], v[152:155], v[4:7]
	ds_read_b128 v[172:175], v241 offset:43840
	s_waitcnt lgkmcnt(12)
	v_mfma_f32_16x16x32_bf16 v[44:47], v[216:219], v[144:147], v[44:47]
	v_mfma_f32_16x16x32_bf16 v[48:51], v[216:219], v[148:151], v[48:51]
	s_waitcnt vmcnt(13)
	ds_write_b128 v213, v[84:87] offset:13824
	global_load_dwordx4 v[76:79], v[74:75], off offset:512
	v_mfma_f32_16x16x32_bf16 v[12:15], v[216:219], v[152:155], v[12:15]
	s_waitcnt lgkmcnt(12)
	v_mfma_f32_16x16x32_bf16 v[24:27], v[176:179], v[156:159], v[24:27]
	s_waitcnt vmcnt(13)
	ds_write_b128 v213, v[88:91] offset:18432
	global_load_dwordx4 v[80:83], v[106:107], off offset:512
	v_mfma_f32_16x16x32_bf16 v[32:35], v[180:183], v[156:159], v[32:35]
	v_mfma_f32_16x16x32_bf16 v[8:11], v[184:187], v[156:159], v[8:11]
	v_mfma_f32_16x16x32_bf16 v[16:19], v[216:219], v[156:159], v[16:19]
	s_waitcnt lgkmcnt(10)
	v_mfma_f32_16x16x32_bf16 v[52:55], v[220:223], v[160:163], v[52:55]
	s_waitcnt lgkmcnt(8)
	v_mfma_f32_16x16x32_bf16 v[60:63], v[224:227], v[160:163], v[60:63]
	s_waitcnt lgkmcnt(7)
	v_mfma_f32_16x16x32_bf16 v[56:59], v[220:223], v[164:167], v[56:59]
	s_waitcnt vmcnt(13)
	ds_write_b128 v213, v[92:95] offset:23040
	global_load_dwordx4 v[84:87], v[188:189], off offset:512
	v_mfma_f32_16x16x32_bf16 v[64:67], v[224:227], v[164:167], v[64:67]
	s_waitcnt lgkmcnt(6)
	v_mfma_f32_16x16x32_bf16 v[36:39], v[228:231], v[160:163], v[36:39]
	s_waitcnt vmcnt(13)
	ds_write_b128 v213, v[96:99] offset:27648
	global_load_dwordx4 v[88:91], v[104:105], off offset:512
	v_mfma_f32_16x16x32_bf16 v[40:43], v[228:231], v[164:167], v[40:43]
	s_waitcnt lgkmcnt(6)
	v_mfma_f32_16x16x32_bf16 v[20:23], v[220:223], v[168:171], v[20:23]
	s_waitcnt vmcnt(13)
	ds_write_b128 v213, v[100:103] offset:32256
	global_load_dwordx4 v[92:95], v[214:215], off offset:512
	v_mfma_f32_16x16x32_bf16 v[28:31], v[224:227], v[168:171], v[28:31]
	v_mfma_f32_16x16x32_bf16 v[4:7], v[228:231], v[168:171], v[4:7]
	global_load_dwordx4 v[96:99], v[236:237], off offset:512
	s_waitcnt lgkmcnt(6)
	v_mfma_f32_16x16x32_bf16 v[44:47], v[232:235], v[160:163], v[44:47]
	v_mfma_f32_16x16x32_bf16 v[48:51], v[232:235], v[164:167], v[48:51]
	global_load_dwordx4 v[100:103], v[238:239], off offset:512
	v_mfma_f32_16x16x32_bf16 v[12:15], v[232:235], v[168:171], v[12:15]
	s_waitcnt lgkmcnt(5)
	v_mfma_f32_16x16x32_bf16 v[24:27], v[220:223], v[172:175], v[24:27]
	v_mfma_f32_16x16x32_bf16 v[32:35], v[224:227], v[172:175], v[32:35]
	v_mfma_f32_16x16x32_bf16 v[8:11], v[228:231], v[172:175], v[8:11]
	v_mfma_f32_16x16x32_bf16 v[16:19], v[232:235], v[172:175], v[16:19]
	s_setprio 0
	s_waitcnt lgkmcnt(0)
	s_barrier
	ds_read_b128 v[144:147], v241
	ds_read_b128 v[176:179], v242 offset:18432
	ds_read_b128 v[180:183], v242 offset:20736
	ds_read_b128 v[148:151], v241 offset:2304
	ds_read_b128 v[184:187], v242 offset:23040
	ds_read_b128 v[152:155], v241 offset:4608
	ds_read_b128 v[216:219], v242 offset:25344
	ds_read_b128 v[156:159], v241 offset:6912
	s_setprio 1
	s_waitcnt lgkmcnt(6)
	v_mfma_f32_16x16x32_bf16 v[52:55], v[176:179], v[144:147], v[52:55]
	s_waitcnt vmcnt(15)
	ds_write_b128 v240, v[108:111]
	s_waitcnt lgkmcnt(6)
	v_mfma_f32_16x16x32_bf16 v[60:63], v[180:183], v[144:147], v[60:63]
	ds_read_b128 v[160:163], v241 offset:64
	s_waitcnt lgkmcnt(6)
	v_mfma_f32_16x16x32_bf16 v[56:59], v[176:179], v[148:151], v[56:59]
	ds_read_b128 v[220:223], v242 offset:18496
	s_waitcnt vmcnt(14)
	ds_write_b128 v240, v[112:115] offset:4608
	v_mfma_f32_16x16x32_bf16 v[64:67], v[180:183], v[148:151], v[64:67]
	ds_read_b128 v[224:227], v242 offset:20800
	s_waitcnt lgkmcnt(8)
	v_mfma_f32_16x16x32_bf16 v[36:39], v[184:187], v[144:147], v[36:39]
	ds_read_b128 v[164:167], v241 offset:2368
	s_waitcnt vmcnt(13)
	ds_write_b128 v240, v[116:119] offset:9216
	global_load_dwordx4 v[108:111], v[72:73], off offset:640
	v_mfma_f32_16x16x32_bf16 v[40:43], v[184:187], v[148:151], v[40:43]
	ds_read_b128 v[228:231], v242 offset:23104
	s_waitcnt lgkmcnt(10)
	v_mfma_f32_16x16x32_bf16 v[20:23], v[176:179], v[152:155], v[20:23]
	ds_read_b128 v[168:171], v241 offset:4672
	v_mfma_f32_16x16x32_bf16 v[28:31], v[180:183], v[152:155], v[28:31]
	ds_read_b128 v[232:235], v242 offset:25408
	v_mfma_f32_16x16x32_bf16 v[4:7], v[184:187], v[152:155], v[4:7]
	ds_read_b128 v[172:175], v241 offset:6976
	s_waitcnt lgkmcnt(12)
	v_mfma_f32_16x16x32_bf16 v[44:47], v[216:219], v[144:147], v[44:47]
	v_mfma_f32_16x16x32_bf16 v[48:51], v[216:219], v[148:151], v[48:51]
	s_waitcnt vmcnt(13)
	ds_write_b128 v240, v[120:123] offset:13824
	global_load_dwordx4 v[112:115], v[74:75], off offset:640
	v_mfma_f32_16x16x32_bf16 v[12:15], v[216:219], v[152:155], v[12:15]
	s_waitcnt lgkmcnt(12)
	v_mfma_f32_16x16x32_bf16 v[24:27], v[176:179], v[156:159], v[24:27]
	s_waitcnt vmcnt(13)
	ds_write_b128 v240, v[124:127] offset:18432
	global_load_dwordx4 v[116:119], v[106:107], off offset:640
	v_mfma_f32_16x16x32_bf16 v[32:35], v[180:183], v[156:159], v[32:35]
	v_mfma_f32_16x16x32_bf16 v[8:11], v[184:187], v[156:159], v[8:11]
	v_mfma_f32_16x16x32_bf16 v[16:19], v[216:219], v[156:159], v[16:19]
	s_waitcnt lgkmcnt(10)
	v_mfma_f32_16x16x32_bf16 v[52:55], v[220:223], v[160:163], v[52:55]
	s_waitcnt lgkmcnt(8)
	v_mfma_f32_16x16x32_bf16 v[60:63], v[224:227], v[160:163], v[60:63]
	s_waitcnt lgkmcnt(7)
	v_mfma_f32_16x16x32_bf16 v[56:59], v[220:223], v[164:167], v[56:59]
	s_waitcnt vmcnt(13)
	ds_write_b128 v240, v[128:131] offset:23040
	global_load_dwordx4 v[120:123], v[188:189], off offset:640
	v_mfma_f32_16x16x32_bf16 v[64:67], v[224:227], v[164:167], v[64:67]
	s_waitcnt lgkmcnt(6)
	v_mfma_f32_16x16x32_bf16 v[36:39], v[228:231], v[160:163], v[36:39]
	s_waitcnt vmcnt(13)
	ds_write_b128 v240, v[136:139] offset:27648
	global_load_dwordx4 v[124:127], v[104:105], off offset:640
	v_mfma_f32_16x16x32_bf16 v[40:43], v[228:231], v[164:167], v[40:43]
	s_waitcnt lgkmcnt(6)
	v_mfma_f32_16x16x32_bf16 v[20:23], v[220:223], v[168:171], v[20:23]
	s_waitcnt vmcnt(13)
	ds_write_b128 v240, v[140:143] offset:32256
	global_load_dwordx4 v[128:131], v[214:215], off offset:640
	v_mfma_f32_16x16x32_bf16 v[28:31], v[224:227], v[168:171], v[28:31]
	v_mfma_f32_16x16x32_bf16 v[4:7], v[228:231], v[168:171], v[4:7]
	global_load_dwordx4 v[136:139], v[236:237], off offset:640
	s_waitcnt lgkmcnt(6)
	v_mfma_f32_16x16x32_bf16 v[44:47], v[232:235], v[160:163], v[44:47]
	v_mfma_f32_16x16x32_bf16 v[48:51], v[232:235], v[164:167], v[48:51]
	global_load_dwordx4 v[140:143], v[238:239], off offset:640
	v_mfma_f32_16x16x32_bf16 v[12:15], v[232:235], v[168:171], v[12:15]
	s_waitcnt lgkmcnt(5)
	v_mfma_f32_16x16x32_bf16 v[24:27], v[220:223], v[172:175], v[24:27]
	v_mfma_f32_16x16x32_bf16 v[32:35], v[224:227], v[172:175], v[32:35]
	v_mfma_f32_16x16x32_bf16 v[8:11], v[228:231], v[172:175], v[8:11]
	v_mfma_f32_16x16x32_bf16 v[16:19], v[232:235], v[172:175], v[16:19]
	s_setprio 0
	s_waitcnt lgkmcnt(0)
	s_barrier
	ds_read_b128 v[144:147], v241 offset:36864
	ds_read_b128 v[176:179], v242 offset:55296
	ds_read_b128 v[180:183], v242 offset:57600
	ds_read_b128 v[148:151], v241 offset:39168
	ds_read_b128 v[184:187], v242 offset:59904
	ds_read_b128 v[152:155], v241 offset:41472
	ds_read_b128 v[216:219], v242 offset:62208
	ds_read_b128 v[156:159], v241 offset:43776
	s_setprio 1
	s_waitcnt lgkmcnt(6)
	v_mfma_f32_16x16x32_bf16 v[52:55], v[176:179], v[144:147], v[52:55]
	s_waitcnt vmcnt(15)
	ds_write_b128 v213, v[68:71]
	s_waitcnt lgkmcnt(6)
	v_mfma_f32_16x16x32_bf16 v[60:63], v[180:183], v[144:147], v[60:63]
	ds_read_b128 v[160:163], v241 offset:36928
	s_waitcnt lgkmcnt(6)
	v_mfma_f32_16x16x32_bf16 v[56:59], v[176:179], v[148:151], v[56:59]
	ds_read_b128 v[220:223], v242 offset:55360
	s_waitcnt vmcnt(14)
	ds_write_b128 v213, v[76:79] offset:4608
	v_mfma_f32_16x16x32_bf16 v[64:67], v[180:183], v[148:151], v[64:67]
	ds_read_b128 v[224:227], v242 offset:57664
	s_waitcnt lgkmcnt(8)
	v_mfma_f32_16x16x32_bf16 v[36:39], v[184:187], v[144:147], v[36:39]
	ds_read_b128 v[164:167], v241 offset:39232
	s_waitcnt vmcnt(13)
	ds_write_b128 v213, v[80:83] offset:9216
	global_load_dwordx4 v[68:71], v[72:73], off offset:768
	v_mfma_f32_16x16x32_bf16 v[40:43], v[184:187], v[148:151], v[40:43]
	ds_read_b128 v[228:231], v242 offset:59968
	s_waitcnt lgkmcnt(10)
	v_mfma_f32_16x16x32_bf16 v[20:23], v[176:179], v[152:155], v[20:23]
	ds_read_b128 v[168:171], v241 offset:41536
	v_mfma_f32_16x16x32_bf16 v[28:31], v[180:183], v[152:155], v[28:31]
	ds_read_b128 v[232:235], v242 offset:62272
	v_mfma_f32_16x16x32_bf16 v[4:7], v[184:187], v[152:155], v[4:7]
	ds_read_b128 v[172:175], v241 offset:43840
	s_waitcnt lgkmcnt(12)
	v_mfma_f32_16x16x32_bf16 v[44:47], v[216:219], v[144:147], v[44:47]
	v_mfma_f32_16x16x32_bf16 v[48:51], v[216:219], v[148:151], v[48:51]
	s_waitcnt vmcnt(13)
	ds_write_b128 v213, v[84:87] offset:13824
	global_load_dwordx4 v[76:79], v[74:75], off offset:768
	v_mfma_f32_16x16x32_bf16 v[12:15], v[216:219], v[152:155], v[12:15]
	s_waitcnt lgkmcnt(12)
	v_mfma_f32_16x16x32_bf16 v[24:27], v[176:179], v[156:159], v[24:27]
	s_waitcnt vmcnt(13)
	ds_write_b128 v213, v[88:91] offset:18432
	global_load_dwordx4 v[80:83], v[106:107], off offset:768
	v_mfma_f32_16x16x32_bf16 v[32:35], v[180:183], v[156:159], v[32:35]
	v_mfma_f32_16x16x32_bf16 v[8:11], v[184:187], v[156:159], v[8:11]
	v_mfma_f32_16x16x32_bf16 v[16:19], v[216:219], v[156:159], v[16:19]
	s_waitcnt lgkmcnt(10)
	v_mfma_f32_16x16x32_bf16 v[52:55], v[220:223], v[160:163], v[52:55]
	s_waitcnt lgkmcnt(8)
	v_mfma_f32_16x16x32_bf16 v[60:63], v[224:227], v[160:163], v[60:63]
	s_waitcnt lgkmcnt(7)
	v_mfma_f32_16x16x32_bf16 v[56:59], v[220:223], v[164:167], v[56:59]
	s_waitcnt vmcnt(13)
	ds_write_b128 v213, v[92:95] offset:23040
	global_load_dwordx4 v[84:87], v[188:189], off offset:768
	v_mfma_f32_16x16x32_bf16 v[64:67], v[224:227], v[164:167], v[64:67]
	s_waitcnt lgkmcnt(6)
	v_mfma_f32_16x16x32_bf16 v[36:39], v[228:231], v[160:163], v[36:39]
	s_waitcnt vmcnt(13)
	ds_write_b128 v213, v[96:99] offset:27648
	global_load_dwordx4 v[88:91], v[104:105], off offset:768
	v_mfma_f32_16x16x32_bf16 v[40:43], v[228:231], v[164:167], v[40:43]
	s_waitcnt lgkmcnt(6)
	v_mfma_f32_16x16x32_bf16 v[20:23], v[220:223], v[168:171], v[20:23]
	s_waitcnt vmcnt(13)
	ds_write_b128 v213, v[100:103] offset:32256
	global_load_dwordx4 v[92:95], v[214:215], off offset:768
	v_mfma_f32_16x16x32_bf16 v[28:31], v[224:227], v[168:171], v[28:31]
	v_mfma_f32_16x16x32_bf16 v[4:7], v[228:231], v[168:171], v[4:7]
	global_load_dwordx4 v[96:99], v[236:237], off offset:768
	s_waitcnt lgkmcnt(6)
	v_mfma_f32_16x16x32_bf16 v[44:47], v[232:235], v[160:163], v[44:47]
	v_mfma_f32_16x16x32_bf16 v[48:51], v[232:235], v[164:167], v[48:51]
	global_load_dwordx4 v[100:103], v[238:239], off offset:768
	v_mfma_f32_16x16x32_bf16 v[12:15], v[232:235], v[168:171], v[12:15]
	s_waitcnt lgkmcnt(5)
	v_mfma_f32_16x16x32_bf16 v[24:27], v[220:223], v[172:175], v[24:27]
	v_mfma_f32_16x16x32_bf16 v[32:35], v[224:227], v[172:175], v[32:35]
	v_mfma_f32_16x16x32_bf16 v[8:11], v[228:231], v[172:175], v[8:11]
	v_mfma_f32_16x16x32_bf16 v[16:19], v[232:235], v[172:175], v[16:19]
	s_setprio 0
	s_waitcnt lgkmcnt(0)
	s_barrier
	ds_read_b128 v[144:147], v241
	ds_read_b128 v[176:179], v242 offset:18432
	ds_read_b128 v[180:183], v242 offset:20736
	ds_read_b128 v[148:151], v241 offset:2304
	ds_read_b128 v[184:187], v242 offset:23040
	ds_read_b128 v[152:155], v241 offset:4608
	ds_read_b128 v[216:219], v242 offset:25344
	ds_read_b128 v[156:159], v241 offset:6912
	s_setprio 1
	s_waitcnt lgkmcnt(6)
	v_mfma_f32_16x16x32_bf16 v[52:55], v[176:179], v[144:147], v[52:55]
	s_waitcnt vmcnt(15)
	ds_write_b128 v240, v[108:111]
	s_waitcnt lgkmcnt(6)
	v_mfma_f32_16x16x32_bf16 v[60:63], v[180:183], v[144:147], v[60:63]
	ds_read_b128 v[160:163], v241 offset:64
	s_waitcnt lgkmcnt(6)
	v_mfma_f32_16x16x32_bf16 v[56:59], v[176:179], v[148:151], v[56:59]
	ds_read_b128 v[220:223], v242 offset:18496
	s_waitcnt vmcnt(14)
	ds_write_b128 v240, v[112:115] offset:4608
	v_mfma_f32_16x16x32_bf16 v[64:67], v[180:183], v[148:151], v[64:67]
	ds_read_b128 v[224:227], v242 offset:20800
	s_waitcnt lgkmcnt(8)
	v_mfma_f32_16x16x32_bf16 v[36:39], v[184:187], v[144:147], v[36:39]
	ds_read_b128 v[164:167], v241 offset:2368
	s_waitcnt vmcnt(13)
	ds_write_b128 v240, v[116:119] offset:9216
	global_load_dwordx4 v[108:111], v[72:73], off offset:896
	v_mfma_f32_16x16x32_bf16 v[40:43], v[184:187], v[148:151], v[40:43]
	ds_read_b128 v[228:231], v242 offset:23104
	s_waitcnt lgkmcnt(10)
	v_mfma_f32_16x16x32_bf16 v[20:23], v[176:179], v[152:155], v[20:23]
	ds_read_b128 v[168:171], v241 offset:4672
	v_mfma_f32_16x16x32_bf16 v[28:31], v[180:183], v[152:155], v[28:31]
	ds_read_b128 v[232:235], v242 offset:25408
	v_mfma_f32_16x16x32_bf16 v[4:7], v[184:187], v[152:155], v[4:7]
	ds_read_b128 v[172:175], v241 offset:6976
	s_waitcnt lgkmcnt(12)
	v_mfma_f32_16x16x32_bf16 v[44:47], v[216:219], v[144:147], v[44:47]
	v_mfma_f32_16x16x32_bf16 v[48:51], v[216:219], v[148:151], v[48:51]
	s_waitcnt vmcnt(13)
	ds_write_b128 v240, v[120:123] offset:13824
	global_load_dwordx4 v[112:115], v[74:75], off offset:896
	v_mfma_f32_16x16x32_bf16 v[12:15], v[216:219], v[152:155], v[12:15]
	s_waitcnt lgkmcnt(12)
	v_mfma_f32_16x16x32_bf16 v[24:27], v[176:179], v[156:159], v[24:27]
	s_waitcnt vmcnt(13)
	ds_write_b128 v240, v[124:127] offset:18432
	global_load_dwordx4 v[116:119], v[106:107], off offset:896
	v_mfma_f32_16x16x32_bf16 v[32:35], v[180:183], v[156:159], v[32:35]
	v_mfma_f32_16x16x32_bf16 v[8:11], v[184:187], v[156:159], v[8:11]
	v_mfma_f32_16x16x32_bf16 v[16:19], v[216:219], v[156:159], v[16:19]
	s_waitcnt lgkmcnt(10)
	v_mfma_f32_16x16x32_bf16 v[52:55], v[220:223], v[160:163], v[52:55]
	s_waitcnt lgkmcnt(8)
	v_mfma_f32_16x16x32_bf16 v[60:63], v[224:227], v[160:163], v[60:63]
	s_waitcnt lgkmcnt(7)
	v_mfma_f32_16x16x32_bf16 v[56:59], v[220:223], v[164:167], v[56:59]
	s_waitcnt vmcnt(13)
	ds_write_b128 v240, v[128:131] offset:23040
	global_load_dwordx4 v[120:123], v[188:189], off offset:896
	v_mfma_f32_16x16x32_bf16 v[64:67], v[224:227], v[164:167], v[64:67]
	s_waitcnt lgkmcnt(6)
	v_mfma_f32_16x16x32_bf16 v[36:39], v[228:231], v[160:163], v[36:39]
	s_waitcnt vmcnt(13)
	ds_write_b128 v240, v[136:139] offset:27648
	global_load_dwordx4 v[124:127], v[104:105], off offset:896
	v_mfma_f32_16x16x32_bf16 v[40:43], v[228:231], v[164:167], v[40:43]
	s_waitcnt lgkmcnt(6)
	v_mfma_f32_16x16x32_bf16 v[20:23], v[220:223], v[168:171], v[20:23]
	s_waitcnt vmcnt(13)
	ds_write_b128 v240, v[140:143] offset:32256
	global_load_dwordx4 v[128:131], v[214:215], off offset:896
	v_mfma_f32_16x16x32_bf16 v[28:31], v[224:227], v[168:171], v[28:31]
	v_mfma_f32_16x16x32_bf16 v[4:7], v[228:231], v[168:171], v[4:7]
	global_load_dwordx4 v[136:139], v[236:237], off offset:896
	s_waitcnt lgkmcnt(6)
	v_mfma_f32_16x16x32_bf16 v[44:47], v[232:235], v[160:163], v[44:47]
	v_mfma_f32_16x16x32_bf16 v[48:51], v[232:235], v[164:167], v[48:51]
	global_load_dwordx4 v[140:143], v[238:239], off offset:896
	v_mfma_f32_16x16x32_bf16 v[12:15], v[232:235], v[168:171], v[12:15]
	s_waitcnt lgkmcnt(5)
	v_mfma_f32_16x16x32_bf16 v[24:27], v[220:223], v[172:175], v[24:27]
	v_mfma_f32_16x16x32_bf16 v[32:35], v[224:227], v[172:175], v[32:35]
	v_mfma_f32_16x16x32_bf16 v[8:11], v[228:231], v[172:175], v[8:11]
	v_mfma_f32_16x16x32_bf16 v[16:19], v[232:235], v[172:175], v[16:19]
	s_setprio 0
	s_waitcnt lgkmcnt(0)
	s_barrier
	ds_read_b128 v[144:147], v241 offset:36864
	ds_read_b128 v[176:179], v242 offset:55296
	ds_read_b128 v[180:183], v242 offset:57600
	ds_read_b128 v[148:151], v241 offset:39168
	ds_read_b128 v[184:187], v242 offset:59904
	ds_read_b128 v[152:155], v241 offset:41472
	ds_read_b128 v[216:219], v242 offset:62208
	ds_read_b128 v[156:159], v241 offset:43776
	s_setprio 1
	s_waitcnt lgkmcnt(6)
	v_mfma_f32_16x16x32_bf16 v[52:55], v[176:179], v[144:147], v[52:55]
	s_waitcnt vmcnt(15)
	ds_write_b128 v213, v[68:71]
	s_waitcnt lgkmcnt(6)
	v_mfma_f32_16x16x32_bf16 v[60:63], v[180:183], v[144:147], v[60:63]
	ds_read_b128 v[160:163], v241 offset:36928
	s_waitcnt lgkmcnt(6)
	v_mfma_f32_16x16x32_bf16 v[56:59], v[176:179], v[148:151], v[56:59]
	ds_read_b128 v[220:223], v242 offset:55360
	s_waitcnt vmcnt(14)
	ds_write_b128 v213, v[76:79] offset:4608
	v_mfma_f32_16x16x32_bf16 v[64:67], v[180:183], v[148:151], v[64:67]
	ds_read_b128 v[224:227], v242 offset:57664
	s_waitcnt lgkmcnt(8)
	v_mfma_f32_16x16x32_bf16 v[36:39], v[184:187], v[144:147], v[36:39]
	ds_read_b128 v[164:167], v241 offset:39232
	s_waitcnt vmcnt(13)
	ds_write_b128 v213, v[80:83] offset:9216
	global_load_dwordx4 v[68:71], v[72:73], off offset:1024
	v_mfma_f32_16x16x32_bf16 v[40:43], v[184:187], v[148:151], v[40:43]
	ds_read_b128 v[228:231], v242 offset:59968
	s_waitcnt lgkmcnt(10)
	v_mfma_f32_16x16x32_bf16 v[20:23], v[176:179], v[152:155], v[20:23]
	ds_read_b128 v[168:171], v241 offset:41536
	v_mfma_f32_16x16x32_bf16 v[28:31], v[180:183], v[152:155], v[28:31]
	ds_read_b128 v[232:235], v242 offset:62272
	v_mfma_f32_16x16x32_bf16 v[4:7], v[184:187], v[152:155], v[4:7]
	ds_read_b128 v[172:175], v241 offset:43840
	s_waitcnt lgkmcnt(12)
	v_mfma_f32_16x16x32_bf16 v[44:47], v[216:219], v[144:147], v[44:47]
	v_mfma_f32_16x16x32_bf16 v[48:51], v[216:219], v[148:151], v[48:51]
	s_waitcnt vmcnt(13)
	ds_write_b128 v213, v[84:87] offset:13824
	global_load_dwordx4 v[76:79], v[74:75], off offset:1024
	v_mfma_f32_16x16x32_bf16 v[12:15], v[216:219], v[152:155], v[12:15]
	s_waitcnt lgkmcnt(12)
	v_mfma_f32_16x16x32_bf16 v[24:27], v[176:179], v[156:159], v[24:27]
	s_waitcnt vmcnt(13)
	ds_write_b128 v213, v[88:91] offset:18432
	global_load_dwordx4 v[80:83], v[106:107], off offset:1024
	v_mfma_f32_16x16x32_bf16 v[32:35], v[180:183], v[156:159], v[32:35]
	v_mfma_f32_16x16x32_bf16 v[8:11], v[184:187], v[156:159], v[8:11]
	v_mfma_f32_16x16x32_bf16 v[16:19], v[216:219], v[156:159], v[16:19]
	s_waitcnt lgkmcnt(10)
	v_mfma_f32_16x16x32_bf16 v[52:55], v[220:223], v[160:163], v[52:55]
	s_waitcnt lgkmcnt(8)
	v_mfma_f32_16x16x32_bf16 v[60:63], v[224:227], v[160:163], v[60:63]
	s_waitcnt lgkmcnt(7)
	v_mfma_f32_16x16x32_bf16 v[56:59], v[220:223], v[164:167], v[56:59]
	s_waitcnt vmcnt(13)
	ds_write_b128 v213, v[92:95] offset:23040
	global_load_dwordx4 v[84:87], v[188:189], off offset:1024
	v_mfma_f32_16x16x32_bf16 v[64:67], v[224:227], v[164:167], v[64:67]
	s_waitcnt lgkmcnt(6)
	v_mfma_f32_16x16x32_bf16 v[36:39], v[228:231], v[160:163], v[36:39]
	s_waitcnt vmcnt(13)
	ds_write_b128 v213, v[96:99] offset:27648
	global_load_dwordx4 v[88:91], v[104:105], off offset:1024
	v_mfma_f32_16x16x32_bf16 v[40:43], v[228:231], v[164:167], v[40:43]
	s_waitcnt lgkmcnt(6)
	v_mfma_f32_16x16x32_bf16 v[20:23], v[220:223], v[168:171], v[20:23]
	s_waitcnt vmcnt(13)
	ds_write_b128 v213, v[100:103] offset:32256
	global_load_dwordx4 v[92:95], v[214:215], off offset:1024
	v_mfma_f32_16x16x32_bf16 v[28:31], v[224:227], v[168:171], v[28:31]
	v_mfma_f32_16x16x32_bf16 v[4:7], v[228:231], v[168:171], v[4:7]
	global_load_dwordx4 v[96:99], v[236:237], off offset:1024
	s_waitcnt lgkmcnt(6)
	v_mfma_f32_16x16x32_bf16 v[44:47], v[232:235], v[160:163], v[44:47]
	v_mfma_f32_16x16x32_bf16 v[48:51], v[232:235], v[164:167], v[48:51]
	global_load_dwordx4 v[100:103], v[238:239], off offset:1024
	v_mfma_f32_16x16x32_bf16 v[12:15], v[232:235], v[168:171], v[12:15]
	s_waitcnt lgkmcnt(5)
	v_mfma_f32_16x16x32_bf16 v[24:27], v[220:223], v[172:175], v[24:27]
	v_mfma_f32_16x16x32_bf16 v[32:35], v[224:227], v[172:175], v[32:35]
	v_mfma_f32_16x16x32_bf16 v[8:11], v[228:231], v[172:175], v[8:11]
	v_mfma_f32_16x16x32_bf16 v[16:19], v[232:235], v[172:175], v[16:19]
	s_setprio 0
	s_waitcnt lgkmcnt(0)
	s_barrier
	ds_read_b128 v[144:147], v241
	ds_read_b128 v[176:179], v242 offset:18432
	ds_read_b128 v[180:183], v242 offset:20736
	ds_read_b128 v[148:151], v241 offset:2304
	ds_read_b128 v[184:187], v242 offset:23040
	ds_read_b128 v[152:155], v241 offset:4608
	ds_read_b128 v[216:219], v242 offset:25344
	ds_read_b128 v[156:159], v241 offset:6912
	s_setprio 1
	s_waitcnt lgkmcnt(6)
	v_mfma_f32_16x16x32_bf16 v[52:55], v[176:179], v[144:147], v[52:55]
	s_waitcnt vmcnt(15)
	ds_write_b128 v240, v[108:111]
	s_waitcnt lgkmcnt(6)
	v_mfma_f32_16x16x32_bf16 v[60:63], v[180:183], v[144:147], v[60:63]
	ds_read_b128 v[160:163], v241 offset:64
	s_waitcnt lgkmcnt(6)
	v_mfma_f32_16x16x32_bf16 v[56:59], v[176:179], v[148:151], v[56:59]
	ds_read_b128 v[220:223], v242 offset:18496
	s_waitcnt vmcnt(14)
	ds_write_b128 v240, v[112:115] offset:4608
	v_mfma_f32_16x16x32_bf16 v[64:67], v[180:183], v[148:151], v[64:67]
	ds_read_b128 v[224:227], v242 offset:20800
	s_waitcnt lgkmcnt(8)
	v_mfma_f32_16x16x32_bf16 v[36:39], v[184:187], v[144:147], v[36:39]
	ds_read_b128 v[164:167], v241 offset:2368
	s_waitcnt vmcnt(13)
	ds_write_b128 v240, v[116:119] offset:9216
	global_load_dwordx4 v[108:111], v[72:73], off offset:1152
	v_mfma_f32_16x16x32_bf16 v[40:43], v[184:187], v[148:151], v[40:43]
	ds_read_b128 v[228:231], v242 offset:23104
	s_waitcnt lgkmcnt(10)
	v_mfma_f32_16x16x32_bf16 v[20:23], v[176:179], v[152:155], v[20:23]
	ds_read_b128 v[168:171], v241 offset:4672
	v_mfma_f32_16x16x32_bf16 v[28:31], v[180:183], v[152:155], v[28:31]
	ds_read_b128 v[232:235], v242 offset:25408
	v_mfma_f32_16x16x32_bf16 v[4:7], v[184:187], v[152:155], v[4:7]
	ds_read_b128 v[172:175], v241 offset:6976
	s_waitcnt lgkmcnt(12)
	v_mfma_f32_16x16x32_bf16 v[44:47], v[216:219], v[144:147], v[44:47]
	v_mfma_f32_16x16x32_bf16 v[48:51], v[216:219], v[148:151], v[48:51]
	s_waitcnt vmcnt(13)
	ds_write_b128 v240, v[120:123] offset:13824
	global_load_dwordx4 v[112:115], v[74:75], off offset:1152
	v_mfma_f32_16x16x32_bf16 v[12:15], v[216:219], v[152:155], v[12:15]
	s_waitcnt lgkmcnt(12)
	v_mfma_f32_16x16x32_bf16 v[24:27], v[176:179], v[156:159], v[24:27]
	s_waitcnt vmcnt(13)
	ds_write_b128 v240, v[124:127] offset:18432
	global_load_dwordx4 v[116:119], v[106:107], off offset:1152
	v_mfma_f32_16x16x32_bf16 v[32:35], v[180:183], v[156:159], v[32:35]
	v_mfma_f32_16x16x32_bf16 v[8:11], v[184:187], v[156:159], v[8:11]
	v_mfma_f32_16x16x32_bf16 v[16:19], v[216:219], v[156:159], v[16:19]
	s_waitcnt lgkmcnt(10)
	v_mfma_f32_16x16x32_bf16 v[52:55], v[220:223], v[160:163], v[52:55]
	s_waitcnt lgkmcnt(8)
	v_mfma_f32_16x16x32_bf16 v[60:63], v[224:227], v[160:163], v[60:63]
	s_waitcnt lgkmcnt(7)
	v_mfma_f32_16x16x32_bf16 v[56:59], v[220:223], v[164:167], v[56:59]
	s_waitcnt vmcnt(13)
	ds_write_b128 v240, v[128:131] offset:23040
	global_load_dwordx4 v[120:123], v[188:189], off offset:1152
	v_mfma_f32_16x16x32_bf16 v[64:67], v[224:227], v[164:167], v[64:67]
	s_waitcnt lgkmcnt(6)
	v_mfma_f32_16x16x32_bf16 v[36:39], v[228:231], v[160:163], v[36:39]
	s_waitcnt vmcnt(13)
	ds_write_b128 v240, v[136:139] offset:27648
	global_load_dwordx4 v[124:127], v[104:105], off offset:1152
	v_mfma_f32_16x16x32_bf16 v[40:43], v[228:231], v[164:167], v[40:43]
	s_waitcnt lgkmcnt(6)
	v_mfma_f32_16x16x32_bf16 v[20:23], v[220:223], v[168:171], v[20:23]
	s_waitcnt vmcnt(13)
	ds_write_b128 v240, v[140:143] offset:32256
	global_load_dwordx4 v[128:131], v[214:215], off offset:1152
	v_mfma_f32_16x16x32_bf16 v[28:31], v[224:227], v[168:171], v[28:31]
	v_mfma_f32_16x16x32_bf16 v[4:7], v[228:231], v[168:171], v[4:7]
	global_load_dwordx4 v[136:139], v[236:237], off offset:1152
	s_waitcnt lgkmcnt(6)
	v_mfma_f32_16x16x32_bf16 v[44:47], v[232:235], v[160:163], v[44:47]
	v_mfma_f32_16x16x32_bf16 v[48:51], v[232:235], v[164:167], v[48:51]
	global_load_dwordx4 v[140:143], v[238:239], off offset:1152
	v_mfma_f32_16x16x32_bf16 v[12:15], v[232:235], v[168:171], v[12:15]
	s_waitcnt lgkmcnt(5)
	v_mfma_f32_16x16x32_bf16 v[24:27], v[220:223], v[172:175], v[24:27]
	v_mfma_f32_16x16x32_bf16 v[32:35], v[224:227], v[172:175], v[32:35]
	v_mfma_f32_16x16x32_bf16 v[8:11], v[228:231], v[172:175], v[8:11]
	v_mfma_f32_16x16x32_bf16 v[16:19], v[232:235], v[172:175], v[16:19]
	s_setprio 0
	s_waitcnt lgkmcnt(0)
	s_barrier
	ds_read_b128 v[144:147], v241 offset:36864
	ds_read_b128 v[176:179], v242 offset:55296
	ds_read_b128 v[180:183], v242 offset:57600
	ds_read_b128 v[148:151], v241 offset:39168
	ds_read_b128 v[184:187], v242 offset:59904
	ds_read_b128 v[152:155], v241 offset:41472
	ds_read_b128 v[216:219], v242 offset:62208
	ds_read_b128 v[156:159], v241 offset:43776
	s_setprio 1
	s_waitcnt lgkmcnt(6)
	v_mfma_f32_16x16x32_bf16 v[52:55], v[176:179], v[144:147], v[52:55]
	s_waitcnt vmcnt(15)
	ds_write_b128 v213, v[68:71]
	s_waitcnt lgkmcnt(6)
	v_mfma_f32_16x16x32_bf16 v[60:63], v[180:183], v[144:147], v[60:63]
	ds_read_b128 v[160:163], v241 offset:36928
	s_waitcnt lgkmcnt(6)
	v_mfma_f32_16x16x32_bf16 v[56:59], v[176:179], v[148:151], v[56:59]
	ds_read_b128 v[220:223], v242 offset:55360
	s_waitcnt vmcnt(14)
	ds_write_b128 v213, v[76:79] offset:4608
	v_mfma_f32_16x16x32_bf16 v[64:67], v[180:183], v[148:151], v[64:67]
	ds_read_b128 v[224:227], v242 offset:57664
	s_waitcnt lgkmcnt(8)
	v_mfma_f32_16x16x32_bf16 v[36:39], v[184:187], v[144:147], v[36:39]
	ds_read_b128 v[164:167], v241 offset:39232
	s_waitcnt vmcnt(13)
	ds_write_b128 v213, v[80:83] offset:9216
	global_load_dwordx4 v[68:71], v[72:73], off offset:1280
	v_mfma_f32_16x16x32_bf16 v[40:43], v[184:187], v[148:151], v[40:43]
	ds_read_b128 v[228:231], v242 offset:59968
	s_waitcnt lgkmcnt(10)
	v_mfma_f32_16x16x32_bf16 v[20:23], v[176:179], v[152:155], v[20:23]
	ds_read_b128 v[168:171], v241 offset:41536
	v_mfma_f32_16x16x32_bf16 v[28:31], v[180:183], v[152:155], v[28:31]
	ds_read_b128 v[232:235], v242 offset:62272
	v_mfma_f32_16x16x32_bf16 v[4:7], v[184:187], v[152:155], v[4:7]
	ds_read_b128 v[172:175], v241 offset:43840
	s_waitcnt lgkmcnt(12)
	v_mfma_f32_16x16x32_bf16 v[44:47], v[216:219], v[144:147], v[44:47]
	v_mfma_f32_16x16x32_bf16 v[48:51], v[216:219], v[148:151], v[48:51]
	s_waitcnt vmcnt(13)
	ds_write_b128 v213, v[84:87] offset:13824
	global_load_dwordx4 v[76:79], v[74:75], off offset:1280
	v_mfma_f32_16x16x32_bf16 v[12:15], v[216:219], v[152:155], v[12:15]
	s_waitcnt lgkmcnt(12)
	v_mfma_f32_16x16x32_bf16 v[24:27], v[176:179], v[156:159], v[24:27]
	s_waitcnt vmcnt(13)
	ds_write_b128 v213, v[88:91] offset:18432
	global_load_dwordx4 v[80:83], v[106:107], off offset:1280
	v_mfma_f32_16x16x32_bf16 v[32:35], v[180:183], v[156:159], v[32:35]
	v_mfma_f32_16x16x32_bf16 v[8:11], v[184:187], v[156:159], v[8:11]
	v_mfma_f32_16x16x32_bf16 v[16:19], v[216:219], v[156:159], v[16:19]
	s_waitcnt lgkmcnt(10)
	v_mfma_f32_16x16x32_bf16 v[52:55], v[220:223], v[160:163], v[52:55]
	s_waitcnt lgkmcnt(8)
	v_mfma_f32_16x16x32_bf16 v[60:63], v[224:227], v[160:163], v[60:63]
	s_waitcnt lgkmcnt(7)
	v_mfma_f32_16x16x32_bf16 v[56:59], v[220:223], v[164:167], v[56:59]
	s_waitcnt vmcnt(13)
	ds_write_b128 v213, v[92:95] offset:23040
	global_load_dwordx4 v[84:87], v[188:189], off offset:1280
	v_mfma_f32_16x16x32_bf16 v[64:67], v[224:227], v[164:167], v[64:67]
	s_waitcnt lgkmcnt(6)
	v_mfma_f32_16x16x32_bf16 v[36:39], v[228:231], v[160:163], v[36:39]
	s_waitcnt vmcnt(13)
	ds_write_b128 v213, v[96:99] offset:27648
	global_load_dwordx4 v[88:91], v[104:105], off offset:1280
	v_mfma_f32_16x16x32_bf16 v[40:43], v[228:231], v[164:167], v[40:43]
	s_waitcnt lgkmcnt(6)
	v_mfma_f32_16x16x32_bf16 v[20:23], v[220:223], v[168:171], v[20:23]
	s_waitcnt vmcnt(13)
	ds_write_b128 v213, v[100:103] offset:32256
	global_load_dwordx4 v[92:95], v[214:215], off offset:1280
	v_mfma_f32_16x16x32_bf16 v[28:31], v[224:227], v[168:171], v[28:31]
	v_mfma_f32_16x16x32_bf16 v[4:7], v[228:231], v[168:171], v[4:7]
	global_load_dwordx4 v[96:99], v[236:237], off offset:1280
	s_waitcnt lgkmcnt(6)
	v_mfma_f32_16x16x32_bf16 v[44:47], v[232:235], v[160:163], v[44:47]
	v_mfma_f32_16x16x32_bf16 v[48:51], v[232:235], v[164:167], v[48:51]
	global_load_dwordx4 v[100:103], v[238:239], off offset:1280
	v_mfma_f32_16x16x32_bf16 v[12:15], v[232:235], v[168:171], v[12:15]
	s_waitcnt lgkmcnt(5)
	v_mfma_f32_16x16x32_bf16 v[24:27], v[220:223], v[172:175], v[24:27]
	v_mfma_f32_16x16x32_bf16 v[32:35], v[224:227], v[172:175], v[32:35]
	v_mfma_f32_16x16x32_bf16 v[8:11], v[228:231], v[172:175], v[8:11]
	v_mfma_f32_16x16x32_bf16 v[16:19], v[232:235], v[172:175], v[16:19]
	s_setprio 0
	s_waitcnt lgkmcnt(0)
	s_barrier
	ds_read_b128 v[144:147], v241
	ds_read_b128 v[176:179], v242 offset:18432
	ds_read_b128 v[180:183], v242 offset:20736
	ds_read_b128 v[148:151], v241 offset:2304
	ds_read_b128 v[184:187], v242 offset:23040
	ds_read_b128 v[152:155], v241 offset:4608
	ds_read_b128 v[216:219], v242 offset:25344
	ds_read_b128 v[156:159], v241 offset:6912
	s_setprio 1
	s_waitcnt lgkmcnt(6)
	v_mfma_f32_16x16x32_bf16 v[52:55], v[176:179], v[144:147], v[52:55]
	s_waitcnt vmcnt(15)
	ds_write_b128 v240, v[108:111]
	s_waitcnt lgkmcnt(6)
	v_mfma_f32_16x16x32_bf16 v[60:63], v[180:183], v[144:147], v[60:63]
	ds_read_b128 v[160:163], v241 offset:64
	s_waitcnt lgkmcnt(6)
	v_mfma_f32_16x16x32_bf16 v[56:59], v[176:179], v[148:151], v[56:59]
	ds_read_b128 v[220:223], v242 offset:18496
	s_waitcnt vmcnt(14)
	ds_write_b128 v240, v[112:115] offset:4608
	v_mfma_f32_16x16x32_bf16 v[64:67], v[180:183], v[148:151], v[64:67]
	ds_read_b128 v[224:227], v242 offset:20800
	s_waitcnt lgkmcnt(8)
	v_mfma_f32_16x16x32_bf16 v[36:39], v[184:187], v[144:147], v[36:39]
	ds_read_b128 v[164:167], v241 offset:2368
	s_waitcnt vmcnt(13)
	ds_write_b128 v240, v[116:119] offset:9216
	global_load_dwordx4 v[108:111], v[72:73], off offset:1408
	v_mfma_f32_16x16x32_bf16 v[40:43], v[184:187], v[148:151], v[40:43]
	ds_read_b128 v[228:231], v242 offset:23104
	s_waitcnt lgkmcnt(10)
	v_mfma_f32_16x16x32_bf16 v[20:23], v[176:179], v[152:155], v[20:23]
	ds_read_b128 v[168:171], v241 offset:4672
	v_mfma_f32_16x16x32_bf16 v[28:31], v[180:183], v[152:155], v[28:31]
	ds_read_b128 v[232:235], v242 offset:25408
	v_mfma_f32_16x16x32_bf16 v[4:7], v[184:187], v[152:155], v[4:7]
	ds_read_b128 v[172:175], v241 offset:6976
	s_waitcnt lgkmcnt(12)
	v_mfma_f32_16x16x32_bf16 v[44:47], v[216:219], v[144:147], v[44:47]
	v_mfma_f32_16x16x32_bf16 v[48:51], v[216:219], v[148:151], v[48:51]
	s_waitcnt vmcnt(13)
	ds_write_b128 v240, v[120:123] offset:13824
	global_load_dwordx4 v[112:115], v[74:75], off offset:1408
	v_mfma_f32_16x16x32_bf16 v[12:15], v[216:219], v[152:155], v[12:15]
	s_waitcnt lgkmcnt(12)
	v_mfma_f32_16x16x32_bf16 v[24:27], v[176:179], v[156:159], v[24:27]
	s_waitcnt vmcnt(13)
	ds_write_b128 v240, v[124:127] offset:18432
	global_load_dwordx4 v[116:119], v[106:107], off offset:1408
	v_mfma_f32_16x16x32_bf16 v[32:35], v[180:183], v[156:159], v[32:35]
	v_mfma_f32_16x16x32_bf16 v[8:11], v[184:187], v[156:159], v[8:11]
	v_mfma_f32_16x16x32_bf16 v[16:19], v[216:219], v[156:159], v[16:19]
	s_waitcnt lgkmcnt(10)
	v_mfma_f32_16x16x32_bf16 v[52:55], v[220:223], v[160:163], v[52:55]
	s_waitcnt lgkmcnt(8)
	v_mfma_f32_16x16x32_bf16 v[60:63], v[224:227], v[160:163], v[60:63]
	s_waitcnt lgkmcnt(7)
	v_mfma_f32_16x16x32_bf16 v[56:59], v[220:223], v[164:167], v[56:59]
	s_waitcnt vmcnt(13)
	ds_write_b128 v240, v[128:131] offset:23040
	global_load_dwordx4 v[120:123], v[188:189], off offset:1408
	v_mfma_f32_16x16x32_bf16 v[64:67], v[224:227], v[164:167], v[64:67]
	s_waitcnt lgkmcnt(6)
	v_mfma_f32_16x16x32_bf16 v[36:39], v[228:231], v[160:163], v[36:39]
	s_waitcnt vmcnt(13)
	ds_write_b128 v240, v[136:139] offset:27648
	global_load_dwordx4 v[124:127], v[104:105], off offset:1408
	v_mfma_f32_16x16x32_bf16 v[40:43], v[228:231], v[164:167], v[40:43]
	s_waitcnt lgkmcnt(6)
	v_mfma_f32_16x16x32_bf16 v[20:23], v[220:223], v[168:171], v[20:23]
	s_waitcnt vmcnt(13)
	ds_write_b128 v240, v[140:143] offset:32256
	global_load_dwordx4 v[128:131], v[214:215], off offset:1408
	v_mfma_f32_16x16x32_bf16 v[28:31], v[224:227], v[168:171], v[28:31]
	v_mfma_f32_16x16x32_bf16 v[4:7], v[228:231], v[168:171], v[4:7]
	global_load_dwordx4 v[136:139], v[236:237], off offset:1408
	s_waitcnt lgkmcnt(6)
	v_mfma_f32_16x16x32_bf16 v[44:47], v[232:235], v[160:163], v[44:47]
	v_mfma_f32_16x16x32_bf16 v[48:51], v[232:235], v[164:167], v[48:51]
	global_load_dwordx4 v[140:143], v[238:239], off offset:1408
	v_mfma_f32_16x16x32_bf16 v[12:15], v[232:235], v[168:171], v[12:15]
	s_waitcnt lgkmcnt(5)
	v_mfma_f32_16x16x32_bf16 v[24:27], v[220:223], v[172:175], v[24:27]
	v_mfma_f32_16x16x32_bf16 v[32:35], v[224:227], v[172:175], v[32:35]
	v_mfma_f32_16x16x32_bf16 v[8:11], v[228:231], v[172:175], v[8:11]
	v_mfma_f32_16x16x32_bf16 v[16:19], v[232:235], v[172:175], v[16:19]
	s_setprio 0
	s_waitcnt lgkmcnt(0)
	s_barrier
	ds_read_b128 v[144:147], v241 offset:36864
	ds_read_b128 v[176:179], v242 offset:55296
	ds_read_b128 v[180:183], v242 offset:57600
	ds_read_b128 v[148:151], v241 offset:39168
	ds_read_b128 v[184:187], v242 offset:59904
	ds_read_b128 v[152:155], v241 offset:41472
	ds_read_b128 v[216:219], v242 offset:62208
	ds_read_b128 v[156:159], v241 offset:43776
	s_setprio 1
	s_waitcnt lgkmcnt(6)
	v_mfma_f32_16x16x32_bf16 v[52:55], v[176:179], v[144:147], v[52:55]
	s_waitcnt vmcnt(15)
	ds_write_b128 v213, v[68:71]
	s_waitcnt lgkmcnt(6)
	v_mfma_f32_16x16x32_bf16 v[60:63], v[180:183], v[144:147], v[60:63]
	ds_read_b128 v[160:163], v241 offset:36928
	s_waitcnt lgkmcnt(6)
	v_mfma_f32_16x16x32_bf16 v[56:59], v[176:179], v[148:151], v[56:59]
	ds_read_b128 v[220:223], v242 offset:55360
	s_waitcnt vmcnt(14)
	ds_write_b128 v213, v[76:79] offset:4608
	v_mfma_f32_16x16x32_bf16 v[64:67], v[180:183], v[148:151], v[64:67]
	ds_read_b128 v[224:227], v242 offset:57664
	s_waitcnt lgkmcnt(8)
	v_mfma_f32_16x16x32_bf16 v[36:39], v[184:187], v[144:147], v[36:39]
	ds_read_b128 v[164:167], v241 offset:39232
	s_waitcnt vmcnt(13)
	ds_write_b128 v213, v[80:83] offset:9216
	global_load_dwordx4 v[68:71], v[72:73], off offset:1536
	v_mfma_f32_16x16x32_bf16 v[40:43], v[184:187], v[148:151], v[40:43]
	ds_read_b128 v[228:231], v242 offset:59968
	s_waitcnt lgkmcnt(10)
	v_mfma_f32_16x16x32_bf16 v[20:23], v[176:179], v[152:155], v[20:23]
	ds_read_b128 v[168:171], v241 offset:41536
	v_mfma_f32_16x16x32_bf16 v[28:31], v[180:183], v[152:155], v[28:31]
	ds_read_b128 v[232:235], v242 offset:62272
	v_mfma_f32_16x16x32_bf16 v[4:7], v[184:187], v[152:155], v[4:7]
	ds_read_b128 v[172:175], v241 offset:43840
	s_waitcnt lgkmcnt(12)
	v_mfma_f32_16x16x32_bf16 v[44:47], v[216:219], v[144:147], v[44:47]
	v_mfma_f32_16x16x32_bf16 v[48:51], v[216:219], v[148:151], v[48:51]
	s_waitcnt vmcnt(13)
	ds_write_b128 v213, v[84:87] offset:13824
	global_load_dwordx4 v[76:79], v[74:75], off offset:1536
	v_mfma_f32_16x16x32_bf16 v[12:15], v[216:219], v[152:155], v[12:15]
	s_waitcnt lgkmcnt(12)
	v_mfma_f32_16x16x32_bf16 v[24:27], v[176:179], v[156:159], v[24:27]
	s_waitcnt vmcnt(13)
	ds_write_b128 v213, v[88:91] offset:18432
	global_load_dwordx4 v[80:83], v[106:107], off offset:1536
	v_mfma_f32_16x16x32_bf16 v[32:35], v[180:183], v[156:159], v[32:35]
	v_mfma_f32_16x16x32_bf16 v[8:11], v[184:187], v[156:159], v[8:11]
	v_mfma_f32_16x16x32_bf16 v[16:19], v[216:219], v[156:159], v[16:19]
	s_waitcnt lgkmcnt(10)
	v_mfma_f32_16x16x32_bf16 v[52:55], v[220:223], v[160:163], v[52:55]
	s_waitcnt lgkmcnt(8)
	v_mfma_f32_16x16x32_bf16 v[60:63], v[224:227], v[160:163], v[60:63]
	s_waitcnt lgkmcnt(7)
	v_mfma_f32_16x16x32_bf16 v[56:59], v[220:223], v[164:167], v[56:59]
	s_waitcnt vmcnt(13)
	ds_write_b128 v213, v[92:95] offset:23040
	global_load_dwordx4 v[84:87], v[188:189], off offset:1536
	v_mfma_f32_16x16x32_bf16 v[64:67], v[224:227], v[164:167], v[64:67]
	s_waitcnt lgkmcnt(6)
	v_mfma_f32_16x16x32_bf16 v[36:39], v[228:231], v[160:163], v[36:39]
	s_waitcnt vmcnt(13)
	ds_write_b128 v213, v[96:99] offset:27648
	global_load_dwordx4 v[88:91], v[104:105], off offset:1536
	v_mfma_f32_16x16x32_bf16 v[40:43], v[228:231], v[164:167], v[40:43]
	s_waitcnt lgkmcnt(6)
	v_mfma_f32_16x16x32_bf16 v[20:23], v[220:223], v[168:171], v[20:23]
	s_waitcnt vmcnt(13)
	ds_write_b128 v213, v[100:103] offset:32256
	global_load_dwordx4 v[92:95], v[214:215], off offset:1536
	v_mfma_f32_16x16x32_bf16 v[28:31], v[224:227], v[168:171], v[28:31]
	v_mfma_f32_16x16x32_bf16 v[4:7], v[228:231], v[168:171], v[4:7]
	global_load_dwordx4 v[96:99], v[236:237], off offset:1536
	s_waitcnt lgkmcnt(6)
	v_mfma_f32_16x16x32_bf16 v[44:47], v[232:235], v[160:163], v[44:47]
	v_mfma_f32_16x16x32_bf16 v[48:51], v[232:235], v[164:167], v[48:51]
	global_load_dwordx4 v[100:103], v[238:239], off offset:1536
	v_mfma_f32_16x16x32_bf16 v[12:15], v[232:235], v[168:171], v[12:15]
	s_waitcnt lgkmcnt(5)
	v_mfma_f32_16x16x32_bf16 v[24:27], v[220:223], v[172:175], v[24:27]
	v_mfma_f32_16x16x32_bf16 v[32:35], v[224:227], v[172:175], v[32:35]
	v_mfma_f32_16x16x32_bf16 v[8:11], v[228:231], v[172:175], v[8:11]
	v_mfma_f32_16x16x32_bf16 v[16:19], v[232:235], v[172:175], v[16:19]
	s_setprio 0
	s_waitcnt lgkmcnt(0)
	s_barrier
	ds_read_b128 v[144:147], v241
	ds_read_b128 v[176:179], v242 offset:18432
	ds_read_b128 v[180:183], v242 offset:20736
	ds_read_b128 v[148:151], v241 offset:2304
	ds_read_b128 v[184:187], v242 offset:23040
	ds_read_b128 v[152:155], v241 offset:4608
	ds_read_b128 v[216:219], v242 offset:25344
	ds_read_b128 v[156:159], v241 offset:6912
	s_setprio 1
	s_waitcnt lgkmcnt(6)
	v_mfma_f32_16x16x32_bf16 v[52:55], v[176:179], v[144:147], v[52:55]
	s_waitcnt vmcnt(15)
	ds_write_b128 v240, v[108:111]
	s_waitcnt lgkmcnt(6)
	v_mfma_f32_16x16x32_bf16 v[60:63], v[180:183], v[144:147], v[60:63]
	ds_read_b128 v[160:163], v241 offset:64
	s_waitcnt lgkmcnt(6)
	v_mfma_f32_16x16x32_bf16 v[56:59], v[176:179], v[148:151], v[56:59]
	ds_read_b128 v[220:223], v242 offset:18496
	s_waitcnt vmcnt(14)
	ds_write_b128 v240, v[112:115] offset:4608
	v_mfma_f32_16x16x32_bf16 v[64:67], v[180:183], v[148:151], v[64:67]
	ds_read_b128 v[224:227], v242 offset:20800
	s_waitcnt lgkmcnt(8)
	v_mfma_f32_16x16x32_bf16 v[36:39], v[184:187], v[144:147], v[36:39]
	ds_read_b128 v[164:167], v241 offset:2368
	s_waitcnt vmcnt(13)
	ds_write_b128 v240, v[116:119] offset:9216
	global_load_dwordx4 v[108:111], v[72:73], off offset:1664
	v_mfma_f32_16x16x32_bf16 v[40:43], v[184:187], v[148:151], v[40:43]
	ds_read_b128 v[228:231], v242 offset:23104
	s_waitcnt lgkmcnt(10)
	v_mfma_f32_16x16x32_bf16 v[20:23], v[176:179], v[152:155], v[20:23]
	ds_read_b128 v[168:171], v241 offset:4672
	v_mfma_f32_16x16x32_bf16 v[28:31], v[180:183], v[152:155], v[28:31]
	ds_read_b128 v[232:235], v242 offset:25408
	v_mfma_f32_16x16x32_bf16 v[4:7], v[184:187], v[152:155], v[4:7]
	ds_read_b128 v[172:175], v241 offset:6976
	s_waitcnt lgkmcnt(12)
	v_mfma_f32_16x16x32_bf16 v[44:47], v[216:219], v[144:147], v[44:47]
	v_mfma_f32_16x16x32_bf16 v[48:51], v[216:219], v[148:151], v[48:51]
	s_waitcnt vmcnt(13)
	ds_write_b128 v240, v[120:123] offset:13824
	global_load_dwordx4 v[112:115], v[74:75], off offset:1664
	v_mfma_f32_16x16x32_bf16 v[12:15], v[216:219], v[152:155], v[12:15]
	s_waitcnt lgkmcnt(12)
	v_mfma_f32_16x16x32_bf16 v[24:27], v[176:179], v[156:159], v[24:27]
	s_waitcnt vmcnt(13)
	ds_write_b128 v240, v[124:127] offset:18432
	global_load_dwordx4 v[116:119], v[106:107], off offset:1664
	v_mfma_f32_16x16x32_bf16 v[32:35], v[180:183], v[156:159], v[32:35]
	v_mfma_f32_16x16x32_bf16 v[8:11], v[184:187], v[156:159], v[8:11]
	v_mfma_f32_16x16x32_bf16 v[16:19], v[216:219], v[156:159], v[16:19]
	s_waitcnt lgkmcnt(10)
	v_mfma_f32_16x16x32_bf16 v[52:55], v[220:223], v[160:163], v[52:55]
	s_waitcnt lgkmcnt(8)
	v_mfma_f32_16x16x32_bf16 v[60:63], v[224:227], v[160:163], v[60:63]
	s_waitcnt lgkmcnt(7)
	v_mfma_f32_16x16x32_bf16 v[56:59], v[220:223], v[164:167], v[56:59]
	s_waitcnt vmcnt(13)
	ds_write_b128 v240, v[128:131] offset:23040
	global_load_dwordx4 v[120:123], v[188:189], off offset:1664
	v_mfma_f32_16x16x32_bf16 v[64:67], v[224:227], v[164:167], v[64:67]
	s_waitcnt lgkmcnt(6)
	v_mfma_f32_16x16x32_bf16 v[36:39], v[228:231], v[160:163], v[36:39]
	s_waitcnt vmcnt(13)
	ds_write_b128 v240, v[136:139] offset:27648
	global_load_dwordx4 v[124:127], v[104:105], off offset:1664
	v_mfma_f32_16x16x32_bf16 v[40:43], v[228:231], v[164:167], v[40:43]
	s_waitcnt lgkmcnt(6)
	v_mfma_f32_16x16x32_bf16 v[20:23], v[220:223], v[168:171], v[20:23]
	s_waitcnt vmcnt(13)
	ds_write_b128 v240, v[140:143] offset:32256
	global_load_dwordx4 v[128:131], v[214:215], off offset:1664
	v_mfma_f32_16x16x32_bf16 v[28:31], v[224:227], v[168:171], v[28:31]
	v_mfma_f32_16x16x32_bf16 v[4:7], v[228:231], v[168:171], v[4:7]
	global_load_dwordx4 v[136:139], v[236:237], off offset:1664
	s_waitcnt lgkmcnt(6)
	v_mfma_f32_16x16x32_bf16 v[44:47], v[232:235], v[160:163], v[44:47]
	v_mfma_f32_16x16x32_bf16 v[48:51], v[232:235], v[164:167], v[48:51]
	global_load_dwordx4 v[140:143], v[238:239], off offset:1664
	v_mfma_f32_16x16x32_bf16 v[12:15], v[232:235], v[168:171], v[12:15]
	s_waitcnt lgkmcnt(5)
	v_mfma_f32_16x16x32_bf16 v[24:27], v[220:223], v[172:175], v[24:27]
	v_mfma_f32_16x16x32_bf16 v[32:35], v[224:227], v[172:175], v[32:35]
	v_mfma_f32_16x16x32_bf16 v[8:11], v[228:231], v[172:175], v[8:11]
	v_mfma_f32_16x16x32_bf16 v[16:19], v[232:235], v[172:175], v[16:19]
	s_setprio 0
	s_waitcnt lgkmcnt(0)
	s_barrier
	ds_read_b128 v[144:147], v241 offset:36864
	ds_read_b128 v[176:179], v242 offset:55296
	ds_read_b128 v[180:183], v242 offset:57600
	ds_read_b128 v[148:151], v241 offset:39168
	ds_read_b128 v[184:187], v242 offset:59904
	ds_read_b128 v[152:155], v241 offset:41472
	ds_read_b128 v[216:219], v242 offset:62208
	ds_read_b128 v[156:159], v241 offset:43776
	s_setprio 1
	s_waitcnt lgkmcnt(6)
	v_mfma_f32_16x16x32_bf16 v[52:55], v[176:179], v[144:147], v[52:55]
	s_waitcnt vmcnt(15)
	ds_write_b128 v213, v[68:71]
	s_waitcnt lgkmcnt(6)
	v_mfma_f32_16x16x32_bf16 v[60:63], v[180:183], v[144:147], v[60:63]
	ds_read_b128 v[160:163], v241 offset:36928
	s_waitcnt lgkmcnt(6)
	v_mfma_f32_16x16x32_bf16 v[56:59], v[176:179], v[148:151], v[56:59]
	ds_read_b128 v[220:223], v242 offset:55360
	s_waitcnt vmcnt(14)
	ds_write_b128 v213, v[76:79] offset:4608
	v_mfma_f32_16x16x32_bf16 v[64:67], v[180:183], v[148:151], v[64:67]
	ds_read_b128 v[224:227], v242 offset:57664
	s_waitcnt lgkmcnt(8)
	v_mfma_f32_16x16x32_bf16 v[36:39], v[184:187], v[144:147], v[36:39]
	ds_read_b128 v[164:167], v241 offset:39232
	s_waitcnt vmcnt(13)
	ds_write_b128 v213, v[80:83] offset:9216
	global_load_dwordx4 v[68:71], v[72:73], off offset:1792
	v_mfma_f32_16x16x32_bf16 v[40:43], v[184:187], v[148:151], v[40:43]
	ds_read_b128 v[228:231], v242 offset:59968
	s_waitcnt lgkmcnt(10)
	v_mfma_f32_16x16x32_bf16 v[20:23], v[176:179], v[152:155], v[20:23]
	ds_read_b128 v[168:171], v241 offset:41536
	v_mfma_f32_16x16x32_bf16 v[28:31], v[180:183], v[152:155], v[28:31]
	ds_read_b128 v[232:235], v242 offset:62272
	v_mfma_f32_16x16x32_bf16 v[4:7], v[184:187], v[152:155], v[4:7]
	ds_read_b128 v[172:175], v241 offset:43840
	s_waitcnt lgkmcnt(12)
	v_mfma_f32_16x16x32_bf16 v[44:47], v[216:219], v[144:147], v[44:47]
	v_mfma_f32_16x16x32_bf16 v[48:51], v[216:219], v[148:151], v[48:51]
	s_waitcnt vmcnt(13)
	ds_write_b128 v213, v[84:87] offset:13824
	global_load_dwordx4 v[76:79], v[74:75], off offset:1792
	v_mfma_f32_16x16x32_bf16 v[12:15], v[216:219], v[152:155], v[12:15]
	s_waitcnt lgkmcnt(12)
	v_mfma_f32_16x16x32_bf16 v[24:27], v[176:179], v[156:159], v[24:27]
	s_waitcnt vmcnt(13)
	ds_write_b128 v213, v[88:91] offset:18432
	global_load_dwordx4 v[80:83], v[106:107], off offset:1792
	v_mfma_f32_16x16x32_bf16 v[32:35], v[180:183], v[156:159], v[32:35]
	v_mfma_f32_16x16x32_bf16 v[8:11], v[184:187], v[156:159], v[8:11]
	v_mfma_f32_16x16x32_bf16 v[16:19], v[216:219], v[156:159], v[16:19]
	s_waitcnt lgkmcnt(10)
	v_mfma_f32_16x16x32_bf16 v[52:55], v[220:223], v[160:163], v[52:55]
	s_waitcnt lgkmcnt(8)
	v_mfma_f32_16x16x32_bf16 v[60:63], v[224:227], v[160:163], v[60:63]
	s_waitcnt lgkmcnt(7)
	v_mfma_f32_16x16x32_bf16 v[56:59], v[220:223], v[164:167], v[56:59]
	s_waitcnt vmcnt(13)
	ds_write_b128 v213, v[92:95] offset:23040
	global_load_dwordx4 v[84:87], v[188:189], off offset:1792
	v_mfma_f32_16x16x32_bf16 v[64:67], v[224:227], v[164:167], v[64:67]
	s_waitcnt lgkmcnt(6)
	v_mfma_f32_16x16x32_bf16 v[36:39], v[228:231], v[160:163], v[36:39]
	s_waitcnt vmcnt(13)
	ds_write_b128 v213, v[96:99] offset:27648
	global_load_dwordx4 v[88:91], v[104:105], off offset:1792
	v_mfma_f32_16x16x32_bf16 v[40:43], v[228:231], v[164:167], v[40:43]
	s_waitcnt lgkmcnt(6)
	v_mfma_f32_16x16x32_bf16 v[20:23], v[220:223], v[168:171], v[20:23]
	s_waitcnt vmcnt(13)
	ds_write_b128 v213, v[100:103] offset:32256
	global_load_dwordx4 v[92:95], v[214:215], off offset:1792
	v_mfma_f32_16x16x32_bf16 v[28:31], v[224:227], v[168:171], v[28:31]
	v_mfma_f32_16x16x32_bf16 v[4:7], v[228:231], v[168:171], v[4:7]
	global_load_dwordx4 v[96:99], v[236:237], off offset:1792
	s_waitcnt lgkmcnt(6)
	v_mfma_f32_16x16x32_bf16 v[44:47], v[232:235], v[160:163], v[44:47]
	v_mfma_f32_16x16x32_bf16 v[48:51], v[232:235], v[164:167], v[48:51]
	global_load_dwordx4 v[100:103], v[238:239], off offset:1792
	v_mfma_f32_16x16x32_bf16 v[12:15], v[232:235], v[168:171], v[12:15]
	s_waitcnt lgkmcnt(5)
	v_mfma_f32_16x16x32_bf16 v[24:27], v[220:223], v[172:175], v[24:27]
	v_mfma_f32_16x16x32_bf16 v[32:35], v[224:227], v[172:175], v[32:35]
	v_mfma_f32_16x16x32_bf16 v[8:11], v[228:231], v[172:175], v[8:11]
	v_mfma_f32_16x16x32_bf16 v[16:19], v[232:235], v[172:175], v[16:19]
	s_setprio 0
	s_waitcnt lgkmcnt(0)
	s_barrier
	ds_read_b128 v[144:147], v241
	ds_read_b128 v[176:179], v242 offset:18432
	ds_read_b128 v[180:183], v242 offset:20736
	ds_read_b128 v[148:151], v241 offset:2304
	ds_read_b128 v[184:187], v242 offset:23040
	ds_read_b128 v[152:155], v241 offset:4608
	ds_read_b128 v[216:219], v242 offset:25344
	ds_read_b128 v[156:159], v241 offset:6912
	s_setprio 1
	s_waitcnt lgkmcnt(6)
	v_mfma_f32_16x16x32_bf16 v[52:55], v[176:179], v[144:147], v[52:55]
	s_waitcnt vmcnt(15)
	ds_write_b128 v240, v[108:111]
	s_waitcnt lgkmcnt(6)
	v_mfma_f32_16x16x32_bf16 v[60:63], v[180:183], v[144:147], v[60:63]
	ds_read_b128 v[160:163], v241 offset:64
	s_waitcnt lgkmcnt(6)
	v_mfma_f32_16x16x32_bf16 v[56:59], v[176:179], v[148:151], v[56:59]
	ds_read_b128 v[220:223], v242 offset:18496
	s_waitcnt vmcnt(14)
	ds_write_b128 v240, v[112:115] offset:4608
	v_mfma_f32_16x16x32_bf16 v[64:67], v[180:183], v[148:151], v[64:67]
	ds_read_b128 v[224:227], v242 offset:20800
	s_waitcnt lgkmcnt(8)
	v_mfma_f32_16x16x32_bf16 v[36:39], v[184:187], v[144:147], v[36:39]
	ds_read_b128 v[164:167], v241 offset:2368
	s_waitcnt vmcnt(13)
	ds_write_b128 v240, v[116:119] offset:9216
	global_load_dwordx4 v[108:111], v[72:73], off offset:1920
	v_mfma_f32_16x16x32_bf16 v[40:43], v[184:187], v[148:151], v[40:43]
	ds_read_b128 v[228:231], v242 offset:23104
	s_waitcnt lgkmcnt(10)
	v_mfma_f32_16x16x32_bf16 v[20:23], v[176:179], v[152:155], v[20:23]
	ds_read_b128 v[168:171], v241 offset:4672
	v_mfma_f32_16x16x32_bf16 v[28:31], v[180:183], v[152:155], v[28:31]
	ds_read_b128 v[232:235], v242 offset:25408
	v_mfma_f32_16x16x32_bf16 v[4:7], v[184:187], v[152:155], v[4:7]
	ds_read_b128 v[172:175], v241 offset:6976
	s_waitcnt lgkmcnt(12)
	v_mfma_f32_16x16x32_bf16 v[44:47], v[216:219], v[144:147], v[44:47]
	v_mfma_f32_16x16x32_bf16 v[48:51], v[216:219], v[148:151], v[48:51]
	s_waitcnt vmcnt(13)
	ds_write_b128 v240, v[120:123] offset:13824
	global_load_dwordx4 v[112:115], v[74:75], off offset:1920
	v_mfma_f32_16x16x32_bf16 v[12:15], v[216:219], v[152:155], v[12:15]
	s_waitcnt lgkmcnt(12)
	v_mfma_f32_16x16x32_bf16 v[24:27], v[176:179], v[156:159], v[24:27]
	s_waitcnt vmcnt(13)
	ds_write_b128 v240, v[124:127] offset:18432
	global_load_dwordx4 v[116:119], v[106:107], off offset:1920
	v_mfma_f32_16x16x32_bf16 v[32:35], v[180:183], v[156:159], v[32:35]
	v_mfma_f32_16x16x32_bf16 v[8:11], v[184:187], v[156:159], v[8:11]
	v_mfma_f32_16x16x32_bf16 v[16:19], v[216:219], v[156:159], v[16:19]
	s_waitcnt lgkmcnt(10)
	v_mfma_f32_16x16x32_bf16 v[52:55], v[220:223], v[160:163], v[52:55]
	s_waitcnt lgkmcnt(8)
	v_mfma_f32_16x16x32_bf16 v[60:63], v[224:227], v[160:163], v[60:63]
	s_waitcnt lgkmcnt(7)
	v_mfma_f32_16x16x32_bf16 v[56:59], v[220:223], v[164:167], v[56:59]
	s_waitcnt vmcnt(13)
	ds_write_b128 v240, v[128:131] offset:23040
	global_load_dwordx4 v[120:123], v[188:189], off offset:1920
	v_mfma_f32_16x16x32_bf16 v[64:67], v[224:227], v[164:167], v[64:67]
	s_waitcnt lgkmcnt(6)
	v_mfma_f32_16x16x32_bf16 v[36:39], v[228:231], v[160:163], v[36:39]
	s_waitcnt vmcnt(13)
	ds_write_b128 v240, v[136:139] offset:27648
	global_load_dwordx4 v[124:127], v[104:105], off offset:1920
	v_mfma_f32_16x16x32_bf16 v[40:43], v[228:231], v[164:167], v[40:43]
	s_waitcnt lgkmcnt(6)
	v_mfma_f32_16x16x32_bf16 v[20:23], v[220:223], v[168:171], v[20:23]
	s_waitcnt vmcnt(13)
	ds_write_b128 v240, v[140:143] offset:32256
	global_load_dwordx4 v[128:131], v[214:215], off offset:1920
	v_mfma_f32_16x16x32_bf16 v[28:31], v[224:227], v[168:171], v[28:31]
	v_mfma_f32_16x16x32_bf16 v[4:7], v[228:231], v[168:171], v[4:7]
	global_load_dwordx4 v[136:139], v[236:237], off offset:1920
	s_waitcnt lgkmcnt(6)
	v_mfma_f32_16x16x32_bf16 v[44:47], v[232:235], v[160:163], v[44:47]
	v_mfma_f32_16x16x32_bf16 v[48:51], v[232:235], v[164:167], v[48:51]
	global_load_dwordx4 v[140:143], v[238:239], off offset:1920
	v_mfma_f32_16x16x32_bf16 v[12:15], v[232:235], v[168:171], v[12:15]
	s_waitcnt lgkmcnt(5)
	v_mfma_f32_16x16x32_bf16 v[24:27], v[220:223], v[172:175], v[24:27]
	v_mfma_f32_16x16x32_bf16 v[32:35], v[224:227], v[172:175], v[32:35]
	v_mfma_f32_16x16x32_bf16 v[8:11], v[228:231], v[172:175], v[8:11]
	v_mfma_f32_16x16x32_bf16 v[16:19], v[232:235], v[172:175], v[16:19]
	s_setprio 0
	s_waitcnt lgkmcnt(0)
	s_barrier
	ds_read_b128 v[144:147], v241 offset:36864
	ds_read_b128 v[176:179], v242 offset:55296
	ds_read_b128 v[180:183], v242 offset:57600
	ds_read_b128 v[148:151], v241 offset:39168
	ds_read_b128 v[184:187], v242 offset:59904
	ds_read_b128 v[152:155], v241 offset:41472
	ds_read_b128 v[216:219], v242 offset:62208
	ds_read_b128 v[156:159], v241 offset:43776
	s_setprio 1
	s_waitcnt lgkmcnt(6)
	v_mfma_f32_16x16x32_bf16 v[52:55], v[176:179], v[144:147], v[52:55]
	s_waitcnt vmcnt(15)
	ds_write_b128 v213, v[68:71]
	s_waitcnt lgkmcnt(6)
	v_mfma_f32_16x16x32_bf16 v[60:63], v[180:183], v[144:147], v[60:63]
	ds_read_b128 v[160:163], v241 offset:36928
	s_waitcnt lgkmcnt(6)
	v_mfma_f32_16x16x32_bf16 v[56:59], v[176:179], v[148:151], v[56:59]
	ds_read_b128 v[220:223], v242 offset:55360
	s_waitcnt vmcnt(14)
	ds_write_b128 v213, v[76:79] offset:4608
	v_mfma_f32_16x16x32_bf16 v[64:67], v[180:183], v[148:151], v[64:67]
	ds_read_b128 v[224:227], v242 offset:57664
	s_waitcnt lgkmcnt(8)
	v_mfma_f32_16x16x32_bf16 v[36:39], v[184:187], v[144:147], v[36:39]
	ds_read_b128 v[164:167], v241 offset:39232
	s_waitcnt vmcnt(13)
	ds_write_b128 v213, v[80:83] offset:9216
	global_load_dwordx4 v[68:71], v[72:73], off offset:2048
	v_mfma_f32_16x16x32_bf16 v[40:43], v[184:187], v[148:151], v[40:43]
	ds_read_b128 v[228:231], v242 offset:59968
	s_waitcnt lgkmcnt(10)
	v_mfma_f32_16x16x32_bf16 v[20:23], v[176:179], v[152:155], v[20:23]
	ds_read_b128 v[168:171], v241 offset:41536
	v_mfma_f32_16x16x32_bf16 v[28:31], v[180:183], v[152:155], v[28:31]
	ds_read_b128 v[232:235], v242 offset:62272
	v_mfma_f32_16x16x32_bf16 v[4:7], v[184:187], v[152:155], v[4:7]
	ds_read_b128 v[172:175], v241 offset:43840
	s_waitcnt lgkmcnt(12)
	v_mfma_f32_16x16x32_bf16 v[44:47], v[216:219], v[144:147], v[44:47]
	v_mfma_f32_16x16x32_bf16 v[48:51], v[216:219], v[148:151], v[48:51]
	s_waitcnt vmcnt(13)
	ds_write_b128 v213, v[84:87] offset:13824
	global_load_dwordx4 v[76:79], v[74:75], off offset:2048
	v_mfma_f32_16x16x32_bf16 v[12:15], v[216:219], v[152:155], v[12:15]
	s_waitcnt lgkmcnt(12)
	v_mfma_f32_16x16x32_bf16 v[24:27], v[176:179], v[156:159], v[24:27]
	s_waitcnt vmcnt(13)
	ds_write_b128 v213, v[88:91] offset:18432
	global_load_dwordx4 v[80:83], v[106:107], off offset:2048
	v_mfma_f32_16x16x32_bf16 v[32:35], v[180:183], v[156:159], v[32:35]
	v_mfma_f32_16x16x32_bf16 v[8:11], v[184:187], v[156:159], v[8:11]
	v_mfma_f32_16x16x32_bf16 v[16:19], v[216:219], v[156:159], v[16:19]
	s_waitcnt lgkmcnt(10)
	v_mfma_f32_16x16x32_bf16 v[52:55], v[220:223], v[160:163], v[52:55]
	s_waitcnt lgkmcnt(8)
	v_mfma_f32_16x16x32_bf16 v[60:63], v[224:227], v[160:163], v[60:63]
	s_waitcnt lgkmcnt(7)
	v_mfma_f32_16x16x32_bf16 v[56:59], v[220:223], v[164:167], v[56:59]
	s_waitcnt vmcnt(13)
	ds_write_b128 v213, v[92:95] offset:23040
	global_load_dwordx4 v[84:87], v[188:189], off offset:2048
	v_mfma_f32_16x16x32_bf16 v[64:67], v[224:227], v[164:167], v[64:67]
	s_waitcnt lgkmcnt(6)
	v_mfma_f32_16x16x32_bf16 v[36:39], v[228:231], v[160:163], v[36:39]
	s_waitcnt vmcnt(13)
	ds_write_b128 v213, v[96:99] offset:27648
	global_load_dwordx4 v[88:91], v[104:105], off offset:2048
	v_mfma_f32_16x16x32_bf16 v[40:43], v[228:231], v[164:167], v[40:43]
	s_waitcnt lgkmcnt(6)
	v_mfma_f32_16x16x32_bf16 v[20:23], v[220:223], v[168:171], v[20:23]
	s_waitcnt vmcnt(13)
	ds_write_b128 v213, v[100:103] offset:32256
	global_load_dwordx4 v[92:95], v[214:215], off offset:2048
	v_mfma_f32_16x16x32_bf16 v[28:31], v[224:227], v[168:171], v[28:31]
	v_mfma_f32_16x16x32_bf16 v[4:7], v[228:231], v[168:171], v[4:7]
	global_load_dwordx4 v[96:99], v[236:237], off offset:2048
	s_waitcnt lgkmcnt(6)
	v_mfma_f32_16x16x32_bf16 v[44:47], v[232:235], v[160:163], v[44:47]
	v_mfma_f32_16x16x32_bf16 v[48:51], v[232:235], v[164:167], v[48:51]
	global_load_dwordx4 v[100:103], v[238:239], off offset:2048
	v_mfma_f32_16x16x32_bf16 v[12:15], v[232:235], v[168:171], v[12:15]
	s_waitcnt lgkmcnt(5)
	v_mfma_f32_16x16x32_bf16 v[24:27], v[220:223], v[172:175], v[24:27]
	v_mfma_f32_16x16x32_bf16 v[32:35], v[224:227], v[172:175], v[32:35]
	v_mfma_f32_16x16x32_bf16 v[8:11], v[228:231], v[172:175], v[8:11]
	v_mfma_f32_16x16x32_bf16 v[16:19], v[232:235], v[172:175], v[16:19]
	s_setprio 0
	s_waitcnt lgkmcnt(0)
	s_barrier
	ds_read_b128 v[144:147], v241
	ds_read_b128 v[176:179], v242 offset:18432
	ds_read_b128 v[180:183], v242 offset:20736
	ds_read_b128 v[148:151], v241 offset:2304
	ds_read_b128 v[184:187], v242 offset:23040
	ds_read_b128 v[152:155], v241 offset:4608
	ds_read_b128 v[216:219], v242 offset:25344
	ds_read_b128 v[156:159], v241 offset:6912
	s_setprio 1
	s_waitcnt lgkmcnt(6)
	v_mfma_f32_16x16x32_bf16 v[52:55], v[176:179], v[144:147], v[52:55]
	s_waitcnt vmcnt(15)
	ds_write_b128 v240, v[108:111]
	s_waitcnt lgkmcnt(6)
	v_mfma_f32_16x16x32_bf16 v[60:63], v[180:183], v[144:147], v[60:63]
	ds_read_b128 v[160:163], v241 offset:64
	s_waitcnt lgkmcnt(6)
	v_mfma_f32_16x16x32_bf16 v[56:59], v[176:179], v[148:151], v[56:59]
	ds_read_b128 v[220:223], v242 offset:18496
	s_waitcnt vmcnt(14)
	ds_write_b128 v240, v[112:115] offset:4608
	v_mfma_f32_16x16x32_bf16 v[64:67], v[180:183], v[148:151], v[64:67]
	ds_read_b128 v[224:227], v242 offset:20800
	s_waitcnt lgkmcnt(8)
	v_mfma_f32_16x16x32_bf16 v[36:39], v[184:187], v[144:147], v[36:39]
	ds_read_b128 v[164:167], v241 offset:2368
	s_waitcnt vmcnt(13)
	ds_write_b128 v240, v[116:119] offset:9216
	global_load_dwordx4 v[108:111], v[72:73], off offset:2176
	v_mfma_f32_16x16x32_bf16 v[40:43], v[184:187], v[148:151], v[40:43]
	ds_read_b128 v[228:231], v242 offset:23104
	s_waitcnt lgkmcnt(10)
	v_mfma_f32_16x16x32_bf16 v[20:23], v[176:179], v[152:155], v[20:23]
	ds_read_b128 v[168:171], v241 offset:4672
	v_mfma_f32_16x16x32_bf16 v[28:31], v[180:183], v[152:155], v[28:31]
	ds_read_b128 v[232:235], v242 offset:25408
	v_mfma_f32_16x16x32_bf16 v[4:7], v[184:187], v[152:155], v[4:7]
	ds_read_b128 v[172:175], v241 offset:6976
	s_waitcnt lgkmcnt(12)
	v_mfma_f32_16x16x32_bf16 v[44:47], v[216:219], v[144:147], v[44:47]
	v_mfma_f32_16x16x32_bf16 v[48:51], v[216:219], v[148:151], v[48:51]
	s_waitcnt vmcnt(13)
	ds_write_b128 v240, v[120:123] offset:13824
	global_load_dwordx4 v[112:115], v[74:75], off offset:2176
	v_mfma_f32_16x16x32_bf16 v[12:15], v[216:219], v[152:155], v[12:15]
	s_waitcnt lgkmcnt(12)
	v_mfma_f32_16x16x32_bf16 v[24:27], v[176:179], v[156:159], v[24:27]
	s_waitcnt vmcnt(13)
	ds_write_b128 v240, v[124:127] offset:18432
	global_load_dwordx4 v[116:119], v[106:107], off offset:2176
	v_mfma_f32_16x16x32_bf16 v[32:35], v[180:183], v[156:159], v[32:35]
	v_mfma_f32_16x16x32_bf16 v[8:11], v[184:187], v[156:159], v[8:11]
	v_mfma_f32_16x16x32_bf16 v[16:19], v[216:219], v[156:159], v[16:19]
	s_waitcnt lgkmcnt(10)
	v_mfma_f32_16x16x32_bf16 v[52:55], v[220:223], v[160:163], v[52:55]
	s_waitcnt lgkmcnt(8)
	v_mfma_f32_16x16x32_bf16 v[60:63], v[224:227], v[160:163], v[60:63]
	s_waitcnt lgkmcnt(7)
	v_mfma_f32_16x16x32_bf16 v[56:59], v[220:223], v[164:167], v[56:59]
	s_waitcnt vmcnt(13)
	ds_write_b128 v240, v[128:131] offset:23040
	global_load_dwordx4 v[120:123], v[188:189], off offset:2176
	v_mfma_f32_16x16x32_bf16 v[64:67], v[224:227], v[164:167], v[64:67]
	s_waitcnt lgkmcnt(6)
	v_mfma_f32_16x16x32_bf16 v[36:39], v[228:231], v[160:163], v[36:39]
	s_waitcnt vmcnt(13)
	ds_write_b128 v240, v[136:139] offset:27648
	global_load_dwordx4 v[124:127], v[104:105], off offset:2176
	v_mfma_f32_16x16x32_bf16 v[40:43], v[228:231], v[164:167], v[40:43]
	s_waitcnt lgkmcnt(6)
	v_mfma_f32_16x16x32_bf16 v[20:23], v[220:223], v[168:171], v[20:23]
	s_waitcnt vmcnt(13)
	ds_write_b128 v240, v[140:143] offset:32256
	global_load_dwordx4 v[128:131], v[214:215], off offset:2176
	v_mfma_f32_16x16x32_bf16 v[28:31], v[224:227], v[168:171], v[28:31]
	v_mfma_f32_16x16x32_bf16 v[4:7], v[228:231], v[168:171], v[4:7]
	global_load_dwordx4 v[136:139], v[236:237], off offset:2176
	s_waitcnt lgkmcnt(6)
	v_mfma_f32_16x16x32_bf16 v[44:47], v[232:235], v[160:163], v[44:47]
	v_mfma_f32_16x16x32_bf16 v[48:51], v[232:235], v[164:167], v[48:51]
	global_load_dwordx4 v[140:143], v[238:239], off offset:2176
	v_mfma_f32_16x16x32_bf16 v[12:15], v[232:235], v[168:171], v[12:15]
	s_waitcnt lgkmcnt(5)
	v_mfma_f32_16x16x32_bf16 v[24:27], v[220:223], v[172:175], v[24:27]
	v_mfma_f32_16x16x32_bf16 v[32:35], v[224:227], v[172:175], v[32:35]
	v_mfma_f32_16x16x32_bf16 v[8:11], v[228:231], v[172:175], v[8:11]
	v_mfma_f32_16x16x32_bf16 v[16:19], v[232:235], v[172:175], v[16:19]
	s_setprio 0
	s_waitcnt lgkmcnt(0)
	s_barrier
	ds_read_b128 v[144:147], v241 offset:36864
	ds_read_b128 v[176:179], v242 offset:55296
	ds_read_b128 v[180:183], v242 offset:57600
	ds_read_b128 v[148:151], v241 offset:39168
	ds_read_b128 v[184:187], v242 offset:59904
	ds_read_b128 v[152:155], v241 offset:41472
	ds_read_b128 v[216:219], v242 offset:62208
	ds_read_b128 v[156:159], v241 offset:43776
	s_setprio 1
	s_waitcnt lgkmcnt(6)
	v_mfma_f32_16x16x32_bf16 v[52:55], v[176:179], v[144:147], v[52:55]
	s_waitcnt vmcnt(15)
	ds_write_b128 v213, v[68:71]
	s_waitcnt lgkmcnt(6)
	v_mfma_f32_16x16x32_bf16 v[60:63], v[180:183], v[144:147], v[60:63]
	ds_read_b128 v[160:163], v241 offset:36928
	s_waitcnt lgkmcnt(6)
	v_mfma_f32_16x16x32_bf16 v[56:59], v[176:179], v[148:151], v[56:59]
	ds_read_b128 v[220:223], v242 offset:55360
	s_waitcnt vmcnt(14)
	ds_write_b128 v213, v[76:79] offset:4608
	v_mfma_f32_16x16x32_bf16 v[64:67], v[180:183], v[148:151], v[64:67]
	ds_read_b128 v[224:227], v242 offset:57664
	s_waitcnt lgkmcnt(8)
	v_mfma_f32_16x16x32_bf16 v[36:39], v[184:187], v[144:147], v[36:39]
	ds_read_b128 v[164:167], v241 offset:39232
	s_waitcnt vmcnt(13)
	ds_write_b128 v213, v[80:83] offset:9216
	global_load_dwordx4 v[68:71], v[72:73], off offset:2304
	v_mfma_f32_16x16x32_bf16 v[40:43], v[184:187], v[148:151], v[40:43]
	ds_read_b128 v[228:231], v242 offset:59968
	s_waitcnt lgkmcnt(10)
	v_mfma_f32_16x16x32_bf16 v[20:23], v[176:179], v[152:155], v[20:23]
	ds_read_b128 v[168:171], v241 offset:41536
	v_mfma_f32_16x16x32_bf16 v[28:31], v[180:183], v[152:155], v[28:31]
	ds_read_b128 v[232:235], v242 offset:62272
	v_mfma_f32_16x16x32_bf16 v[4:7], v[184:187], v[152:155], v[4:7]
	ds_read_b128 v[172:175], v241 offset:43840
	s_waitcnt lgkmcnt(12)
	v_mfma_f32_16x16x32_bf16 v[44:47], v[216:219], v[144:147], v[44:47]
	v_mfma_f32_16x16x32_bf16 v[48:51], v[216:219], v[148:151], v[48:51]
	s_waitcnt vmcnt(13)
	ds_write_b128 v213, v[84:87] offset:13824
	global_load_dwordx4 v[76:79], v[74:75], off offset:2304
	v_mfma_f32_16x16x32_bf16 v[12:15], v[216:219], v[152:155], v[12:15]
	s_waitcnt lgkmcnt(12)
	v_mfma_f32_16x16x32_bf16 v[24:27], v[176:179], v[156:159], v[24:27]
	s_waitcnt vmcnt(13)
	ds_write_b128 v213, v[88:91] offset:18432
	global_load_dwordx4 v[80:83], v[106:107], off offset:2304
	v_mfma_f32_16x16x32_bf16 v[32:35], v[180:183], v[156:159], v[32:35]
	v_mfma_f32_16x16x32_bf16 v[8:11], v[184:187], v[156:159], v[8:11]
	v_mfma_f32_16x16x32_bf16 v[16:19], v[216:219], v[156:159], v[16:19]
	s_waitcnt lgkmcnt(10)
	v_mfma_f32_16x16x32_bf16 v[52:55], v[220:223], v[160:163], v[52:55]
	s_waitcnt lgkmcnt(8)
	v_mfma_f32_16x16x32_bf16 v[60:63], v[224:227], v[160:163], v[60:63]
	s_waitcnt lgkmcnt(7)
	v_mfma_f32_16x16x32_bf16 v[56:59], v[220:223], v[164:167], v[56:59]
	s_waitcnt vmcnt(13)
	ds_write_b128 v213, v[92:95] offset:23040
	global_load_dwordx4 v[84:87], v[188:189], off offset:2304
	v_mfma_f32_16x16x32_bf16 v[64:67], v[224:227], v[164:167], v[64:67]
	s_waitcnt lgkmcnt(6)
	v_mfma_f32_16x16x32_bf16 v[36:39], v[228:231], v[160:163], v[36:39]
	s_waitcnt vmcnt(13)
	ds_write_b128 v213, v[96:99] offset:27648
	global_load_dwordx4 v[88:91], v[104:105], off offset:2304
	v_mfma_f32_16x16x32_bf16 v[40:43], v[228:231], v[164:167], v[40:43]
	s_waitcnt lgkmcnt(6)
	v_mfma_f32_16x16x32_bf16 v[20:23], v[220:223], v[168:171], v[20:23]
	s_waitcnt vmcnt(13)
	ds_write_b128 v213, v[100:103] offset:32256
	global_load_dwordx4 v[92:95], v[214:215], off offset:2304
	v_mfma_f32_16x16x32_bf16 v[28:31], v[224:227], v[168:171], v[28:31]
	v_mfma_f32_16x16x32_bf16 v[4:7], v[228:231], v[168:171], v[4:7]
	global_load_dwordx4 v[96:99], v[236:237], off offset:2304
	s_waitcnt lgkmcnt(6)
	v_mfma_f32_16x16x32_bf16 v[44:47], v[232:235], v[160:163], v[44:47]
	v_mfma_f32_16x16x32_bf16 v[48:51], v[232:235], v[164:167], v[48:51]
	global_load_dwordx4 v[100:103], v[238:239], off offset:2304
	v_mfma_f32_16x16x32_bf16 v[12:15], v[232:235], v[168:171], v[12:15]
	s_waitcnt lgkmcnt(5)
	v_mfma_f32_16x16x32_bf16 v[24:27], v[220:223], v[172:175], v[24:27]
	v_mfma_f32_16x16x32_bf16 v[32:35], v[224:227], v[172:175], v[32:35]
	v_mfma_f32_16x16x32_bf16 v[8:11], v[228:231], v[172:175], v[8:11]
	v_mfma_f32_16x16x32_bf16 v[16:19], v[232:235], v[172:175], v[16:19]
	s_setprio 0
	s_waitcnt lgkmcnt(0)
	s_barrier
	ds_read_b128 v[144:147], v241
	ds_read_b128 v[176:179], v242 offset:18432
	ds_read_b128 v[180:183], v242 offset:20736
	ds_read_b128 v[148:151], v241 offset:2304
	ds_read_b128 v[184:187], v242 offset:23040
	ds_read_b128 v[152:155], v241 offset:4608
	ds_read_b128 v[216:219], v242 offset:25344
	ds_read_b128 v[156:159], v241 offset:6912
	s_setprio 1
	s_waitcnt lgkmcnt(6)
	v_mfma_f32_16x16x32_bf16 v[52:55], v[176:179], v[144:147], v[52:55]
	s_waitcnt vmcnt(15)
	ds_write_b128 v240, v[108:111]
	s_waitcnt lgkmcnt(6)
	v_mfma_f32_16x16x32_bf16 v[60:63], v[180:183], v[144:147], v[60:63]
	ds_read_b128 v[160:163], v241 offset:64
	s_waitcnt lgkmcnt(6)
	v_mfma_f32_16x16x32_bf16 v[56:59], v[176:179], v[148:151], v[56:59]
	ds_read_b128 v[220:223], v242 offset:18496
	s_waitcnt vmcnt(14)
	ds_write_b128 v240, v[112:115] offset:4608
	v_mfma_f32_16x16x32_bf16 v[64:67], v[180:183], v[148:151], v[64:67]
	ds_read_b128 v[224:227], v242 offset:20800
	s_waitcnt lgkmcnt(8)
	v_mfma_f32_16x16x32_bf16 v[36:39], v[184:187], v[144:147], v[36:39]
	ds_read_b128 v[164:167], v241 offset:2368
	s_waitcnt vmcnt(13)
	ds_write_b128 v240, v[116:119] offset:9216
	global_load_dwordx4 v[108:111], v[72:73], off offset:2432
	v_mfma_f32_16x16x32_bf16 v[40:43], v[184:187], v[148:151], v[40:43]
	ds_read_b128 v[228:231], v242 offset:23104
	s_waitcnt lgkmcnt(10)
	v_mfma_f32_16x16x32_bf16 v[20:23], v[176:179], v[152:155], v[20:23]
	ds_read_b128 v[168:171], v241 offset:4672
	v_mfma_f32_16x16x32_bf16 v[28:31], v[180:183], v[152:155], v[28:31]
	ds_read_b128 v[232:235], v242 offset:25408
	v_mfma_f32_16x16x32_bf16 v[4:7], v[184:187], v[152:155], v[4:7]
	ds_read_b128 v[172:175], v241 offset:6976
	s_waitcnt lgkmcnt(12)
	v_mfma_f32_16x16x32_bf16 v[44:47], v[216:219], v[144:147], v[44:47]
	v_mfma_f32_16x16x32_bf16 v[48:51], v[216:219], v[148:151], v[48:51]
	s_waitcnt vmcnt(13)
	ds_write_b128 v240, v[120:123] offset:13824
	global_load_dwordx4 v[112:115], v[74:75], off offset:2432
	v_mfma_f32_16x16x32_bf16 v[12:15], v[216:219], v[152:155], v[12:15]
	s_waitcnt lgkmcnt(12)
	v_mfma_f32_16x16x32_bf16 v[24:27], v[176:179], v[156:159], v[24:27]
	s_waitcnt vmcnt(13)
	ds_write_b128 v240, v[124:127] offset:18432
	global_load_dwordx4 v[116:119], v[106:107], off offset:2432
	v_mfma_f32_16x16x32_bf16 v[32:35], v[180:183], v[156:159], v[32:35]
	v_mfma_f32_16x16x32_bf16 v[8:11], v[184:187], v[156:159], v[8:11]
	v_mfma_f32_16x16x32_bf16 v[16:19], v[216:219], v[156:159], v[16:19]
	s_waitcnt lgkmcnt(10)
	v_mfma_f32_16x16x32_bf16 v[52:55], v[220:223], v[160:163], v[52:55]
	s_waitcnt lgkmcnt(8)
	v_mfma_f32_16x16x32_bf16 v[60:63], v[224:227], v[160:163], v[60:63]
	s_waitcnt lgkmcnt(7)
	v_mfma_f32_16x16x32_bf16 v[56:59], v[220:223], v[164:167], v[56:59]
	s_waitcnt vmcnt(13)
	ds_write_b128 v240, v[128:131] offset:23040
	global_load_dwordx4 v[120:123], v[188:189], off offset:2432
	v_mfma_f32_16x16x32_bf16 v[64:67], v[224:227], v[164:167], v[64:67]
	s_waitcnt lgkmcnt(6)
	v_mfma_f32_16x16x32_bf16 v[36:39], v[228:231], v[160:163], v[36:39]
	s_waitcnt vmcnt(13)
	ds_write_b128 v240, v[136:139] offset:27648
	global_load_dwordx4 v[124:127], v[104:105], off offset:2432
	v_mfma_f32_16x16x32_bf16 v[40:43], v[228:231], v[164:167], v[40:43]
	s_waitcnt lgkmcnt(6)
	v_mfma_f32_16x16x32_bf16 v[20:23], v[220:223], v[168:171], v[20:23]
	s_waitcnt vmcnt(13)
	ds_write_b128 v240, v[140:143] offset:32256
	global_load_dwordx4 v[128:131], v[214:215], off offset:2432
	v_mfma_f32_16x16x32_bf16 v[28:31], v[224:227], v[168:171], v[28:31]
	v_mfma_f32_16x16x32_bf16 v[4:7], v[228:231], v[168:171], v[4:7]
	global_load_dwordx4 v[136:139], v[236:237], off offset:2432
	s_waitcnt lgkmcnt(6)
	v_mfma_f32_16x16x32_bf16 v[44:47], v[232:235], v[160:163], v[44:47]
	v_mfma_f32_16x16x32_bf16 v[48:51], v[232:235], v[164:167], v[48:51]
	global_load_dwordx4 v[140:143], v[238:239], off offset:2432
	v_mfma_f32_16x16x32_bf16 v[12:15], v[232:235], v[168:171], v[12:15]
	s_waitcnt lgkmcnt(5)
	v_mfma_f32_16x16x32_bf16 v[24:27], v[220:223], v[172:175], v[24:27]
	v_mfma_f32_16x16x32_bf16 v[32:35], v[224:227], v[172:175], v[32:35]
	v_mfma_f32_16x16x32_bf16 v[8:11], v[228:231], v[172:175], v[8:11]
	v_mfma_f32_16x16x32_bf16 v[16:19], v[232:235], v[172:175], v[16:19]
	s_setprio 0
	s_waitcnt lgkmcnt(0)
	s_barrier
	ds_read_b128 v[144:147], v241 offset:36864
	ds_read_b128 v[176:179], v242 offset:55296
	ds_read_b128 v[180:183], v242 offset:57600
	ds_read_b128 v[148:151], v241 offset:39168
	ds_read_b128 v[184:187], v242 offset:59904
	ds_read_b128 v[152:155], v241 offset:41472
	ds_read_b128 v[216:219], v242 offset:62208
	ds_read_b128 v[156:159], v241 offset:43776
	s_setprio 1
	s_waitcnt lgkmcnt(6)
	v_mfma_f32_16x16x32_bf16 v[52:55], v[176:179], v[144:147], v[52:55]
	s_waitcnt vmcnt(15)
	ds_write_b128 v213, v[68:71]
	s_waitcnt lgkmcnt(6)
	v_mfma_f32_16x16x32_bf16 v[60:63], v[180:183], v[144:147], v[60:63]
	ds_read_b128 v[160:163], v241 offset:36928
	s_waitcnt lgkmcnt(6)
	v_mfma_f32_16x16x32_bf16 v[56:59], v[176:179], v[148:151], v[56:59]
	ds_read_b128 v[220:223], v242 offset:55360
	s_waitcnt vmcnt(14)
	ds_write_b128 v213, v[76:79] offset:4608
	v_mfma_f32_16x16x32_bf16 v[64:67], v[180:183], v[148:151], v[64:67]
	ds_read_b128 v[224:227], v242 offset:57664
	s_waitcnt lgkmcnt(8)
	v_mfma_f32_16x16x32_bf16 v[36:39], v[184:187], v[144:147], v[36:39]
	ds_read_b128 v[164:167], v241 offset:39232
	s_waitcnt vmcnt(13)
	ds_write_b128 v213, v[80:83] offset:9216
	global_load_dwordx4 v[68:71], v[72:73], off offset:2560
	v_mfma_f32_16x16x32_bf16 v[40:43], v[184:187], v[148:151], v[40:43]
	ds_read_b128 v[228:231], v242 offset:59968
	s_waitcnt lgkmcnt(10)
	v_mfma_f32_16x16x32_bf16 v[20:23], v[176:179], v[152:155], v[20:23]
	ds_read_b128 v[168:171], v241 offset:41536
	v_mfma_f32_16x16x32_bf16 v[28:31], v[180:183], v[152:155], v[28:31]
	ds_read_b128 v[232:235], v242 offset:62272
	v_mfma_f32_16x16x32_bf16 v[4:7], v[184:187], v[152:155], v[4:7]
	ds_read_b128 v[172:175], v241 offset:43840
	s_waitcnt lgkmcnt(12)
	v_mfma_f32_16x16x32_bf16 v[44:47], v[216:219], v[144:147], v[44:47]
	v_mfma_f32_16x16x32_bf16 v[48:51], v[216:219], v[148:151], v[48:51]
	s_waitcnt vmcnt(13)
	ds_write_b128 v213, v[84:87] offset:13824
	global_load_dwordx4 v[76:79], v[74:75], off offset:2560
	v_mfma_f32_16x16x32_bf16 v[12:15], v[216:219], v[152:155], v[12:15]
	s_waitcnt lgkmcnt(12)
	v_mfma_f32_16x16x32_bf16 v[24:27], v[176:179], v[156:159], v[24:27]
	s_waitcnt vmcnt(13)
	ds_write_b128 v213, v[88:91] offset:18432
	global_load_dwordx4 v[80:83], v[106:107], off offset:2560
	v_mfma_f32_16x16x32_bf16 v[32:35], v[180:183], v[156:159], v[32:35]
	v_mfma_f32_16x16x32_bf16 v[8:11], v[184:187], v[156:159], v[8:11]
	v_mfma_f32_16x16x32_bf16 v[16:19], v[216:219], v[156:159], v[16:19]
	s_waitcnt lgkmcnt(10)
	v_mfma_f32_16x16x32_bf16 v[52:55], v[220:223], v[160:163], v[52:55]
	s_waitcnt lgkmcnt(8)
	v_mfma_f32_16x16x32_bf16 v[60:63], v[224:227], v[160:163], v[60:63]
	s_waitcnt lgkmcnt(7)
	v_mfma_f32_16x16x32_bf16 v[56:59], v[220:223], v[164:167], v[56:59]
	s_waitcnt vmcnt(13)
	ds_write_b128 v213, v[92:95] offset:23040
	global_load_dwordx4 v[84:87], v[188:189], off offset:2560
	v_mfma_f32_16x16x32_bf16 v[64:67], v[224:227], v[164:167], v[64:67]
	s_waitcnt lgkmcnt(6)
	v_mfma_f32_16x16x32_bf16 v[36:39], v[228:231], v[160:163], v[36:39]
	s_waitcnt vmcnt(13)
	ds_write_b128 v213, v[96:99] offset:27648
	global_load_dwordx4 v[88:91], v[104:105], off offset:2560
	v_mfma_f32_16x16x32_bf16 v[40:43], v[228:231], v[164:167], v[40:43]
	s_waitcnt lgkmcnt(6)
	v_mfma_f32_16x16x32_bf16 v[20:23], v[220:223], v[168:171], v[20:23]
	s_waitcnt vmcnt(13)
	ds_write_b128 v213, v[100:103] offset:32256
	global_load_dwordx4 v[92:95], v[214:215], off offset:2560
	v_mfma_f32_16x16x32_bf16 v[28:31], v[224:227], v[168:171], v[28:31]
	v_mfma_f32_16x16x32_bf16 v[4:7], v[228:231], v[168:171], v[4:7]
	global_load_dwordx4 v[96:99], v[236:237], off offset:2560
	s_waitcnt lgkmcnt(6)
	v_mfma_f32_16x16x32_bf16 v[44:47], v[232:235], v[160:163], v[44:47]
	v_mfma_f32_16x16x32_bf16 v[48:51], v[232:235], v[164:167], v[48:51]
	global_load_dwordx4 v[100:103], v[238:239], off offset:2560
	v_mfma_f32_16x16x32_bf16 v[12:15], v[232:235], v[168:171], v[12:15]
	s_waitcnt lgkmcnt(5)
	v_mfma_f32_16x16x32_bf16 v[24:27], v[220:223], v[172:175], v[24:27]
	v_mfma_f32_16x16x32_bf16 v[32:35], v[224:227], v[172:175], v[32:35]
	v_mfma_f32_16x16x32_bf16 v[8:11], v[228:231], v[172:175], v[8:11]
	v_mfma_f32_16x16x32_bf16 v[16:19], v[232:235], v[172:175], v[16:19]
	s_setprio 0
	s_waitcnt lgkmcnt(0)
	s_barrier
	ds_read_b128 v[144:147], v241
	ds_read_b128 v[176:179], v242 offset:18432
	ds_read_b128 v[180:183], v242 offset:20736
	ds_read_b128 v[148:151], v241 offset:2304
	ds_read_b128 v[184:187], v242 offset:23040
	ds_read_b128 v[152:155], v241 offset:4608
	ds_read_b128 v[216:219], v242 offset:25344
	ds_read_b128 v[156:159], v241 offset:6912
	s_setprio 1
	s_waitcnt lgkmcnt(6)
	v_mfma_f32_16x16x32_bf16 v[52:55], v[176:179], v[144:147], v[52:55]
	s_waitcnt vmcnt(15)
	ds_write_b128 v240, v[108:111]
	s_waitcnt lgkmcnt(6)
	v_mfma_f32_16x16x32_bf16 v[60:63], v[180:183], v[144:147], v[60:63]
	ds_read_b128 v[160:163], v241 offset:64
	s_waitcnt lgkmcnt(6)
	v_mfma_f32_16x16x32_bf16 v[56:59], v[176:179], v[148:151], v[56:59]
	ds_read_b128 v[220:223], v242 offset:18496
	s_waitcnt vmcnt(14)
	ds_write_b128 v240, v[112:115] offset:4608
	v_mfma_f32_16x16x32_bf16 v[64:67], v[180:183], v[148:151], v[64:67]
	ds_read_b128 v[224:227], v242 offset:20800
	s_waitcnt lgkmcnt(8)
	v_mfma_f32_16x16x32_bf16 v[36:39], v[184:187], v[144:147], v[36:39]
	ds_read_b128 v[164:167], v241 offset:2368
	s_waitcnt vmcnt(13)
	ds_write_b128 v240, v[116:119] offset:9216
	global_load_dwordx4 v[108:111], v[72:73], off offset:2688
	v_mfma_f32_16x16x32_bf16 v[40:43], v[184:187], v[148:151], v[40:43]
	ds_read_b128 v[228:231], v242 offset:23104
	s_waitcnt lgkmcnt(10)
	v_mfma_f32_16x16x32_bf16 v[20:23], v[176:179], v[152:155], v[20:23]
	ds_read_b128 v[168:171], v241 offset:4672
	v_mfma_f32_16x16x32_bf16 v[28:31], v[180:183], v[152:155], v[28:31]
	ds_read_b128 v[232:235], v242 offset:25408
	v_mfma_f32_16x16x32_bf16 v[4:7], v[184:187], v[152:155], v[4:7]
	ds_read_b128 v[172:175], v241 offset:6976
	s_waitcnt lgkmcnt(12)
	v_mfma_f32_16x16x32_bf16 v[44:47], v[216:219], v[144:147], v[44:47]
	v_mfma_f32_16x16x32_bf16 v[48:51], v[216:219], v[148:151], v[48:51]
	s_waitcnt vmcnt(13)
	ds_write_b128 v240, v[120:123] offset:13824
	global_load_dwordx4 v[112:115], v[74:75], off offset:2688
	v_mfma_f32_16x16x32_bf16 v[12:15], v[216:219], v[152:155], v[12:15]
	s_waitcnt lgkmcnt(12)
	v_mfma_f32_16x16x32_bf16 v[24:27], v[176:179], v[156:159], v[24:27]
	s_waitcnt vmcnt(13)
	ds_write_b128 v240, v[124:127] offset:18432
	global_load_dwordx4 v[116:119], v[106:107], off offset:2688
	v_mfma_f32_16x16x32_bf16 v[32:35], v[180:183], v[156:159], v[32:35]
	v_mfma_f32_16x16x32_bf16 v[8:11], v[184:187], v[156:159], v[8:11]
	v_mfma_f32_16x16x32_bf16 v[16:19], v[216:219], v[156:159], v[16:19]
	s_waitcnt lgkmcnt(10)
	v_mfma_f32_16x16x32_bf16 v[52:55], v[220:223], v[160:163], v[52:55]
	s_waitcnt lgkmcnt(8)
	v_mfma_f32_16x16x32_bf16 v[60:63], v[224:227], v[160:163], v[60:63]
	s_waitcnt lgkmcnt(7)
	v_mfma_f32_16x16x32_bf16 v[56:59], v[220:223], v[164:167], v[56:59]
	s_waitcnt vmcnt(13)
	ds_write_b128 v240, v[128:131] offset:23040
	global_load_dwordx4 v[120:123], v[188:189], off offset:2688
	v_mfma_f32_16x16x32_bf16 v[64:67], v[224:227], v[164:167], v[64:67]
	s_waitcnt lgkmcnt(6)
	v_mfma_f32_16x16x32_bf16 v[36:39], v[228:231], v[160:163], v[36:39]
	s_waitcnt vmcnt(13)
	ds_write_b128 v240, v[136:139] offset:27648
	global_load_dwordx4 v[124:127], v[104:105], off offset:2688
	v_mfma_f32_16x16x32_bf16 v[40:43], v[228:231], v[164:167], v[40:43]
	s_waitcnt lgkmcnt(6)
	v_mfma_f32_16x16x32_bf16 v[20:23], v[220:223], v[168:171], v[20:23]
	s_waitcnt vmcnt(13)
	ds_write_b128 v240, v[140:143] offset:32256
	global_load_dwordx4 v[128:131], v[214:215], off offset:2688
	v_mfma_f32_16x16x32_bf16 v[28:31], v[224:227], v[168:171], v[28:31]
	v_mfma_f32_16x16x32_bf16 v[4:7], v[228:231], v[168:171], v[4:7]
	global_load_dwordx4 v[136:139], v[236:237], off offset:2688
	s_waitcnt lgkmcnt(6)
	v_mfma_f32_16x16x32_bf16 v[44:47], v[232:235], v[160:163], v[44:47]
	v_mfma_f32_16x16x32_bf16 v[48:51], v[232:235], v[164:167], v[48:51]
	global_load_dwordx4 v[140:143], v[238:239], off offset:2688
	v_mfma_f32_16x16x32_bf16 v[12:15], v[232:235], v[168:171], v[12:15]
	s_waitcnt lgkmcnt(5)
	v_mfma_f32_16x16x32_bf16 v[24:27], v[220:223], v[172:175], v[24:27]
	v_mfma_f32_16x16x32_bf16 v[32:35], v[224:227], v[172:175], v[32:35]
	v_mfma_f32_16x16x32_bf16 v[8:11], v[228:231], v[172:175], v[8:11]
	v_mfma_f32_16x16x32_bf16 v[16:19], v[232:235], v[172:175], v[16:19]
	s_setprio 0
	s_waitcnt lgkmcnt(0)
	s_barrier
	ds_read_b128 v[144:147], v241 offset:36864
	ds_read_b128 v[176:179], v242 offset:55296
	ds_read_b128 v[180:183], v242 offset:57600
	ds_read_b128 v[148:151], v241 offset:39168
	ds_read_b128 v[184:187], v242 offset:59904
	ds_read_b128 v[152:155], v241 offset:41472
	ds_read_b128 v[216:219], v242 offset:62208
	ds_read_b128 v[156:159], v241 offset:43776
	s_setprio 1
	s_waitcnt lgkmcnt(6)
	v_mfma_f32_16x16x32_bf16 v[52:55], v[176:179], v[144:147], v[52:55]
	s_waitcnt vmcnt(15)
	ds_write_b128 v213, v[68:71]
	s_waitcnt lgkmcnt(6)
	v_mfma_f32_16x16x32_bf16 v[60:63], v[180:183], v[144:147], v[60:63]
	ds_read_b128 v[160:163], v241 offset:36928
	s_waitcnt lgkmcnt(6)
	v_mfma_f32_16x16x32_bf16 v[56:59], v[176:179], v[148:151], v[56:59]
	ds_read_b128 v[220:223], v242 offset:55360
	s_waitcnt vmcnt(14)
	ds_write_b128 v213, v[76:79] offset:4608
	v_mfma_f32_16x16x32_bf16 v[64:67], v[180:183], v[148:151], v[64:67]
	ds_read_b128 v[224:227], v242 offset:57664
	s_waitcnt lgkmcnt(8)
	v_mfma_f32_16x16x32_bf16 v[36:39], v[184:187], v[144:147], v[36:39]
	ds_read_b128 v[164:167], v241 offset:39232
	s_waitcnt vmcnt(13)
	ds_write_b128 v213, v[80:83] offset:9216
	global_load_dwordx4 v[68:71], v[72:73], off offset:2816
	v_mfma_f32_16x16x32_bf16 v[40:43], v[184:187], v[148:151], v[40:43]
	ds_read_b128 v[228:231], v242 offset:59968
	s_waitcnt lgkmcnt(10)
	v_mfma_f32_16x16x32_bf16 v[20:23], v[176:179], v[152:155], v[20:23]
	ds_read_b128 v[168:171], v241 offset:41536
	v_mfma_f32_16x16x32_bf16 v[28:31], v[180:183], v[152:155], v[28:31]
	ds_read_b128 v[232:235], v242 offset:62272
	v_mfma_f32_16x16x32_bf16 v[4:7], v[184:187], v[152:155], v[4:7]
	ds_read_b128 v[172:175], v241 offset:43840
	s_waitcnt lgkmcnt(12)
	v_mfma_f32_16x16x32_bf16 v[44:47], v[216:219], v[144:147], v[44:47]
	v_mfma_f32_16x16x32_bf16 v[48:51], v[216:219], v[148:151], v[48:51]
	s_waitcnt vmcnt(13)
	ds_write_b128 v213, v[84:87] offset:13824
	global_load_dwordx4 v[76:79], v[74:75], off offset:2816
	v_mfma_f32_16x16x32_bf16 v[12:15], v[216:219], v[152:155], v[12:15]
	s_waitcnt lgkmcnt(12)
	v_mfma_f32_16x16x32_bf16 v[24:27], v[176:179], v[156:159], v[24:27]
	s_waitcnt vmcnt(13)
	ds_write_b128 v213, v[88:91] offset:18432
	global_load_dwordx4 v[80:83], v[106:107], off offset:2816
	v_mfma_f32_16x16x32_bf16 v[32:35], v[180:183], v[156:159], v[32:35]
	v_mfma_f32_16x16x32_bf16 v[8:11], v[184:187], v[156:159], v[8:11]
	v_mfma_f32_16x16x32_bf16 v[16:19], v[216:219], v[156:159], v[16:19]
	s_waitcnt lgkmcnt(10)
	v_mfma_f32_16x16x32_bf16 v[52:55], v[220:223], v[160:163], v[52:55]
	s_waitcnt lgkmcnt(8)
	v_mfma_f32_16x16x32_bf16 v[60:63], v[224:227], v[160:163], v[60:63]
	s_waitcnt lgkmcnt(7)
	v_mfma_f32_16x16x32_bf16 v[56:59], v[220:223], v[164:167], v[56:59]
	s_waitcnt vmcnt(13)
	ds_write_b128 v213, v[92:95] offset:23040
	global_load_dwordx4 v[84:87], v[188:189], off offset:2816
	v_mfma_f32_16x16x32_bf16 v[64:67], v[224:227], v[164:167], v[64:67]
	s_waitcnt lgkmcnt(6)
	v_mfma_f32_16x16x32_bf16 v[36:39], v[228:231], v[160:163], v[36:39]
	s_waitcnt vmcnt(13)
	ds_write_b128 v213, v[96:99] offset:27648
	global_load_dwordx4 v[88:91], v[104:105], off offset:2816
	v_mfma_f32_16x16x32_bf16 v[40:43], v[228:231], v[164:167], v[40:43]
	s_waitcnt lgkmcnt(6)
	v_mfma_f32_16x16x32_bf16 v[20:23], v[220:223], v[168:171], v[20:23]
	s_waitcnt vmcnt(13)
	ds_write_b128 v213, v[100:103] offset:32256
	global_load_dwordx4 v[92:95], v[214:215], off offset:2816
	v_mfma_f32_16x16x32_bf16 v[28:31], v[224:227], v[168:171], v[28:31]
	v_mfma_f32_16x16x32_bf16 v[4:7], v[228:231], v[168:171], v[4:7]
	global_load_dwordx4 v[96:99], v[236:237], off offset:2816
	s_waitcnt lgkmcnt(6)
	v_mfma_f32_16x16x32_bf16 v[44:47], v[232:235], v[160:163], v[44:47]
	v_mfma_f32_16x16x32_bf16 v[48:51], v[232:235], v[164:167], v[48:51]
	global_load_dwordx4 v[100:103], v[238:239], off offset:2816
	v_mfma_f32_16x16x32_bf16 v[12:15], v[232:235], v[168:171], v[12:15]
	s_waitcnt lgkmcnt(5)
	v_mfma_f32_16x16x32_bf16 v[24:27], v[220:223], v[172:175], v[24:27]
	v_mfma_f32_16x16x32_bf16 v[32:35], v[224:227], v[172:175], v[32:35]
	v_mfma_f32_16x16x32_bf16 v[8:11], v[228:231], v[172:175], v[8:11]
	v_mfma_f32_16x16x32_bf16 v[16:19], v[232:235], v[172:175], v[16:19]
	s_setprio 0
	s_waitcnt lgkmcnt(0)
	s_barrier
	ds_read_b128 v[144:147], v241
	ds_read_b128 v[176:179], v242 offset:18432
	ds_read_b128 v[180:183], v242 offset:20736
	ds_read_b128 v[148:151], v241 offset:2304
	ds_read_b128 v[184:187], v242 offset:23040
	ds_read_b128 v[152:155], v241 offset:4608
	ds_read_b128 v[216:219], v242 offset:25344
	ds_read_b128 v[156:159], v241 offset:6912
	s_setprio 1
	s_waitcnt lgkmcnt(6)
	v_mfma_f32_16x16x32_bf16 v[52:55], v[176:179], v[144:147], v[52:55]
	s_waitcnt vmcnt(15)
	ds_write_b128 v240, v[108:111]
	s_waitcnt lgkmcnt(6)
	v_mfma_f32_16x16x32_bf16 v[60:63], v[180:183], v[144:147], v[60:63]
	ds_read_b128 v[160:163], v241 offset:64
	s_waitcnt lgkmcnt(6)
	v_mfma_f32_16x16x32_bf16 v[56:59], v[176:179], v[148:151], v[56:59]
	ds_read_b128 v[220:223], v242 offset:18496
	s_waitcnt vmcnt(14)
	ds_write_b128 v240, v[112:115] offset:4608
	v_mfma_f32_16x16x32_bf16 v[64:67], v[180:183], v[148:151], v[64:67]
	ds_read_b128 v[224:227], v242 offset:20800
	s_waitcnt lgkmcnt(8)
	v_mfma_f32_16x16x32_bf16 v[36:39], v[184:187], v[144:147], v[36:39]
	ds_read_b128 v[164:167], v241 offset:2368
	s_waitcnt vmcnt(13)
	ds_write_b128 v240, v[116:119] offset:9216
	global_load_dwordx4 v[108:111], v[72:73], off offset:2944
	v_mfma_f32_16x16x32_bf16 v[40:43], v[184:187], v[148:151], v[40:43]
	ds_read_b128 v[228:231], v242 offset:23104
	s_waitcnt lgkmcnt(10)
	v_mfma_f32_16x16x32_bf16 v[20:23], v[176:179], v[152:155], v[20:23]
	ds_read_b128 v[168:171], v241 offset:4672
	v_mfma_f32_16x16x32_bf16 v[28:31], v[180:183], v[152:155], v[28:31]
	ds_read_b128 v[232:235], v242 offset:25408
	v_mfma_f32_16x16x32_bf16 v[4:7], v[184:187], v[152:155], v[4:7]
	ds_read_b128 v[172:175], v241 offset:6976
	s_waitcnt lgkmcnt(12)
	v_mfma_f32_16x16x32_bf16 v[44:47], v[216:219], v[144:147], v[44:47]
	v_mfma_f32_16x16x32_bf16 v[48:51], v[216:219], v[148:151], v[48:51]
	s_waitcnt vmcnt(13)
	ds_write_b128 v240, v[120:123] offset:13824
	global_load_dwordx4 v[112:115], v[74:75], off offset:2944
	v_mfma_f32_16x16x32_bf16 v[12:15], v[216:219], v[152:155], v[12:15]
	s_waitcnt lgkmcnt(12)
	v_mfma_f32_16x16x32_bf16 v[24:27], v[176:179], v[156:159], v[24:27]
	s_waitcnt vmcnt(13)
	ds_write_b128 v240, v[124:127] offset:18432
	global_load_dwordx4 v[116:119], v[106:107], off offset:2944
	v_mfma_f32_16x16x32_bf16 v[32:35], v[180:183], v[156:159], v[32:35]
	v_mfma_f32_16x16x32_bf16 v[8:11], v[184:187], v[156:159], v[8:11]
	v_mfma_f32_16x16x32_bf16 v[16:19], v[216:219], v[156:159], v[16:19]
	s_waitcnt lgkmcnt(10)
	v_mfma_f32_16x16x32_bf16 v[52:55], v[220:223], v[160:163], v[52:55]
	s_waitcnt lgkmcnt(8)
	v_mfma_f32_16x16x32_bf16 v[60:63], v[224:227], v[160:163], v[60:63]
	s_waitcnt lgkmcnt(7)
	v_mfma_f32_16x16x32_bf16 v[56:59], v[220:223], v[164:167], v[56:59]
	s_waitcnt vmcnt(13)
	ds_write_b128 v240, v[128:131] offset:23040
	global_load_dwordx4 v[120:123], v[188:189], off offset:2944
	v_mfma_f32_16x16x32_bf16 v[64:67], v[224:227], v[164:167], v[64:67]
	s_waitcnt lgkmcnt(6)
	v_mfma_f32_16x16x32_bf16 v[36:39], v[228:231], v[160:163], v[36:39]
	s_waitcnt vmcnt(13)
	ds_write_b128 v240, v[136:139] offset:27648
	global_load_dwordx4 v[124:127], v[104:105], off offset:2944
	v_mfma_f32_16x16x32_bf16 v[40:43], v[228:231], v[164:167], v[40:43]
	s_waitcnt lgkmcnt(6)
	v_mfma_f32_16x16x32_bf16 v[20:23], v[220:223], v[168:171], v[20:23]
	s_waitcnt vmcnt(13)
	ds_write_b128 v240, v[140:143] offset:32256
	global_load_dwordx4 v[128:131], v[214:215], off offset:2944
	v_mfma_f32_16x16x32_bf16 v[28:31], v[224:227], v[168:171], v[28:31]
	v_mfma_f32_16x16x32_bf16 v[4:7], v[228:231], v[168:171], v[4:7]
	global_load_dwordx4 v[136:139], v[236:237], off offset:2944
	s_waitcnt lgkmcnt(6)
	v_mfma_f32_16x16x32_bf16 v[44:47], v[232:235], v[160:163], v[44:47]
	v_mfma_f32_16x16x32_bf16 v[48:51], v[232:235], v[164:167], v[48:51]
	global_load_dwordx4 v[140:143], v[238:239], off offset:2944
	v_mfma_f32_16x16x32_bf16 v[12:15], v[232:235], v[168:171], v[12:15]
	s_waitcnt lgkmcnt(5)
	v_mfma_f32_16x16x32_bf16 v[24:27], v[220:223], v[172:175], v[24:27]
	v_mfma_f32_16x16x32_bf16 v[32:35], v[224:227], v[172:175], v[32:35]
	v_mfma_f32_16x16x32_bf16 v[8:11], v[228:231], v[172:175], v[8:11]
	v_mfma_f32_16x16x32_bf16 v[16:19], v[232:235], v[172:175], v[16:19]
	s_setprio 0
	s_waitcnt lgkmcnt(0)
	s_barrier
	ds_read_b128 v[144:147], v241 offset:36864
	ds_read_b128 v[176:179], v242 offset:55296
	ds_read_b128 v[180:183], v242 offset:57600
	ds_read_b128 v[148:151], v241 offset:39168
	ds_read_b128 v[184:187], v242 offset:59904
	ds_read_b128 v[152:155], v241 offset:41472
	ds_read_b128 v[216:219], v242 offset:62208
	ds_read_b128 v[156:159], v241 offset:43776
	s_setprio 1
	s_waitcnt lgkmcnt(6)
	v_mfma_f32_16x16x32_bf16 v[52:55], v[176:179], v[144:147], v[52:55]
	s_waitcnt vmcnt(15)
	ds_write_b128 v213, v[68:71]
	s_waitcnt lgkmcnt(6)
	v_mfma_f32_16x16x32_bf16 v[60:63], v[180:183], v[144:147], v[60:63]
	ds_read_b128 v[160:163], v241 offset:36928
	s_waitcnt lgkmcnt(6)
	v_mfma_f32_16x16x32_bf16 v[56:59], v[176:179], v[148:151], v[56:59]
	ds_read_b128 v[220:223], v242 offset:55360
	s_waitcnt vmcnt(14)
	ds_write_b128 v213, v[76:79] offset:4608
	v_mfma_f32_16x16x32_bf16 v[64:67], v[180:183], v[148:151], v[64:67]
	ds_read_b128 v[224:227], v242 offset:57664
	s_waitcnt lgkmcnt(8)
	v_mfma_f32_16x16x32_bf16 v[36:39], v[184:187], v[144:147], v[36:39]
	ds_read_b128 v[164:167], v241 offset:39232
	s_waitcnt vmcnt(13)
	ds_write_b128 v213, v[80:83] offset:9216
	global_load_dwordx4 v[68:71], v[72:73], off offset:3072
	v_mfma_f32_16x16x32_bf16 v[40:43], v[184:187], v[148:151], v[40:43]
	ds_read_b128 v[228:231], v242 offset:59968
	s_waitcnt lgkmcnt(10)
	v_mfma_f32_16x16x32_bf16 v[20:23], v[176:179], v[152:155], v[20:23]
	ds_read_b128 v[168:171], v241 offset:41536
	v_mfma_f32_16x16x32_bf16 v[28:31], v[180:183], v[152:155], v[28:31]
	ds_read_b128 v[232:235], v242 offset:62272
	v_mfma_f32_16x16x32_bf16 v[4:7], v[184:187], v[152:155], v[4:7]
	ds_read_b128 v[172:175], v241 offset:43840
	s_waitcnt lgkmcnt(12)
	v_mfma_f32_16x16x32_bf16 v[44:47], v[216:219], v[144:147], v[44:47]
	v_mfma_f32_16x16x32_bf16 v[48:51], v[216:219], v[148:151], v[48:51]
	s_waitcnt vmcnt(13)
	ds_write_b128 v213, v[84:87] offset:13824
	global_load_dwordx4 v[76:79], v[74:75], off offset:3072
	v_mfma_f32_16x16x32_bf16 v[12:15], v[216:219], v[152:155], v[12:15]
	s_waitcnt lgkmcnt(12)
	v_mfma_f32_16x16x32_bf16 v[24:27], v[176:179], v[156:159], v[24:27]
	s_waitcnt vmcnt(13)
	ds_write_b128 v213, v[88:91] offset:18432
	global_load_dwordx4 v[80:83], v[106:107], off offset:3072
	v_mfma_f32_16x16x32_bf16 v[32:35], v[180:183], v[156:159], v[32:35]
	v_mfma_f32_16x16x32_bf16 v[8:11], v[184:187], v[156:159], v[8:11]
	v_mfma_f32_16x16x32_bf16 v[16:19], v[216:219], v[156:159], v[16:19]
	s_waitcnt lgkmcnt(10)
	v_mfma_f32_16x16x32_bf16 v[52:55], v[220:223], v[160:163], v[52:55]
	s_waitcnt lgkmcnt(8)
	v_mfma_f32_16x16x32_bf16 v[60:63], v[224:227], v[160:163], v[60:63]
	s_waitcnt lgkmcnt(7)
	v_mfma_f32_16x16x32_bf16 v[56:59], v[220:223], v[164:167], v[56:59]
	s_waitcnt vmcnt(13)
	ds_write_b128 v213, v[92:95] offset:23040
	global_load_dwordx4 v[84:87], v[188:189], off offset:3072
	v_mfma_f32_16x16x32_bf16 v[64:67], v[224:227], v[164:167], v[64:67]
	s_waitcnt lgkmcnt(6)
	v_mfma_f32_16x16x32_bf16 v[36:39], v[228:231], v[160:163], v[36:39]
	s_waitcnt vmcnt(13)
	ds_write_b128 v213, v[96:99] offset:27648
	global_load_dwordx4 v[88:91], v[104:105], off offset:3072
	v_mfma_f32_16x16x32_bf16 v[40:43], v[228:231], v[164:167], v[40:43]
	s_waitcnt lgkmcnt(6)
	v_mfma_f32_16x16x32_bf16 v[20:23], v[220:223], v[168:171], v[20:23]
	s_waitcnt vmcnt(13)
	ds_write_b128 v213, v[100:103] offset:32256
	global_load_dwordx4 v[92:95], v[214:215], off offset:3072
	v_mfma_f32_16x16x32_bf16 v[28:31], v[224:227], v[168:171], v[28:31]
	v_mfma_f32_16x16x32_bf16 v[4:7], v[228:231], v[168:171], v[4:7]
	global_load_dwordx4 v[96:99], v[236:237], off offset:3072
	s_waitcnt lgkmcnt(6)
	v_mfma_f32_16x16x32_bf16 v[44:47], v[232:235], v[160:163], v[44:47]
	v_mfma_f32_16x16x32_bf16 v[48:51], v[232:235], v[164:167], v[48:51]
	global_load_dwordx4 v[100:103], v[238:239], off offset:3072
	v_mfma_f32_16x16x32_bf16 v[12:15], v[232:235], v[168:171], v[12:15]
	s_waitcnt lgkmcnt(5)
	v_mfma_f32_16x16x32_bf16 v[24:27], v[220:223], v[172:175], v[24:27]
	v_mfma_f32_16x16x32_bf16 v[32:35], v[224:227], v[172:175], v[32:35]
	v_mfma_f32_16x16x32_bf16 v[8:11], v[228:231], v[172:175], v[8:11]
	v_mfma_f32_16x16x32_bf16 v[16:19], v[232:235], v[172:175], v[16:19]
	s_setprio 0
	s_waitcnt lgkmcnt(0)
	s_barrier
	ds_read_b128 v[144:147], v241
	ds_read_b128 v[176:179], v242 offset:18432
	ds_read_b128 v[180:183], v242 offset:20736
	ds_read_b128 v[148:151], v241 offset:2304
	ds_read_b128 v[184:187], v242 offset:23040
	ds_read_b128 v[152:155], v241 offset:4608
	ds_read_b128 v[216:219], v242 offset:25344
	ds_read_b128 v[156:159], v241 offset:6912
	s_setprio 1
	s_waitcnt lgkmcnt(6)
	v_mfma_f32_16x16x32_bf16 v[52:55], v[176:179], v[144:147], v[52:55]
	s_waitcnt vmcnt(15)
	ds_write_b128 v240, v[108:111]
	s_waitcnt lgkmcnt(6)
	v_mfma_f32_16x16x32_bf16 v[60:63], v[180:183], v[144:147], v[60:63]
	ds_read_b128 v[160:163], v241 offset:64
	s_waitcnt lgkmcnt(6)
	v_mfma_f32_16x16x32_bf16 v[56:59], v[176:179], v[148:151], v[56:59]
	ds_read_b128 v[220:223], v242 offset:18496
	s_waitcnt vmcnt(14)
	ds_write_b128 v240, v[112:115] offset:4608
	v_mfma_f32_16x16x32_bf16 v[64:67], v[180:183], v[148:151], v[64:67]
	ds_read_b128 v[224:227], v242 offset:20800
	s_waitcnt lgkmcnt(8)
	v_mfma_f32_16x16x32_bf16 v[36:39], v[184:187], v[144:147], v[36:39]
	ds_read_b128 v[164:167], v241 offset:2368
	s_waitcnt vmcnt(13)
	ds_write_b128 v240, v[116:119] offset:9216
	global_load_dwordx4 v[108:111], v[72:73], off offset:3200
	v_mfma_f32_16x16x32_bf16 v[40:43], v[184:187], v[148:151], v[40:43]
	ds_read_b128 v[228:231], v242 offset:23104
	s_waitcnt lgkmcnt(10)
	v_mfma_f32_16x16x32_bf16 v[20:23], v[176:179], v[152:155], v[20:23]
	ds_read_b128 v[168:171], v241 offset:4672
	v_mfma_f32_16x16x32_bf16 v[28:31], v[180:183], v[152:155], v[28:31]
	ds_read_b128 v[232:235], v242 offset:25408
	v_mfma_f32_16x16x32_bf16 v[4:7], v[184:187], v[152:155], v[4:7]
	ds_read_b128 v[172:175], v241 offset:6976
	s_waitcnt lgkmcnt(12)
	v_mfma_f32_16x16x32_bf16 v[44:47], v[216:219], v[144:147], v[44:47]
	v_mfma_f32_16x16x32_bf16 v[48:51], v[216:219], v[148:151], v[48:51]
	s_waitcnt vmcnt(13)
	ds_write_b128 v240, v[120:123] offset:13824
	global_load_dwordx4 v[112:115], v[74:75], off offset:3200
	v_mfma_f32_16x16x32_bf16 v[12:15], v[216:219], v[152:155], v[12:15]
	s_waitcnt lgkmcnt(12)
	v_mfma_f32_16x16x32_bf16 v[24:27], v[176:179], v[156:159], v[24:27]
	s_waitcnt vmcnt(13)
	ds_write_b128 v240, v[124:127] offset:18432
	global_load_dwordx4 v[116:119], v[106:107], off offset:3200
	v_mfma_f32_16x16x32_bf16 v[32:35], v[180:183], v[156:159], v[32:35]
	v_mfma_f32_16x16x32_bf16 v[8:11], v[184:187], v[156:159], v[8:11]
	v_mfma_f32_16x16x32_bf16 v[16:19], v[216:219], v[156:159], v[16:19]
	s_waitcnt lgkmcnt(10)
	v_mfma_f32_16x16x32_bf16 v[52:55], v[220:223], v[160:163], v[52:55]
	s_waitcnt lgkmcnt(8)
	v_mfma_f32_16x16x32_bf16 v[60:63], v[224:227], v[160:163], v[60:63]
	s_waitcnt lgkmcnt(7)
	v_mfma_f32_16x16x32_bf16 v[56:59], v[220:223], v[164:167], v[56:59]
	s_waitcnt vmcnt(13)
	ds_write_b128 v240, v[128:131] offset:23040
	global_load_dwordx4 v[120:123], v[188:189], off offset:3200
	v_mfma_f32_16x16x32_bf16 v[64:67], v[224:227], v[164:167], v[64:67]
	s_waitcnt lgkmcnt(6)
	v_mfma_f32_16x16x32_bf16 v[36:39], v[228:231], v[160:163], v[36:39]
	s_waitcnt vmcnt(13)
	ds_write_b128 v240, v[136:139] offset:27648
	global_load_dwordx4 v[124:127], v[104:105], off offset:3200
	v_mfma_f32_16x16x32_bf16 v[40:43], v[228:231], v[164:167], v[40:43]
	s_waitcnt lgkmcnt(6)
	v_mfma_f32_16x16x32_bf16 v[20:23], v[220:223], v[168:171], v[20:23]
	s_waitcnt vmcnt(13)
	ds_write_b128 v240, v[140:143] offset:32256
	global_load_dwordx4 v[128:131], v[214:215], off offset:3200
	v_mfma_f32_16x16x32_bf16 v[28:31], v[224:227], v[168:171], v[28:31]
	v_mfma_f32_16x16x32_bf16 v[4:7], v[228:231], v[168:171], v[4:7]
	global_load_dwordx4 v[136:139], v[236:237], off offset:3200
	s_waitcnt lgkmcnt(6)
	v_mfma_f32_16x16x32_bf16 v[44:47], v[232:235], v[160:163], v[44:47]
	v_mfma_f32_16x16x32_bf16 v[48:51], v[232:235], v[164:167], v[48:51]
	global_load_dwordx4 v[140:143], v[238:239], off offset:3200
	v_mfma_f32_16x16x32_bf16 v[12:15], v[232:235], v[168:171], v[12:15]
	s_waitcnt lgkmcnt(5)
	v_mfma_f32_16x16x32_bf16 v[24:27], v[220:223], v[172:175], v[24:27]
	v_mfma_f32_16x16x32_bf16 v[32:35], v[224:227], v[172:175], v[32:35]
	v_mfma_f32_16x16x32_bf16 v[8:11], v[228:231], v[172:175], v[8:11]
	v_mfma_f32_16x16x32_bf16 v[16:19], v[232:235], v[172:175], v[16:19]
	s_setprio 0
	s_waitcnt lgkmcnt(0)
	s_barrier
	ds_read_b128 v[144:147], v241 offset:36864
	ds_read_b128 v[176:179], v242 offset:55296
	ds_read_b128 v[180:183], v242 offset:57600
	ds_read_b128 v[148:151], v241 offset:39168
	ds_read_b128 v[184:187], v242 offset:59904
	ds_read_b128 v[152:155], v241 offset:41472
	ds_read_b128 v[216:219], v242 offset:62208
	ds_read_b128 v[156:159], v241 offset:43776
	s_setprio 1
	s_waitcnt lgkmcnt(6)
	v_mfma_f32_16x16x32_bf16 v[52:55], v[176:179], v[144:147], v[52:55]
	s_waitcnt vmcnt(15)
	ds_write_b128 v213, v[68:71]
	s_waitcnt lgkmcnt(6)
	v_mfma_f32_16x16x32_bf16 v[60:63], v[180:183], v[144:147], v[60:63]
	ds_read_b128 v[160:163], v241 offset:36928
	s_waitcnt lgkmcnt(6)
	v_mfma_f32_16x16x32_bf16 v[56:59], v[176:179], v[148:151], v[56:59]
	ds_read_b128 v[220:223], v242 offset:55360
	s_waitcnt vmcnt(14)
	ds_write_b128 v213, v[76:79] offset:4608
	v_mfma_f32_16x16x32_bf16 v[64:67], v[180:183], v[148:151], v[64:67]
	ds_read_b128 v[224:227], v242 offset:57664
	s_waitcnt lgkmcnt(8)
	v_mfma_f32_16x16x32_bf16 v[36:39], v[184:187], v[144:147], v[36:39]
	ds_read_b128 v[164:167], v241 offset:39232
	s_waitcnt vmcnt(13)
	ds_write_b128 v213, v[80:83] offset:9216
	global_load_dwordx4 v[68:71], v[72:73], off offset:3328
	v_mfma_f32_16x16x32_bf16 v[40:43], v[184:187], v[148:151], v[40:43]
	ds_read_b128 v[228:231], v242 offset:59968
	s_waitcnt lgkmcnt(10)
	v_mfma_f32_16x16x32_bf16 v[20:23], v[176:179], v[152:155], v[20:23]
	ds_read_b128 v[168:171], v241 offset:41536
	v_mfma_f32_16x16x32_bf16 v[28:31], v[180:183], v[152:155], v[28:31]
	ds_read_b128 v[232:235], v242 offset:62272
	v_mfma_f32_16x16x32_bf16 v[4:7], v[184:187], v[152:155], v[4:7]
	ds_read_b128 v[172:175], v241 offset:43840
	s_waitcnt lgkmcnt(12)
	v_mfma_f32_16x16x32_bf16 v[44:47], v[216:219], v[144:147], v[44:47]
	v_mfma_f32_16x16x32_bf16 v[48:51], v[216:219], v[148:151], v[48:51]
	s_waitcnt vmcnt(13)
	ds_write_b128 v213, v[84:87] offset:13824
	global_load_dwordx4 v[76:79], v[74:75], off offset:3328
	v_mfma_f32_16x16x32_bf16 v[12:15], v[216:219], v[152:155], v[12:15]
	s_waitcnt lgkmcnt(12)
	v_mfma_f32_16x16x32_bf16 v[24:27], v[176:179], v[156:159], v[24:27]
	s_waitcnt vmcnt(13)
	ds_write_b128 v213, v[88:91] offset:18432
	global_load_dwordx4 v[80:83], v[106:107], off offset:3328
	v_mfma_f32_16x16x32_bf16 v[32:35], v[180:183], v[156:159], v[32:35]
	v_mfma_f32_16x16x32_bf16 v[8:11], v[184:187], v[156:159], v[8:11]
	v_mfma_f32_16x16x32_bf16 v[16:19], v[216:219], v[156:159], v[16:19]
	s_waitcnt lgkmcnt(10)
	v_mfma_f32_16x16x32_bf16 v[52:55], v[220:223], v[160:163], v[52:55]
	s_waitcnt lgkmcnt(8)
	v_mfma_f32_16x16x32_bf16 v[60:63], v[224:227], v[160:163], v[60:63]
	s_waitcnt lgkmcnt(7)
	v_mfma_f32_16x16x32_bf16 v[56:59], v[220:223], v[164:167], v[56:59]
	s_waitcnt vmcnt(13)
	ds_write_b128 v213, v[92:95] offset:23040
	global_load_dwordx4 v[84:87], v[188:189], off offset:3328
	v_mfma_f32_16x16x32_bf16 v[64:67], v[224:227], v[164:167], v[64:67]
	s_waitcnt lgkmcnt(6)
	v_mfma_f32_16x16x32_bf16 v[36:39], v[228:231], v[160:163], v[36:39]
	s_waitcnt vmcnt(13)
	ds_write_b128 v213, v[96:99] offset:27648
	global_load_dwordx4 v[88:91], v[104:105], off offset:3328
	v_mfma_f32_16x16x32_bf16 v[40:43], v[228:231], v[164:167], v[40:43]
	s_waitcnt lgkmcnt(6)
	v_mfma_f32_16x16x32_bf16 v[20:23], v[220:223], v[168:171], v[20:23]
	s_waitcnt vmcnt(13)
	ds_write_b128 v213, v[100:103] offset:32256
	global_load_dwordx4 v[92:95], v[214:215], off offset:3328
	v_mfma_f32_16x16x32_bf16 v[28:31], v[224:227], v[168:171], v[28:31]
	v_mfma_f32_16x16x32_bf16 v[4:7], v[228:231], v[168:171], v[4:7]
	global_load_dwordx4 v[96:99], v[236:237], off offset:3328
	s_waitcnt lgkmcnt(6)
	v_mfma_f32_16x16x32_bf16 v[44:47], v[232:235], v[160:163], v[44:47]
	v_mfma_f32_16x16x32_bf16 v[48:51], v[232:235], v[164:167], v[48:51]
	global_load_dwordx4 v[100:103], v[238:239], off offset:3328
	v_mfma_f32_16x16x32_bf16 v[12:15], v[232:235], v[168:171], v[12:15]
	s_waitcnt lgkmcnt(5)
	v_mfma_f32_16x16x32_bf16 v[24:27], v[220:223], v[172:175], v[24:27]
	v_mfma_f32_16x16x32_bf16 v[32:35], v[224:227], v[172:175], v[32:35]
	v_mfma_f32_16x16x32_bf16 v[8:11], v[228:231], v[172:175], v[8:11]
	v_mfma_f32_16x16x32_bf16 v[16:19], v[232:235], v[172:175], v[16:19]
	s_setprio 0
	s_waitcnt lgkmcnt(0)
	s_barrier
	ds_read_b128 v[144:147], v241
	ds_read_b128 v[176:179], v242 offset:18432
	ds_read_b128 v[180:183], v242 offset:20736
	ds_read_b128 v[148:151], v241 offset:2304
	ds_read_b128 v[184:187], v242 offset:23040
	ds_read_b128 v[152:155], v241 offset:4608
	ds_read_b128 v[216:219], v242 offset:25344
	ds_read_b128 v[156:159], v241 offset:6912
	s_setprio 1
	s_waitcnt lgkmcnt(6)
	v_mfma_f32_16x16x32_bf16 v[52:55], v[176:179], v[144:147], v[52:55]
	s_waitcnt vmcnt(15)
	ds_write_b128 v240, v[108:111]
	s_waitcnt lgkmcnt(6)
	v_mfma_f32_16x16x32_bf16 v[60:63], v[180:183], v[144:147], v[60:63]
	ds_read_b128 v[160:163], v241 offset:64
	s_waitcnt lgkmcnt(6)
	v_mfma_f32_16x16x32_bf16 v[56:59], v[176:179], v[148:151], v[56:59]
	ds_read_b128 v[220:223], v242 offset:18496
	s_waitcnt vmcnt(14)
	ds_write_b128 v240, v[112:115] offset:4608
	v_mfma_f32_16x16x32_bf16 v[64:67], v[180:183], v[148:151], v[64:67]
	ds_read_b128 v[224:227], v242 offset:20800
	s_waitcnt lgkmcnt(8)
	v_mfma_f32_16x16x32_bf16 v[36:39], v[184:187], v[144:147], v[36:39]
	ds_read_b128 v[164:167], v241 offset:2368
	s_waitcnt vmcnt(13)
	ds_write_b128 v240, v[116:119] offset:9216
	global_load_dwordx4 v[108:111], v[72:73], off offset:3456
	v_mfma_f32_16x16x32_bf16 v[40:43], v[184:187], v[148:151], v[40:43]
	ds_read_b128 v[228:231], v242 offset:23104
	s_waitcnt lgkmcnt(10)
	v_mfma_f32_16x16x32_bf16 v[20:23], v[176:179], v[152:155], v[20:23]
	ds_read_b128 v[168:171], v241 offset:4672
	v_mfma_f32_16x16x32_bf16 v[28:31], v[180:183], v[152:155], v[28:31]
	ds_read_b128 v[232:235], v242 offset:25408
	v_mfma_f32_16x16x32_bf16 v[4:7], v[184:187], v[152:155], v[4:7]
	ds_read_b128 v[172:175], v241 offset:6976
	s_waitcnt lgkmcnt(12)
	v_mfma_f32_16x16x32_bf16 v[44:47], v[216:219], v[144:147], v[44:47]
	v_mfma_f32_16x16x32_bf16 v[48:51], v[216:219], v[148:151], v[48:51]
	s_waitcnt vmcnt(13)
	ds_write_b128 v240, v[120:123] offset:13824
	global_load_dwordx4 v[112:115], v[74:75], off offset:3456
	v_mfma_f32_16x16x32_bf16 v[12:15], v[216:219], v[152:155], v[12:15]
	s_waitcnt lgkmcnt(12)
	v_mfma_f32_16x16x32_bf16 v[24:27], v[176:179], v[156:159], v[24:27]
	s_waitcnt vmcnt(13)
	ds_write_b128 v240, v[124:127] offset:18432
	global_load_dwordx4 v[116:119], v[106:107], off offset:3456
	v_mfma_f32_16x16x32_bf16 v[32:35], v[180:183], v[156:159], v[32:35]
	v_mfma_f32_16x16x32_bf16 v[8:11], v[184:187], v[156:159], v[8:11]
	v_mfma_f32_16x16x32_bf16 v[16:19], v[216:219], v[156:159], v[16:19]
	s_waitcnt lgkmcnt(10)
	v_mfma_f32_16x16x32_bf16 v[52:55], v[220:223], v[160:163], v[52:55]
	s_waitcnt lgkmcnt(8)
	v_mfma_f32_16x16x32_bf16 v[60:63], v[224:227], v[160:163], v[60:63]
	s_waitcnt lgkmcnt(7)
	v_mfma_f32_16x16x32_bf16 v[56:59], v[220:223], v[164:167], v[56:59]
	s_waitcnt vmcnt(13)
	ds_write_b128 v240, v[128:131] offset:23040
	global_load_dwordx4 v[120:123], v[188:189], off offset:3456
	v_mfma_f32_16x16x32_bf16 v[64:67], v[224:227], v[164:167], v[64:67]
	s_waitcnt lgkmcnt(6)
	v_mfma_f32_16x16x32_bf16 v[36:39], v[228:231], v[160:163], v[36:39]
	s_waitcnt vmcnt(13)
	ds_write_b128 v240, v[136:139] offset:27648
	global_load_dwordx4 v[124:127], v[104:105], off offset:3456
	v_mfma_f32_16x16x32_bf16 v[40:43], v[228:231], v[164:167], v[40:43]
	s_waitcnt lgkmcnt(6)
	v_mfma_f32_16x16x32_bf16 v[20:23], v[220:223], v[168:171], v[20:23]
	s_waitcnt vmcnt(13)
	ds_write_b128 v240, v[140:143] offset:32256
	global_load_dwordx4 v[128:131], v[214:215], off offset:3456
	v_mfma_f32_16x16x32_bf16 v[28:31], v[224:227], v[168:171], v[28:31]
	v_mfma_f32_16x16x32_bf16 v[4:7], v[228:231], v[168:171], v[4:7]
	global_load_dwordx4 v[136:139], v[236:237], off offset:3456
	s_waitcnt lgkmcnt(6)
	v_mfma_f32_16x16x32_bf16 v[44:47], v[232:235], v[160:163], v[44:47]
	v_mfma_f32_16x16x32_bf16 v[48:51], v[232:235], v[164:167], v[48:51]
	global_load_dwordx4 v[140:143], v[238:239], off offset:3456
	v_mfma_f32_16x16x32_bf16 v[12:15], v[232:235], v[168:171], v[12:15]
	s_waitcnt lgkmcnt(5)
	v_mfma_f32_16x16x32_bf16 v[24:27], v[220:223], v[172:175], v[24:27]
	v_mfma_f32_16x16x32_bf16 v[32:35], v[224:227], v[172:175], v[32:35]
	v_mfma_f32_16x16x32_bf16 v[8:11], v[228:231], v[172:175], v[8:11]
	v_mfma_f32_16x16x32_bf16 v[16:19], v[232:235], v[172:175], v[16:19]
	s_setprio 0
	s_waitcnt lgkmcnt(0)
	s_barrier
	ds_read_b128 v[144:147], v241 offset:36864
	ds_read_b128 v[176:179], v242 offset:55296
	ds_read_b128 v[180:183], v242 offset:57600
	ds_read_b128 v[148:151], v241 offset:39168
	ds_read_b128 v[184:187], v242 offset:59904
	ds_read_b128 v[152:155], v241 offset:41472
	ds_read_b128 v[216:219], v242 offset:62208
	ds_read_b128 v[156:159], v241 offset:43776
	s_setprio 1
	s_waitcnt lgkmcnt(6)
	v_mfma_f32_16x16x32_bf16 v[52:55], v[176:179], v[144:147], v[52:55]
	s_waitcnt vmcnt(15)
	ds_write_b128 v213, v[68:71]
	s_waitcnt lgkmcnt(6)
	v_mfma_f32_16x16x32_bf16 v[60:63], v[180:183], v[144:147], v[60:63]
	ds_read_b128 v[160:163], v241 offset:36928
	s_waitcnt lgkmcnt(6)
	v_mfma_f32_16x16x32_bf16 v[56:59], v[176:179], v[148:151], v[56:59]
	ds_read_b128 v[220:223], v242 offset:55360
	s_waitcnt vmcnt(14)
	ds_write_b128 v213, v[76:79] offset:4608
	v_mfma_f32_16x16x32_bf16 v[64:67], v[180:183], v[148:151], v[64:67]
	ds_read_b128 v[224:227], v242 offset:57664
	s_waitcnt lgkmcnt(8)
	v_mfma_f32_16x16x32_bf16 v[36:39], v[184:187], v[144:147], v[36:39]
	ds_read_b128 v[164:167], v241 offset:39232
	s_waitcnt vmcnt(13)
	ds_write_b128 v213, v[80:83] offset:9216
	global_load_dwordx4 v[68:71], v[72:73], off offset:3584
	v_mfma_f32_16x16x32_bf16 v[40:43], v[184:187], v[148:151], v[40:43]
	ds_read_b128 v[228:231], v242 offset:59968
	s_waitcnt lgkmcnt(10)
	v_mfma_f32_16x16x32_bf16 v[20:23], v[176:179], v[152:155], v[20:23]
	ds_read_b128 v[168:171], v241 offset:41536
	v_mfma_f32_16x16x32_bf16 v[28:31], v[180:183], v[152:155], v[28:31]
	ds_read_b128 v[232:235], v242 offset:62272
	v_mfma_f32_16x16x32_bf16 v[4:7], v[184:187], v[152:155], v[4:7]
	ds_read_b128 v[172:175], v241 offset:43840
	s_waitcnt lgkmcnt(12)
	v_mfma_f32_16x16x32_bf16 v[44:47], v[216:219], v[144:147], v[44:47]
	v_mfma_f32_16x16x32_bf16 v[48:51], v[216:219], v[148:151], v[48:51]
	s_waitcnt vmcnt(13)
	ds_write_b128 v213, v[84:87] offset:13824
	global_load_dwordx4 v[76:79], v[74:75], off offset:3584
	v_mfma_f32_16x16x32_bf16 v[12:15], v[216:219], v[152:155], v[12:15]
	s_waitcnt lgkmcnt(12)
	v_mfma_f32_16x16x32_bf16 v[24:27], v[176:179], v[156:159], v[24:27]
	s_waitcnt vmcnt(13)
	ds_write_b128 v213, v[88:91] offset:18432
	global_load_dwordx4 v[80:83], v[106:107], off offset:3584
	v_mfma_f32_16x16x32_bf16 v[32:35], v[180:183], v[156:159], v[32:35]
	v_mfma_f32_16x16x32_bf16 v[8:11], v[184:187], v[156:159], v[8:11]
	v_mfma_f32_16x16x32_bf16 v[16:19], v[216:219], v[156:159], v[16:19]
	s_waitcnt lgkmcnt(10)
	v_mfma_f32_16x16x32_bf16 v[52:55], v[220:223], v[160:163], v[52:55]
	s_waitcnt lgkmcnt(8)
	v_mfma_f32_16x16x32_bf16 v[60:63], v[224:227], v[160:163], v[60:63]
	s_waitcnt lgkmcnt(7)
	v_mfma_f32_16x16x32_bf16 v[56:59], v[220:223], v[164:167], v[56:59]
	s_waitcnt vmcnt(13)
	ds_write_b128 v213, v[92:95] offset:23040
	global_load_dwordx4 v[84:87], v[188:189], off offset:3584
	v_mfma_f32_16x16x32_bf16 v[64:67], v[224:227], v[164:167], v[64:67]
	s_waitcnt lgkmcnt(6)
	v_mfma_f32_16x16x32_bf16 v[36:39], v[228:231], v[160:163], v[36:39]
	s_waitcnt vmcnt(13)
	ds_write_b128 v213, v[96:99] offset:27648
	global_load_dwordx4 v[88:91], v[104:105], off offset:3584
	v_mfma_f32_16x16x32_bf16 v[40:43], v[228:231], v[164:167], v[40:43]
	s_waitcnt lgkmcnt(6)
	v_mfma_f32_16x16x32_bf16 v[20:23], v[220:223], v[168:171], v[20:23]
	s_waitcnt vmcnt(13)
	ds_write_b128 v213, v[100:103] offset:32256
	global_load_dwordx4 v[92:95], v[214:215], off offset:3584
	v_mfma_f32_16x16x32_bf16 v[28:31], v[224:227], v[168:171], v[28:31]
	v_mfma_f32_16x16x32_bf16 v[4:7], v[228:231], v[168:171], v[4:7]
	global_load_dwordx4 v[96:99], v[236:237], off offset:3584
	s_waitcnt lgkmcnt(6)
	v_mfma_f32_16x16x32_bf16 v[44:47], v[232:235], v[160:163], v[44:47]
	v_mfma_f32_16x16x32_bf16 v[48:51], v[232:235], v[164:167], v[48:51]
	global_load_dwordx4 v[100:103], v[238:239], off offset:3584
	v_mfma_f32_16x16x32_bf16 v[12:15], v[232:235], v[168:171], v[12:15]
	s_waitcnt lgkmcnt(5)
	v_mfma_f32_16x16x32_bf16 v[24:27], v[220:223], v[172:175], v[24:27]
	v_mfma_f32_16x16x32_bf16 v[32:35], v[224:227], v[172:175], v[32:35]
	v_mfma_f32_16x16x32_bf16 v[8:11], v[228:231], v[172:175], v[8:11]
	v_mfma_f32_16x16x32_bf16 v[16:19], v[232:235], v[172:175], v[16:19]
	s_setprio 0
	s_waitcnt lgkmcnt(0)
	s_barrier
	ds_read_b128 v[144:147], v241
	ds_read_b128 v[176:179], v242 offset:18432
	ds_read_b128 v[180:183], v242 offset:20736
	ds_read_b128 v[148:151], v241 offset:2304
	ds_read_b128 v[184:187], v242 offset:23040
	ds_read_b128 v[152:155], v241 offset:4608
	ds_read_b128 v[216:219], v242 offset:25344
	ds_read_b128 v[156:159], v241 offset:6912
	s_setprio 1
	s_waitcnt lgkmcnt(6)
	v_mfma_f32_16x16x32_bf16 v[52:55], v[176:179], v[144:147], v[52:55]
	s_waitcnt vmcnt(15)
	ds_write_b128 v240, v[108:111]
	s_waitcnt lgkmcnt(6)
	v_mfma_f32_16x16x32_bf16 v[60:63], v[180:183], v[144:147], v[60:63]
	ds_read_b128 v[160:163], v241 offset:64
	s_waitcnt lgkmcnt(6)
	v_mfma_f32_16x16x32_bf16 v[56:59], v[176:179], v[148:151], v[56:59]
	ds_read_b128 v[220:223], v242 offset:18496
	s_waitcnt vmcnt(14)
	ds_write_b128 v240, v[112:115] offset:4608
	v_mfma_f32_16x16x32_bf16 v[64:67], v[180:183], v[148:151], v[64:67]
	ds_read_b128 v[224:227], v242 offset:20800
	s_waitcnt lgkmcnt(8)
	v_mfma_f32_16x16x32_bf16 v[36:39], v[184:187], v[144:147], v[36:39]
	ds_read_b128 v[164:167], v241 offset:2368
	s_waitcnt vmcnt(13)
	ds_write_b128 v240, v[116:119] offset:9216
	global_load_dwordx4 v[108:111], v[72:73], off offset:3712
	v_mfma_f32_16x16x32_bf16 v[40:43], v[184:187], v[148:151], v[40:43]
	ds_read_b128 v[228:231], v242 offset:23104
	s_waitcnt lgkmcnt(10)
	v_mfma_f32_16x16x32_bf16 v[20:23], v[176:179], v[152:155], v[20:23]
	ds_read_b128 v[168:171], v241 offset:4672
	v_mfma_f32_16x16x32_bf16 v[28:31], v[180:183], v[152:155], v[28:31]
	ds_read_b128 v[232:235], v242 offset:25408
	v_mfma_f32_16x16x32_bf16 v[4:7], v[184:187], v[152:155], v[4:7]
	ds_read_b128 v[172:175], v241 offset:6976
	s_waitcnt lgkmcnt(12)
	v_mfma_f32_16x16x32_bf16 v[44:47], v[216:219], v[144:147], v[44:47]
	v_mfma_f32_16x16x32_bf16 v[48:51], v[216:219], v[148:151], v[48:51]
	s_waitcnt vmcnt(13)
	ds_write_b128 v240, v[120:123] offset:13824
	global_load_dwordx4 v[112:115], v[74:75], off offset:3712
	v_mfma_f32_16x16x32_bf16 v[12:15], v[216:219], v[152:155], v[12:15]
	s_waitcnt lgkmcnt(12)
	v_mfma_f32_16x16x32_bf16 v[24:27], v[176:179], v[156:159], v[24:27]
	s_waitcnt vmcnt(13)
	ds_write_b128 v240, v[124:127] offset:18432
	global_load_dwordx4 v[116:119], v[106:107], off offset:3712
	v_mfma_f32_16x16x32_bf16 v[32:35], v[180:183], v[156:159], v[32:35]
	v_mfma_f32_16x16x32_bf16 v[8:11], v[184:187], v[156:159], v[8:11]
	v_mfma_f32_16x16x32_bf16 v[16:19], v[216:219], v[156:159], v[16:19]
	s_waitcnt lgkmcnt(10)
	v_mfma_f32_16x16x32_bf16 v[52:55], v[220:223], v[160:163], v[52:55]
	s_waitcnt lgkmcnt(8)
	v_mfma_f32_16x16x32_bf16 v[60:63], v[224:227], v[160:163], v[60:63]
	s_waitcnt lgkmcnt(7)
	v_mfma_f32_16x16x32_bf16 v[56:59], v[220:223], v[164:167], v[56:59]
	s_waitcnt vmcnt(13)
	ds_write_b128 v240, v[128:131] offset:23040
	global_load_dwordx4 v[120:123], v[188:189], off offset:3712
	v_mfma_f32_16x16x32_bf16 v[64:67], v[224:227], v[164:167], v[64:67]
	s_waitcnt lgkmcnt(6)
	v_mfma_f32_16x16x32_bf16 v[36:39], v[228:231], v[160:163], v[36:39]
	s_waitcnt vmcnt(13)
	ds_write_b128 v240, v[136:139] offset:27648
	global_load_dwordx4 v[124:127], v[104:105], off offset:3712
	v_mfma_f32_16x16x32_bf16 v[40:43], v[228:231], v[164:167], v[40:43]
	s_waitcnt lgkmcnt(6)
	v_mfma_f32_16x16x32_bf16 v[20:23], v[220:223], v[168:171], v[20:23]
	s_waitcnt vmcnt(13)
	ds_write_b128 v240, v[140:143] offset:32256
	global_load_dwordx4 v[128:131], v[214:215], off offset:3712
	v_mfma_f32_16x16x32_bf16 v[28:31], v[224:227], v[168:171], v[28:31]
	v_mfma_f32_16x16x32_bf16 v[4:7], v[228:231], v[168:171], v[4:7]
	global_load_dwordx4 v[136:139], v[236:237], off offset:3712
	s_waitcnt lgkmcnt(6)
	v_mfma_f32_16x16x32_bf16 v[44:47], v[232:235], v[160:163], v[44:47]
	v_mfma_f32_16x16x32_bf16 v[48:51], v[232:235], v[164:167], v[48:51]
	global_load_dwordx4 v[140:143], v[238:239], off offset:3712
	v_mfma_f32_16x16x32_bf16 v[12:15], v[232:235], v[168:171], v[12:15]
	s_waitcnt lgkmcnt(5)
	v_mfma_f32_16x16x32_bf16 v[24:27], v[220:223], v[172:175], v[24:27]
	v_mfma_f32_16x16x32_bf16 v[32:35], v[224:227], v[172:175], v[32:35]
	v_mfma_f32_16x16x32_bf16 v[8:11], v[228:231], v[172:175], v[8:11]
	v_mfma_f32_16x16x32_bf16 v[16:19], v[232:235], v[172:175], v[16:19]
	s_setprio 0
	s_waitcnt lgkmcnt(0)
	s_barrier
	ds_read_b128 v[144:147], v241 offset:36864
	ds_read_b128 v[176:179], v242 offset:55296
	ds_read_b128 v[180:183], v242 offset:57600
	ds_read_b128 v[148:151], v241 offset:39168
	ds_read_b128 v[184:187], v242 offset:59904
	ds_read_b128 v[152:155], v241 offset:41472
	ds_read_b128 v[216:219], v242 offset:62208
	ds_read_b128 v[156:159], v241 offset:43776
	s_setprio 1
	s_waitcnt lgkmcnt(6)
	v_mfma_f32_16x16x32_bf16 v[52:55], v[176:179], v[144:147], v[52:55]
	s_waitcnt vmcnt(15)
	ds_write_b128 v213, v[68:71]
	s_waitcnt lgkmcnt(6)
	v_mfma_f32_16x16x32_bf16 v[60:63], v[180:183], v[144:147], v[60:63]
	ds_read_b128 v[160:163], v241 offset:36928
	s_waitcnt lgkmcnt(6)
	v_mfma_f32_16x16x32_bf16 v[56:59], v[176:179], v[148:151], v[56:59]
	ds_read_b128 v[220:223], v242 offset:55360
	s_waitcnt vmcnt(14)
	ds_write_b128 v213, v[76:79] offset:4608
	v_mfma_f32_16x16x32_bf16 v[64:67], v[180:183], v[148:151], v[64:67]
	ds_read_b128 v[224:227], v242 offset:57664
	s_waitcnt lgkmcnt(8)
	v_mfma_f32_16x16x32_bf16 v[36:39], v[184:187], v[144:147], v[36:39]
	ds_read_b128 v[164:167], v241 offset:39232
	s_waitcnt vmcnt(13)
	ds_write_b128 v213, v[80:83] offset:9216
	global_load_dwordx4 v[68:71], v[72:73], off offset:3840
	v_mfma_f32_16x16x32_bf16 v[40:43], v[184:187], v[148:151], v[40:43]
	ds_read_b128 v[228:231], v242 offset:59968
	s_waitcnt lgkmcnt(10)
	v_mfma_f32_16x16x32_bf16 v[20:23], v[176:179], v[152:155], v[20:23]
	ds_read_b128 v[168:171], v241 offset:41536
	v_mfma_f32_16x16x32_bf16 v[28:31], v[180:183], v[152:155], v[28:31]
	ds_read_b128 v[232:235], v242 offset:62272
	v_mfma_f32_16x16x32_bf16 v[4:7], v[184:187], v[152:155], v[4:7]
	ds_read_b128 v[172:175], v241 offset:43840
	s_waitcnt lgkmcnt(12)
	v_mfma_f32_16x16x32_bf16 v[44:47], v[216:219], v[144:147], v[44:47]
	v_mfma_f32_16x16x32_bf16 v[48:51], v[216:219], v[148:151], v[48:51]
	s_waitcnt vmcnt(13)
	ds_write_b128 v213, v[84:87] offset:13824
	global_load_dwordx4 v[76:79], v[74:75], off offset:3840
	v_mfma_f32_16x16x32_bf16 v[12:15], v[216:219], v[152:155], v[12:15]
	s_waitcnt lgkmcnt(12)
	v_mfma_f32_16x16x32_bf16 v[24:27], v[176:179], v[156:159], v[24:27]
	s_waitcnt vmcnt(13)
	ds_write_b128 v213, v[88:91] offset:18432
	global_load_dwordx4 v[80:83], v[106:107], off offset:3840
	v_mfma_f32_16x16x32_bf16 v[32:35], v[180:183], v[156:159], v[32:35]
	v_mfma_f32_16x16x32_bf16 v[8:11], v[184:187], v[156:159], v[8:11]
	v_mfma_f32_16x16x32_bf16 v[16:19], v[216:219], v[156:159], v[16:19]
	s_waitcnt lgkmcnt(10)
	v_mfma_f32_16x16x32_bf16 v[52:55], v[220:223], v[160:163], v[52:55]
	s_waitcnt lgkmcnt(8)
	v_mfma_f32_16x16x32_bf16 v[60:63], v[224:227], v[160:163], v[60:63]
	s_waitcnt lgkmcnt(7)
	v_mfma_f32_16x16x32_bf16 v[56:59], v[220:223], v[164:167], v[56:59]
	s_waitcnt vmcnt(13)
	ds_write_b128 v213, v[92:95] offset:23040
	global_load_dwordx4 v[84:87], v[188:189], off offset:3840
	v_mfma_f32_16x16x32_bf16 v[64:67], v[224:227], v[164:167], v[64:67]
	s_waitcnt lgkmcnt(6)
	v_mfma_f32_16x16x32_bf16 v[36:39], v[228:231], v[160:163], v[36:39]
	s_waitcnt vmcnt(13)
	ds_write_b128 v213, v[96:99] offset:27648
	global_load_dwordx4 v[88:91], v[104:105], off offset:3840
	v_mfma_f32_16x16x32_bf16 v[40:43], v[228:231], v[164:167], v[40:43]
	s_waitcnt lgkmcnt(6)
	v_mfma_f32_16x16x32_bf16 v[20:23], v[220:223], v[168:171], v[20:23]
	s_waitcnt vmcnt(13)
	ds_write_b128 v213, v[100:103] offset:32256
	global_load_dwordx4 v[92:95], v[214:215], off offset:3840
	v_mfma_f32_16x16x32_bf16 v[28:31], v[224:227], v[168:171], v[28:31]
	v_mfma_f32_16x16x32_bf16 v[4:7], v[228:231], v[168:171], v[4:7]
	global_load_dwordx4 v[96:99], v[236:237], off offset:3840
	s_waitcnt lgkmcnt(6)
	v_mfma_f32_16x16x32_bf16 v[44:47], v[232:235], v[160:163], v[44:47]
	v_mfma_f32_16x16x32_bf16 v[48:51], v[232:235], v[164:167], v[48:51]
	global_load_dwordx4 v[100:103], v[238:239], off offset:3840
	v_mfma_f32_16x16x32_bf16 v[12:15], v[232:235], v[168:171], v[12:15]
	s_waitcnt lgkmcnt(5)
	v_mfma_f32_16x16x32_bf16 v[24:27], v[220:223], v[172:175], v[24:27]
	v_mfma_f32_16x16x32_bf16 v[32:35], v[224:227], v[172:175], v[32:35]
	v_mfma_f32_16x16x32_bf16 v[8:11], v[228:231], v[172:175], v[8:11]
	v_mfma_f32_16x16x32_bf16 v[16:19], v[232:235], v[172:175], v[16:19]
	s_setprio 0
	s_waitcnt lgkmcnt(0)
	s_barrier
	ds_read_b128 v[144:147], v241
	ds_read_b128 v[176:179], v242 offset:18432
	ds_read_b128 v[180:183], v242 offset:20736
	ds_read_b128 v[148:151], v241 offset:2304
	ds_read_b128 v[184:187], v242 offset:23040
	ds_read_b128 v[152:155], v241 offset:4608
	ds_read_b128 v[216:219], v242 offset:25344
	ds_read_b128 v[156:159], v241 offset:6912
	s_setprio 1
	s_waitcnt lgkmcnt(6)
	v_mfma_f32_16x16x32_bf16 v[52:55], v[176:179], v[144:147], v[52:55]
	s_waitcnt vmcnt(15)
	ds_write_b128 v240, v[108:111]
	s_waitcnt lgkmcnt(6)
	v_mfma_f32_16x16x32_bf16 v[60:63], v[180:183], v[144:147], v[60:63]
	ds_read_b128 v[160:163], v241 offset:64
	s_waitcnt lgkmcnt(6)
	v_mfma_f32_16x16x32_bf16 v[56:59], v[176:179], v[148:151], v[56:59]
	ds_read_b128 v[220:223], v242 offset:18496
	s_waitcnt vmcnt(14)
	ds_write_b128 v240, v[112:115] offset:4608
	v_mfma_f32_16x16x32_bf16 v[64:67], v[180:183], v[148:151], v[64:67]
	ds_read_b128 v[224:227], v242 offset:20800
	s_waitcnt lgkmcnt(8)
	v_mfma_f32_16x16x32_bf16 v[36:39], v[184:187], v[144:147], v[36:39]
	ds_read_b128 v[164:167], v241 offset:2368
	s_waitcnt vmcnt(13)
	ds_write_b128 v240, v[116:119] offset:9216
	global_load_dwordx4 v[108:111], v[72:73], off offset:3968
	v_mfma_f32_16x16x32_bf16 v[40:43], v[184:187], v[148:151], v[40:43]
	ds_read_b128 v[228:231], v242 offset:23104
	s_waitcnt lgkmcnt(10)
	v_mfma_f32_16x16x32_bf16 v[20:23], v[176:179], v[152:155], v[20:23]
	ds_read_b128 v[168:171], v241 offset:4672
	v_mfma_f32_16x16x32_bf16 v[28:31], v[180:183], v[152:155], v[28:31]
	ds_read_b128 v[232:235], v242 offset:25408
	v_mfma_f32_16x16x32_bf16 v[4:7], v[184:187], v[152:155], v[4:7]
	ds_read_b128 v[172:175], v241 offset:6976
	s_waitcnt lgkmcnt(12)
	v_mfma_f32_16x16x32_bf16 v[44:47], v[216:219], v[144:147], v[44:47]
	v_mfma_f32_16x16x32_bf16 v[48:51], v[216:219], v[148:151], v[48:51]
	s_waitcnt vmcnt(13)
	ds_write_b128 v240, v[120:123] offset:13824
	global_load_dwordx4 v[112:115], v[74:75], off offset:3968
	v_mfma_f32_16x16x32_bf16 v[12:15], v[216:219], v[152:155], v[12:15]
	s_waitcnt lgkmcnt(12)
	v_mfma_f32_16x16x32_bf16 v[24:27], v[176:179], v[156:159], v[24:27]
	s_waitcnt vmcnt(13)
	ds_write_b128 v240, v[124:127] offset:18432
	global_load_dwordx4 v[116:119], v[106:107], off offset:3968
	v_mfma_f32_16x16x32_bf16 v[32:35], v[180:183], v[156:159], v[32:35]
	v_mfma_f32_16x16x32_bf16 v[8:11], v[184:187], v[156:159], v[8:11]
	v_mfma_f32_16x16x32_bf16 v[16:19], v[216:219], v[156:159], v[16:19]
	s_waitcnt lgkmcnt(10)
	v_mfma_f32_16x16x32_bf16 v[52:55], v[220:223], v[160:163], v[52:55]
	s_waitcnt lgkmcnt(8)
	v_mfma_f32_16x16x32_bf16 v[60:63], v[224:227], v[160:163], v[60:63]
	s_waitcnt lgkmcnt(7)
	v_mfma_f32_16x16x32_bf16 v[56:59], v[220:223], v[164:167], v[56:59]
	s_waitcnt vmcnt(13)
	ds_write_b128 v240, v[128:131] offset:23040
	global_load_dwordx4 v[120:123], v[188:189], off offset:3968
	v_mfma_f32_16x16x32_bf16 v[64:67], v[224:227], v[164:167], v[64:67]
	s_waitcnt lgkmcnt(6)
	v_mfma_f32_16x16x32_bf16 v[36:39], v[228:231], v[160:163], v[36:39]
	s_waitcnt vmcnt(13)
	ds_write_b128 v240, v[136:139] offset:27648
	global_load_dwordx4 v[124:127], v[104:105], off offset:3968
	v_mfma_f32_16x16x32_bf16 v[40:43], v[228:231], v[164:167], v[40:43]
	s_waitcnt lgkmcnt(6)
	v_mfma_f32_16x16x32_bf16 v[20:23], v[220:223], v[168:171], v[20:23]
	s_waitcnt vmcnt(13)
	ds_write_b128 v240, v[140:143] offset:32256
	global_load_dwordx4 v[128:131], v[214:215], off offset:3968
	v_mfma_f32_16x16x32_bf16 v[28:31], v[224:227], v[168:171], v[28:31]
	v_mfma_f32_16x16x32_bf16 v[4:7], v[228:231], v[168:171], v[4:7]
	global_load_dwordx4 v[136:139], v[236:237], off offset:3968
	s_waitcnt lgkmcnt(6)
	v_mfma_f32_16x16x32_bf16 v[44:47], v[232:235], v[160:163], v[44:47]
	v_mfma_f32_16x16x32_bf16 v[48:51], v[232:235], v[164:167], v[48:51]
	global_load_dwordx4 v[140:143], v[238:239], off offset:3968
	v_mfma_f32_16x16x32_bf16 v[12:15], v[232:235], v[168:171], v[12:15]
	s_waitcnt lgkmcnt(5)
	v_mfma_f32_16x16x32_bf16 v[24:27], v[220:223], v[172:175], v[24:27]
	v_mfma_f32_16x16x32_bf16 v[32:35], v[224:227], v[172:175], v[32:35]
	v_mfma_f32_16x16x32_bf16 v[8:11], v[228:231], v[172:175], v[8:11]
	v_mfma_f32_16x16x32_bf16 v[16:19], v[232:235], v[172:175], v[16:19]
	s_setprio 0
	s_waitcnt lgkmcnt(0)
	s_barrier
	ds_read_b128 v[144:147], v241 offset:36864
	ds_read_b128 v[176:179], v242 offset:55296
	ds_read_b128 v[180:183], v242 offset:57600
	ds_read_b128 v[148:151], v241 offset:39168
	ds_read_b128 v[184:187], v242 offset:59904
	ds_read_b128 v[152:155], v241 offset:41472
	ds_read_b128 v[216:219], v242 offset:62208
	ds_read_b128 v[156:159], v241 offset:43776
	s_setprio 1
	s_waitcnt lgkmcnt(6)
	v_mfma_f32_16x16x32_bf16 v[52:55], v[176:179], v[144:147], v[52:55]
	s_waitcnt vmcnt(15)
	ds_write_b128 v213, v[68:71]
	s_waitcnt lgkmcnt(6)
	v_mfma_f32_16x16x32_bf16 v[60:63], v[180:183], v[144:147], v[60:63]
	ds_read_b128 v[160:163], v241 offset:36928
	s_waitcnt lgkmcnt(6)
	v_mfma_f32_16x16x32_bf16 v[56:59], v[176:179], v[148:151], v[56:59]
	ds_read_b128 v[220:223], v242 offset:55360
	s_waitcnt vmcnt(14)
	ds_write_b128 v213, v[76:79] offset:4608
	v_mfma_f32_16x16x32_bf16 v[64:67], v[180:183], v[148:151], v[64:67]
	ds_read_b128 v[224:227], v242 offset:57664
	s_waitcnt lgkmcnt(8)
	v_mfma_f32_16x16x32_bf16 v[36:39], v[184:187], v[144:147], v[36:39]
	ds_read_b128 v[164:167], v241 offset:39232
	s_waitcnt vmcnt(13)
	ds_write_b128 v213, v[80:83] offset:9216
	v_add_co_u32_e32 v72, vcc, 0x1000, v72
	s_nop 1
	v_addc_co_u32_e32 v73, vcc, 0, v73, vcc
	v_add_co_u32_e32 v74, vcc, 0x1000, v74
	s_nop 1
	v_addc_co_u32_e32 v75, vcc, 0, v75, vcc
	v_add_co_u32_e32 v106, vcc, 0x1000, v106
	s_nop 1
	v_addc_co_u32_e32 v107, vcc, 0, v107, vcc
	v_add_co_u32_e32 v188, vcc, 0x1000, v188
	s_nop 1
	v_addc_co_u32_e32 v189, vcc, 0, v189, vcc
	v_add_co_u32_e32 v104, vcc, 0x1000, v104
	s_nop 1
	v_addc_co_u32_e32 v105, vcc, 0, v105, vcc
	v_add_co_u32_e32 v214, vcc, 0x1000, v214
	s_nop 1
	v_addc_co_u32_e32 v215, vcc, 0, v215, vcc
	v_add_co_u32_e32 v236, vcc, 0x1000, v236
	s_nop 1
	v_addc_co_u32_e32 v237, vcc, 0, v237, vcc
	v_add_co_u32_e32 v238, vcc, 0x1000, v238
	s_nop 1
	v_addc_co_u32_e32 v239, vcc, 0, v239, vcc
	global_load_dwordx4 v[68:71], v[72:73], off
	v_mfma_f32_16x16x32_bf16 v[40:43], v[184:187], v[148:151], v[40:43]
	ds_read_b128 v[228:231], v242 offset:59968
	s_waitcnt lgkmcnt(10)
	v_mfma_f32_16x16x32_bf16 v[20:23], v[176:179], v[152:155], v[20:23]
	ds_read_b128 v[168:171], v241 offset:41536
	v_mfma_f32_16x16x32_bf16 v[28:31], v[180:183], v[152:155], v[28:31]
	ds_read_b128 v[232:235], v242 offset:62272
	v_mfma_f32_16x16x32_bf16 v[4:7], v[184:187], v[152:155], v[4:7]
	ds_read_b128 v[172:175], v241 offset:43840
	s_waitcnt lgkmcnt(12)
	v_mfma_f32_16x16x32_bf16 v[44:47], v[216:219], v[144:147], v[44:47]
	v_mfma_f32_16x16x32_bf16 v[48:51], v[216:219], v[148:151], v[48:51]
	s_waitcnt vmcnt(13)
	ds_write_b128 v213, v[84:87] offset:13824
	global_load_dwordx4 v[76:79], v[74:75], off
	v_mfma_f32_16x16x32_bf16 v[12:15], v[216:219], v[152:155], v[12:15]
	s_waitcnt lgkmcnt(12)
	v_mfma_f32_16x16x32_bf16 v[24:27], v[176:179], v[156:159], v[24:27]
	s_waitcnt vmcnt(13)
	ds_write_b128 v213, v[88:91] offset:18432
	global_load_dwordx4 v[80:83], v[106:107], off
	v_mfma_f32_16x16x32_bf16 v[32:35], v[180:183], v[156:159], v[32:35]
	v_mfma_f32_16x16x32_bf16 v[8:11], v[184:187], v[156:159], v[8:11]
	v_mfma_f32_16x16x32_bf16 v[16:19], v[216:219], v[156:159], v[16:19]
	s_waitcnt lgkmcnt(10)
	v_mfma_f32_16x16x32_bf16 v[52:55], v[220:223], v[160:163], v[52:55]
	s_waitcnt lgkmcnt(8)
	v_mfma_f32_16x16x32_bf16 v[60:63], v[224:227], v[160:163], v[60:63]
	s_waitcnt lgkmcnt(7)
	v_mfma_f32_16x16x32_bf16 v[56:59], v[220:223], v[164:167], v[56:59]
	s_waitcnt vmcnt(13)
	ds_write_b128 v213, v[92:95] offset:23040
	global_load_dwordx4 v[84:87], v[188:189], off
	v_mfma_f32_16x16x32_bf16 v[64:67], v[224:227], v[164:167], v[64:67]
	s_waitcnt lgkmcnt(6)
	v_mfma_f32_16x16x32_bf16 v[36:39], v[228:231], v[160:163], v[36:39]
	s_waitcnt vmcnt(13)
	ds_write_b128 v213, v[96:99] offset:27648
	global_load_dwordx4 v[88:91], v[104:105], off
	v_mfma_f32_16x16x32_bf16 v[40:43], v[228:231], v[164:167], v[40:43]
	s_waitcnt lgkmcnt(6)
	v_mfma_f32_16x16x32_bf16 v[20:23], v[220:223], v[168:171], v[20:23]
	s_waitcnt vmcnt(13)
	ds_write_b128 v213, v[100:103] offset:32256
	global_load_dwordx4 v[92:95], v[214:215], off
	v_mfma_f32_16x16x32_bf16 v[28:31], v[224:227], v[168:171], v[28:31]
	v_mfma_f32_16x16x32_bf16 v[4:7], v[228:231], v[168:171], v[4:7]
	global_load_dwordx4 v[96:99], v[236:237], off
	s_waitcnt lgkmcnt(6)
	v_mfma_f32_16x16x32_bf16 v[44:47], v[232:235], v[160:163], v[44:47]
	v_mfma_f32_16x16x32_bf16 v[48:51], v[232:235], v[164:167], v[48:51]
	global_load_dwordx4 v[100:103], v[238:239], off
	v_mfma_f32_16x16x32_bf16 v[12:15], v[232:235], v[168:171], v[12:15]
	s_waitcnt lgkmcnt(5)
	v_mfma_f32_16x16x32_bf16 v[24:27], v[220:223], v[172:175], v[24:27]
	v_mfma_f32_16x16x32_bf16 v[32:35], v[224:227], v[172:175], v[32:35]
	v_mfma_f32_16x16x32_bf16 v[8:11], v[228:231], v[172:175], v[8:11]
	v_mfma_f32_16x16x32_bf16 v[16:19], v[232:235], v[172:175], v[16:19]
	s_setprio 0
	s_waitcnt lgkmcnt(0)
	s_barrier
	ds_read_b128 v[144:147], v241
	ds_read_b128 v[176:179], v242 offset:18432
	ds_read_b128 v[180:183], v242 offset:20736
	ds_read_b128 v[148:151], v241 offset:2304
	ds_read_b128 v[184:187], v242 offset:23040
	ds_read_b128 v[152:155], v241 offset:4608
	ds_read_b128 v[216:219], v242 offset:25344
	ds_read_b128 v[156:159], v241 offset:6912
	s_setprio 1
	s_waitcnt lgkmcnt(6)
	v_mfma_f32_16x16x32_bf16 v[52:55], v[176:179], v[144:147], v[52:55]
	s_waitcnt vmcnt(15)
	ds_write_b128 v240, v[108:111]
	s_waitcnt lgkmcnt(6)
	v_mfma_f32_16x16x32_bf16 v[60:63], v[180:183], v[144:147], v[60:63]
	ds_read_b128 v[160:163], v241 offset:64
	s_waitcnt lgkmcnt(6)
	v_mfma_f32_16x16x32_bf16 v[56:59], v[176:179], v[148:151], v[56:59]
	ds_read_b128 v[220:223], v242 offset:18496
	s_waitcnt vmcnt(14)
	ds_write_b128 v240, v[112:115] offset:4608
	v_mfma_f32_16x16x32_bf16 v[64:67], v[180:183], v[148:151], v[64:67]
	ds_read_b128 v[224:227], v242 offset:20800
	s_waitcnt lgkmcnt(8)
	v_mfma_f32_16x16x32_bf16 v[36:39], v[184:187], v[144:147], v[36:39]
	ds_read_b128 v[164:167], v241 offset:2368
	s_waitcnt vmcnt(13)
	ds_write_b128 v240, v[116:119] offset:9216
	global_load_dwordx4 v[108:111], v[72:73], off offset:128
	v_mfma_f32_16x16x32_bf16 v[40:43], v[184:187], v[148:151], v[40:43]
	ds_read_b128 v[228:231], v242 offset:23104
	s_waitcnt lgkmcnt(10)
	v_mfma_f32_16x16x32_bf16 v[20:23], v[176:179], v[152:155], v[20:23]
	ds_read_b128 v[168:171], v241 offset:4672
	v_mfma_f32_16x16x32_bf16 v[28:31], v[180:183], v[152:155], v[28:31]
	ds_read_b128 v[232:235], v242 offset:25408
	v_mfma_f32_16x16x32_bf16 v[4:7], v[184:187], v[152:155], v[4:7]
	ds_read_b128 v[172:175], v241 offset:6976
	s_waitcnt lgkmcnt(12)
	v_mfma_f32_16x16x32_bf16 v[44:47], v[216:219], v[144:147], v[44:47]
	v_mfma_f32_16x16x32_bf16 v[48:51], v[216:219], v[148:151], v[48:51]
	s_waitcnt vmcnt(13)
	ds_write_b128 v240, v[120:123] offset:13824
	global_load_dwordx4 v[112:115], v[74:75], off offset:128
	v_mfma_f32_16x16x32_bf16 v[12:15], v[216:219], v[152:155], v[12:15]
	s_waitcnt lgkmcnt(12)
	v_mfma_f32_16x16x32_bf16 v[24:27], v[176:179], v[156:159], v[24:27]
	s_waitcnt vmcnt(13)
	ds_write_b128 v240, v[124:127] offset:18432
	global_load_dwordx4 v[116:119], v[106:107], off offset:128
	v_mfma_f32_16x16x32_bf16 v[32:35], v[180:183], v[156:159], v[32:35]
	v_mfma_f32_16x16x32_bf16 v[8:11], v[184:187], v[156:159], v[8:11]
	v_mfma_f32_16x16x32_bf16 v[16:19], v[216:219], v[156:159], v[16:19]
	s_waitcnt lgkmcnt(10)
	v_mfma_f32_16x16x32_bf16 v[52:55], v[220:223], v[160:163], v[52:55]
	s_waitcnt lgkmcnt(8)
	v_mfma_f32_16x16x32_bf16 v[60:63], v[224:227], v[160:163], v[60:63]
	s_waitcnt lgkmcnt(7)
	v_mfma_f32_16x16x32_bf16 v[56:59], v[220:223], v[164:167], v[56:59]
	s_waitcnt vmcnt(13)
	ds_write_b128 v240, v[128:131] offset:23040
	global_load_dwordx4 v[120:123], v[188:189], off offset:128
	v_mfma_f32_16x16x32_bf16 v[64:67], v[224:227], v[164:167], v[64:67]
	s_waitcnt lgkmcnt(6)
	v_mfma_f32_16x16x32_bf16 v[36:39], v[228:231], v[160:163], v[36:39]
	s_waitcnt vmcnt(13)
	ds_write_b128 v240, v[136:139] offset:27648
	global_load_dwordx4 v[124:127], v[104:105], off offset:128
	v_mfma_f32_16x16x32_bf16 v[40:43], v[228:231], v[164:167], v[40:43]
	s_waitcnt lgkmcnt(6)
	v_mfma_f32_16x16x32_bf16 v[20:23], v[220:223], v[168:171], v[20:23]
	s_waitcnt vmcnt(13)
	ds_write_b128 v240, v[140:143] offset:32256
	global_load_dwordx4 v[128:131], v[214:215], off offset:128
	v_mfma_f32_16x16x32_bf16 v[28:31], v[224:227], v[168:171], v[28:31]
	v_mfma_f32_16x16x32_bf16 v[4:7], v[228:231], v[168:171], v[4:7]
	global_load_dwordx4 v[136:139], v[236:237], off offset:128
	s_waitcnt lgkmcnt(6)
	v_mfma_f32_16x16x32_bf16 v[44:47], v[232:235], v[160:163], v[44:47]
	v_mfma_f32_16x16x32_bf16 v[48:51], v[232:235], v[164:167], v[48:51]
	global_load_dwordx4 v[140:143], v[238:239], off offset:128
	v_mfma_f32_16x16x32_bf16 v[12:15], v[232:235], v[168:171], v[12:15]
	s_waitcnt lgkmcnt(5)
	v_mfma_f32_16x16x32_bf16 v[24:27], v[220:223], v[172:175], v[24:27]
	v_mfma_f32_16x16x32_bf16 v[32:35], v[224:227], v[172:175], v[32:35]
	v_mfma_f32_16x16x32_bf16 v[8:11], v[228:231], v[172:175], v[8:11]
	v_mfma_f32_16x16x32_bf16 v[16:19], v[232:235], v[172:175], v[16:19]
	s_setprio 0
	s_waitcnt lgkmcnt(0)
	s_barrier
	ds_read_b128 v[144:147], v241 offset:36864
	ds_read_b128 v[176:179], v242 offset:55296
	ds_read_b128 v[180:183], v242 offset:57600
	ds_read_b128 v[148:151], v241 offset:39168
	ds_read_b128 v[184:187], v242 offset:59904
	ds_read_b128 v[152:155], v241 offset:41472
	ds_read_b128 v[216:219], v242 offset:62208
	ds_read_b128 v[156:159], v241 offset:43776
	s_setprio 1
	s_waitcnt lgkmcnt(6)
	v_mfma_f32_16x16x32_bf16 v[52:55], v[176:179], v[144:147], v[52:55]
	s_waitcnt vmcnt(15)
	ds_write_b128 v213, v[68:71]
	s_waitcnt lgkmcnt(6)
	v_mfma_f32_16x16x32_bf16 v[60:63], v[180:183], v[144:147], v[60:63]
	ds_read_b128 v[160:163], v241 offset:36928
	s_waitcnt lgkmcnt(6)
	v_mfma_f32_16x16x32_bf16 v[56:59], v[176:179], v[148:151], v[56:59]
	ds_read_b128 v[220:223], v242 offset:55360
	s_waitcnt vmcnt(14)
	ds_write_b128 v213, v[76:79] offset:4608
	v_mfma_f32_16x16x32_bf16 v[64:67], v[180:183], v[148:151], v[64:67]
	ds_read_b128 v[224:227], v242 offset:57664
	s_waitcnt lgkmcnt(8)
	v_mfma_f32_16x16x32_bf16 v[36:39], v[184:187], v[144:147], v[36:39]
	ds_read_b128 v[164:167], v241 offset:39232
	s_waitcnt vmcnt(13)
	ds_write_b128 v213, v[80:83] offset:9216
	global_load_dwordx4 v[68:71], v[72:73], off offset:256
	v_mfma_f32_16x16x32_bf16 v[40:43], v[184:187], v[148:151], v[40:43]
	ds_read_b128 v[228:231], v242 offset:59968
	s_waitcnt lgkmcnt(10)
	v_mfma_f32_16x16x32_bf16 v[20:23], v[176:179], v[152:155], v[20:23]
	ds_read_b128 v[168:171], v241 offset:41536
	v_mfma_f32_16x16x32_bf16 v[28:31], v[180:183], v[152:155], v[28:31]
	ds_read_b128 v[232:235], v242 offset:62272
	v_mfma_f32_16x16x32_bf16 v[4:7], v[184:187], v[152:155], v[4:7]
	ds_read_b128 v[172:175], v241 offset:43840
	s_waitcnt lgkmcnt(12)
	v_mfma_f32_16x16x32_bf16 v[44:47], v[216:219], v[144:147], v[44:47]
	v_mfma_f32_16x16x32_bf16 v[48:51], v[216:219], v[148:151], v[48:51]
	s_waitcnt vmcnt(13)
	ds_write_b128 v213, v[84:87] offset:13824
	global_load_dwordx4 v[76:79], v[74:75], off offset:256
	v_mfma_f32_16x16x32_bf16 v[12:15], v[216:219], v[152:155], v[12:15]
	s_waitcnt lgkmcnt(12)
	v_mfma_f32_16x16x32_bf16 v[24:27], v[176:179], v[156:159], v[24:27]
	s_waitcnt vmcnt(13)
	ds_write_b128 v213, v[88:91] offset:18432
	global_load_dwordx4 v[80:83], v[106:107], off offset:256
	v_mfma_f32_16x16x32_bf16 v[32:35], v[180:183], v[156:159], v[32:35]
	v_mfma_f32_16x16x32_bf16 v[8:11], v[184:187], v[156:159], v[8:11]
	v_mfma_f32_16x16x32_bf16 v[16:19], v[216:219], v[156:159], v[16:19]
	s_waitcnt lgkmcnt(10)
	v_mfma_f32_16x16x32_bf16 v[52:55], v[220:223], v[160:163], v[52:55]
	s_waitcnt lgkmcnt(8)
	v_mfma_f32_16x16x32_bf16 v[60:63], v[224:227], v[160:163], v[60:63]
	s_waitcnt lgkmcnt(7)
	v_mfma_f32_16x16x32_bf16 v[56:59], v[220:223], v[164:167], v[56:59]
	s_waitcnt vmcnt(13)
	ds_write_b128 v213, v[92:95] offset:23040
	global_load_dwordx4 v[84:87], v[188:189], off offset:256
	v_mfma_f32_16x16x32_bf16 v[64:67], v[224:227], v[164:167], v[64:67]
	s_waitcnt lgkmcnt(6)
	v_mfma_f32_16x16x32_bf16 v[36:39], v[228:231], v[160:163], v[36:39]
	s_waitcnt vmcnt(13)
	ds_write_b128 v213, v[96:99] offset:27648
	global_load_dwordx4 v[88:91], v[104:105], off offset:256
	v_mfma_f32_16x16x32_bf16 v[40:43], v[228:231], v[164:167], v[40:43]
	s_waitcnt lgkmcnt(6)
	v_mfma_f32_16x16x32_bf16 v[20:23], v[220:223], v[168:171], v[20:23]
	s_waitcnt vmcnt(13)
	ds_write_b128 v213, v[100:103] offset:32256
	global_load_dwordx4 v[92:95], v[214:215], off offset:256
	v_mfma_f32_16x16x32_bf16 v[28:31], v[224:227], v[168:171], v[28:31]
	v_mfma_f32_16x16x32_bf16 v[4:7], v[228:231], v[168:171], v[4:7]
	global_load_dwordx4 v[96:99], v[236:237], off offset:256
	s_waitcnt lgkmcnt(6)
	v_mfma_f32_16x16x32_bf16 v[44:47], v[232:235], v[160:163], v[44:47]
	v_mfma_f32_16x16x32_bf16 v[48:51], v[232:235], v[164:167], v[48:51]
	global_load_dwordx4 v[100:103], v[238:239], off offset:256
	v_mfma_f32_16x16x32_bf16 v[12:15], v[232:235], v[168:171], v[12:15]
	s_waitcnt lgkmcnt(5)
	v_mfma_f32_16x16x32_bf16 v[24:27], v[220:223], v[172:175], v[24:27]
	v_mfma_f32_16x16x32_bf16 v[32:35], v[224:227], v[172:175], v[32:35]
	v_mfma_f32_16x16x32_bf16 v[8:11], v[228:231], v[172:175], v[8:11]
	v_mfma_f32_16x16x32_bf16 v[16:19], v[232:235], v[172:175], v[16:19]
	s_setprio 0
	s_waitcnt lgkmcnt(0)
	s_barrier
	ds_read_b128 v[144:147], v241
	ds_read_b128 v[176:179], v242 offset:18432
	ds_read_b128 v[180:183], v242 offset:20736
	ds_read_b128 v[148:151], v241 offset:2304
	ds_read_b128 v[184:187], v242 offset:23040
	ds_read_b128 v[152:155], v241 offset:4608
	ds_read_b128 v[216:219], v242 offset:25344
	ds_read_b128 v[156:159], v241 offset:6912
	s_setprio 1
	s_waitcnt lgkmcnt(6)
	v_mfma_f32_16x16x32_bf16 v[52:55], v[176:179], v[144:147], v[52:55]
	s_waitcnt vmcnt(15)
	ds_write_b128 v240, v[108:111]
	s_waitcnt lgkmcnt(6)
	v_mfma_f32_16x16x32_bf16 v[60:63], v[180:183], v[144:147], v[60:63]
	ds_read_b128 v[160:163], v241 offset:64
	s_waitcnt lgkmcnt(6)
	v_mfma_f32_16x16x32_bf16 v[56:59], v[176:179], v[148:151], v[56:59]
	ds_read_b128 v[220:223], v242 offset:18496
	s_waitcnt vmcnt(14)
	ds_write_b128 v240, v[112:115] offset:4608
	v_mfma_f32_16x16x32_bf16 v[64:67], v[180:183], v[148:151], v[64:67]
	ds_read_b128 v[224:227], v242 offset:20800
	s_waitcnt lgkmcnt(8)
	v_mfma_f32_16x16x32_bf16 v[36:39], v[184:187], v[144:147], v[36:39]
	ds_read_b128 v[164:167], v241 offset:2368
	s_waitcnt vmcnt(13)
	ds_write_b128 v240, v[116:119] offset:9216
	global_load_dwordx4 v[108:111], v[72:73], off offset:384
	v_mfma_f32_16x16x32_bf16 v[40:43], v[184:187], v[148:151], v[40:43]
	ds_read_b128 v[228:231], v242 offset:23104
	s_waitcnt lgkmcnt(10)
	v_mfma_f32_16x16x32_bf16 v[20:23], v[176:179], v[152:155], v[20:23]
	ds_read_b128 v[168:171], v241 offset:4672
	v_mfma_f32_16x16x32_bf16 v[28:31], v[180:183], v[152:155], v[28:31]
	ds_read_b128 v[232:235], v242 offset:25408
	v_mfma_f32_16x16x32_bf16 v[4:7], v[184:187], v[152:155], v[4:7]
	ds_read_b128 v[172:175], v241 offset:6976
	s_waitcnt lgkmcnt(12)
	v_mfma_f32_16x16x32_bf16 v[44:47], v[216:219], v[144:147], v[44:47]
	v_mfma_f32_16x16x32_bf16 v[48:51], v[216:219], v[148:151], v[48:51]
	s_waitcnt vmcnt(13)
	ds_write_b128 v240, v[120:123] offset:13824
	global_load_dwordx4 v[112:115], v[74:75], off offset:384
	v_mfma_f32_16x16x32_bf16 v[12:15], v[216:219], v[152:155], v[12:15]
	s_waitcnt lgkmcnt(12)
	v_mfma_f32_16x16x32_bf16 v[24:27], v[176:179], v[156:159], v[24:27]
	s_waitcnt vmcnt(13)
	ds_write_b128 v240, v[124:127] offset:18432
	global_load_dwordx4 v[116:119], v[106:107], off offset:384
	v_mfma_f32_16x16x32_bf16 v[32:35], v[180:183], v[156:159], v[32:35]
	v_mfma_f32_16x16x32_bf16 v[8:11], v[184:187], v[156:159], v[8:11]
	v_mfma_f32_16x16x32_bf16 v[16:19], v[216:219], v[156:159], v[16:19]
	s_waitcnt lgkmcnt(10)
	v_mfma_f32_16x16x32_bf16 v[52:55], v[220:223], v[160:163], v[52:55]
	s_waitcnt lgkmcnt(8)
	v_mfma_f32_16x16x32_bf16 v[60:63], v[224:227], v[160:163], v[60:63]
	s_waitcnt lgkmcnt(7)
	v_mfma_f32_16x16x32_bf16 v[56:59], v[220:223], v[164:167], v[56:59]
	s_waitcnt vmcnt(13)
	ds_write_b128 v240, v[128:131] offset:23040
	global_load_dwordx4 v[120:123], v[188:189], off offset:384
	v_mfma_f32_16x16x32_bf16 v[64:67], v[224:227], v[164:167], v[64:67]
	s_waitcnt lgkmcnt(6)
	v_mfma_f32_16x16x32_bf16 v[36:39], v[228:231], v[160:163], v[36:39]
	s_waitcnt vmcnt(13)
	ds_write_b128 v240, v[136:139] offset:27648
	global_load_dwordx4 v[124:127], v[104:105], off offset:384
	v_mfma_f32_16x16x32_bf16 v[40:43], v[228:231], v[164:167], v[40:43]
	s_waitcnt lgkmcnt(6)
	v_mfma_f32_16x16x32_bf16 v[20:23], v[220:223], v[168:171], v[20:23]
	s_waitcnt vmcnt(13)
	ds_write_b128 v240, v[140:143] offset:32256
	global_load_dwordx4 v[128:131], v[214:215], off offset:384
	v_mfma_f32_16x16x32_bf16 v[28:31], v[224:227], v[168:171], v[28:31]
	v_mfma_f32_16x16x32_bf16 v[4:7], v[228:231], v[168:171], v[4:7]
	global_load_dwordx4 v[136:139], v[236:237], off offset:384
	s_waitcnt lgkmcnt(6)
	v_mfma_f32_16x16x32_bf16 v[44:47], v[232:235], v[160:163], v[44:47]
	v_mfma_f32_16x16x32_bf16 v[48:51], v[232:235], v[164:167], v[48:51]
	global_load_dwordx4 v[140:143], v[238:239], off offset:384
	v_mfma_f32_16x16x32_bf16 v[12:15], v[232:235], v[168:171], v[12:15]
	s_waitcnt lgkmcnt(5)
	v_mfma_f32_16x16x32_bf16 v[24:27], v[220:223], v[172:175], v[24:27]
	v_mfma_f32_16x16x32_bf16 v[32:35], v[224:227], v[172:175], v[32:35]
	v_mfma_f32_16x16x32_bf16 v[8:11], v[228:231], v[172:175], v[8:11]
	v_mfma_f32_16x16x32_bf16 v[16:19], v[232:235], v[172:175], v[16:19]
	s_setprio 0
	s_waitcnt lgkmcnt(0)
	s_barrier
	ds_read_b128 v[144:147], v241 offset:36864
	ds_read_b128 v[176:179], v242 offset:55296
	ds_read_b128 v[180:183], v242 offset:57600
	ds_read_b128 v[148:151], v241 offset:39168
	ds_read_b128 v[184:187], v242 offset:59904
	ds_read_b128 v[152:155], v241 offset:41472
	ds_read_b128 v[216:219], v242 offset:62208
	ds_read_b128 v[156:159], v241 offset:43776
	s_setprio 1
	s_waitcnt lgkmcnt(6)
	v_mfma_f32_16x16x32_bf16 v[52:55], v[176:179], v[144:147], v[52:55]
	s_waitcnt vmcnt(15)
	ds_write_b128 v213, v[68:71]
	s_waitcnt lgkmcnt(6)
	v_mfma_f32_16x16x32_bf16 v[60:63], v[180:183], v[144:147], v[60:63]
	ds_read_b128 v[160:163], v241 offset:36928
	s_waitcnt lgkmcnt(6)
	v_mfma_f32_16x16x32_bf16 v[56:59], v[176:179], v[148:151], v[56:59]
	ds_read_b128 v[220:223], v242 offset:55360
	s_waitcnt vmcnt(14)
	ds_write_b128 v213, v[76:79] offset:4608
	v_mfma_f32_16x16x32_bf16 v[64:67], v[180:183], v[148:151], v[64:67]
	ds_read_b128 v[224:227], v242 offset:57664
	s_waitcnt lgkmcnt(8)
	v_mfma_f32_16x16x32_bf16 v[36:39], v[184:187], v[144:147], v[36:39]
	ds_read_b128 v[164:167], v241 offset:39232
	s_waitcnt vmcnt(13)
	ds_write_b128 v213, v[80:83] offset:9216
	global_load_dwordx4 v[68:71], v[72:73], off offset:512
	v_mfma_f32_16x16x32_bf16 v[40:43], v[184:187], v[148:151], v[40:43]
	ds_read_b128 v[228:231], v242 offset:59968
	s_waitcnt lgkmcnt(10)
	v_mfma_f32_16x16x32_bf16 v[20:23], v[176:179], v[152:155], v[20:23]
	ds_read_b128 v[168:171], v241 offset:41536
	v_mfma_f32_16x16x32_bf16 v[28:31], v[180:183], v[152:155], v[28:31]
	ds_read_b128 v[232:235], v242 offset:62272
	v_mfma_f32_16x16x32_bf16 v[4:7], v[184:187], v[152:155], v[4:7]
	ds_read_b128 v[172:175], v241 offset:43840
	s_waitcnt lgkmcnt(12)
	v_mfma_f32_16x16x32_bf16 v[44:47], v[216:219], v[144:147], v[44:47]
	v_mfma_f32_16x16x32_bf16 v[48:51], v[216:219], v[148:151], v[48:51]
	s_waitcnt vmcnt(13)
	ds_write_b128 v213, v[84:87] offset:13824
	global_load_dwordx4 v[76:79], v[74:75], off offset:512
	v_mfma_f32_16x16x32_bf16 v[12:15], v[216:219], v[152:155], v[12:15]
	s_waitcnt lgkmcnt(12)
	v_mfma_f32_16x16x32_bf16 v[24:27], v[176:179], v[156:159], v[24:27]
	s_waitcnt vmcnt(13)
	ds_write_b128 v213, v[88:91] offset:18432
	global_load_dwordx4 v[80:83], v[106:107], off offset:512
	v_mfma_f32_16x16x32_bf16 v[32:35], v[180:183], v[156:159], v[32:35]
	v_mfma_f32_16x16x32_bf16 v[8:11], v[184:187], v[156:159], v[8:11]
	v_mfma_f32_16x16x32_bf16 v[16:19], v[216:219], v[156:159], v[16:19]
	s_waitcnt lgkmcnt(10)
	v_mfma_f32_16x16x32_bf16 v[52:55], v[220:223], v[160:163], v[52:55]
	s_waitcnt lgkmcnt(8)
	v_mfma_f32_16x16x32_bf16 v[60:63], v[224:227], v[160:163], v[60:63]
	s_waitcnt lgkmcnt(7)
	v_mfma_f32_16x16x32_bf16 v[56:59], v[220:223], v[164:167], v[56:59]
	s_waitcnt vmcnt(13)
	ds_write_b128 v213, v[92:95] offset:23040
	global_load_dwordx4 v[84:87], v[188:189], off offset:512
	v_mfma_f32_16x16x32_bf16 v[64:67], v[224:227], v[164:167], v[64:67]
	s_waitcnt lgkmcnt(6)
	v_mfma_f32_16x16x32_bf16 v[36:39], v[228:231], v[160:163], v[36:39]
	s_waitcnt vmcnt(13)
	ds_write_b128 v213, v[96:99] offset:27648
	global_load_dwordx4 v[88:91], v[104:105], off offset:512
	v_mfma_f32_16x16x32_bf16 v[40:43], v[228:231], v[164:167], v[40:43]
	s_waitcnt lgkmcnt(6)
	v_mfma_f32_16x16x32_bf16 v[20:23], v[220:223], v[168:171], v[20:23]
	s_waitcnt vmcnt(13)
	ds_write_b128 v213, v[100:103] offset:32256
	global_load_dwordx4 v[92:95], v[214:215], off offset:512
	v_mfma_f32_16x16x32_bf16 v[28:31], v[224:227], v[168:171], v[28:31]
	v_mfma_f32_16x16x32_bf16 v[4:7], v[228:231], v[168:171], v[4:7]
	global_load_dwordx4 v[96:99], v[236:237], off offset:512
	s_waitcnt lgkmcnt(6)
	v_mfma_f32_16x16x32_bf16 v[44:47], v[232:235], v[160:163], v[44:47]
	v_mfma_f32_16x16x32_bf16 v[48:51], v[232:235], v[164:167], v[48:51]
	global_load_dwordx4 v[100:103], v[238:239], off offset:512
	v_mfma_f32_16x16x32_bf16 v[12:15], v[232:235], v[168:171], v[12:15]
	s_waitcnt lgkmcnt(5)
	v_mfma_f32_16x16x32_bf16 v[24:27], v[220:223], v[172:175], v[24:27]
	v_mfma_f32_16x16x32_bf16 v[32:35], v[224:227], v[172:175], v[32:35]
	v_mfma_f32_16x16x32_bf16 v[8:11], v[228:231], v[172:175], v[8:11]
	v_mfma_f32_16x16x32_bf16 v[16:19], v[232:235], v[172:175], v[16:19]
	s_setprio 0
	s_waitcnt lgkmcnt(0)
	s_barrier
	ds_read_b128 v[144:147], v241
	ds_read_b128 v[176:179], v242 offset:18432
	ds_read_b128 v[180:183], v242 offset:20736
	ds_read_b128 v[148:151], v241 offset:2304
	ds_read_b128 v[184:187], v242 offset:23040
	ds_read_b128 v[152:155], v241 offset:4608
	ds_read_b128 v[216:219], v242 offset:25344
	ds_read_b128 v[156:159], v241 offset:6912
	s_setprio 1
	s_waitcnt lgkmcnt(6)
	v_mfma_f32_16x16x32_bf16 v[52:55], v[176:179], v[144:147], v[52:55]
	s_waitcnt vmcnt(15)
	ds_write_b128 v240, v[108:111]
	s_waitcnt lgkmcnt(6)
	v_mfma_f32_16x16x32_bf16 v[60:63], v[180:183], v[144:147], v[60:63]
	ds_read_b128 v[160:163], v241 offset:64
	s_waitcnt lgkmcnt(6)
	v_mfma_f32_16x16x32_bf16 v[56:59], v[176:179], v[148:151], v[56:59]
	ds_read_b128 v[220:223], v242 offset:18496
	s_waitcnt vmcnt(14)
	ds_write_b128 v240, v[112:115] offset:4608
	v_mfma_f32_16x16x32_bf16 v[64:67], v[180:183], v[148:151], v[64:67]
	ds_read_b128 v[224:227], v242 offset:20800
	s_waitcnt lgkmcnt(8)
	v_mfma_f32_16x16x32_bf16 v[36:39], v[184:187], v[144:147], v[36:39]
	ds_read_b128 v[164:167], v241 offset:2368
	s_waitcnt vmcnt(13)
	ds_write_b128 v240, v[116:119] offset:9216
	global_load_dwordx4 v[108:111], v[72:73], off offset:640
	v_mfma_f32_16x16x32_bf16 v[40:43], v[184:187], v[148:151], v[40:43]
	ds_read_b128 v[228:231], v242 offset:23104
	s_waitcnt lgkmcnt(10)
	v_mfma_f32_16x16x32_bf16 v[20:23], v[176:179], v[152:155], v[20:23]
	ds_read_b128 v[168:171], v241 offset:4672
	v_mfma_f32_16x16x32_bf16 v[28:31], v[180:183], v[152:155], v[28:31]
	ds_read_b128 v[232:235], v242 offset:25408
	v_mfma_f32_16x16x32_bf16 v[4:7], v[184:187], v[152:155], v[4:7]
	ds_read_b128 v[172:175], v241 offset:6976
	s_waitcnt lgkmcnt(12)
	v_mfma_f32_16x16x32_bf16 v[44:47], v[216:219], v[144:147], v[44:47]
	v_mfma_f32_16x16x32_bf16 v[48:51], v[216:219], v[148:151], v[48:51]
	s_waitcnt vmcnt(13)
	ds_write_b128 v240, v[120:123] offset:13824
	global_load_dwordx4 v[112:115], v[74:75], off offset:640
	v_mfma_f32_16x16x32_bf16 v[12:15], v[216:219], v[152:155], v[12:15]
	s_waitcnt lgkmcnt(12)
	v_mfma_f32_16x16x32_bf16 v[24:27], v[176:179], v[156:159], v[24:27]
	s_waitcnt vmcnt(13)
	ds_write_b128 v240, v[124:127] offset:18432
	global_load_dwordx4 v[116:119], v[106:107], off offset:640
	v_mfma_f32_16x16x32_bf16 v[32:35], v[180:183], v[156:159], v[32:35]
	v_mfma_f32_16x16x32_bf16 v[8:11], v[184:187], v[156:159], v[8:11]
	v_mfma_f32_16x16x32_bf16 v[16:19], v[216:219], v[156:159], v[16:19]
	s_waitcnt lgkmcnt(10)
	v_mfma_f32_16x16x32_bf16 v[52:55], v[220:223], v[160:163], v[52:55]
	s_waitcnt lgkmcnt(8)
	v_mfma_f32_16x16x32_bf16 v[60:63], v[224:227], v[160:163], v[60:63]
	s_waitcnt lgkmcnt(7)
	v_mfma_f32_16x16x32_bf16 v[56:59], v[220:223], v[164:167], v[56:59]
	s_waitcnt vmcnt(13)
	ds_write_b128 v240, v[128:131] offset:23040
	global_load_dwordx4 v[120:123], v[188:189], off offset:640
	v_mfma_f32_16x16x32_bf16 v[64:67], v[224:227], v[164:167], v[64:67]
	s_waitcnt lgkmcnt(6)
	v_mfma_f32_16x16x32_bf16 v[36:39], v[228:231], v[160:163], v[36:39]
	s_waitcnt vmcnt(13)
	ds_write_b128 v240, v[136:139] offset:27648
	global_load_dwordx4 v[124:127], v[104:105], off offset:640
	v_mfma_f32_16x16x32_bf16 v[40:43], v[228:231], v[164:167], v[40:43]
	s_waitcnt lgkmcnt(6)
	v_mfma_f32_16x16x32_bf16 v[20:23], v[220:223], v[168:171], v[20:23]
	s_waitcnt vmcnt(13)
	ds_write_b128 v240, v[140:143] offset:32256
	global_load_dwordx4 v[128:131], v[214:215], off offset:640
	v_mfma_f32_16x16x32_bf16 v[28:31], v[224:227], v[168:171], v[28:31]
	v_mfma_f32_16x16x32_bf16 v[4:7], v[228:231], v[168:171], v[4:7]
	global_load_dwordx4 v[136:139], v[236:237], off offset:640
	s_waitcnt lgkmcnt(6)
	v_mfma_f32_16x16x32_bf16 v[44:47], v[232:235], v[160:163], v[44:47]
	v_mfma_f32_16x16x32_bf16 v[48:51], v[232:235], v[164:167], v[48:51]
	global_load_dwordx4 v[140:143], v[238:239], off offset:640
	v_mfma_f32_16x16x32_bf16 v[12:15], v[232:235], v[168:171], v[12:15]
	s_waitcnt lgkmcnt(5)
	v_mfma_f32_16x16x32_bf16 v[24:27], v[220:223], v[172:175], v[24:27]
	v_mfma_f32_16x16x32_bf16 v[32:35], v[224:227], v[172:175], v[32:35]
	v_mfma_f32_16x16x32_bf16 v[8:11], v[228:231], v[172:175], v[8:11]
	v_mfma_f32_16x16x32_bf16 v[16:19], v[232:235], v[172:175], v[16:19]
	s_setprio 0
	s_waitcnt lgkmcnt(0)
	s_barrier
	ds_read_b128 v[144:147], v241 offset:36864
	ds_read_b128 v[176:179], v242 offset:55296
	ds_read_b128 v[180:183], v242 offset:57600
	ds_read_b128 v[148:151], v241 offset:39168
	ds_read_b128 v[184:187], v242 offset:59904
	ds_read_b128 v[152:155], v241 offset:41472
	ds_read_b128 v[216:219], v242 offset:62208
	ds_read_b128 v[156:159], v241 offset:43776
	s_setprio 1
	s_waitcnt lgkmcnt(6)
	v_mfma_f32_16x16x32_bf16 v[52:55], v[176:179], v[144:147], v[52:55]
	s_waitcnt vmcnt(15)
	ds_write_b128 v213, v[68:71]
	s_waitcnt lgkmcnt(6)
	v_mfma_f32_16x16x32_bf16 v[60:63], v[180:183], v[144:147], v[60:63]
	ds_read_b128 v[160:163], v241 offset:36928
	s_waitcnt lgkmcnt(6)
	v_mfma_f32_16x16x32_bf16 v[56:59], v[176:179], v[148:151], v[56:59]
	ds_read_b128 v[220:223], v242 offset:55360
	s_waitcnt vmcnt(14)
	ds_write_b128 v213, v[76:79] offset:4608
	v_mfma_f32_16x16x32_bf16 v[64:67], v[180:183], v[148:151], v[64:67]
	ds_read_b128 v[224:227], v242 offset:57664
	s_waitcnt lgkmcnt(8)
	v_mfma_f32_16x16x32_bf16 v[36:39], v[184:187], v[144:147], v[36:39]
	ds_read_b128 v[164:167], v241 offset:39232
	s_waitcnt vmcnt(13)
	ds_write_b128 v213, v[80:83] offset:9216
	global_load_dwordx4 v[68:71], v[72:73], off offset:768
	v_mfma_f32_16x16x32_bf16 v[40:43], v[184:187], v[148:151], v[40:43]
	ds_read_b128 v[228:231], v242 offset:59968
	s_waitcnt lgkmcnt(10)
	v_mfma_f32_16x16x32_bf16 v[20:23], v[176:179], v[152:155], v[20:23]
	ds_read_b128 v[168:171], v241 offset:41536
	v_mfma_f32_16x16x32_bf16 v[28:31], v[180:183], v[152:155], v[28:31]
	ds_read_b128 v[232:235], v242 offset:62272
	v_mfma_f32_16x16x32_bf16 v[4:7], v[184:187], v[152:155], v[4:7]
	ds_read_b128 v[172:175], v241 offset:43840
	s_waitcnt lgkmcnt(12)
	v_mfma_f32_16x16x32_bf16 v[44:47], v[216:219], v[144:147], v[44:47]
	v_mfma_f32_16x16x32_bf16 v[48:51], v[216:219], v[148:151], v[48:51]
	s_waitcnt vmcnt(13)
	ds_write_b128 v213, v[84:87] offset:13824
	global_load_dwordx4 v[76:79], v[74:75], off offset:768
	v_mfma_f32_16x16x32_bf16 v[12:15], v[216:219], v[152:155], v[12:15]
	s_waitcnt lgkmcnt(12)
	v_mfma_f32_16x16x32_bf16 v[24:27], v[176:179], v[156:159], v[24:27]
	s_waitcnt vmcnt(13)
	ds_write_b128 v213, v[88:91] offset:18432
	global_load_dwordx4 v[80:83], v[106:107], off offset:768
	v_mfma_f32_16x16x32_bf16 v[32:35], v[180:183], v[156:159], v[32:35]
	v_mfma_f32_16x16x32_bf16 v[8:11], v[184:187], v[156:159], v[8:11]
	v_mfma_f32_16x16x32_bf16 v[16:19], v[216:219], v[156:159], v[16:19]
	s_waitcnt lgkmcnt(10)
	v_mfma_f32_16x16x32_bf16 v[52:55], v[220:223], v[160:163], v[52:55]
	s_waitcnt lgkmcnt(8)
	v_mfma_f32_16x16x32_bf16 v[60:63], v[224:227], v[160:163], v[60:63]
	s_waitcnt lgkmcnt(7)
	v_mfma_f32_16x16x32_bf16 v[56:59], v[220:223], v[164:167], v[56:59]
	s_waitcnt vmcnt(13)
	ds_write_b128 v213, v[92:95] offset:23040
	global_load_dwordx4 v[84:87], v[188:189], off offset:768
	v_mfma_f32_16x16x32_bf16 v[64:67], v[224:227], v[164:167], v[64:67]
	s_waitcnt lgkmcnt(6)
	v_mfma_f32_16x16x32_bf16 v[36:39], v[228:231], v[160:163], v[36:39]
	s_waitcnt vmcnt(13)
	ds_write_b128 v213, v[96:99] offset:27648
	global_load_dwordx4 v[88:91], v[104:105], off offset:768
	v_mfma_f32_16x16x32_bf16 v[40:43], v[228:231], v[164:167], v[40:43]
	s_waitcnt lgkmcnt(6)
	v_mfma_f32_16x16x32_bf16 v[20:23], v[220:223], v[168:171], v[20:23]
	s_waitcnt vmcnt(13)
	ds_write_b128 v213, v[100:103] offset:32256
	global_load_dwordx4 v[92:95], v[214:215], off offset:768
	v_mfma_f32_16x16x32_bf16 v[28:31], v[224:227], v[168:171], v[28:31]
	v_mfma_f32_16x16x32_bf16 v[4:7], v[228:231], v[168:171], v[4:7]
	global_load_dwordx4 v[96:99], v[236:237], off offset:768
	s_waitcnt lgkmcnt(6)
	v_mfma_f32_16x16x32_bf16 v[44:47], v[232:235], v[160:163], v[44:47]
	v_mfma_f32_16x16x32_bf16 v[48:51], v[232:235], v[164:167], v[48:51]
	global_load_dwordx4 v[100:103], v[238:239], off offset:768
	v_mfma_f32_16x16x32_bf16 v[12:15], v[232:235], v[168:171], v[12:15]
	s_waitcnt lgkmcnt(5)
	v_mfma_f32_16x16x32_bf16 v[24:27], v[220:223], v[172:175], v[24:27]
	v_mfma_f32_16x16x32_bf16 v[32:35], v[224:227], v[172:175], v[32:35]
	v_mfma_f32_16x16x32_bf16 v[8:11], v[228:231], v[172:175], v[8:11]
	v_mfma_f32_16x16x32_bf16 v[16:19], v[232:235], v[172:175], v[16:19]
	s_setprio 0
	s_waitcnt lgkmcnt(0)
	s_barrier
	ds_read_b128 v[144:147], v241
	ds_read_b128 v[176:179], v242 offset:18432
	ds_read_b128 v[180:183], v242 offset:20736
	ds_read_b128 v[148:151], v241 offset:2304
	ds_read_b128 v[184:187], v242 offset:23040
	ds_read_b128 v[152:155], v241 offset:4608
	ds_read_b128 v[216:219], v242 offset:25344
	ds_read_b128 v[156:159], v241 offset:6912
	s_setprio 1
	s_waitcnt lgkmcnt(6)
	v_mfma_f32_16x16x32_bf16 v[52:55], v[176:179], v[144:147], v[52:55]
	s_waitcnt vmcnt(15)
	ds_write_b128 v240, v[108:111]
	s_waitcnt lgkmcnt(6)
	v_mfma_f32_16x16x32_bf16 v[60:63], v[180:183], v[144:147], v[60:63]
	ds_read_b128 v[160:163], v241 offset:64
	s_waitcnt lgkmcnt(6)
	v_mfma_f32_16x16x32_bf16 v[56:59], v[176:179], v[148:151], v[56:59]
	ds_read_b128 v[220:223], v242 offset:18496
	s_waitcnt vmcnt(14)
	ds_write_b128 v240, v[112:115] offset:4608
	v_mfma_f32_16x16x32_bf16 v[64:67], v[180:183], v[148:151], v[64:67]
	ds_read_b128 v[224:227], v242 offset:20800
	s_waitcnt lgkmcnt(8)
	v_mfma_f32_16x16x32_bf16 v[36:39], v[184:187], v[144:147], v[36:39]
	ds_read_b128 v[164:167], v241 offset:2368
	s_waitcnt vmcnt(13)
	ds_write_b128 v240, v[116:119] offset:9216
	global_load_dwordx4 v[108:111], v[72:73], off offset:896
	v_mfma_f32_16x16x32_bf16 v[40:43], v[184:187], v[148:151], v[40:43]
	ds_read_b128 v[228:231], v242 offset:23104
	s_waitcnt lgkmcnt(10)
	v_mfma_f32_16x16x32_bf16 v[20:23], v[176:179], v[152:155], v[20:23]
	ds_read_b128 v[168:171], v241 offset:4672
	v_mfma_f32_16x16x32_bf16 v[28:31], v[180:183], v[152:155], v[28:31]
	ds_read_b128 v[232:235], v242 offset:25408
	v_mfma_f32_16x16x32_bf16 v[4:7], v[184:187], v[152:155], v[4:7]
	ds_read_b128 v[172:175], v241 offset:6976
	s_waitcnt lgkmcnt(12)
	v_mfma_f32_16x16x32_bf16 v[44:47], v[216:219], v[144:147], v[44:47]
	v_mfma_f32_16x16x32_bf16 v[48:51], v[216:219], v[148:151], v[48:51]
	s_waitcnt vmcnt(13)
	ds_write_b128 v240, v[120:123] offset:13824
	global_load_dwordx4 v[112:115], v[74:75], off offset:896
	v_mfma_f32_16x16x32_bf16 v[12:15], v[216:219], v[152:155], v[12:15]
	s_waitcnt lgkmcnt(12)
	v_mfma_f32_16x16x32_bf16 v[24:27], v[176:179], v[156:159], v[24:27]
	s_waitcnt vmcnt(13)
	ds_write_b128 v240, v[124:127] offset:18432
	global_load_dwordx4 v[116:119], v[106:107], off offset:896
	v_mfma_f32_16x16x32_bf16 v[32:35], v[180:183], v[156:159], v[32:35]
	v_mfma_f32_16x16x32_bf16 v[8:11], v[184:187], v[156:159], v[8:11]
	v_mfma_f32_16x16x32_bf16 v[16:19], v[216:219], v[156:159], v[16:19]
	s_waitcnt lgkmcnt(10)
	v_mfma_f32_16x16x32_bf16 v[52:55], v[220:223], v[160:163], v[52:55]
	s_waitcnt lgkmcnt(8)
	v_mfma_f32_16x16x32_bf16 v[60:63], v[224:227], v[160:163], v[60:63]
	s_waitcnt lgkmcnt(7)
	v_mfma_f32_16x16x32_bf16 v[56:59], v[220:223], v[164:167], v[56:59]
	s_waitcnt vmcnt(13)
	ds_write_b128 v240, v[128:131] offset:23040
	global_load_dwordx4 v[120:123], v[188:189], off offset:896
	v_mfma_f32_16x16x32_bf16 v[64:67], v[224:227], v[164:167], v[64:67]
	s_waitcnt lgkmcnt(6)
	v_mfma_f32_16x16x32_bf16 v[36:39], v[228:231], v[160:163], v[36:39]
	s_waitcnt vmcnt(13)
	ds_write_b128 v240, v[136:139] offset:27648
	global_load_dwordx4 v[124:127], v[104:105], off offset:896
	v_mfma_f32_16x16x32_bf16 v[40:43], v[228:231], v[164:167], v[40:43]
	s_waitcnt lgkmcnt(6)
	v_mfma_f32_16x16x32_bf16 v[20:23], v[220:223], v[168:171], v[20:23]
	s_waitcnt vmcnt(13)
	ds_write_b128 v240, v[140:143] offset:32256
	global_load_dwordx4 v[128:131], v[214:215], off offset:896
	v_mfma_f32_16x16x32_bf16 v[28:31], v[224:227], v[168:171], v[28:31]
	v_mfma_f32_16x16x32_bf16 v[4:7], v[228:231], v[168:171], v[4:7]
	global_load_dwordx4 v[136:139], v[236:237], off offset:896
	s_waitcnt lgkmcnt(6)
	v_mfma_f32_16x16x32_bf16 v[44:47], v[232:235], v[160:163], v[44:47]
	v_mfma_f32_16x16x32_bf16 v[48:51], v[232:235], v[164:167], v[48:51]
	global_load_dwordx4 v[140:143], v[238:239], off offset:896
	v_mfma_f32_16x16x32_bf16 v[12:15], v[232:235], v[168:171], v[12:15]
	s_waitcnt lgkmcnt(5)
	v_mfma_f32_16x16x32_bf16 v[24:27], v[220:223], v[172:175], v[24:27]
	v_mfma_f32_16x16x32_bf16 v[32:35], v[224:227], v[172:175], v[32:35]
	v_mfma_f32_16x16x32_bf16 v[8:11], v[228:231], v[172:175], v[8:11]
	v_mfma_f32_16x16x32_bf16 v[16:19], v[232:235], v[172:175], v[16:19]
	s_setprio 0
	s_waitcnt lgkmcnt(0)
	s_barrier
	ds_read_b128 v[144:147], v241 offset:36864
	ds_read_b128 v[176:179], v242 offset:55296
	ds_read_b128 v[180:183], v242 offset:57600
	ds_read_b128 v[148:151], v241 offset:39168
	ds_read_b128 v[184:187], v242 offset:59904
	ds_read_b128 v[152:155], v241 offset:41472
	ds_read_b128 v[216:219], v242 offset:62208
	ds_read_b128 v[156:159], v241 offset:43776
	s_setprio 1
	s_waitcnt lgkmcnt(6)
	v_mfma_f32_16x16x32_bf16 v[52:55], v[176:179], v[144:147], v[52:55]
	s_waitcnt vmcnt(15)
	ds_write_b128 v213, v[68:71]
	s_waitcnt lgkmcnt(6)
	v_mfma_f32_16x16x32_bf16 v[60:63], v[180:183], v[144:147], v[60:63]
	ds_read_b128 v[160:163], v241 offset:36928
	s_waitcnt lgkmcnt(6)
	v_mfma_f32_16x16x32_bf16 v[56:59], v[176:179], v[148:151], v[56:59]
	ds_read_b128 v[220:223], v242 offset:55360
	s_waitcnt vmcnt(14)
	ds_write_b128 v213, v[76:79] offset:4608
	v_mfma_f32_16x16x32_bf16 v[64:67], v[180:183], v[148:151], v[64:67]
	ds_read_b128 v[224:227], v242 offset:57664
	s_waitcnt lgkmcnt(8)
	v_mfma_f32_16x16x32_bf16 v[36:39], v[184:187], v[144:147], v[36:39]
	ds_read_b128 v[164:167], v241 offset:39232
	s_waitcnt vmcnt(13)
	ds_write_b128 v213, v[80:83] offset:9216
	global_load_dwordx4 v[68:71], v[72:73], off offset:1024
	v_mfma_f32_16x16x32_bf16 v[40:43], v[184:187], v[148:151], v[40:43]
	ds_read_b128 v[228:231], v242 offset:59968
	s_waitcnt lgkmcnt(10)
	v_mfma_f32_16x16x32_bf16 v[20:23], v[176:179], v[152:155], v[20:23]
	ds_read_b128 v[168:171], v241 offset:41536
	v_mfma_f32_16x16x32_bf16 v[28:31], v[180:183], v[152:155], v[28:31]
	ds_read_b128 v[232:235], v242 offset:62272
	v_mfma_f32_16x16x32_bf16 v[4:7], v[184:187], v[152:155], v[4:7]
	ds_read_b128 v[172:175], v241 offset:43840
	s_waitcnt lgkmcnt(12)
	v_mfma_f32_16x16x32_bf16 v[44:47], v[216:219], v[144:147], v[44:47]
	v_mfma_f32_16x16x32_bf16 v[48:51], v[216:219], v[148:151], v[48:51]
	s_waitcnt vmcnt(13)
	ds_write_b128 v213, v[84:87] offset:13824
	global_load_dwordx4 v[76:79], v[74:75], off offset:1024
	v_mfma_f32_16x16x32_bf16 v[12:15], v[216:219], v[152:155], v[12:15]
	s_waitcnt lgkmcnt(12)
	v_mfma_f32_16x16x32_bf16 v[24:27], v[176:179], v[156:159], v[24:27]
	s_waitcnt vmcnt(13)
	ds_write_b128 v213, v[88:91] offset:18432
	global_load_dwordx4 v[80:83], v[106:107], off offset:1024
	v_mfma_f32_16x16x32_bf16 v[32:35], v[180:183], v[156:159], v[32:35]
	v_mfma_f32_16x16x32_bf16 v[8:11], v[184:187], v[156:159], v[8:11]
	v_mfma_f32_16x16x32_bf16 v[16:19], v[216:219], v[156:159], v[16:19]
	s_waitcnt lgkmcnt(10)
	v_mfma_f32_16x16x32_bf16 v[52:55], v[220:223], v[160:163], v[52:55]
	s_waitcnt lgkmcnt(8)
	v_mfma_f32_16x16x32_bf16 v[60:63], v[224:227], v[160:163], v[60:63]
	s_waitcnt lgkmcnt(7)
	v_mfma_f32_16x16x32_bf16 v[56:59], v[220:223], v[164:167], v[56:59]
	s_waitcnt vmcnt(13)
	ds_write_b128 v213, v[92:95] offset:23040
	global_load_dwordx4 v[84:87], v[188:189], off offset:1024
	v_mfma_f32_16x16x32_bf16 v[64:67], v[224:227], v[164:167], v[64:67]
	s_waitcnt lgkmcnt(6)
	v_mfma_f32_16x16x32_bf16 v[36:39], v[228:231], v[160:163], v[36:39]
	s_waitcnt vmcnt(13)
	ds_write_b128 v213, v[96:99] offset:27648
	global_load_dwordx4 v[88:91], v[104:105], off offset:1024
	v_mfma_f32_16x16x32_bf16 v[40:43], v[228:231], v[164:167], v[40:43]
	s_waitcnt lgkmcnt(6)
	v_mfma_f32_16x16x32_bf16 v[20:23], v[220:223], v[168:171], v[20:23]
	s_waitcnt vmcnt(13)
	ds_write_b128 v213, v[100:103] offset:32256
	global_load_dwordx4 v[92:95], v[214:215], off offset:1024
	v_mfma_f32_16x16x32_bf16 v[28:31], v[224:227], v[168:171], v[28:31]
	v_mfma_f32_16x16x32_bf16 v[4:7], v[228:231], v[168:171], v[4:7]
	global_load_dwordx4 v[96:99], v[236:237], off offset:1024
	s_waitcnt lgkmcnt(6)
	v_mfma_f32_16x16x32_bf16 v[44:47], v[232:235], v[160:163], v[44:47]
	v_mfma_f32_16x16x32_bf16 v[48:51], v[232:235], v[164:167], v[48:51]
	global_load_dwordx4 v[100:103], v[238:239], off offset:1024
	v_mfma_f32_16x16x32_bf16 v[12:15], v[232:235], v[168:171], v[12:15]
	s_waitcnt lgkmcnt(5)
	v_mfma_f32_16x16x32_bf16 v[24:27], v[220:223], v[172:175], v[24:27]
	v_mfma_f32_16x16x32_bf16 v[32:35], v[224:227], v[172:175], v[32:35]
	v_mfma_f32_16x16x32_bf16 v[8:11], v[228:231], v[172:175], v[8:11]
	v_mfma_f32_16x16x32_bf16 v[16:19], v[232:235], v[172:175], v[16:19]
	s_setprio 0
	s_waitcnt lgkmcnt(0)
	s_barrier
	ds_read_b128 v[144:147], v241
	ds_read_b128 v[176:179], v242 offset:18432
	ds_read_b128 v[180:183], v242 offset:20736
	ds_read_b128 v[148:151], v241 offset:2304
	ds_read_b128 v[184:187], v242 offset:23040
	ds_read_b128 v[152:155], v241 offset:4608
	ds_read_b128 v[216:219], v242 offset:25344
	ds_read_b128 v[156:159], v241 offset:6912
	s_setprio 1
	s_waitcnt lgkmcnt(6)
	v_mfma_f32_16x16x32_bf16 v[52:55], v[176:179], v[144:147], v[52:55]
	s_waitcnt vmcnt(15)
	ds_write_b128 v240, v[108:111]
	s_waitcnt lgkmcnt(6)
	v_mfma_f32_16x16x32_bf16 v[60:63], v[180:183], v[144:147], v[60:63]
	ds_read_b128 v[160:163], v241 offset:64
	s_waitcnt lgkmcnt(6)
	v_mfma_f32_16x16x32_bf16 v[56:59], v[176:179], v[148:151], v[56:59]
	ds_read_b128 v[220:223], v242 offset:18496
	s_waitcnt vmcnt(14)
	ds_write_b128 v240, v[112:115] offset:4608
	v_mfma_f32_16x16x32_bf16 v[64:67], v[180:183], v[148:151], v[64:67]
	ds_read_b128 v[224:227], v242 offset:20800
	s_waitcnt lgkmcnt(8)
	v_mfma_f32_16x16x32_bf16 v[36:39], v[184:187], v[144:147], v[36:39]
	ds_read_b128 v[164:167], v241 offset:2368
	s_waitcnt vmcnt(13)
	ds_write_b128 v240, v[116:119] offset:9216
	global_load_dwordx4 v[108:111], v[72:73], off offset:1152
	v_mfma_f32_16x16x32_bf16 v[40:43], v[184:187], v[148:151], v[40:43]
	ds_read_b128 v[228:231], v242 offset:23104
	s_waitcnt lgkmcnt(10)
	v_mfma_f32_16x16x32_bf16 v[20:23], v[176:179], v[152:155], v[20:23]
	ds_read_b128 v[168:171], v241 offset:4672
	v_mfma_f32_16x16x32_bf16 v[28:31], v[180:183], v[152:155], v[28:31]
	ds_read_b128 v[232:235], v242 offset:25408
	v_mfma_f32_16x16x32_bf16 v[4:7], v[184:187], v[152:155], v[4:7]
	ds_read_b128 v[172:175], v241 offset:6976
	s_waitcnt lgkmcnt(12)
	v_mfma_f32_16x16x32_bf16 v[44:47], v[216:219], v[144:147], v[44:47]
	v_mfma_f32_16x16x32_bf16 v[48:51], v[216:219], v[148:151], v[48:51]
	s_waitcnt vmcnt(13)
	ds_write_b128 v240, v[120:123] offset:13824
	global_load_dwordx4 v[112:115], v[74:75], off offset:1152
	v_mfma_f32_16x16x32_bf16 v[12:15], v[216:219], v[152:155], v[12:15]
	s_waitcnt lgkmcnt(12)
	v_mfma_f32_16x16x32_bf16 v[24:27], v[176:179], v[156:159], v[24:27]
	s_waitcnt vmcnt(13)
	ds_write_b128 v240, v[124:127] offset:18432
	global_load_dwordx4 v[116:119], v[106:107], off offset:1152
	v_mfma_f32_16x16x32_bf16 v[32:35], v[180:183], v[156:159], v[32:35]
	v_mfma_f32_16x16x32_bf16 v[8:11], v[184:187], v[156:159], v[8:11]
	v_mfma_f32_16x16x32_bf16 v[16:19], v[216:219], v[156:159], v[16:19]
	s_waitcnt lgkmcnt(10)
	v_mfma_f32_16x16x32_bf16 v[52:55], v[220:223], v[160:163], v[52:55]
	s_waitcnt lgkmcnt(8)
	v_mfma_f32_16x16x32_bf16 v[60:63], v[224:227], v[160:163], v[60:63]
	s_waitcnt lgkmcnt(7)
	v_mfma_f32_16x16x32_bf16 v[56:59], v[220:223], v[164:167], v[56:59]
	s_waitcnt vmcnt(13)
	ds_write_b128 v240, v[128:131] offset:23040
	global_load_dwordx4 v[120:123], v[188:189], off offset:1152
	v_mfma_f32_16x16x32_bf16 v[64:67], v[224:227], v[164:167], v[64:67]
	s_waitcnt lgkmcnt(6)
	v_mfma_f32_16x16x32_bf16 v[36:39], v[228:231], v[160:163], v[36:39]
	s_waitcnt vmcnt(13)
	ds_write_b128 v240, v[136:139] offset:27648
	global_load_dwordx4 v[124:127], v[104:105], off offset:1152
	v_mfma_f32_16x16x32_bf16 v[40:43], v[228:231], v[164:167], v[40:43]
	s_waitcnt lgkmcnt(6)
	v_mfma_f32_16x16x32_bf16 v[20:23], v[220:223], v[168:171], v[20:23]
	s_waitcnt vmcnt(13)
	ds_write_b128 v240, v[140:143] offset:32256
	global_load_dwordx4 v[128:131], v[214:215], off offset:1152
	v_mfma_f32_16x16x32_bf16 v[28:31], v[224:227], v[168:171], v[28:31]
	v_mfma_f32_16x16x32_bf16 v[4:7], v[228:231], v[168:171], v[4:7]
	global_load_dwordx4 v[136:139], v[236:237], off offset:1152
	s_waitcnt lgkmcnt(6)
	v_mfma_f32_16x16x32_bf16 v[44:47], v[232:235], v[160:163], v[44:47]
	v_mfma_f32_16x16x32_bf16 v[48:51], v[232:235], v[164:167], v[48:51]
	global_load_dwordx4 v[140:143], v[238:239], off offset:1152
	v_mfma_f32_16x16x32_bf16 v[12:15], v[232:235], v[168:171], v[12:15]
	s_waitcnt lgkmcnt(5)
	v_mfma_f32_16x16x32_bf16 v[24:27], v[220:223], v[172:175], v[24:27]
	v_mfma_f32_16x16x32_bf16 v[32:35], v[224:227], v[172:175], v[32:35]
	v_mfma_f32_16x16x32_bf16 v[8:11], v[228:231], v[172:175], v[8:11]
	v_mfma_f32_16x16x32_bf16 v[16:19], v[232:235], v[172:175], v[16:19]
	s_setprio 0
	s_waitcnt lgkmcnt(0)
	s_barrier
	ds_read_b128 v[144:147], v241 offset:36864
	ds_read_b128 v[176:179], v242 offset:55296
	ds_read_b128 v[180:183], v242 offset:57600
	ds_read_b128 v[148:151], v241 offset:39168
	ds_read_b128 v[184:187], v242 offset:59904
	ds_read_b128 v[152:155], v241 offset:41472
	ds_read_b128 v[216:219], v242 offset:62208
	ds_read_b128 v[156:159], v241 offset:43776
	s_setprio 1
	s_waitcnt lgkmcnt(6)
	v_mfma_f32_16x16x32_bf16 v[52:55], v[176:179], v[144:147], v[52:55]
	s_waitcnt vmcnt(15)
	ds_write_b128 v213, v[68:71]
	s_waitcnt lgkmcnt(6)
	v_mfma_f32_16x16x32_bf16 v[60:63], v[180:183], v[144:147], v[60:63]
	ds_read_b128 v[160:163], v241 offset:36928
	s_waitcnt lgkmcnt(6)
	v_mfma_f32_16x16x32_bf16 v[56:59], v[176:179], v[148:151], v[56:59]
	ds_read_b128 v[220:223], v242 offset:55360
	s_waitcnt vmcnt(14)
	ds_write_b128 v213, v[76:79] offset:4608
	v_mfma_f32_16x16x32_bf16 v[64:67], v[180:183], v[148:151], v[64:67]
	ds_read_b128 v[224:227], v242 offset:57664
	s_waitcnt lgkmcnt(8)
	v_mfma_f32_16x16x32_bf16 v[36:39], v[184:187], v[144:147], v[36:39]
	ds_read_b128 v[164:167], v241 offset:39232
	s_waitcnt vmcnt(13)
	ds_write_b128 v213, v[80:83] offset:9216
	global_load_dwordx4 v[68:71], v[72:73], off offset:1280
	v_mfma_f32_16x16x32_bf16 v[40:43], v[184:187], v[148:151], v[40:43]
	ds_read_b128 v[228:231], v242 offset:59968
	s_waitcnt lgkmcnt(10)
	v_mfma_f32_16x16x32_bf16 v[20:23], v[176:179], v[152:155], v[20:23]
	ds_read_b128 v[168:171], v241 offset:41536
	v_mfma_f32_16x16x32_bf16 v[28:31], v[180:183], v[152:155], v[28:31]
	ds_read_b128 v[232:235], v242 offset:62272
	v_mfma_f32_16x16x32_bf16 v[4:7], v[184:187], v[152:155], v[4:7]
	ds_read_b128 v[172:175], v241 offset:43840
	s_waitcnt lgkmcnt(12)
	v_mfma_f32_16x16x32_bf16 v[44:47], v[216:219], v[144:147], v[44:47]
	v_mfma_f32_16x16x32_bf16 v[48:51], v[216:219], v[148:151], v[48:51]
	s_waitcnt vmcnt(13)
	ds_write_b128 v213, v[84:87] offset:13824
	global_load_dwordx4 v[76:79], v[74:75], off offset:1280
	v_mfma_f32_16x16x32_bf16 v[12:15], v[216:219], v[152:155], v[12:15]
	s_waitcnt lgkmcnt(12)
	v_mfma_f32_16x16x32_bf16 v[24:27], v[176:179], v[156:159], v[24:27]
	s_waitcnt vmcnt(13)
	ds_write_b128 v213, v[88:91] offset:18432
	global_load_dwordx4 v[80:83], v[106:107], off offset:1280
	v_mfma_f32_16x16x32_bf16 v[32:35], v[180:183], v[156:159], v[32:35]
	v_mfma_f32_16x16x32_bf16 v[8:11], v[184:187], v[156:159], v[8:11]
	v_mfma_f32_16x16x32_bf16 v[16:19], v[216:219], v[156:159], v[16:19]
	s_waitcnt lgkmcnt(10)
	v_mfma_f32_16x16x32_bf16 v[52:55], v[220:223], v[160:163], v[52:55]
	s_waitcnt lgkmcnt(8)
	v_mfma_f32_16x16x32_bf16 v[60:63], v[224:227], v[160:163], v[60:63]
	s_waitcnt lgkmcnt(7)
	v_mfma_f32_16x16x32_bf16 v[56:59], v[220:223], v[164:167], v[56:59]
	s_waitcnt vmcnt(13)
	ds_write_b128 v213, v[92:95] offset:23040
	global_load_dwordx4 v[84:87], v[188:189], off offset:1280
	v_mfma_f32_16x16x32_bf16 v[64:67], v[224:227], v[164:167], v[64:67]
	s_waitcnt lgkmcnt(6)
	v_mfma_f32_16x16x32_bf16 v[36:39], v[228:231], v[160:163], v[36:39]
	s_waitcnt vmcnt(13)
	ds_write_b128 v213, v[96:99] offset:27648
	global_load_dwordx4 v[88:91], v[104:105], off offset:1280
	v_mfma_f32_16x16x32_bf16 v[40:43], v[228:231], v[164:167], v[40:43]
	s_waitcnt lgkmcnt(6)
	v_mfma_f32_16x16x32_bf16 v[20:23], v[220:223], v[168:171], v[20:23]
	s_waitcnt vmcnt(13)
	ds_write_b128 v213, v[100:103] offset:32256
	global_load_dwordx4 v[92:95], v[214:215], off offset:1280
	v_mfma_f32_16x16x32_bf16 v[28:31], v[224:227], v[168:171], v[28:31]
	v_mfma_f32_16x16x32_bf16 v[4:7], v[228:231], v[168:171], v[4:7]
	global_load_dwordx4 v[96:99], v[236:237], off offset:1280
	s_waitcnt lgkmcnt(6)
	v_mfma_f32_16x16x32_bf16 v[44:47], v[232:235], v[160:163], v[44:47]
	v_mfma_f32_16x16x32_bf16 v[48:51], v[232:235], v[164:167], v[48:51]
	global_load_dwordx4 v[100:103], v[238:239], off offset:1280
	v_mfma_f32_16x16x32_bf16 v[12:15], v[232:235], v[168:171], v[12:15]
	s_waitcnt lgkmcnt(5)
	v_mfma_f32_16x16x32_bf16 v[24:27], v[220:223], v[172:175], v[24:27]
	v_mfma_f32_16x16x32_bf16 v[32:35], v[224:227], v[172:175], v[32:35]
	v_mfma_f32_16x16x32_bf16 v[8:11], v[228:231], v[172:175], v[8:11]
	v_mfma_f32_16x16x32_bf16 v[16:19], v[232:235], v[172:175], v[16:19]
	s_setprio 0
	s_waitcnt lgkmcnt(0)
	s_barrier
	ds_read_b128 v[144:147], v241
	ds_read_b128 v[176:179], v242 offset:18432
	ds_read_b128 v[180:183], v242 offset:20736
	ds_read_b128 v[148:151], v241 offset:2304
	ds_read_b128 v[184:187], v242 offset:23040
	ds_read_b128 v[152:155], v241 offset:4608
	ds_read_b128 v[216:219], v242 offset:25344
	ds_read_b128 v[156:159], v241 offset:6912
	s_setprio 1
	s_waitcnt lgkmcnt(6)
	v_mfma_f32_16x16x32_bf16 v[52:55], v[176:179], v[144:147], v[52:55]
	s_waitcnt vmcnt(15)
	ds_write_b128 v240, v[108:111]
	s_waitcnt lgkmcnt(6)
	v_mfma_f32_16x16x32_bf16 v[60:63], v[180:183], v[144:147], v[60:63]
	ds_read_b128 v[160:163], v241 offset:64
	s_waitcnt lgkmcnt(6)
	v_mfma_f32_16x16x32_bf16 v[56:59], v[176:179], v[148:151], v[56:59]
	ds_read_b128 v[220:223], v242 offset:18496
	s_waitcnt vmcnt(14)
	ds_write_b128 v240, v[112:115] offset:4608
	v_mfma_f32_16x16x32_bf16 v[64:67], v[180:183], v[148:151], v[64:67]
	ds_read_b128 v[224:227], v242 offset:20800
	s_waitcnt lgkmcnt(8)
	v_mfma_f32_16x16x32_bf16 v[36:39], v[184:187], v[144:147], v[36:39]
	ds_read_b128 v[164:167], v241 offset:2368
	s_waitcnt vmcnt(13)
	ds_write_b128 v240, v[116:119] offset:9216
	global_load_dwordx4 v[108:111], v[72:73], off offset:1408
	v_mfma_f32_16x16x32_bf16 v[40:43], v[184:187], v[148:151], v[40:43]
	ds_read_b128 v[228:231], v242 offset:23104
	s_waitcnt lgkmcnt(10)
	v_mfma_f32_16x16x32_bf16 v[20:23], v[176:179], v[152:155], v[20:23]
	ds_read_b128 v[168:171], v241 offset:4672
	v_mfma_f32_16x16x32_bf16 v[28:31], v[180:183], v[152:155], v[28:31]
	ds_read_b128 v[232:235], v242 offset:25408
	v_mfma_f32_16x16x32_bf16 v[4:7], v[184:187], v[152:155], v[4:7]
	ds_read_b128 v[172:175], v241 offset:6976
	s_waitcnt lgkmcnt(12)
	v_mfma_f32_16x16x32_bf16 v[44:47], v[216:219], v[144:147], v[44:47]
	v_mfma_f32_16x16x32_bf16 v[48:51], v[216:219], v[148:151], v[48:51]
	s_waitcnt vmcnt(13)
	ds_write_b128 v240, v[120:123] offset:13824
	global_load_dwordx4 v[112:115], v[74:75], off offset:1408
	v_mfma_f32_16x16x32_bf16 v[12:15], v[216:219], v[152:155], v[12:15]
	s_waitcnt lgkmcnt(12)
	v_mfma_f32_16x16x32_bf16 v[24:27], v[176:179], v[156:159], v[24:27]
	s_waitcnt vmcnt(13)
	ds_write_b128 v240, v[124:127] offset:18432
	global_load_dwordx4 v[116:119], v[106:107], off offset:1408
	v_mfma_f32_16x16x32_bf16 v[32:35], v[180:183], v[156:159], v[32:35]
	v_mfma_f32_16x16x32_bf16 v[8:11], v[184:187], v[156:159], v[8:11]
	v_mfma_f32_16x16x32_bf16 v[16:19], v[216:219], v[156:159], v[16:19]
	s_waitcnt lgkmcnt(10)
	v_mfma_f32_16x16x32_bf16 v[52:55], v[220:223], v[160:163], v[52:55]
	s_waitcnt lgkmcnt(8)
	v_mfma_f32_16x16x32_bf16 v[60:63], v[224:227], v[160:163], v[60:63]
	s_waitcnt lgkmcnt(7)
	v_mfma_f32_16x16x32_bf16 v[56:59], v[220:223], v[164:167], v[56:59]
	s_waitcnt vmcnt(13)
	ds_write_b128 v240, v[128:131] offset:23040
	global_load_dwordx4 v[120:123], v[188:189], off offset:1408
	v_mfma_f32_16x16x32_bf16 v[64:67], v[224:227], v[164:167], v[64:67]
	s_waitcnt lgkmcnt(6)
	v_mfma_f32_16x16x32_bf16 v[36:39], v[228:231], v[160:163], v[36:39]
	s_waitcnt vmcnt(13)
	ds_write_b128 v240, v[136:139] offset:27648
	global_load_dwordx4 v[124:127], v[104:105], off offset:1408
	v_mfma_f32_16x16x32_bf16 v[40:43], v[228:231], v[164:167], v[40:43]
	s_waitcnt lgkmcnt(6)
	v_mfma_f32_16x16x32_bf16 v[20:23], v[220:223], v[168:171], v[20:23]
	s_waitcnt vmcnt(13)
	ds_write_b128 v240, v[140:143] offset:32256
	global_load_dwordx4 v[128:131], v[214:215], off offset:1408
	v_mfma_f32_16x16x32_bf16 v[28:31], v[224:227], v[168:171], v[28:31]
	v_mfma_f32_16x16x32_bf16 v[4:7], v[228:231], v[168:171], v[4:7]
	global_load_dwordx4 v[136:139], v[236:237], off offset:1408
	s_waitcnt lgkmcnt(6)
	v_mfma_f32_16x16x32_bf16 v[44:47], v[232:235], v[160:163], v[44:47]
	v_mfma_f32_16x16x32_bf16 v[48:51], v[232:235], v[164:167], v[48:51]
	global_load_dwordx4 v[140:143], v[238:239], off offset:1408
	v_mfma_f32_16x16x32_bf16 v[12:15], v[232:235], v[168:171], v[12:15]
	s_waitcnt lgkmcnt(5)
	v_mfma_f32_16x16x32_bf16 v[24:27], v[220:223], v[172:175], v[24:27]
	v_mfma_f32_16x16x32_bf16 v[32:35], v[224:227], v[172:175], v[32:35]
	v_mfma_f32_16x16x32_bf16 v[8:11], v[228:231], v[172:175], v[8:11]
	v_mfma_f32_16x16x32_bf16 v[16:19], v[232:235], v[172:175], v[16:19]
	s_setprio 0
	s_waitcnt lgkmcnt(0)
	s_barrier
	ds_read_b128 v[144:147], v241 offset:36864
	ds_read_b128 v[176:179], v242 offset:55296
	ds_read_b128 v[180:183], v242 offset:57600
	ds_read_b128 v[148:151], v241 offset:39168
	ds_read_b128 v[184:187], v242 offset:59904
	ds_read_b128 v[152:155], v241 offset:41472
	ds_read_b128 v[216:219], v242 offset:62208
	ds_read_b128 v[156:159], v241 offset:43776
	s_setprio 1
	s_waitcnt lgkmcnt(6)
	v_mfma_f32_16x16x32_bf16 v[52:55], v[176:179], v[144:147], v[52:55]
	s_waitcnt vmcnt(15)
	ds_write_b128 v213, v[68:71]
	s_waitcnt lgkmcnt(6)
	v_mfma_f32_16x16x32_bf16 v[60:63], v[180:183], v[144:147], v[60:63]
	ds_read_b128 v[160:163], v241 offset:36928
	s_waitcnt lgkmcnt(6)
	v_mfma_f32_16x16x32_bf16 v[56:59], v[176:179], v[148:151], v[56:59]
	ds_read_b128 v[220:223], v242 offset:55360
	s_waitcnt vmcnt(14)
	ds_write_b128 v213, v[76:79] offset:4608
	v_mfma_f32_16x16x32_bf16 v[64:67], v[180:183], v[148:151], v[64:67]
	ds_read_b128 v[224:227], v242 offset:57664
	s_waitcnt lgkmcnt(8)
	v_mfma_f32_16x16x32_bf16 v[36:39], v[184:187], v[144:147], v[36:39]
	ds_read_b128 v[164:167], v241 offset:39232
	s_waitcnt vmcnt(13)
	ds_write_b128 v213, v[80:83] offset:9216
	v_mfma_f32_16x16x32_bf16 v[40:43], v[184:187], v[148:151], v[40:43]
	ds_read_b128 v[228:231], v242 offset:59968
	s_waitcnt lgkmcnt(10)
	v_mfma_f32_16x16x32_bf16 v[20:23], v[176:179], v[152:155], v[20:23]
	ds_read_b128 v[168:171], v241 offset:41536
	v_mfma_f32_16x16x32_bf16 v[28:31], v[180:183], v[152:155], v[28:31]
	ds_read_b128 v[232:235], v242 offset:62272
	v_mfma_f32_16x16x32_bf16 v[4:7], v[184:187], v[152:155], v[4:7]
	ds_read_b128 v[172:175], v241 offset:43840
	s_waitcnt lgkmcnt(12)
	v_mfma_f32_16x16x32_bf16 v[44:47], v[216:219], v[144:147], v[44:47]
	v_mfma_f32_16x16x32_bf16 v[48:51], v[216:219], v[148:151], v[48:51]
	s_waitcnt vmcnt(12)
	ds_write_b128 v213, v[84:87] offset:13824
	v_mfma_f32_16x16x32_bf16 v[12:15], v[216:219], v[152:155], v[12:15]
	s_waitcnt lgkmcnt(12)
	v_mfma_f32_16x16x32_bf16 v[24:27], v[176:179], v[156:159], v[24:27]
	s_waitcnt vmcnt(11)
	ds_write_b128 v213, v[88:91] offset:18432
	v_mfma_f32_16x16x32_bf16 v[32:35], v[180:183], v[156:159], v[32:35]
	v_mfma_f32_16x16x32_bf16 v[8:11], v[184:187], v[156:159], v[8:11]
	v_mfma_f32_16x16x32_bf16 v[16:19], v[216:219], v[156:159], v[16:19]
	s_waitcnt lgkmcnt(10)
	v_mfma_f32_16x16x32_bf16 v[52:55], v[220:223], v[160:163], v[52:55]
	s_waitcnt lgkmcnt(8)
	v_mfma_f32_16x16x32_bf16 v[60:63], v[224:227], v[160:163], v[60:63]
	s_waitcnt lgkmcnt(7)
	v_mfma_f32_16x16x32_bf16 v[56:59], v[220:223], v[164:167], v[56:59]
	s_waitcnt vmcnt(10)
	ds_write_b128 v213, v[92:95] offset:23040
	v_mfma_f32_16x16x32_bf16 v[64:67], v[224:227], v[164:167], v[64:67]
	s_waitcnt lgkmcnt(6)
	v_mfma_f32_16x16x32_bf16 v[36:39], v[228:231], v[160:163], v[36:39]
	s_waitcnt vmcnt(9)
	ds_write_b128 v213, v[96:99] offset:27648
	v_mfma_f32_16x16x32_bf16 v[40:43], v[228:231], v[164:167], v[40:43]
	s_waitcnt lgkmcnt(6)
	v_mfma_f32_16x16x32_bf16 v[20:23], v[220:223], v[168:171], v[20:23]
	s_waitcnt vmcnt(8)
	ds_write_b128 v213, v[100:103] offset:32256
	v_mfma_f32_16x16x32_bf16 v[28:31], v[224:227], v[168:171], v[28:31]
	v_mfma_f32_16x16x32_bf16 v[4:7], v[228:231], v[168:171], v[4:7]
	s_waitcnt lgkmcnt(6)
	v_mfma_f32_16x16x32_bf16 v[44:47], v[232:235], v[160:163], v[44:47]
	v_mfma_f32_16x16x32_bf16 v[48:51], v[232:235], v[164:167], v[48:51]
	v_mfma_f32_16x16x32_bf16 v[12:15], v[232:235], v[168:171], v[12:15]
	s_waitcnt lgkmcnt(5)
	v_mfma_f32_16x16x32_bf16 v[24:27], v[220:223], v[172:175], v[24:27]
	v_mfma_f32_16x16x32_bf16 v[32:35], v[224:227], v[172:175], v[32:35]
	v_mfma_f32_16x16x32_bf16 v[8:11], v[228:231], v[172:175], v[8:11]
	v_mfma_f32_16x16x32_bf16 v[16:19], v[232:235], v[172:175], v[16:19]
	s_setprio 0
	s_waitcnt lgkmcnt(0)
	s_barrier
	ds_read_b128 v[144:147], v241
	ds_read_b128 v[176:179], v242 offset:18432
	ds_read_b128 v[180:183], v242 offset:20736
	ds_read_b128 v[148:151], v241 offset:2304
	ds_read_b128 v[184:187], v242 offset:23040
	ds_read_b128 v[152:155], v241 offset:4608
	ds_read_b128 v[216:219], v242 offset:25344
	ds_read_b128 v[156:159], v241 offset:6912
	s_setprio 1
	s_waitcnt lgkmcnt(6)
	v_mfma_f32_16x16x32_bf16 v[52:55], v[176:179], v[144:147], v[52:55]
	s_waitcnt vmcnt(7)
	ds_write_b128 v240, v[108:111]
	s_waitcnt lgkmcnt(6)
	v_mfma_f32_16x16x32_bf16 v[60:63], v[180:183], v[144:147], v[60:63]
	ds_read_b128 v[160:163], v241 offset:64
	s_waitcnt lgkmcnt(6)
	v_mfma_f32_16x16x32_bf16 v[56:59], v[176:179], v[148:151], v[56:59]
	ds_read_b128 v[220:223], v242 offset:18496
	s_waitcnt vmcnt(6)
	ds_write_b128 v240, v[112:115] offset:4608
	v_mfma_f32_16x16x32_bf16 v[64:67], v[180:183], v[148:151], v[64:67]
	ds_read_b128 v[224:227], v242 offset:20800
	s_waitcnt lgkmcnt(8)
	v_mfma_f32_16x16x32_bf16 v[36:39], v[184:187], v[144:147], v[36:39]
	ds_read_b128 v[164:167], v241 offset:2368
	s_waitcnt vmcnt(5)
	ds_write_b128 v240, v[116:119] offset:9216
	v_mfma_f32_16x16x32_bf16 v[40:43], v[184:187], v[148:151], v[40:43]
	ds_read_b128 v[228:231], v242 offset:23104
	s_waitcnt lgkmcnt(10)
	v_mfma_f32_16x16x32_bf16 v[20:23], v[176:179], v[152:155], v[20:23]
	ds_read_b128 v[168:171], v241 offset:4672
	v_mfma_f32_16x16x32_bf16 v[28:31], v[180:183], v[152:155], v[28:31]
	ds_read_b128 v[232:235], v242 offset:25408
	v_mfma_f32_16x16x32_bf16 v[4:7], v[184:187], v[152:155], v[4:7]
	ds_read_b128 v[172:175], v241 offset:6976
	s_waitcnt lgkmcnt(12)
	v_mfma_f32_16x16x32_bf16 v[44:47], v[216:219], v[144:147], v[44:47]
	v_mfma_f32_16x16x32_bf16 v[48:51], v[216:219], v[148:151], v[48:51]
	s_waitcnt vmcnt(4)
	ds_write_b128 v240, v[120:123] offset:13824
	v_mfma_f32_16x16x32_bf16 v[12:15], v[216:219], v[152:155], v[12:15]
	s_waitcnt lgkmcnt(12)
	v_mfma_f32_16x16x32_bf16 v[24:27], v[176:179], v[156:159], v[24:27]
	s_waitcnt vmcnt(3)
	ds_write_b128 v240, v[124:127] offset:18432
	v_mfma_f32_16x16x32_bf16 v[32:35], v[180:183], v[156:159], v[32:35]
	v_mfma_f32_16x16x32_bf16 v[8:11], v[184:187], v[156:159], v[8:11]
	v_mfma_f32_16x16x32_bf16 v[16:19], v[216:219], v[156:159], v[16:19]
	s_waitcnt lgkmcnt(10)
	v_mfma_f32_16x16x32_bf16 v[52:55], v[220:223], v[160:163], v[52:55]
	s_waitcnt lgkmcnt(8)
	v_mfma_f32_16x16x32_bf16 v[60:63], v[224:227], v[160:163], v[60:63]
	s_waitcnt lgkmcnt(7)
	v_mfma_f32_16x16x32_bf16 v[56:59], v[220:223], v[164:167], v[56:59]
	s_waitcnt vmcnt(2)
	ds_write_b128 v240, v[128:131] offset:23040
	v_mfma_f32_16x16x32_bf16 v[64:67], v[224:227], v[164:167], v[64:67]
	s_waitcnt lgkmcnt(6)
	v_mfma_f32_16x16x32_bf16 v[36:39], v[228:231], v[160:163], v[36:39]
	s_waitcnt vmcnt(1)
	ds_write_b128 v240, v[136:139] offset:27648
	v_mfma_f32_16x16x32_bf16 v[40:43], v[228:231], v[164:167], v[40:43]
	s_waitcnt lgkmcnt(6)
	v_mfma_f32_16x16x32_bf16 v[20:23], v[220:223], v[168:171], v[20:23]
	s_waitcnt vmcnt(0)
	ds_write_b128 v240, v[140:143] offset:32256
	v_mfma_f32_16x16x32_bf16 v[28:31], v[224:227], v[168:171], v[28:31]
	v_mfma_f32_16x16x32_bf16 v[4:7], v[228:231], v[168:171], v[4:7]
	s_waitcnt lgkmcnt(6)
	v_mfma_f32_16x16x32_bf16 v[44:47], v[232:235], v[160:163], v[44:47]
	v_mfma_f32_16x16x32_bf16 v[48:51], v[232:235], v[164:167], v[48:51]
	v_mfma_f32_16x16x32_bf16 v[12:15], v[232:235], v[168:171], v[12:15]
	s_waitcnt lgkmcnt(5)
	v_mfma_f32_16x16x32_bf16 v[24:27], v[220:223], v[172:175], v[24:27]
	v_mfma_f32_16x16x32_bf16 v[32:35], v[224:227], v[172:175], v[32:35]
	v_mfma_f32_16x16x32_bf16 v[8:11], v[228:231], v[172:175], v[8:11]
	v_mfma_f32_16x16x32_bf16 v[16:19], v[232:235], v[172:175], v[16:19]
	s_setprio 0
	s_waitcnt lgkmcnt(0)
	s_barrier
	ds_read_b128 v[144:147], v241 offset:36864
	ds_read_b128 v[176:179], v242 offset:55296
	ds_read_b128 v[180:183], v242 offset:57600
	ds_read_b128 v[148:151], v241 offset:39168
	ds_read_b128 v[184:187], v242 offset:59904
	ds_read_b128 v[152:155], v241 offset:41472
	ds_read_b128 v[216:219], v242 offset:62208
	ds_read_b128 v[156:159], v241 offset:43776
	s_setprio 1
	s_waitcnt lgkmcnt(6)
	v_mfma_f32_16x16x32_bf16 v[52:55], v[176:179], v[144:147], v[52:55]
	s_waitcnt lgkmcnt(5)
	v_mfma_f32_16x16x32_bf16 v[60:63], v[180:183], v[144:147], v[60:63]
	ds_read_b128 v[160:163], v241 offset:36928
	s_waitcnt lgkmcnt(5)
	v_mfma_f32_16x16x32_bf16 v[56:59], v[176:179], v[148:151], v[56:59]
	ds_read_b128 v[220:223], v242 offset:55360
	v_mfma_f32_16x16x32_bf16 v[64:67], v[180:183], v[148:151], v[64:67]
	ds_read_b128 v[224:227], v242 offset:57664
	s_waitcnt lgkmcnt(6)
	v_mfma_f32_16x16x32_bf16 v[36:39], v[184:187], v[144:147], v[36:39]
	ds_read_b128 v[164:167], v241 offset:39232
	v_mfma_f32_16x16x32_bf16 v[40:43], v[184:187], v[148:151], v[40:43]
	ds_read_b128 v[228:231], v242 offset:59968
	s_waitcnt lgkmcnt(7)
	v_mfma_f32_16x16x32_bf16 v[20:23], v[176:179], v[152:155], v[20:23]
	ds_read_b128 v[168:171], v241 offset:41536
	v_mfma_f32_16x16x32_bf16 v[28:31], v[180:183], v[152:155], v[28:31]
	ds_read_b128 v[232:235], v242 offset:62272
	v_mfma_f32_16x16x32_bf16 v[4:7], v[184:187], v[152:155], v[4:7]
	ds_read_b128 v[172:175], v241 offset:43840
	s_waitcnt lgkmcnt(9)
	v_mfma_f32_16x16x32_bf16 v[44:47], v[216:219], v[144:147], v[44:47]
	v_mfma_f32_16x16x32_bf16 v[48:51], v[216:219], v[148:151], v[48:51]
	v_mfma_f32_16x16x32_bf16 v[12:15], v[216:219], v[152:155], v[12:15]
	s_waitcnt lgkmcnt(8)
	v_mfma_f32_16x16x32_bf16 v[24:27], v[176:179], v[156:159], v[24:27]
	v_mfma_f32_16x16x32_bf16 v[32:35], v[180:183], v[156:159], v[32:35]
	v_mfma_f32_16x16x32_bf16 v[8:11], v[184:187], v[156:159], v[8:11]
	v_mfma_f32_16x16x32_bf16 v[16:19], v[216:219], v[156:159], v[16:19]
	s_waitcnt lgkmcnt(6)
	v_mfma_f32_16x16x32_bf16 v[52:55], v[220:223], v[160:163], v[52:55]
	s_waitcnt lgkmcnt(5)
	v_mfma_f32_16x16x32_bf16 v[60:63], v[224:227], v[160:163], v[60:63]
	s_waitcnt lgkmcnt(4)
	v_mfma_f32_16x16x32_bf16 v[56:59], v[220:223], v[164:167], v[56:59]
	v_mfma_f32_16x16x32_bf16 v[64:67], v[224:227], v[164:167], v[64:67]
	s_waitcnt lgkmcnt(3)
	v_mfma_f32_16x16x32_bf16 v[36:39], v[228:231], v[160:163], v[36:39]
	v_mfma_f32_16x16x32_bf16 v[40:43], v[228:231], v[164:167], v[40:43]
	s_waitcnt lgkmcnt(2)
	v_mfma_f32_16x16x32_bf16 v[20:23], v[220:223], v[168:171], v[20:23]
	v_mfma_f32_16x16x32_bf16 v[28:31], v[224:227], v[168:171], v[28:31]
	v_mfma_f32_16x16x32_bf16 v[4:7], v[228:231], v[168:171], v[4:7]
	s_waitcnt lgkmcnt(1)
	v_mfma_f32_16x16x32_bf16 v[44:47], v[232:235], v[160:163], v[44:47]
	v_mfma_f32_16x16x32_bf16 v[48:51], v[232:235], v[164:167], v[48:51]
	v_mfma_f32_16x16x32_bf16 v[12:15], v[232:235], v[168:171], v[12:15]
	s_waitcnt lgkmcnt(0)
	v_mfma_f32_16x16x32_bf16 v[24:27], v[220:223], v[172:175], v[24:27]
	v_mfma_f32_16x16x32_bf16 v[32:35], v[224:227], v[172:175], v[32:35]
	v_mfma_f32_16x16x32_bf16 v[8:11], v[228:231], v[172:175], v[8:11]
	v_mfma_f32_16x16x32_bf16 v[16:19], v[232:235], v[172:175], v[16:19]
	s_setprio 0
	s_barrier
	s_nop 7
	s_nop 4
	s_nop 4
	v_permlane16_swap_b32_e32 v52, v56
	v_permlane16_swap_b32_e32 v53, v57
	v_permlane16_swap_b32_e32 v54, v58
	v_permlane16_swap_b32_e32 v55, v59
	v_permlane16_swap_b32_e32 v60, v64
	v_permlane16_swap_b32_e32 v61, v65
	v_permlane16_swap_b32_e32 v62, v66
	v_permlane16_swap_b32_e32 v63, v67
	v_permlane16_swap_b32_e32 v36, v40
	v_permlane16_swap_b32_e32 v37, v41
	v_permlane16_swap_b32_e32 v38, v42
	v_permlane16_swap_b32_e32 v39, v43
	v_permlane16_swap_b32_e32 v44, v48
	v_permlane16_swap_b32_e32 v45, v49
	v_permlane16_swap_b32_e32 v46, v50
	v_permlane16_swap_b32_e32 v47, v51
	v_permlane16_swap_b32_e32 v20, v24
	v_permlane16_swap_b32_e32 v21, v25
	v_permlane16_swap_b32_e32 v22, v26
	v_permlane16_swap_b32_e32 v23, v27
	v_permlane16_swap_b32_e32 v28, v32
	v_permlane16_swap_b32_e32 v29, v33
	v_permlane16_swap_b32_e32 v30, v34
	v_permlane16_swap_b32_e32 v31, v35
	v_permlane16_swap_b32_e32 v4, v8
	v_permlane16_swap_b32_e32 v5, v9
	v_permlane16_swap_b32_e32 v6, v10
	v_permlane16_swap_b32_e32 v7, v11
	v_permlane16_swap_b32_e32 v12, v16
	v_permlane16_swap_b32_e32 v13, v17
	v_permlane16_swap_b32_e32 v14, v18
	v_permlane16_swap_b32_e32 v15, v19
	s_nop 1
	v_permlane32_swap_b32_e32 v52, v56
	v_permlane32_swap_b32_e32 v53, v57
	v_permlane32_swap_b32_e32 v54, v58
	v_permlane32_swap_b32_e32 v55, v59
	v_permlane32_swap_b32_e32 v60, v64
	v_permlane32_swap_b32_e32 v61, v65
	v_permlane32_swap_b32_e32 v62, v66
	v_permlane32_swap_b32_e32 v63, v67
	v_permlane32_swap_b32_e32 v36, v40
	v_permlane32_swap_b32_e32 v37, v41
	v_permlane32_swap_b32_e32 v38, v42
	v_permlane32_swap_b32_e32 v39, v43
	v_permlane32_swap_b32_e32 v44, v48
	v_permlane32_swap_b32_e32 v45, v49
	v_permlane32_swap_b32_e32 v46, v50
	v_permlane32_swap_b32_e32 v47, v51
	v_permlane32_swap_b32_e32 v20, v24
	v_permlane32_swap_b32_e32 v21, v25
	v_permlane32_swap_b32_e32 v22, v26
	v_permlane32_swap_b32_e32 v23, v27
	v_permlane32_swap_b32_e32 v28, v32
	v_permlane32_swap_b32_e32 v29, v33
	v_permlane32_swap_b32_e32 v30, v34
	v_permlane32_swap_b32_e32 v31, v35
	v_permlane32_swap_b32_e32 v4, v8
	v_permlane32_swap_b32_e32 v5, v9
	v_permlane32_swap_b32_e32 v6, v10
	v_permlane32_swap_b32_e32 v7, v11
	v_permlane32_swap_b32_e32 v12, v16
	v_permlane32_swap_b32_e32 v13, v17
	v_permlane32_swap_b32_e32 v14, v18
	v_permlane32_swap_b32_e32 v15, v19
	s_nop 1
	s_branch .LBB0_574
